# GEMM loops: all 16 LDS-DMA loads per iteration in saddr form (scalar base + lane offset), address chains kept in SGPRs; no VALU in load segments
# baseline (speedup 1.0000x reference)
; #define PG8_STAGE(bufoff, gbase, voff) do { _Pragma("unroll") for (int _i = 0; _i < 2; ++_i) \
;         __builtin_amdgcn_global_load_lds((const unsigned*)((const char*)(gbase) + (voff)[_i]), (LAS unsigned*)(lds + (bufoff) + ldsw + _i * 8192), 16, 0, 0); } while (0)
; #define PG8_LDA(dst, b, h) do { _Pragma("unroll") for (int m = 0; m < 4; ++m) _Pragma("unroll") for (int k = 0; k < 2; ++k) dst[m][k] = *(const LAS bf16x8*)(lds + PG8_SA(b, h) + aoff + m * 2048 + k * 1024); } while (0)
; #define PG8_LDB(dst, b, h) do { _Pragma("unroll") for (int n = 0; n < 2; ++n) _Pragma("unroll") for (int k = 0; k < 2; ++k) dst[n][k] = *(const LAS bf16x8*)(lds + PG8_SB(b, h) + boff + n * 2048 + k * 1024); } while (0)
; #define PG8_MMA(ai, bj, At, Bt) do { __builtin_amdgcn_s_setprio(1); _Pragma("unroll") for (int m = 0; m < 4; ++m) _Pragma("unroll") for (int n = 0; n < 2; ++n) _Pragma("unroll") for (int k = 0; k < 2; ++k) \
;         acc[ai][bj][m][n] = __builtin_amdgcn_mfma_f32_16x16x32_bf16(Bt[n][k], At[m][k], acc[ai][bj][m][n], 0, 0, 0); __builtin_amdgcn_s_setprio(0); } while (0)
; #define PG8_WAIT_V(n) asm volatile("s_waitcnt vmcnt(" #n ")" ::: "memory")
; #define PG8_BAR __builtin_amdgcn_s_barrier()
; template <class Sched, class Epi>
; __device__ __forceinline__ void gemm_phase(LAS unsigned char* lds, const Sched& S, const Epi& E, const int K, const int lda, const int ldb) {
;     ...
;         for (int t = 0; t < nt; t += 2) {
;             const bool last = (t == nt - 2);
;             const char* a1 = cA + (size_t)(t + 1) * kstep;
;             const char* a2 = last ? nA : cA + (size_t)(t + 2) * kstep; const char* b2 = last ? nB : cB + (size_t)(t + 2) * kstep;
;             const char* a3 = a2 + kstep; const char* b3 = b2 + kstep;
;             PG8_LDB(B0, 0, 0); PG8_SCHED; PG8_LDA(At, 0, 0); PG8_STAGE(PG8_SA(1, 1), a1 + hstepA, voffA);
;             PG8_WAIT_L(8); PG8_BAR; PG8_WAIT_L(0); PG8_MMA(0, 0, At, B0); PG8_BAR; PG8_SCHED;
;             PG8_LDB(B1, 0, 1); PG8_STAGE(PG8_SB(0, 0), b2, voffB);
;             PG8_BAR; PG8_WAIT_L(0); PG8_MMA(0, 1, At, B1); PG8_BAR;
;             PG8_LDA(At, 0, 1); PG8_STAGE(PG8_SA(0, 0), a2, voffA);
;             PG8_BAR; PG8_WAIT_L(0); if (!chalf) PG8_MMA(1, 0, At, B0); PG8_BAR; PG8_SCHED;
;             PG8_STAGE(PG8_SB(0, 1), b2 + hstepB, voffB);
;             PG8_WAIT_V(6); PG8_BAR; if (!chalf) PG8_MMA(1, 1, At, B1); PG8_BAR;
.LBB0_393:
	ds_read_b128 v[146:149], v228
	ds_read_b128 v[150:153], v228 offset:1024
	ds_read_b128 v[154:157], v228 offset:2048
	ds_read_b128 v[158:161], v228 offset:3072
	s_add_u32 s4, s38, 0xfff80080
	s_addc_u32 s5, s39, -1
	s_cmp_eq_u32 s27, 28
	s_cselect_b32 s43, s29, s5
	s_cselect_b32 s42, s28, s4
	s_cselect_b32 s41, s35, s21
	s_cselect_b32 s40, s34, s19
	s_add_i32 m0, s10, 0xc000
	s_waitcnt lgkmcnt(0)
	ds_read_b128 v[162:165], v229
	ds_read_b128 v[166:169], v229 offset:1024
	ds_read_b128 v[170:173], v229 offset:2048
	ds_read_b128 v[174:177], v229 offset:3072
	ds_read_b128 v[178:181], v229 offset:4096
	ds_read_b128 v[182:185], v229 offset:5120
	ds_read_b128 v[186:189], v229 offset:6144
	ds_read_b128 v[190:193], v229 offset:7168
	global_load_lds_dwordx4 v206, s[38:39]
	s_add_i32 m0, s10, 0xe000
	s_nop 0
	global_load_lds_dwordx4 v204, s[38:39]
	s_waitcnt lgkmcnt(8)
	s_barrier
	s_waitcnt lgkmcnt(0)
	s_setprio 1
	s_waitcnt lgkmcnt(0)
	v_mfma_f32_16x16x32_bf16 v[126:129], v[146:149], v[162:165], v[126:129]
	v_mfma_f32_16x16x32_bf16 v[122:125], v[154:157], v[162:165], v[122:125]
	v_mfma_f32_16x16x32_bf16 v[114:117], v[146:149], v[170:173], v[114:117]
	v_mfma_f32_16x16x32_bf16 v[106:109], v[154:157], v[170:173], v[106:109]
	v_mfma_f32_16x16x32_bf16 v[98:101], v[146:149], v[178:181], v[98:101]
	v_mfma_f32_16x16x32_bf16 v[90:93], v[154:157], v[178:181], v[90:93]
	v_mfma_f32_16x16x32_bf16 v[82:85], v[146:149], v[186:189], v[82:85]
	v_mfma_f32_16x16x32_bf16 v[74:77], v[154:157], v[186:189], v[74:77]
	v_mfma_f32_16x16x32_bf16 v[126:129], v[150:153], v[166:169], v[126:129]
	v_mfma_f32_16x16x32_bf16 v[122:125], v[158:161], v[166:169], v[122:125]
	v_mfma_f32_16x16x32_bf16 v[114:117], v[150:153], v[174:177], v[114:117]
	v_mfma_f32_16x16x32_bf16 v[106:109], v[158:161], v[174:177], v[106:109]
	v_mfma_f32_16x16x32_bf16 v[98:101], v[150:153], v[182:185], v[98:101]
	v_mfma_f32_16x16x32_bf16 v[90:93], v[158:161], v[182:185], v[90:93]
	v_mfma_f32_16x16x32_bf16 v[82:85], v[150:153], v[190:193], v[82:85]
	v_mfma_f32_16x16x32_bf16 v[74:77], v[158:161], v[190:193], v[74:77]
	s_setprio 0
	s_barrier
	s_add_i32 s4, s54, s9
	s_add_u32 s60, s40, s14
	s_addc_u32 s61, s41, s15
	s_mov_b32 m0, s4
	ds_read_b128 v[130:133], v231
	ds_read_b128 v[134:137], v231 offset:1024
	ds_read_b128 v[138:141], v231 offset:2048
	ds_read_b128 v[142:145], v231 offset:3072
	global_load_lds_dwordx4 v196, s[40:41]
	s_add_u32 s62, s40, s14
	s_addc_u32 s63, s41, s15
	s_add_i32 m0, s4, 0x2000
	s_nop 0
	global_load_lds_dwordx4 v200, s[40:41]
	s_barrier
	s_waitcnt lgkmcnt(0)
	s_setprio 1
	s_waitcnt lgkmcnt(0)
	v_mfma_f32_16x16x32_bf16 v[118:121], v[130:133], v[162:165], v[118:121]
	v_mfma_f32_16x16x32_bf16 v[110:113], v[138:141], v[162:165], v[110:113]
	v_mfma_f32_16x16x32_bf16 v[102:105], v[130:133], v[170:173], v[102:105]
	v_mfma_f32_16x16x32_bf16 v[94:97], v[138:141], v[170:173], v[94:97]
	v_mfma_f32_16x16x32_bf16 v[86:89], v[130:133], v[178:181], v[86:89]
	v_mfma_f32_16x16x32_bf16 v[78:81], v[138:141], v[178:181], v[78:81]
	v_mfma_f32_16x16x32_bf16 v[70:73], v[130:133], v[186:189], v[70:73]
	v_mfma_f32_16x16x32_bf16 v[66:69], v[138:141], v[186:189], v[66:69]
	v_mfma_f32_16x16x32_bf16 v[118:121], v[134:137], v[166:169], v[118:121]
	v_mfma_f32_16x16x32_bf16 v[110:113], v[142:145], v[166:169], v[110:113]
	v_mfma_f32_16x16x32_bf16 v[102:105], v[134:137], v[174:177], v[102:105]
	v_mfma_f32_16x16x32_bf16 v[94:97], v[142:145], v[174:177], v[94:97]
	v_mfma_f32_16x16x32_bf16 v[86:89], v[134:137], v[182:185], v[86:89]
	v_mfma_f32_16x16x32_bf16 v[78:81], v[142:145], v[182:185], v[78:81]
	v_mfma_f32_16x16x32_bf16 v[70:73], v[134:137], v[190:193], v[70:73]
	v_mfma_f32_16x16x32_bf16 v[66:69], v[142:145], v[190:193], v[66:69]
	s_setprio 0
	s_mov_b32 m0, s10
	s_add_u32 s64, s42, s14
	s_addc_u32 s65, s43, s15
	s_barrier
	ds_read_b128 v[186:189], v229 offset:16384
	ds_read_b128 v[190:193], v229 offset:17408
	ds_read_b128 v[178:181], v229 offset:18432
	ds_read_b128 v[182:185], v229 offset:19456
	ds_read_b128 v[170:173], v229 offset:20480
	ds_read_b128 v[174:177], v229 offset:21504
	ds_read_b128 v[162:165], v229 offset:22528
	ds_read_b128 v[166:169], v229 offset:23552
	global_load_lds_dwordx4 v194, s[42:43]
	s_add_u32 s66, s42, s14
	s_addc_u32 s67, s43, s15
	s_mov_b32 m0, s11
	v_cmp_ne_u32_e64 s[4:5], 1, v232
	global_load_lds_dwordx4 v198, s[42:43]
	s_barrier
	s_waitcnt lgkmcnt(0)
	s_andn2_b64 vcc, exec, s[36:37]
	s_cbranch_vccnz .LBB0_395
	s_setprio 1
	s_waitcnt lgkmcnt(0)
	v_mfma_f32_16x16x32_bf16 v[62:65], v[146:149], v[186:189], v[62:65]
	v_mfma_f32_16x16x32_bf16 v[58:61], v[154:157], v[186:189], v[58:61]
	v_mfma_f32_16x16x32_bf16 v[46:49], v[146:149], v[178:181], v[46:49]
	v_mfma_f32_16x16x32_bf16 v[42:45], v[154:157], v[178:181], v[42:45]
	v_mfma_f32_16x16x32_bf16 v[30:33], v[146:149], v[170:173], v[30:33]
	v_mfma_f32_16x16x32_bf16 v[26:29], v[154:157], v[170:173], v[26:29]
	v_mfma_f32_16x16x32_bf16 v[14:17], v[146:149], v[162:165], v[14:17]
	v_mfma_f32_16x16x32_bf16 v[10:13], v[154:157], v[162:165], v[10:13]
	v_mfma_f32_16x16x32_bf16 v[62:65], v[150:153], v[190:193], v[62:65]
	v_mfma_f32_16x16x32_bf16 v[58:61], v[158:161], v[190:193], v[58:61]
	v_mfma_f32_16x16x32_bf16 v[46:49], v[150:153], v[182:185], v[46:49]
	v_mfma_f32_16x16x32_bf16 v[42:45], v[158:161], v[182:185], v[42:45]
	v_mfma_f32_16x16x32_bf16 v[30:33], v[150:153], v[174:177], v[30:33]
	v_mfma_f32_16x16x32_bf16 v[26:29], v[158:161], v[174:177], v[26:29]
	v_mfma_f32_16x16x32_bf16 v[14:17], v[150:153], v[166:169], v[14:17]
	v_mfma_f32_16x16x32_bf16 v[10:13], v[158:161], v[166:169], v[10:13]
	s_setprio 0

; #define PG8_STAGE(bufoff, gbase, voff) do { _Pragma("unroll") for (int _i = 0; _i < 2; ++_i) \
;         __builtin_amdgcn_global_load_lds((const unsigned*)((const char*)(gbase) + (voff)[_i]), (LAS unsigned*)(lds + (bufoff) + ldsw + _i * 8192), 16, 0, 0); } while (0)
; #define PG8_LDA(dst, b, h) do { _Pragma("unroll") for (int m = 0; m < 4; ++m) _Pragma("unroll") for (int k = 0; k < 2; ++k) dst[m][k] = *(const LAS bf16x8*)(lds + PG8_SA(b, h) + aoff + m * 2048 + k * 1024); } while (0)
; #define PG8_LDB(dst, b, h) do { _Pragma("unroll") for (int n = 0; n < 2; ++n) _Pragma("unroll") for (int k = 0; k < 2; ++k) dst[n][k] = *(const LAS bf16x8*)(lds + PG8_SB(b, h) + boff + n * 2048 + k * 1024); } while (0)
; #define PG8_MMA(ai, bj, At, Bt) do { __builtin_amdgcn_s_setprio(1); _Pragma("unroll") for (int m = 0; m < 4; ++m) _Pragma("unroll") for (int n = 0; n < 2; ++n) _Pragma("unroll") for (int k = 0; k < 2; ++k) \
;         acc[ai][bj][m][n] = __builtin_amdgcn_mfma_f32_16x16x32_bf16(Bt[n][k], At[m][k], acc[ai][bj][m][n], 0, 0, 0); __builtin_amdgcn_s_setprio(0); } while (0)
; #define PG8_WAIT_V(n) asm volatile("s_waitcnt vmcnt(" #n ")" ::: "memory")
; #define PG8_WAIT_L(n) asm volatile("s_waitcnt lgkmcnt(" #n ")" ::: "memory")
; #define PG8_BAR __builtin_amdgcn_s_barrier()
; #define PG8_SCHED __builtin_amdgcn_sched_barrier(0)
; template <class Sched, class Epi>
; __device__ __forceinline__ void gemm_phase(LAS unsigned char* lds, const Sched& S, const Epi& E, const int K, const int lda, const int ldb) {
;     ...
;             PG8_STAGE(PG8_SB(0, 1), b2 + hstepB, voffB);
;             PG8_WAIT_V(6); PG8_BAR; if (!chalf) PG8_MMA(1, 1, At, B1); PG8_BAR;
;             PG8_LDB(B0, 1, 0); PG8_SCHED; PG8_LDA(At, 1, 0); PG8_STAGE(PG8_SA(0, 1), a2 + hstepA, voffA);
;             PG8_WAIT_L(8); PG8_BAR; PG8_WAIT_L(0); PG8_MMA(0, 0, At, B0); PG8_BAR; PG8_SCHED;
;             PG8_LDB(B1, 1, 1); PG8_STAGE(PG8_SB(1, 0), b3, voffB);
;             PG8_BAR; PG8_WAIT_L(0); PG8_MMA(0, 1, At, B1); PG8_BAR;
;             PG8_LDA(At, 1, 1); PG8_STAGE(PG8_SA(1, 0), a3, voffA);
;             PG8_BAR; PG8_WAIT_L(0); if (!chalf) PG8_MMA(1, 0, At, B0); PG8_BAR; PG8_SCHED;
;             PG8_STAGE(PG8_SB(1, 1), b3 + hstepB, voffB);
;             PG8_WAIT_V(6); PG8_BAR; if (!chalf) PG8_MMA(1, 1, At, B1); PG8_BAR;
.LBB0_397:
	s_add_i32 s57, 16, 0x18000
	v_add_u32_e32 v130, s57, v220
	s_barrier
	ds_read_b128 v[146:149], v130
	ds_read_b128 v[150:153], v130 offset:1024
	ds_read_b128 v[154:157], v130 offset:2048
	ds_read_b128 v[158:161], v130 offset:3072
	s_add_u32 s42, s42, 0x80000
	s_addc_u32 s43, s43, 0
	s_mov_b32 m0, s31
	s_waitcnt lgkmcnt(0)
	ds_read_b128 v[162:165], v229 offset:32768
	ds_read_b128 v[166:169], v229 offset:33792
	ds_read_b128 v[170:173], v229 offset:34816
	ds_read_b128 v[174:177], v229 offset:35840
	ds_read_b128 v[178:181], v229 offset:36864
	ds_read_b128 v[182:185], v229 offset:37888
	ds_read_b128 v[186:189], v229 offset:38912
	ds_read_b128 v[190:193], v229 offset:39936
	global_load_lds_dwordx4 v194, s[42:43]
	s_mov_b32 m0, s33
	s_nop 0
	global_load_lds_dwordx4 v198, s[42:43]
	s_waitcnt lgkmcnt(8)
	s_barrier
	s_waitcnt lgkmcnt(0)
	s_setprio 1
	s_waitcnt lgkmcnt(0)
	v_mfma_f32_16x16x32_bf16 v[126:129], v[146:149], v[162:165], v[126:129]
	v_mfma_f32_16x16x32_bf16 v[122:125], v[154:157], v[162:165], v[122:125]
	v_mfma_f32_16x16x32_bf16 v[114:117], v[146:149], v[170:173], v[114:117]
	v_mfma_f32_16x16x32_bf16 v[106:109], v[154:157], v[170:173], v[106:109]
	v_mfma_f32_16x16x32_bf16 v[98:101], v[146:149], v[178:181], v[98:101]
	v_mfma_f32_16x16x32_bf16 v[90:93], v[154:157], v[178:181], v[90:93]
	v_mfma_f32_16x16x32_bf16 v[82:85], v[146:149], v[186:189], v[82:85]
	v_mfma_f32_16x16x32_bf16 v[74:77], v[154:157], v[186:189], v[74:77]
	v_mfma_f32_16x16x32_bf16 v[126:129], v[150:153], v[166:169], v[126:129]
	v_mfma_f32_16x16x32_bf16 v[122:125], v[158:161], v[166:169], v[122:125]
	v_mfma_f32_16x16x32_bf16 v[114:117], v[150:153], v[174:177], v[114:117]
	v_mfma_f32_16x16x32_bf16 v[106:109], v[158:161], v[174:177], v[106:109]
	v_mfma_f32_16x16x32_bf16 v[98:101], v[150:153], v[182:185], v[98:101]
	v_mfma_f32_16x16x32_bf16 v[90:93], v[158:161], v[182:185], v[90:93]
	v_mfma_f32_16x16x32_bf16 v[82:85], v[150:153], v[190:193], v[82:85]
	v_mfma_f32_16x16x32_bf16 v[74:77], v[158:161], v[190:193], v[74:77]
	s_setprio 0
	s_barrier
	s_add_i32 s42, s57, s9
	v_add_u32_e32 v142, 0x1c000, v230
	s_mov_b32 m0, s42
	ds_read_b128 v[130:133], v142
	ds_read_b128 v[134:137], v142 offset:1024
	ds_read_b128 v[138:141], v142 offset:2048
	ds_read_b128 v[142:145], v142 offset:3072
	global_load_lds_dwordx4 v196, s[60:61]
	s_add_i32 m0, s42, 0x2000
	s_nop 0
	global_load_lds_dwordx4 v200, s[62:63]
	s_barrier
	s_waitcnt lgkmcnt(0)
	s_setprio 1
	s_waitcnt lgkmcnt(0)
	v_mfma_f32_16x16x32_bf16 v[118:121], v[130:133], v[162:165], v[118:121]
	v_mfma_f32_16x16x32_bf16 v[110:113], v[138:141], v[162:165], v[110:113]
	v_mfma_f32_16x16x32_bf16 v[102:105], v[130:133], v[170:173], v[102:105]
	v_mfma_f32_16x16x32_bf16 v[94:97], v[138:141], v[170:173], v[94:97]
	v_mfma_f32_16x16x32_bf16 v[86:89], v[130:133], v[178:181], v[86:89]
	v_mfma_f32_16x16x32_bf16 v[78:81], v[138:141], v[178:181], v[78:81]
	v_mfma_f32_16x16x32_bf16 v[70:73], v[130:133], v[186:189], v[70:73]
	v_mfma_f32_16x16x32_bf16 v[66:69], v[138:141], v[186:189], v[66:69]
	v_mfma_f32_16x16x32_bf16 v[118:121], v[134:137], v[166:169], v[118:121]
	v_mfma_f32_16x16x32_bf16 v[110:113], v[142:145], v[166:169], v[110:113]
	v_mfma_f32_16x16x32_bf16 v[102:105], v[134:137], v[174:177], v[102:105]
	v_mfma_f32_16x16x32_bf16 v[94:97], v[142:145], v[174:177], v[94:97]
	v_mfma_f32_16x16x32_bf16 v[86:89], v[134:137], v[182:185], v[86:89]
	v_mfma_f32_16x16x32_bf16 v[78:81], v[142:145], v[182:185], v[78:81]
	v_mfma_f32_16x16x32_bf16 v[70:73], v[134:137], v[190:193], v[70:73]
	v_mfma_f32_16x16x32_bf16 v[66:69], v[142:145], v[190:193], v[66:69]
	s_setprio 0
	s_mov_b32 m0, s46
	s_barrier
	ds_read_b128 v[186:189], v229 offset:49152
	ds_read_b128 v[190:193], v229 offset:50176
	ds_read_b128 v[178:181], v229 offset:51200
	ds_read_b128 v[182:185], v229 offset:52224
	ds_read_b128 v[170:173], v229 offset:53248
	ds_read_b128 v[174:177], v229 offset:54272
	ds_read_b128 v[162:165], v229 offset:55296
	ds_read_b128 v[166:169], v229 offset:56320
	global_load_lds_dwordx4 v194, s[64:65]
	s_mov_b32 m0, s47
	s_and_b64 vcc, exec, s[4:5]
	global_load_lds_dwordx4 v198, s[66:67]
	s_barrier
	s_waitcnt lgkmcnt(0)
	s_cbranch_vccnz .LBB0_399
	s_setprio 1
	s_waitcnt lgkmcnt(0)
	v_mfma_f32_16x16x32_bf16 v[62:65], v[146:149], v[186:189], v[62:65]
	v_mfma_f32_16x16x32_bf16 v[58:61], v[154:157], v[186:189], v[58:61]
	v_mfma_f32_16x16x32_bf16 v[46:49], v[146:149], v[178:181], v[46:49]
	v_mfma_f32_16x16x32_bf16 v[42:45], v[154:157], v[178:181], v[42:45]
	v_mfma_f32_16x16x32_bf16 v[30:33], v[146:149], v[170:173], v[30:33]
	v_mfma_f32_16x16x32_bf16 v[26:29], v[154:157], v[170:173], v[26:29]
	v_mfma_f32_16x16x32_bf16 v[14:17], v[146:149], v[162:165], v[14:17]
	v_mfma_f32_16x16x32_bf16 v[10:13], v[154:157], v[162:165], v[10:13]
	v_mfma_f32_16x16x32_bf16 v[62:65], v[150:153], v[190:193], v[62:65]
	v_mfma_f32_16x16x32_bf16 v[58:61], v[158:161], v[190:193], v[58:61]
	v_mfma_f32_16x16x32_bf16 v[46:49], v[150:153], v[182:185], v[46:49]
	v_mfma_f32_16x16x32_bf16 v[42:45], v[158:161], v[182:185], v[42:45]
	v_mfma_f32_16x16x32_bf16 v[30:33], v[150:153], v[174:177], v[30:33]
	v_mfma_f32_16x16x32_bf16 v[26:29], v[158:161], v[174:177], v[26:29]
	v_mfma_f32_16x16x32_bf16 v[14:17], v[150:153], v[166:169], v[14:17]
	v_mfma_f32_16x16x32_bf16 v[10:13], v[158:161], v[166:169], v[10:13]
	s_setprio 0

; #define PG8_STAGE(bufoff, gbase, voff) do { _Pragma("unroll") for (int _i = 0; _i < 2; ++_i) \
;         __builtin_amdgcn_global_load_lds((const unsigned*)((const char*)(gbase) + (voff)[_i]), (LAS unsigned*)(lds + (bufoff) + ldsw + _i * 8192), 16, 0, 0); } while (0)
; #define PG8_LDA(dst, b, h) do { _Pragma("unroll") for (int m = 0; m < 4; ++m) _Pragma("unroll") for (int k = 0; k < 2; ++k) dst[m][k] = *(const LAS bf16x8*)(lds + PG8_SA(b, h) + aoff + m * 2048 + k * 1024); } while (0)
; #define PG8_LDB(dst, b, h) do { _Pragma("unroll") for (int n = 0; n < 2; ++n) _Pragma("unroll") for (int k = 0; k < 2; ++k) dst[n][k] = *(const LAS bf16x8*)(lds + PG8_SB(b, h) + boff + n * 2048 + k * 1024); } while (0)
; #define PG8_WAIT_V(n) asm volatile("s_waitcnt vmcnt(" #n ")" ::: "memory")
; #define PG8_WAIT_L(n) asm volatile("s_waitcnt lgkmcnt(" #n ")" ::: "memory")
; #define PG8_BAR __builtin_amdgcn_s_barrier()
; #define PG8_SCHED __builtin_amdgcn_sched_barrier(0)
; template <class Sched, class Epi>
; __device__ __forceinline__ void gemm_phase(LAS unsigned char* lds, const Sched& S, const Epi& E, const int K, const int lda, const int ldb) {
;     ...
;         for (int t = 0; t < nt; t += 2) {
;             const bool last = (t == nt - 2);
;             const char* a1 = cA + (size_t)(t + 1) * kstep;
;             const char* a2 = last ? nA : cA + (size_t)(t + 2) * kstep; const char* b2 = last ? nB : cB + (size_t)(t + 2) * kstep;
;             const char* a3 = a2 + kstep; const char* b3 = b2 + kstep;
;             PG8_LDB(B0, 0, 0); PG8_SCHED; PG8_LDA(At, 0, 0); PG8_STAGE(PG8_SA(1, 1), a1 + hstepA, voffA);
;             PG8_WAIT_L(8); PG8_BAR; PG8_WAIT_L(0); PG8_MMA(0, 0, At, B0); PG8_BAR; PG8_SCHED;
;             PG8_LDB(B1, 0, 1); PG8_STAGE(PG8_SB(0, 0), b2, voffB);
;             PG8_BAR; PG8_WAIT_L(0); PG8_MMA(0, 1, At, B1); PG8_BAR;
;             PG8_LDA(At, 0, 1); PG8_STAGE(PG8_SA(0, 0), a2, voffA);
;             PG8_BAR; PG8_WAIT_L(0); if (!chalf) PG8_MMA(1, 0, At, B0); PG8_BAR; PG8_SCHED;
;             PG8_STAGE(PG8_SB(0, 1), b2 + hstepB, voffB);
;             PG8_WAIT_V(6); PG8_BAR; if (!chalf) PG8_MMA(1, 1, At, B1); PG8_BAR;
;             PG8_LDB(B0, 1, 0); PG8_SCHED; PG8_LDA(At, 1, 0); PG8_STAGE(PG8_SA(0, 1), a2 + hstepA, voffA);
;             PG8_WAIT_L(8); PG8_BAR; PG8_WAIT_L(0); PG8_MMA(0, 0, At, B0); PG8_BAR; PG8_SCHED;
.LBB0_430:
	ds_read_b128 v[2:5], v92
	ds_read_b128 v[6:9], v92 offset:1024
	ds_read_b128 v[10:13], v92 offset:2048
	ds_read_b128 v[14:17], v92 offset:3072
	s_add_u32 s52, s24, 0x40080
	s_addc_u32 s53, s25, 0
	s_mov_b32 m0, s46
	ds_read_b128 v[18:21], v93
	ds_read_b128 v[22:25], v93 offset:1024
	ds_read_b128 v[26:29], v93 offset:2048
	ds_read_b128 v[30:33], v93 offset:3072
	ds_read_b128 v[34:37], v93 offset:4096
	ds_read_b128 v[38:41], v93 offset:5120
	ds_read_b128 v[42:45], v93 offset:6144
	ds_read_b128 v[46:49], v93 offset:7168
	global_load_lds_dwordx4 v80, s[52:53]
	s_mov_b32 m0, s47
	s_nop 0
	global_load_lds_dwordx4 v76, s[52:53]
	s_waitcnt lgkmcnt(8)
	s_barrier
	s_waitcnt lgkmcnt(0)
	s_setprio 1
	s_waitcnt lgkmcnt(0)
	v_mfma_f32_16x16x32_bf16 v[50:53], v[2:5], v[18:21], 0
	v_mfma_f32_16x16x32_bf16 v[54:57], v[10:13], v[18:21], 0
	v_mfma_f32_16x16x32_bf16 v[58:61], v[2:5], v[26:29], 0
	v_mfma_f32_16x16x32_bf16 v[62:65], v[10:13], v[26:29], 0
	v_mfma_f32_16x16x32_bf16 v[66:69], v[2:5], v[34:37], 0
	v_mfma_f32_16x16x32_bf16 v[70:73], v[10:13], v[34:37], 0
	v_mfma_f32_16x16x32_bf16 v[96:99], v[2:5], v[42:45], 0
	v_mfma_f32_16x16x32_bf16 v[100:103], v[10:13], v[42:45], 0
	v_mfma_f32_16x16x32_bf16 v[50:53], v[6:9], v[22:25], v[50:53]
	v_mfma_f32_16x16x32_bf16 v[54:57], v[14:17], v[22:25], v[54:57]
	v_mfma_f32_16x16x32_bf16 v[58:61], v[6:9], v[30:33], v[58:61]
	v_mfma_f32_16x16x32_bf16 v[62:65], v[14:17], v[30:33], v[62:65]
	v_mfma_f32_16x16x32_bf16 v[66:69], v[6:9], v[38:41], v[66:69]
	v_mfma_f32_16x16x32_bf16 v[70:73], v[14:17], v[38:41], v[70:73]
	v_mfma_f32_16x16x32_bf16 v[96:99], v[6:9], v[46:49], v[96:99]
	v_mfma_f32_16x16x32_bf16 v[100:103], v[14:17], v[46:49], v[100:103]
	s_setprio 0
	s_barrier
	v_lshl_add_u64 v[216:217], s[26:27], 0, v[78:79]
	s_mov_b32 m0, s48
	v_lshl_add_u64 v[120:121], v[216:217], 0, s[8:9]
	v_lshl_add_u64 v[218:219], s[26:27], 0, v[74:75]
	s_add_i32 s52, s48, 0x2000
	ds_read_b128 v[104:107], v94
	ds_read_b128 v[108:111], v94 offset:1024
	ds_read_b128 v[112:115], v94 offset:2048
	ds_read_b128 v[116:119], v94 offset:3072
	global_load_lds_dwordx4 v[120:121], off
	v_lshl_add_u64 v[120:121], v[218:219], 0, s[8:9]
	s_mov_b32 m0, s52
	s_nop 0
	global_load_lds_dwordx4 v[120:121], off
	s_barrier
	s_waitcnt lgkmcnt(0)
	s_setprio 1
	s_waitcnt lgkmcnt(0)
	v_mfma_f32_16x16x32_bf16 v[120:123], v[104:107], v[18:21], 0
	v_mfma_f32_16x16x32_bf16 v[18:21], v[112:115], v[18:21], 0
	v_mfma_f32_16x16x32_bf16 v[120:123], v[108:111], v[22:25], v[120:123]
	v_mfma_f32_16x16x32_bf16 v[18:21], v[116:119], v[22:25], v[18:21]
	v_mfma_f32_16x16x32_bf16 v[22:25], v[104:107], v[26:29], 0
	v_mfma_f32_16x16x32_bf16 v[26:29], v[112:115], v[26:29], 0
	v_mfma_f32_16x16x32_bf16 v[22:25], v[108:111], v[30:33], v[22:25]
	v_mfma_f32_16x16x32_bf16 v[26:29], v[116:119], v[30:33], v[26:29]
	v_mfma_f32_16x16x32_bf16 v[30:33], v[104:107], v[34:37], 0
	v_mfma_f32_16x16x32_bf16 v[34:37], v[112:115], v[34:37], 0
	v_mfma_f32_16x16x32_bf16 v[30:33], v[108:111], v[38:41], v[30:33]
	v_mfma_f32_16x16x32_bf16 v[34:37], v[116:119], v[38:41], v[34:37]
	v_mfma_f32_16x16x32_bf16 v[38:41], v[104:107], v[42:45], 0
	v_mfma_f32_16x16x32_bf16 v[42:45], v[112:115], v[42:45], 0
	v_mfma_f32_16x16x32_bf16 v[38:41], v[108:111], v[46:49], v[38:41]
	v_mfma_f32_16x16x32_bf16 v[42:45], v[116:119], v[46:49], v[42:45]
	s_setprio 0
	v_lshl_add_u64 v[220:221], s[24:25], 0, v[80:81]
	s_mov_b32 m0, s11
	v_lshl_add_u64 v[152:153], v[220:221], 0, s[8:9]
	v_lshl_add_u64 v[222:223], s[24:25], 0, v[76:77]
	s_barrier
	ds_read_b128 v[46:49], v93 offset:16384
	ds_read_b128 v[124:127], v93 offset:17408
	ds_read_b128 v[128:131], v93 offset:18432
	ds_read_b128 v[132:135], v93 offset:19456
	ds_read_b128 v[136:139], v93 offset:20480
	ds_read_b128 v[140:143], v93 offset:21504
	ds_read_b128 v[144:147], v93 offset:22528
	ds_read_b128 v[148:151], v93 offset:23552
	global_load_lds_dwordx4 v[152:153], off
	v_lshl_add_u64 v[152:153], v[222:223], 0, s[8:9]
	s_mov_b32 m0, s28
	s_nop 0
	global_load_lds_dwordx4 v[152:153], off
	s_barrier
	s_waitcnt lgkmcnt(0)
	s_setprio 1
	s_waitcnt lgkmcnt(0)
	v_mfma_f32_16x16x32_bf16 v[152:155], v[2:5], v[46:49], 0
	v_mfma_f32_16x16x32_bf16 v[160:163], v[2:5], v[128:131], 0
	v_mfma_f32_16x16x32_bf16 v[168:171], v[2:5], v[136:139], 0
	v_mfma_f32_16x16x32_bf16 v[2:5], v[2:5], v[144:147], 0
	v_mfma_f32_16x16x32_bf16 v[152:155], v[6:9], v[124:127], v[152:155]
	v_mfma_f32_16x16x32_bf16 v[156:159], v[10:13], v[46:49], 0
	v_mfma_f32_16x16x32_bf16 v[160:163], v[6:9], v[132:135], v[160:163]
	v_mfma_f32_16x16x32_bf16 v[164:167], v[10:13], v[128:131], 0
	v_mfma_f32_16x16x32_bf16 v[168:171], v[6:9], v[140:143], v[168:171]
	v_mfma_f32_16x16x32_bf16 v[172:175], v[10:13], v[136:139], 0
	v_mfma_f32_16x16x32_bf16 v[2:5], v[6:9], v[148:151], v[2:5]
	v_mfma_f32_16x16x32_bf16 v[6:9], v[10:13], v[144:147], 0
	v_mfma_f32_16x16x32_bf16 v[156:159], v[14:17], v[124:127], v[156:159]
	v_mfma_f32_16x16x32_bf16 v[164:167], v[14:17], v[132:135], v[164:167]
	v_mfma_f32_16x16x32_bf16 v[172:175], v[14:17], v[140:143], v[172:175]
	v_mfma_f32_16x16x32_bf16 v[6:9], v[14:17], v[148:151], v[6:9]
	s_setprio 0
	s_barrier
	s_add_u32 s56, s26, 0x10100
	s_addc_u32 s57, s27, 0
	s_add_i32 s54, s45, s2
	s_mov_b32 m0, s54
	s_add_i32 s53, s54, 0x2000
	global_load_lds_dwordx4 v78, s[56:57]
	s_mov_b32 m0, s53
	s_nop 0
	global_load_lds_dwordx4 v74, s[56:57]
	s_waitcnt vmcnt(6)
	s_barrier
; #define PG8_STAGE(bufoff, gbase, voff) do { _Pragma("unroll") for (int _i = 0; _i < 2; ++_i) \
;         __builtin_amdgcn_global_load_lds((const unsigned*)((const char*)(gbase) + (voff)[_i]), (LAS unsigned*)(lds + (bufoff) + ldsw + _i * 8192), 16, 0, 0); } while (0)
; #define PG8_LDA(dst, b, h) do { _Pragma("unroll") for (int m = 0; m < 4; ++m) _Pragma("unroll") for (int k = 0; k < 2; ++k) dst[m][k] = *(const LAS bf16x8*)(lds + PG8_SA(b, h) + aoff + m * 2048 + k * 1024); } while (0)
; #define PG8_LDB(dst, b, h) do { _Pragma("unroll") for (int n = 0; n < 2; ++n) _Pragma("unroll") for (int k = 0; k < 2; ++k) dst[n][k] = *(const LAS bf16x8*)(lds + PG8_SB(b, h) + boff + n * 2048 + k * 1024); } while (0)
; #define PG8_MMA(ai, bj, At, Bt) do { __builtin_amdgcn_s_setprio(1); _Pragma("unroll") for (int m = 0; m < 4; ++m) _Pragma("unroll") for (int n = 0; n < 2; ++n) _Pragma("unroll") for (int k = 0; k < 2; ++k) \
;         acc[ai][bj][m][n] = __builtin_amdgcn_mfma_f32_16x16x32_bf16(Bt[n][k], At[m][k], acc[ai][bj][m][n], 0, 0, 0); __builtin_amdgcn_s_setprio(0); } while (0)
; #define PG8_WAIT_V(n) asm volatile("s_waitcnt vmcnt(" #n ")" ::: "memory")
; #define PG8_WAIT_L(n) asm volatile("s_waitcnt lgkmcnt(" #n ")" ::: "memory")
; #define PG8_BAR __builtin_amdgcn_s_barrier()
; #define PG8_SCHED __builtin_amdgcn_sched_barrier(0)
; template <class Sched, class Epi>
; __device__ __forceinline__ void gemm_phase(LAS unsigned char* lds, const Sched& S, const Epi& E, const int K, const int lda, const int ldb) {
;     ...
;             PG8_WAIT_V(6); PG8_BAR; if (!chalf) PG8_MMA(1, 1, At, B1); PG8_BAR;
;             PG8_LDB(B0, 1, 0); PG8_SCHED; PG8_LDA(At, 1, 0); PG8_STAGE(PG8_SA(0, 1), a2 + hstepA, voffA);
;             PG8_WAIT_L(8); PG8_BAR; PG8_WAIT_L(0); PG8_MMA(0, 0, At, B0); PG8_BAR; PG8_SCHED;
;             PG8_LDB(B1, 1, 1); PG8_STAGE(PG8_SB(1, 0), b3, voffB);
;             PG8_BAR; PG8_WAIT_L(0); PG8_MMA(0, 1, At, B1); PG8_BAR;
;             PG8_LDA(At, 1, 1); PG8_STAGE(PG8_SA(1, 0), a3, voffA);
;             PG8_BAR; PG8_WAIT_L(0); if (!chalf) PG8_MMA(1, 0, At, B0); PG8_BAR; PG8_SCHED;
;             PG8_STAGE(PG8_SB(1, 1), b3 + hstepB, voffB);
;             PG8_WAIT_V(6); PG8_BAR; if (!chalf) PG8_MMA(1, 1, At, B1); PG8_BAR;
	s_setprio 1
	v_mfma_f32_16x16x32_bf16 v[10:13], v[104:107], v[46:49], 0
	v_mfma_f32_16x16x32_bf16 v[14:17], v[112:115], v[46:49], 0
	v_mfma_f32_16x16x32_bf16 v[10:13], v[108:111], v[124:127], v[10:13]
	v_mfma_f32_16x16x32_bf16 v[14:17], v[116:119], v[124:127], v[14:17]
	v_mfma_f32_16x16x32_bf16 v[46:49], v[104:107], v[128:131], 0
	v_mfma_f32_16x16x32_bf16 v[124:127], v[112:115], v[128:131], 0
	v_mfma_f32_16x16x32_bf16 v[128:131], v[104:107], v[136:139], 0
	v_mfma_f32_16x16x32_bf16 v[104:107], v[104:107], v[144:147], 0
	v_mfma_f32_16x16x32_bf16 v[46:49], v[108:111], v[132:135], v[46:49]
	v_mfma_f32_16x16x32_bf16 v[124:127], v[116:119], v[132:135], v[124:127]
	v_mfma_f32_16x16x32_bf16 v[128:131], v[108:111], v[140:143], v[128:131]
	v_mfma_f32_16x16x32_bf16 v[132:135], v[112:115], v[136:139], 0
	v_mfma_f32_16x16x32_bf16 v[104:107], v[108:111], v[148:151], v[104:107]
	v_mfma_f32_16x16x32_bf16 v[108:111], v[112:115], v[144:147], 0
	v_mfma_f32_16x16x32_bf16 v[132:135], v[116:119], v[140:143], v[132:135]
	v_mfma_f32_16x16x32_bf16 v[108:111], v[116:119], v[148:151], v[108:111]
	s_setprio 0
	s_add_i32 s55, 16, 0x18000
	v_add_u32_e32 v95, s55, v84
	s_barrier
	ds_read_b128 v[112:115], v95
	ds_read_b128 v[116:119], v95 offset:1024
	ds_read_b128 v[136:139], v95 offset:2048
	ds_read_b128 v[140:143], v95 offset:3072
	s_add_u32 s56, s24, 0x40100
	s_addc_u32 s57, s25, 0
	s_mov_b32 m0, s29
	ds_read_b128 v[144:147], v93 offset:32768
	ds_read_b128 v[148:151], v93 offset:33792
	ds_read_b128 v[176:179], v93 offset:34816
	ds_read_b128 v[180:183], v93 offset:35840
	ds_read_b128 v[184:187], v93 offset:36864
	ds_read_b128 v[188:191], v93 offset:37888
	ds_read_b128 v[192:195], v93 offset:38912
	ds_read_b128 v[196:199], v93 offset:39936
	global_load_lds_dwordx4 v80, s[56:57]
	s_mov_b32 m0, s30
	s_nop 0
	global_load_lds_dwordx4 v76, s[56:57]
	s_waitcnt lgkmcnt(8)
	s_barrier
	s_waitcnt lgkmcnt(0)
	s_setprio 1
	s_waitcnt lgkmcnt(0)
	v_mfma_f32_16x16x32_bf16 v[50:53], v[112:115], v[144:147], v[50:53]
	v_mfma_f32_16x16x32_bf16 v[54:57], v[136:139], v[144:147], v[54:57]
	v_mfma_f32_16x16x32_bf16 v[58:61], v[112:115], v[176:179], v[58:61]
	v_mfma_f32_16x16x32_bf16 v[62:65], v[136:139], v[176:179], v[62:65]
	v_mfma_f32_16x16x32_bf16 v[66:69], v[112:115], v[184:187], v[66:69]
	v_mfma_f32_16x16x32_bf16 v[70:73], v[136:139], v[184:187], v[70:73]
	v_mfma_f32_16x16x32_bf16 v[96:99], v[112:115], v[192:195], v[96:99]
	v_mfma_f32_16x16x32_bf16 v[100:103], v[136:139], v[192:195], v[100:103]
	v_mfma_f32_16x16x32_bf16 v[50:53], v[116:119], v[148:151], v[50:53]
	v_mfma_f32_16x16x32_bf16 v[54:57], v[140:143], v[148:151], v[54:57]
	v_mfma_f32_16x16x32_bf16 v[58:61], v[116:119], v[180:183], v[58:61]
	v_mfma_f32_16x16x32_bf16 v[62:65], v[140:143], v[180:183], v[62:65]
	v_mfma_f32_16x16x32_bf16 v[66:69], v[116:119], v[188:191], v[66:69]
	v_mfma_f32_16x16x32_bf16 v[70:73], v[140:143], v[188:191], v[70:73]
	v_mfma_f32_16x16x32_bf16 v[96:99], v[116:119], v[196:199], v[96:99]
	v_mfma_f32_16x16x32_bf16 v[100:103], v[140:143], v[196:199], v[100:103]
	s_setprio 0
	s_barrier
	s_add_i32 s57, 16, 0x1c000
	s_add_i32 s56, s55, s2
	v_add_u32_e32 v228, s57, v84
	v_lshl_add_u64 v[216:217], v[216:217], 0, s[16:17]
	s_mov_b32 m0, s56
	s_add_i32 s55, s56, 0x2000
	ds_read_b128 v[200:203], v228
	ds_read_b128 v[204:207], v228 offset:1024
	ds_read_b128 v[208:211], v228 offset:2048
	ds_read_b128 v[212:215], v228 offset:3072
	global_load_lds_dwordx4 v[216:217], off
	v_lshl_add_u64 v[216:217], v[218:219], 0, s[16:17]
	s_mov_b32 m0, s55
	s_nop 0
	global_load_lds_dwordx4 v[216:217], off
	s_barrier
	s_waitcnt lgkmcnt(0)
	s_setprio 1
	s_waitcnt lgkmcnt(0)
	v_mfma_f32_16x16x32_bf16 v[120:123], v[200:203], v[144:147], v[120:123]
	v_mfma_f32_16x16x32_bf16 v[18:21], v[208:211], v[144:147], v[18:21]
	v_mfma_f32_16x16x32_bf16 v[22:25], v[200:203], v[176:179], v[22:25]
	v_mfma_f32_16x16x32_bf16 v[26:29], v[208:211], v[176:179], v[26:29]
	v_mfma_f32_16x16x32_bf16 v[30:33], v[200:203], v[184:187], v[30:33]
	v_mfma_f32_16x16x32_bf16 v[34:37], v[208:211], v[184:187], v[34:37]
	v_mfma_f32_16x16x32_bf16 v[38:41], v[200:203], v[192:195], v[38:41]
	v_mfma_f32_16x16x32_bf16 v[42:45], v[208:211], v[192:195], v[42:45]
	v_mfma_f32_16x16x32_bf16 v[120:123], v[204:207], v[148:151], v[120:123]
	v_mfma_f32_16x16x32_bf16 v[18:21], v[212:215], v[148:151], v[18:21]
	v_mfma_f32_16x16x32_bf16 v[22:25], v[204:207], v[180:183], v[22:25]
	v_mfma_f32_16x16x32_bf16 v[26:29], v[212:215], v[180:183], v[26:29]
	v_mfma_f32_16x16x32_bf16 v[30:33], v[204:207], v[188:191], v[30:33]
	v_mfma_f32_16x16x32_bf16 v[34:37], v[212:215], v[188:191], v[34:37]
	v_mfma_f32_16x16x32_bf16 v[38:41], v[204:207], v[196:199], v[38:41]
	v_mfma_f32_16x16x32_bf16 v[42:45], v[212:215], v[196:199], v[42:45]
	s_setprio 0
	s_mov_b32 m0, s33
	v_lshl_add_u64 v[216:217], v[220:221], 0, s[16:17]
	s_barrier
	ds_read_b128 v[144:147], v93 offset:49152
	ds_read_b128 v[148:151], v93 offset:50176
	ds_read_b128 v[176:179], v93 offset:51200
	ds_read_b128 v[180:183], v93 offset:52224
	ds_read_b128 v[184:187], v93 offset:53248
	ds_read_b128 v[188:191], v93 offset:54272
	ds_read_b128 v[192:195], v93 offset:55296
	ds_read_b128 v[196:199], v93 offset:56320
	global_load_lds_dwordx4 v[216:217], off
	v_lshl_add_u64 v[216:217], v[222:223], 0, s[16:17]
	s_mov_b32 m0, s34
	s_nop 0
	global_load_lds_dwordx4 v[216:217], off
	s_barrier
; #define PG8_STAGE(bufoff, gbase, voff) do { _Pragma("unroll") for (int _i = 0; _i < 2; ++_i) \
;         __builtin_amdgcn_global_load_lds((const unsigned*)((const char*)(gbase) + (voff)[_i]), (LAS unsigned*)(lds + (bufoff) + ldsw + _i * 8192), 16, 0, 0); } while (0)
; #define PG8_LDA(dst, b, h) do { _Pragma("unroll") for (int m = 0; m < 4; ++m) _Pragma("unroll") for (int k = 0; k < 2; ++k) dst[m][k] = *(const LAS bf16x8*)(lds + PG8_SA(b, h) + aoff + m * 2048 + k * 1024); } while (0)
; #define PG8_LDB(dst, b, h) do { _Pragma("unroll") for (int n = 0; n < 2; ++n) _Pragma("unroll") for (int k = 0; k < 2; ++k) dst[n][k] = *(const LAS bf16x8*)(lds + PG8_SB(b, h) + boff + n * 2048 + k * 1024); } while (0)
; #define PG8_WAIT_V(n) asm volatile("s_waitcnt vmcnt(" #n ")" ::: "memory")
; #define PG8_WAIT_L(n) asm volatile("s_waitcnt lgkmcnt(" #n ")" ::: "memory")
; #define PG8_BAR __builtin_amdgcn_s_barrier()
; template <class Sched, class Epi>
; __device__ __forceinline__ void gemm_phase(LAS unsigned char* lds, const Sched& S, const Epi& E, const int K, const int lda, const int ldb) {
;     ...
;             PG8_LDB(B0, 0, 0); PG8_SCHED; PG8_LDA(At, 0, 0); PG8_STAGE(PG8_SA(1, 1), a1 + hstepA, voffA);
;             PG8_WAIT_L(8); PG8_BAR; PG8_WAIT_L(0); PG8_MMA(0, 0, At, B0); PG8_BAR; PG8_SCHED;
;             PG8_LDB(B1, 0, 1); PG8_STAGE(PG8_SB(0, 0), b2, voffB);
;             PG8_BAR; PG8_WAIT_L(0); PG8_MMA(0, 1, At, B1); PG8_BAR;
;             PG8_LDA(At, 0, 1); PG8_STAGE(PG8_SA(0, 0), a2, voffA);
;             PG8_BAR; PG8_WAIT_L(0); if (!chalf) PG8_MMA(1, 0, At, B0); PG8_BAR; PG8_SCHED;
;             PG8_STAGE(PG8_SB(0, 1), b2 + hstepB, voffB);
;             PG8_WAIT_V(6); PG8_BAR; if (!chalf) PG8_MMA(1, 1, At, B1); PG8_BAR;
;             PG8_LDB(B0, 1, 0); PG8_SCHED; PG8_LDA(At, 1, 0); PG8_STAGE(PG8_SA(0, 1), a2 + hstepA, voffA);
;             PG8_WAIT_L(8); PG8_BAR; PG8_WAIT_L(0); PG8_MMA(0, 0, At, B0); PG8_BAR; PG8_SCHED;
;             PG8_LDB(B1, 1, 1); PG8_STAGE(PG8_SB(1, 0), b3, voffB);
;             PG8_BAR; PG8_WAIT_L(0); PG8_MMA(0, 1, At, B1); PG8_BAR;
;             PG8_LDA(At, 1, 1); PG8_STAGE(PG8_SA(1, 0), a3, voffA);
;             PG8_BAR; PG8_WAIT_L(0); if (!chalf) PG8_MMA(1, 0, At, B0); PG8_BAR; PG8_SCHED;
;             PG8_STAGE(PG8_SB(1, 1), b3 + hstepB, voffB);
;             PG8_WAIT_V(6); PG8_BAR; if (!chalf) PG8_MMA(1, 1, At, B1); PG8_BAR;
	s_waitcnt lgkmcnt(0)
	s_setprio 1
	s_waitcnt lgkmcnt(0)
	v_mfma_f32_16x16x32_bf16 v[152:155], v[112:115], v[144:147], v[152:155]
	v_mfma_f32_16x16x32_bf16 v[156:159], v[136:139], v[144:147], v[156:159]
	v_mfma_f32_16x16x32_bf16 v[160:163], v[112:115], v[176:179], v[160:163]
	v_mfma_f32_16x16x32_bf16 v[164:167], v[136:139], v[176:179], v[164:167]
	v_mfma_f32_16x16x32_bf16 v[168:171], v[112:115], v[184:187], v[168:171]
	v_mfma_f32_16x16x32_bf16 v[172:175], v[136:139], v[184:187], v[172:175]
	v_mfma_f32_16x16x32_bf16 v[2:5], v[112:115], v[192:195], v[2:5]
	v_mfma_f32_16x16x32_bf16 v[6:9], v[136:139], v[192:195], v[6:9]
	v_mfma_f32_16x16x32_bf16 v[152:155], v[116:119], v[148:151], v[152:155]
	v_mfma_f32_16x16x32_bf16 v[156:159], v[140:143], v[148:151], v[156:159]
	v_mfma_f32_16x16x32_bf16 v[160:163], v[116:119], v[180:183], v[160:163]
	v_mfma_f32_16x16x32_bf16 v[164:167], v[140:143], v[180:183], v[164:167]
	v_mfma_f32_16x16x32_bf16 v[168:171], v[116:119], v[188:191], v[168:171]
	v_mfma_f32_16x16x32_bf16 v[172:175], v[140:143], v[188:191], v[172:175]
	v_mfma_f32_16x16x32_bf16 v[2:5], v[116:119], v[196:199], v[2:5]
	v_mfma_f32_16x16x32_bf16 v[6:9], v[140:143], v[196:199], v[6:9]
	s_setprio 0
	s_barrier
	s_add_u32 s58, s26, 0x10180
	s_addc_u32 s59, s27, 0
	s_add_i32 s27, s57, s2
	s_mov_b32 m0, s27
	s_add_i32 s26, s27, 0x2000
	global_load_lds_dwordx4 v78, s[58:59]
	s_mov_b32 m0, s26
	s_nop 0
	global_load_lds_dwordx4 v74, s[58:59]
	s_waitcnt vmcnt(6)
	s_barrier
	s_setprio 1
	v_mfma_f32_16x16x32_bf16 v[10:13], v[200:203], v[144:147], v[10:13]
	v_mfma_f32_16x16x32_bf16 v[14:17], v[208:211], v[144:147], v[14:17]
	v_mfma_f32_16x16x32_bf16 v[46:49], v[200:203], v[176:179], v[46:49]
	v_mfma_f32_16x16x32_bf16 v[112:115], v[208:211], v[176:179], v[124:127]
	v_mfma_f32_16x16x32_bf16 v[116:119], v[200:203], v[184:187], v[128:131]
	v_mfma_f32_16x16x32_bf16 v[124:127], v[208:211], v[184:187], v[132:135]
	v_mfma_f32_16x16x32_bf16 v[104:107], v[200:203], v[192:195], v[104:107]
	v_mfma_f32_16x16x32_bf16 v[108:111], v[208:211], v[192:195], v[108:111]
	v_mfma_f32_16x16x32_bf16 v[10:13], v[204:207], v[148:151], v[10:13]
	v_mfma_f32_16x16x32_bf16 v[14:17], v[212:215], v[148:151], v[14:17]
	v_mfma_f32_16x16x32_bf16 v[46:49], v[204:207], v[180:183], v[46:49]
	v_mfma_f32_16x16x32_bf16 v[112:115], v[212:215], v[180:183], v[112:115]
	v_mfma_f32_16x16x32_bf16 v[116:119], v[204:207], v[188:191], v[116:119]
	v_mfma_f32_16x16x32_bf16 v[124:127], v[212:215], v[188:191], v[124:127]
	v_mfma_f32_16x16x32_bf16 v[104:107], v[204:207], v[196:199], v[104:107]
	v_mfma_f32_16x16x32_bf16 v[108:111], v[212:215], v[196:199], v[108:111]
	s_setprio 0
	s_barrier
	ds_read_b128 v[128:131], v92
	ds_read_b128 v[132:135], v92 offset:1024
	ds_read_b128 v[136:139], v92 offset:2048
	ds_read_b128 v[140:143], v92 offset:3072
	s_add_u32 s24, s24, 0x40180
	s_addc_u32 s25, s25, 0
	s_mov_b32 m0, s46
	ds_read_b128 v[144:147], v93
	ds_read_b128 v[148:151], v93 offset:1024
	ds_read_b128 v[176:179], v93 offset:2048
	ds_read_b128 v[180:183], v93 offset:3072
	ds_read_b128 v[184:187], v93 offset:4096
	ds_read_b128 v[188:191], v93 offset:5120
	ds_read_b128 v[192:195], v93 offset:6144
	ds_read_b128 v[196:199], v93 offset:7168
	global_load_lds_dwordx4 v80, s[24:25]
	s_mov_b32 m0, s47
	s_nop 0
	global_load_lds_dwordx4 v76, s[24:25]
	s_waitcnt lgkmcnt(8)
	s_barrier
	s_waitcnt lgkmcnt(0)
	s_setprio 1
	s_waitcnt lgkmcnt(0)
	v_mfma_f32_16x16x32_bf16 v[50:53], v[128:131], v[144:147], v[50:53]
	v_mfma_f32_16x16x32_bf16 v[54:57], v[136:139], v[144:147], v[54:57]
	v_mfma_f32_16x16x32_bf16 v[58:61], v[128:131], v[176:179], v[58:61]
	v_mfma_f32_16x16x32_bf16 v[62:65], v[136:139], v[176:179], v[62:65]
	v_mfma_f32_16x16x32_bf16 v[66:69], v[128:131], v[184:187], v[66:69]
	v_mfma_f32_16x16x32_bf16 v[70:73], v[136:139], v[184:187], v[70:73]
	v_mfma_f32_16x16x32_bf16 v[96:99], v[128:131], v[192:195], v[96:99]
	v_mfma_f32_16x16x32_bf16 v[100:103], v[136:139], v[192:195], v[100:103]
	v_mfma_f32_16x16x32_bf16 v[50:53], v[132:135], v[148:151], v[50:53]
	v_mfma_f32_16x16x32_bf16 v[54:57], v[140:143], v[148:151], v[54:57]
	v_mfma_f32_16x16x32_bf16 v[58:61], v[132:135], v[180:183], v[58:61]
	v_mfma_f32_16x16x32_bf16 v[62:65], v[140:143], v[180:183], v[62:65]
	v_mfma_f32_16x16x32_bf16 v[66:69], v[132:135], v[188:191], v[66:69]
	v_mfma_f32_16x16x32_bf16 v[70:73], v[140:143], v[188:191], v[70:73]
	v_mfma_f32_16x16x32_bf16 v[96:99], v[132:135], v[196:199], v[96:99]
	v_mfma_f32_16x16x32_bf16 v[100:103], v[140:143], v[196:199], v[100:103]
	s_setprio 0
	s_barrier
	s_mov_b32 m0, s48
	s_add_u32 s68, s22, s12
	s_addc_u32 s69, s23, s13
	ds_read_b128 v[200:203], v94
	ds_read_b128 v[204:207], v94 offset:1024
	ds_read_b128 v[208:211], v94 offset:2048
	ds_read_b128 v[212:215], v94 offset:3072
	global_load_lds_dwordx4 v78, s[22:23]
	s_add_u32 s70, s22, s12
	s_addc_u32 s71, s23, s13
	s_mov_b32 m0, s52
	s_nop 0
	global_load_lds_dwordx4 v74, s[22:23]
	s_barrier
	s_waitcnt lgkmcnt(0)
	s_setprio 1
	s_waitcnt lgkmcnt(0)
	v_mfma_f32_16x16x32_bf16 v[120:123], v[200:203], v[144:147], v[120:123]
	v_mfma_f32_16x16x32_bf16 v[18:21], v[208:211], v[144:147], v[18:21]
	v_mfma_f32_16x16x32_bf16 v[22:25], v[200:203], v[176:179], v[22:25]
	v_mfma_f32_16x16x32_bf16 v[26:29], v[208:211], v[176:179], v[26:29]
	v_mfma_f32_16x16x32_bf16 v[30:33], v[200:203], v[184:187], v[30:33]
	v_mfma_f32_16x16x32_bf16 v[34:37], v[208:211], v[184:187], v[34:37]
	v_mfma_f32_16x16x32_bf16 v[38:41], v[200:203], v[192:195], v[38:41]
	v_mfma_f32_16x16x32_bf16 v[42:45], v[208:211], v[192:195], v[42:45]
	v_mfma_f32_16x16x32_bf16 v[120:123], v[204:207], v[148:151], v[120:123]
	v_mfma_f32_16x16x32_bf16 v[18:21], v[212:215], v[148:151], v[18:21]
	v_mfma_f32_16x16x32_bf16 v[22:25], v[204:207], v[180:183], v[22:25]
	v_mfma_f32_16x16x32_bf16 v[26:29], v[212:215], v[180:183], v[26:29]
	v_mfma_f32_16x16x32_bf16 v[30:33], v[204:207], v[188:191], v[30:33]
	v_mfma_f32_16x16x32_bf16 v[34:37], v[212:215], v[188:191], v[34:37]
	v_mfma_f32_16x16x32_bf16 v[38:41], v[204:207], v[196:199], v[38:41]
	v_mfma_f32_16x16x32_bf16 v[42:45], v[212:215], v[196:199], v[42:45]
	s_setprio 0
	s_mov_b32 m0, s11
	s_add_u32 s72, s20, s12
	s_addc_u32 s73, s21, s13
	s_barrier
; #define PG8_STAGE(bufoff, gbase, voff) do { _Pragma("unroll") for (int _i = 0; _i < 2; ++_i) \
;         __builtin_amdgcn_global_load_lds((const unsigned*)((const char*)(gbase) + (voff)[_i]), (LAS unsigned*)(lds + (bufoff) + ldsw + _i * 8192), 16, 0, 0); } while (0)
; #define PG8_LDA(dst, b, h) do { _Pragma("unroll") for (int m = 0; m < 4; ++m) _Pragma("unroll") for (int k = 0; k < 2; ++k) dst[m][k] = *(const LAS bf16x8*)(lds + PG8_SA(b, h) + aoff + m * 2048 + k * 1024); } while (0)
; #define PG8_LDB(dst, b, h) do { _Pragma("unroll") for (int n = 0; n < 2; ++n) _Pragma("unroll") for (int k = 0; k < 2; ++k) dst[n][k] = *(const LAS bf16x8*)(lds + PG8_SB(b, h) + boff + n * 2048 + k * 1024); } while (0)
; #define PG8_MMA(ai, bj, At, Bt) do { __builtin_amdgcn_s_setprio(1); _Pragma("unroll") for (int m = 0; m < 4; ++m) _Pragma("unroll") for (int n = 0; n < 2; ++n) _Pragma("unroll") for (int k = 0; k < 2; ++k) \
;         acc[ai][bj][m][n] = __builtin_amdgcn_mfma_f32_16x16x32_bf16(Bt[n][k], At[m][k], acc[ai][bj][m][n], 0, 0, 0); __builtin_amdgcn_s_setprio(0); } while (0)
; #define PG8_WAIT_V(n) asm volatile("s_waitcnt vmcnt(" #n ")" ::: "memory")
; #define PG8_WAIT_L(n) asm volatile("s_waitcnt lgkmcnt(" #n ")" ::: "memory")
; #define PG8_BAR __builtin_amdgcn_s_barrier()
; #define PG8_SCHED __builtin_amdgcn_sched_barrier(0)
; template <class Sched, class Epi>
; __device__ __forceinline__ void gemm_phase(LAS unsigned char* lds, const Sched& S, const Epi& E, const int K, const int lda, const int ldb) {
;     ...
;             PG8_LDA(At, 0, 1); PG8_STAGE(PG8_SA(0, 0), a2, voffA);
;             PG8_BAR; PG8_WAIT_L(0); if (!chalf) PG8_MMA(1, 0, At, B0); PG8_BAR; PG8_SCHED;
;             PG8_STAGE(PG8_SB(0, 1), b2 + hstepB, voffB);
;             PG8_WAIT_V(6); PG8_BAR; if (!chalf) PG8_MMA(1, 1, At, B1); PG8_BAR;
;             PG8_LDB(B0, 1, 0); PG8_SCHED; PG8_LDA(At, 1, 0); PG8_STAGE(PG8_SA(0, 1), a2 + hstepA, voffA);
;             PG8_WAIT_L(8); PG8_BAR; PG8_WAIT_L(0); PG8_MMA(0, 0, At, B0); PG8_BAR; PG8_SCHED;
;             PG8_LDB(B1, 1, 1); PG8_STAGE(PG8_SB(1, 0), b3, voffB);
;             PG8_BAR; PG8_WAIT_L(0); PG8_MMA(0, 1, At, B1); PG8_BAR;
;             PG8_LDA(At, 1, 1); PG8_STAGE(PG8_SA(1, 0), a3, voffA);
	ds_read_b128 v[144:147], v93 offset:16384
	ds_read_b128 v[148:151], v93 offset:17408
	ds_read_b128 v[176:179], v93 offset:18432
	ds_read_b128 v[180:183], v93 offset:19456
	ds_read_b128 v[184:187], v93 offset:20480
	ds_read_b128 v[188:191], v93 offset:21504
	ds_read_b128 v[192:195], v93 offset:22528
	ds_read_b128 v[196:199], v93 offset:23552
	global_load_lds_dwordx4 v80, s[20:21]
	s_add_u32 s74, s20, s12
	s_addc_u32 s75, s21, s13
	s_mov_b32 m0, s28
	s_nop 0
	global_load_lds_dwordx4 v76, s[20:21]
	s_barrier
	s_waitcnt lgkmcnt(0)
	s_setprio 1
	s_waitcnt lgkmcnt(0)
	v_mfma_f32_16x16x32_bf16 v[152:155], v[128:131], v[144:147], v[152:155]
	v_mfma_f32_16x16x32_bf16 v[156:159], v[136:139], v[144:147], v[156:159]
	v_mfma_f32_16x16x32_bf16 v[160:163], v[128:131], v[176:179], v[160:163]
	v_mfma_f32_16x16x32_bf16 v[164:167], v[136:139], v[176:179], v[164:167]
	v_mfma_f32_16x16x32_bf16 v[168:171], v[128:131], v[184:187], v[168:171]
	v_mfma_f32_16x16x32_bf16 v[172:175], v[136:139], v[184:187], v[172:175]
	v_mfma_f32_16x16x32_bf16 v[2:5], v[128:131], v[192:195], v[2:5]
	v_mfma_f32_16x16x32_bf16 v[6:9], v[136:139], v[192:195], v[6:9]
	v_mfma_f32_16x16x32_bf16 v[152:155], v[132:135], v[148:151], v[152:155]
	v_mfma_f32_16x16x32_bf16 v[156:159], v[140:143], v[148:151], v[156:159]
	v_mfma_f32_16x16x32_bf16 v[160:163], v[132:135], v[180:183], v[160:163]
	v_mfma_f32_16x16x32_bf16 v[164:167], v[140:143], v[180:183], v[164:167]
	v_mfma_f32_16x16x32_bf16 v[168:171], v[132:135], v[188:191], v[168:171]
	v_mfma_f32_16x16x32_bf16 v[172:175], v[140:143], v[188:191], v[172:175]
	v_mfma_f32_16x16x32_bf16 v[2:5], v[132:135], v[196:199], v[2:5]
	v_mfma_f32_16x16x32_bf16 v[128:131], v[140:143], v[196:199], v[6:9]
	s_setprio 0
	s_barrier
	s_add_u32 s24, s22, 0x10000
	s_addc_u32 s25, s23, 0
	s_mov_b32 m0, s54
	s_nop 0
	global_load_lds_dwordx4 v78, s[24:25]
	s_mov_b32 m0, s53
	s_nop 0
	global_load_lds_dwordx4 v74, s[24:25]
	s_waitcnt vmcnt(6)
	s_barrier
	s_setprio 1
	v_mfma_f32_16x16x32_bf16 v[6:9], v[200:203], v[144:147], v[10:13]
	v_mfma_f32_16x16x32_bf16 v[10:13], v[204:207], v[148:151], v[6:9]
	v_mfma_f32_16x16x32_bf16 v[6:9], v[208:211], v[144:147], v[14:17]
	v_mfma_f32_16x16x32_bf16 v[14:17], v[212:215], v[148:151], v[6:9]
	v_mfma_f32_16x16x32_bf16 v[6:9], v[200:203], v[176:179], v[46:49]
	v_mfma_f32_16x16x32_bf16 v[46:49], v[204:207], v[180:183], v[6:9]
	v_mfma_f32_16x16x32_bf16 v[6:9], v[208:211], v[176:179], v[112:115]
	v_mfma_f32_16x16x32_bf16 v[112:115], v[212:215], v[180:183], v[6:9]
	v_mfma_f32_16x16x32_bf16 v[6:9], v[200:203], v[184:187], v[116:119]
	v_mfma_f32_16x16x32_bf16 v[116:119], v[204:207], v[188:191], v[6:9]
	v_mfma_f32_16x16x32_bf16 v[6:9], v[208:211], v[184:187], v[124:127]
	v_mfma_f32_16x16x32_bf16 v[124:127], v[212:215], v[188:191], v[6:9]
	v_mfma_f32_16x16x32_bf16 v[6:9], v[200:203], v[192:195], v[104:107]
	v_mfma_f32_16x16x32_bf16 v[104:107], v[204:207], v[196:199], v[6:9]
	v_mfma_f32_16x16x32_bf16 v[6:9], v[208:211], v[192:195], v[108:111]
	v_mfma_f32_16x16x32_bf16 v[108:111], v[212:215], v[196:199], v[6:9]
	s_setprio 0
	s_barrier
	s_nop 4
	ds_read_b128 v[6:9], v95
	ds_read_b128 v[132:135], v95 offset:1024
	ds_read_b128 v[136:139], v95 offset:2048
	ds_read_b128 v[140:143], v95 offset:3072
	s_add_u32 s24, s20, 0x40000
	s_addc_u32 s25, s21, 0
	s_mov_b32 m0, s29
	ds_read_b128 v[144:147], v93 offset:32768
	ds_read_b128 v[148:151], v93 offset:33792
	ds_read_b128 v[176:179], v93 offset:34816
	ds_read_b128 v[180:183], v93 offset:35840
	ds_read_b128 v[184:187], v93 offset:36864
	ds_read_b128 v[188:191], v93 offset:37888
	ds_read_b128 v[192:195], v93 offset:38912
	ds_read_b128 v[196:199], v93 offset:39936
	global_load_lds_dwordx4 v80, s[24:25]
	s_mov_b32 m0, s30
	s_nop 0
	global_load_lds_dwordx4 v76, s[24:25]
	s_waitcnt lgkmcnt(8)
	s_barrier
	s_waitcnt lgkmcnt(0)
	s_setprio 1
	s_waitcnt lgkmcnt(0)
	v_mfma_f32_16x16x32_bf16 v[50:53], v[6:9], v[144:147], v[50:53]
	v_mfma_f32_16x16x32_bf16 v[200:203], v[132:135], v[148:151], v[50:53]
	v_mfma_f32_16x16x32_bf16 v[50:53], v[136:139], v[144:147], v[54:57]
	v_mfma_f32_16x16x32_bf16 v[204:207], v[140:143], v[148:151], v[50:53]
	v_mfma_f32_16x16x32_bf16 v[50:53], v[6:9], v[176:179], v[58:61]
	v_mfma_f32_16x16x32_bf16 v[208:211], v[132:135], v[180:183], v[50:53]
	v_mfma_f32_16x16x32_bf16 v[50:53], v[136:139], v[176:179], v[62:65]
	v_mfma_f32_16x16x32_bf16 v[212:215], v[140:143], v[180:183], v[50:53]
	v_mfma_f32_16x16x32_bf16 v[50:53], v[6:9], v[184:187], v[66:69]
	v_mfma_f32_16x16x32_bf16 v[216:219], v[132:135], v[188:191], v[50:53]
	v_mfma_f32_16x16x32_bf16 v[50:53], v[136:139], v[184:187], v[70:73]
	v_mfma_f32_16x16x32_bf16 v[220:223], v[140:143], v[188:191], v[50:53]
	v_mfma_f32_16x16x32_bf16 v[50:53], v[6:9], v[192:195], v[96:99]
	v_mfma_f32_16x16x32_bf16 v[54:57], v[132:135], v[196:199], v[50:53]
	v_mfma_f32_16x16x32_bf16 v[50:53], v[136:139], v[192:195], v[100:103]
	v_mfma_f32_16x16x32_bf16 v[50:53], v[140:143], v[196:199], v[50:53]
	s_setprio 0
	s_barrier
	s_mov_b32 m0, s56
	ds_read_b128 v[96:99], v228
	ds_read_b128 v[100:103], v228 offset:1024
	ds_read_b128 v[224:227], v228 offset:2048
	ds_read_b128 v[228:231], v228 offset:3072
	global_load_lds_dwordx4 v78, s[68:69]
	s_mov_b32 m0, s55
	s_nop 0
	global_load_lds_dwordx4 v74, s[70:71]
	s_barrier
; #define PG8_STAGE(bufoff, gbase, voff) do { _Pragma("unroll") for (int _i = 0; _i < 2; ++_i) \
;         __builtin_amdgcn_global_load_lds((const unsigned*)((const char*)(gbase) + (voff)[_i]), (LAS unsigned*)(lds + (bufoff) + ldsw + _i * 8192), 16, 0, 0); } while (0)
; #define PG8_LDA(dst, b, h) do { _Pragma("unroll") for (int m = 0; m < 4; ++m) _Pragma("unroll") for (int k = 0; k < 2; ++k) dst[m][k] = *(const LAS bf16x8*)(lds + PG8_SA(b, h) + aoff + m * 2048 + k * 1024); } while (0)
; #define PG8_MMA(ai, bj, At, Bt) do { __builtin_amdgcn_s_setprio(1); _Pragma("unroll") for (int m = 0; m < 4; ++m) _Pragma("unroll") for (int n = 0; n < 2; ++n) _Pragma("unroll") for (int k = 0; k < 2; ++k) \
;         acc[ai][bj][m][n] = __builtin_amdgcn_mfma_f32_16x16x32_bf16(Bt[n][k], At[m][k], acc[ai][bj][m][n], 0, 0, 0); __builtin_amdgcn_s_setprio(0); } while (0)
; #define PG8_WAIT_V(n) asm volatile("s_waitcnt vmcnt(" #n ")" ::: "memory")
; #define PG8_WAIT_L(n) asm volatile("s_waitcnt lgkmcnt(" #n ")" ::: "memory")
; #define PG8_BAR __builtin_amdgcn_s_barrier()
; #define PG8_SCHED __builtin_amdgcn_sched_barrier(0)
; #define EPI_FOR_ROWS _Pragma("unroll") for (int ai = 0; ai < 2; ++ai) if (ai == 0 || !u.half) _Pragma("unroll") for (int m = 0; m < 4; ++m)
; template <class Sched, class Epi>
; __device__ __forceinline__ void gemm_phase(LAS unsigned char* lds, const Sched& S, const Epi& E, const int K, const int lda, const int ldb) {
;     ...
;             PG8_BAR; PG8_WAIT_L(0); PG8_MMA(0, 1, At, B1); PG8_BAR;
;             PG8_LDA(At, 1, 1); PG8_STAGE(PG8_SA(1, 0), a3, voffA);
;             PG8_BAR; PG8_WAIT_L(0); if (!chalf) PG8_MMA(1, 0, At, B0); PG8_BAR; PG8_SCHED;
;             PG8_STAGE(PG8_SB(1, 1), b3 + hstepB, voffB);
;             PG8_WAIT_V(6); PG8_BAR; if (!chalf) PG8_MMA(1, 1, At, B1); PG8_BAR;
;     __device__ __forceinline__ void operator()(EPI_ARGS) const {
;         const int l = u.z >> 2, grp = u.z & 3; bf16_t* O = (bf16_t*)(ws + l * SZ_LAYER + LO_WP);
;         EPI_FOR_ROWS { bf16_t* rp = O + (size_t)EPI_ROW * 2048 + u.pn * 1024 + grp * 256;
	s_waitcnt lgkmcnt(0)
	s_setprio 1
	s_waitcnt lgkmcnt(0)
	v_mfma_f32_16x16x32_bf16 v[18:21], v[224:227], v[144:147], v[18:21]
	v_mfma_f32_16x16x32_bf16 v[58:61], v[96:99], v[144:147], v[120:123]
	v_mfma_f32_16x16x32_bf16 v[144:147], v[228:231], v[148:151], v[18:21]
	v_mfma_f32_16x16x32_bf16 v[18:21], v[96:99], v[176:179], v[22:25]
	v_mfma_f32_16x16x32_bf16 v[120:123], v[100:103], v[148:151], v[58:61]
	v_mfma_f32_16x16x32_bf16 v[148:151], v[100:103], v[180:183], v[18:21]
	v_mfma_f32_16x16x32_bf16 v[18:21], v[224:227], v[176:179], v[26:29]
	v_mfma_f32_16x16x32_bf16 v[176:179], v[228:231], v[180:183], v[18:21]
	v_mfma_f32_16x16x32_bf16 v[18:21], v[96:99], v[184:187], v[30:33]
	v_mfma_f32_16x16x32_bf16 v[180:183], v[100:103], v[188:191], v[18:21]
	v_mfma_f32_16x16x32_bf16 v[18:21], v[224:227], v[184:187], v[34:37]
	v_mfma_f32_16x16x32_bf16 v[184:187], v[228:231], v[188:191], v[18:21]
	v_mfma_f32_16x16x32_bf16 v[18:21], v[96:99], v[192:195], v[38:41]
	v_mfma_f32_16x16x32_bf16 v[70:73], v[100:103], v[196:199], v[18:21]
	v_mfma_f32_16x16x32_bf16 v[18:21], v[224:227], v[192:195], v[42:45]
	v_mfma_f32_16x16x32_bf16 v[62:65], v[228:231], v[196:199], v[18:21]
	s_setprio 0
	s_mov_b32 m0, s33
	s_nop 4
	s_barrier
	ds_read_b128 v[26:29], v93 offset:49152
	ds_read_b128 v[30:33], v93 offset:50176
	ds_read_b128 v[42:45], v93 offset:51200
	ds_read_b128 v[188:191], v93 offset:52224
	ds_read_b128 v[192:195], v93 offset:53248
	ds_read_b128 v[196:199], v93 offset:54272
	ds_read_b128 v[232:235], v93 offset:55296
	ds_read_b128 v[236:239], v93 offset:56320
	global_load_lds_dwordx4 v80, s[72:73]
	s_mov_b32 m0, s34
	s_nop 0
	global_load_lds_dwordx4 v76, s[74:75]
	s_barrier
	s_waitcnt lgkmcnt(0)
	s_setprio 1
	s_waitcnt lgkmcnt(0)
	v_mfma_f32_16x16x32_bf16 v[18:21], v[6:9], v[26:29], v[152:155]
	v_mfma_f32_16x16x32_bf16 v[66:69], v[132:135], v[30:33], v[18:21]
	v_mfma_f32_16x16x32_bf16 v[18:21], v[136:139], v[26:29], v[156:159]
	v_mfma_f32_16x16x32_bf16 v[58:61], v[140:143], v[30:33], v[18:21]
	v_mfma_f32_16x16x32_bf16 v[18:21], v[6:9], v[42:45], v[160:163]
	v_mfma_f32_16x16x32_bf16 v[38:41], v[132:135], v[188:191], v[18:21]
	v_mfma_f32_16x16x32_bf16 v[18:21], v[136:139], v[42:45], v[164:167]
	v_mfma_f32_16x16x32_bf16 v[34:37], v[140:143], v[188:191], v[18:21]
	v_mfma_f32_16x16x32_bf16 v[18:21], v[6:9], v[192:195], v[168:171]
	v_mfma_f32_16x16x32_bf16 v[2:5], v[6:9], v[232:235], v[2:5]
	v_mfma_f32_16x16x32_bf16 v[22:25], v[132:135], v[196:199], v[18:21]
	v_mfma_f32_16x16x32_bf16 v[18:21], v[136:139], v[192:195], v[172:175]
	v_mfma_f32_16x16x32_bf16 v[6:9], v[132:135], v[236:239], v[2:5]
	v_mfma_f32_16x16x32_bf16 v[2:5], v[136:139], v[232:235], v[128:131]
	v_mfma_f32_16x16x32_bf16 v[18:21], v[140:143], v[196:199], v[18:21]
	v_mfma_f32_16x16x32_bf16 v[2:5], v[140:143], v[236:239], v[2:5]
	s_setprio 0
	s_barrier
	s_add_u32 s24, s22, 0x10080
	s_addc_u32 s25, s23, 0
	s_mov_b32 m0, s27
	s_nop 0
	global_load_lds_dwordx4 v78, s[24:25]
	s_mov_b32 m0, s26
	s_nop 0
	global_load_lds_dwordx4 v74, s[24:25]
	s_waitcnt vmcnt(6)
	s_barrier
	s_setprio 1
	v_mfma_f32_16x16x32_bf16 v[10:13], v[96:99], v[26:29], v[10:13]
	v_mfma_f32_16x16x32_bf16 v[128:131], v[100:103], v[30:33], v[10:13]
	v_mfma_f32_16x16x32_bf16 v[10:13], v[224:227], v[26:29], v[14:17]
	v_mfma_f32_16x16x32_bf16 v[132:135], v[228:231], v[30:33], v[10:13]
	v_mfma_f32_16x16x32_bf16 v[10:13], v[96:99], v[42:45], v[46:49]
	v_mfma_f32_16x16x32_bf16 v[46:49], v[100:103], v[188:191], v[10:13]
	v_mfma_f32_16x16x32_bf16 v[10:13], v[224:227], v[42:45], v[112:115]
	v_mfma_f32_16x16x32_bf16 v[42:45], v[228:231], v[188:191], v[10:13]
	v_mfma_f32_16x16x32_bf16 v[10:13], v[96:99], v[192:195], v[116:119]
	v_mfma_f32_16x16x32_bf16 v[30:33], v[100:103], v[196:199], v[10:13]
	v_mfma_f32_16x16x32_bf16 v[10:13], v[224:227], v[192:195], v[124:127]
	v_mfma_f32_16x16x32_bf16 v[26:29], v[228:231], v[196:199], v[10:13]
	v_mfma_f32_16x16x32_bf16 v[10:13], v[96:99], v[232:235], v[104:107]
	v_mfma_f32_16x16x32_bf16 v[14:17], v[100:103], v[236:239], v[10:13]
	v_mfma_f32_16x16x32_bf16 v[10:13], v[224:227], v[232:235], v[108:111]
	v_mfma_f32_16x16x32_bf16 v[10:13], v[228:231], v[236:239], v[10:13]
	s_setprio 0
	s_ashr_i32 s24, s4, 2
	s_mul_hi_i32 s25, s24, 0x6e22000
	s_mul_i32 s24, s24, 0x6e22000
	s_add_u32 s24, s6, s24
	s_addc_u32 s25, s7, s25
	s_add_u32 s24, s24, 0x4a00000
	v_add_u32_e32 v96, s35, v1
	s_addc_u32 s25, s25, 0
	v_ashrrev_i32_e32 v97, 31, v96
	s_lshl_b32 s26, s19, 10
	v_lshlrev_b64 v[96:97], 12, v[96:97]
	s_ashr_i32 s27, s26, 31
	v_lshl_add_u64 v[96:97], s[24:25], 0, v[96:97]
	s_lshl_b64 s[26:27], s[26:27], 1
	s_lshl_b32 s4, s4, 9
	v_lshl_add_u64 v[96:97], v[96:97], 0, s[26:27]
	s_and_b32 s4, s4, 0x600
	v_lshl_add_u64 v[96:97], v[96:97], 0, s[4:5]
	s_mov_b32 s19, s5
	v_lshl_add_u64 v[96:97], v[96:97], 0, s[18:19]
	s_barrier
; __device__ __forceinline__ unsigned cvt_pk_bf16(float lo, float hi) { unsigned r; asm volatile("v_cvt_pk_bf16_f32 %0, %1, %2" : "=v"(r) : "v"(lo), "v"(hi)); return r; }
; #define EPI_FOR_ROWS _Pragma("unroll") for (int ai = 0; ai < 2; ++ai) if (ai == 0 || !u.half) _Pragma("unroll") for (int m = 0; m < 4; ++m)
;     __device__ __forceinline__ bool next(int i, Unit& u) const {
;         const long L = (long)i * G + c; if (L >= 64) return false;
;         const int l = (int)L >> 5, grp = ((int)L >> 3) & 3, pm = ((int)L >> 1) & 3; u.row0 = pm * 256; u.half = 0; u.pn = (int)L & 1; u.z = l * 4 + grp;
;     __device__ __forceinline__ void operator()(EPI_ARGS) const {
;         const int l = u.z >> 2, grp = u.z & 3; bf16_t* O = (bf16_t*)(ws + l * SZ_LAYER + LO_WP);
;         EPI_FOR_ROWS { bf16_t* rp = O + (size_t)EPI_ROW * 2048 + u.pn * 1024 + grp * 256;
; #pragma unroll
;             for (int bj = 0; bj < 2; ++bj) { const f32x4 v0 = acc[ai][bj][m][0], v1 = acc[ai][bj][m][1]; u32x4 o;
;                 o[0] = cvt_pk_bf16(v0[0], v0[1]); o[1] = cvt_pk_bf16(v0[2], v0[3]); o[2] = cvt_pk_bf16(v1[0], v1[1]); o[3] = cvt_pk_bf16(v1[2], v1[3]);
;                 *(u32x4*)(rp + wc * 32 + 8 * fq + bj * 128) = o; } }
;     }
	v_lshl_add_u64 v[100:101], v[96:97], 0, v[82:83]
	v_cvt_pk_bf16_f32 v96, v200, v201
	v_cvt_pk_bf16_f32 v97, v202, v203
	v_cvt_pk_bf16_f32 v98, v204, v205
	v_cvt_pk_bf16_f32 v99, v206, v207
	global_store_dwordx4 v[100:101], v[96:99], off
	s_add_i32 s37, s37, s31
	s_add_u32 s14, s14, s39
	v_cvt_pk_bf16_f32 v96, v120, v121
	v_cvt_pk_bf16_f32 v97, v122, v123
	v_cvt_pk_bf16_f32 v98, v144, v145
	v_cvt_pk_bf16_f32 v99, v146, v147
	global_store_dwordx4 v[100:101], v[96:99], off offset:256
	s_addc_u32 s15, s15, s40
	s_add_u32 s0, s0, s31
	v_add_u32_e32 v96, s35, v85
	v_ashrrev_i32_e32 v97, 31, v96
	v_lshlrev_b64 v[96:97], 12, v[96:97]
	v_lshl_add_u64 v[96:97], s[24:25], 0, v[96:97]
	v_lshl_add_u64 v[96:97], v[96:97], 0, s[26:27]
	v_lshl_add_u64 v[96:97], v[96:97], 0, s[4:5]
	v_lshl_add_u64 v[96:97], v[96:97], 0, s[18:19]
	v_lshl_add_u64 v[100:101], v[96:97], 0, v[82:83]
	v_cvt_pk_bf16_f32 v96, v208, v209
	v_cvt_pk_bf16_f32 v97, v210, v211
	v_cvt_pk_bf16_f32 v98, v212, v213
	v_cvt_pk_bf16_f32 v99, v214, v215
	global_store_dwordx4 v[100:101], v[96:99], off
	s_addc_u32 s38, s38, s36
	s_nop 0
	v_cvt_pk_bf16_f32 v96, v148, v149
	v_cvt_pk_bf16_f32 v97, v150, v151
	v_cvt_pk_bf16_f32 v98, v176, v177
	v_cvt_pk_bf16_f32 v99, v178, v179
	global_store_dwordx4 v[100:101], v[96:99], off offset:256
	s_nop 1
	v_add_u32_e32 v96, s35, v86
	v_ashrrev_i32_e32 v97, 31, v96
	v_lshlrev_b64 v[96:97], 12, v[96:97]
	v_lshl_add_u64 v[96:97], s[24:25], 0, v[96:97]
	v_lshl_add_u64 v[96:97], v[96:97], 0, s[26:27]
	v_lshl_add_u64 v[96:97], v[96:97], 0, s[4:5]
	v_lshl_add_u64 v[96:97], v[96:97], 0, s[18:19]
	v_lshl_add_u64 v[100:101], v[96:97], 0, v[82:83]
	v_cvt_pk_bf16_f32 v96, v216, v217
	v_cvt_pk_bf16_f32 v97, v218, v219
	v_cvt_pk_bf16_f32 v98, v220, v221
	v_cvt_pk_bf16_f32 v99, v222, v223
	global_store_dwordx4 v[100:101], v[96:99], off
	s_nop 1
	v_cvt_pk_bf16_f32 v96, v180, v181
	v_cvt_pk_bf16_f32 v97, v182, v183
	v_cvt_pk_bf16_f32 v98, v184, v185
	v_cvt_pk_bf16_f32 v99, v186, v187
	global_store_dwordx4 v[100:101], v[96:99], off offset:256
	v_cvt_pk_bf16_f32 v54, v54, v55
	v_cvt_pk_bf16_f32 v55, v56, v57
	v_cvt_pk_bf16_f32 v56, v50, v51
	v_cvt_pk_bf16_f32 v57, v52, v53
	s_nop 1
	v_add_u32_e32 v96, s35, v87
	v_ashrrev_i32_e32 v97, 31, v96
	v_lshlrev_b64 v[96:97], 12, v[96:97]
	v_lshl_add_u64 v[96:97], s[24:25], 0, v[96:97]
	v_lshl_add_u64 v[96:97], v[96:97], 0, s[26:27]
	v_lshl_add_u64 v[96:97], v[96:97], 0, s[4:5]
	v_lshl_add_u64 v[96:97], v[96:97], 0, s[18:19]
	v_lshl_add_u64 v[96:97], v[96:97], 0, v[82:83]
	global_store_dwordx4 v[96:97], v[54:57], off
	v_cvt_pk_bf16_f32 v50, v70, v71
	v_cvt_pk_bf16_f32 v51, v72, v73
	v_cvt_pk_bf16_f32 v52, v62, v63
	v_cvt_pk_bf16_f32 v53, v64, v65
	global_store_dwordx4 v[96:97], v[50:53], off offset:256
	s_nop 1
	v_add_u32_e32 v50, s35, v88
	v_ashrrev_i32_e32 v51, 31, v50
	v_lshlrev_b64 v[50:51], 12, v[50:51]
	v_lshl_add_u64 v[50:51], s[24:25], 0, v[50:51]
	v_lshl_add_u64 v[50:51], v[50:51], 0, s[26:27]
	v_lshl_add_u64 v[50:51], v[50:51], 0, s[4:5]
	v_lshl_add_u64 v[50:51], v[50:51], 0, s[18:19]
	v_lshl_add_u64 v[54:55], v[50:51], 0, v[82:83]
	v_cvt_pk_bf16_f32 v50, v66, v67
	v_cvt_pk_bf16_f32 v51, v68, v69
	v_cvt_pk_bf16_f32 v52, v58, v59
	v_cvt_pk_bf16_f32 v53, v60, v61
	global_store_dwordx4 v[54:55], v[50:53], off
	s_nop 1
	v_cvt_pk_bf16_f32 v50, v128, v129
	v_cvt_pk_bf16_f32 v51, v130, v131
	v_cvt_pk_bf16_f32 v52, v132, v133
	v_cvt_pk_bf16_f32 v53, v134, v135
	global_store_dwordx4 v[54:55], v[50:53], off offset:256
	v_cvt_pk_bf16_f32 v38, v38, v39
	v_cvt_pk_bf16_f32 v39, v40, v41
	v_cvt_pk_bf16_f32 v40, v34, v35
	v_cvt_pk_bf16_f32 v41, v36, v37
	s_nop 1
	v_add_u32_e32 v50, s35, v89
	v_ashrrev_i32_e32 v51, 31, v50
	v_lshlrev_b64 v[50:51], 12, v[50:51]
	v_lshl_add_u64 v[50:51], s[24:25], 0, v[50:51]
	v_lshl_add_u64 v[50:51], v[50:51], 0, s[26:27]
	v_lshl_add_u64 v[50:51], v[50:51], 0, s[4:5]
	v_lshl_add_u64 v[50:51], v[50:51], 0, s[18:19]
	v_lshl_add_u64 v[50:51], v[50:51], 0, v[82:83]
	global_store_dwordx4 v[50:51], v[38:41], off
	v_cvt_pk_bf16_f32 v34, v46, v47
	v_cvt_pk_bf16_f32 v35, v48, v49
	v_cvt_pk_bf16_f32 v36, v42, v43
	v_cvt_pk_bf16_f32 v37, v44, v45
	global_store_dwordx4 v[50:51], v[34:37], off offset:256
	v_cvt_pk_bf16_f32 v22, v22, v23
	v_cvt_pk_bf16_f32 v23, v24, v25
	v_cvt_pk_bf16_f32 v24, v18, v19
	v_cvt_pk_bf16_f32 v25, v20, v21
	s_nop 1
	v_add_u32_e32 v34, s35, v90
	v_ashrrev_i32_e32 v35, 31, v34
	v_lshlrev_b64 v[34:35], 12, v[34:35]
	v_lshl_add_u64 v[34:35], s[24:25], 0, v[34:35]
	v_lshl_add_u64 v[34:35], v[34:35], 0, s[26:27]
	v_lshl_add_u64 v[34:35], v[34:35], 0, s[4:5]
	v_lshl_add_u64 v[34:35], v[34:35], 0, s[18:19]
	v_lshl_add_u64 v[34:35], v[34:35], 0, v[82:83]
	global_store_dwordx4 v[34:35], v[22:25], off
	v_cvt_pk_bf16_f32 v18, v30, v31
	v_cvt_pk_bf16_f32 v19, v32, v33
	v_cvt_pk_bf16_f32 v20, v26, v27
	v_cvt_pk_bf16_f32 v21, v28, v29
	global_store_dwordx4 v[34:35], v[18:21], off offset:256
	v_cvt_pk_bf16_f32 v6, v6, v7
	v_cvt_pk_bf16_f32 v7, v8, v9
	v_cvt_pk_bf16_f32 v8, v2, v3
	v_cvt_pk_bf16_f32 v9, v4, v5
	s_nop 1
	v_add_u32_e32 v18, s35, v91
	v_ashrrev_i32_e32 v19, 31, v18
	v_lshlrev_b64 v[18:19], 12, v[18:19]
	v_lshl_add_u64 v[18:19], s[24:25], 0, v[18:19]
	v_lshl_add_u64 v[18:19], v[18:19], 0, s[26:27]
	s_add_u32 s24, s43, s0
	v_lshl_add_u64 v[18:19], v[18:19], 0, s[4:5]
	s_addc_u32 s25, s44, s38
	v_lshl_add_u64 v[18:19], v[18:19], 0, s[18:19]
	v_cmp_lt_i64_e64 s[24:25], s[24:25], 64
	v_lshl_add_u64 v[18:19], v[18:19], 0, v[82:83]
	s_and_b64 vcc, exec, s[24:25]
	s_mov_b32 s4, s51
	s_mov_b32 s19, s49
	s_mov_b32 s35, s50
	s_mov_b64 s[26:27], s[22:23]
	s_mov_b64 s[24:25], s[20:21]
	global_store_dwordx4 v[18:19], v[6:9], off
	v_cvt_pk_bf16_f32 v2, v14, v15
	v_cvt_pk_bf16_f32 v3, v16, v17
	v_cvt_pk_bf16_f32 v4, v10, v11
	v_cvt_pk_bf16_f32 v5, v12, v13
	global_store_dwordx4 v[18:19], v[2:5], off offset:256
	s_cbranch_vccz .LBB0_433

; #define PG8_STAGE(bufoff, gbase, voff) do { _Pragma("unroll") for (int _i = 0; _i < 2; ++_i) \
;         __builtin_amdgcn_global_load_lds((const unsigned*)((const char*)(gbase) + (voff)[_i]), (LAS unsigned*)(lds + (bufoff) + ldsw + _i * 8192), 16, 0, 0); } while (0)
; #define PG8_LDA(dst, b, h) do { _Pragma("unroll") for (int m = 0; m < 4; ++m) _Pragma("unroll") for (int k = 0; k < 2; ++k) dst[m][k] = *(const LAS bf16x8*)(lds + PG8_SA(b, h) + aoff + m * 2048 + k * 1024); } while (0)
; #define PG8_LDB(dst, b, h) do { _Pragma("unroll") for (int n = 0; n < 2; ++n) _Pragma("unroll") for (int k = 0; k < 2; ++k) dst[n][k] = *(const LAS bf16x8*)(lds + PG8_SB(b, h) + boff + n * 2048 + k * 1024); } while (0)
; #define PG8_MMA(ai, bj, At, Bt) do { __builtin_amdgcn_s_setprio(1); _Pragma("unroll") for (int m = 0; m < 4; ++m) _Pragma("unroll") for (int n = 0; n < 2; ++n) _Pragma("unroll") for (int k = 0; k < 2; ++k) \
;         acc[ai][bj][m][n] = __builtin_amdgcn_mfma_f32_16x16x32_bf16(Bt[n][k], At[m][k], acc[ai][bj][m][n], 0, 0, 0); __builtin_amdgcn_s_setprio(0); } while (0)
; #define PG8_WAIT_L(n) asm volatile("s_waitcnt lgkmcnt(" #n ")" ::: "memory")
; #define PG8_BAR __builtin_amdgcn_s_barrier()
; #define PG8_SCHED __builtin_amdgcn_sched_barrier(0)
; template <class Sched, class Epi>
; __device__ __forceinline__ void gemm_phase(LAS unsigned char* lds, const Sched& S, const Epi& E, const int K, const int lda, const int ldb) {
;     ...
;             PG8_LDB(B0, 0, 0); PG8_SCHED; PG8_LDA(At, 0, 0); PG8_STAGE(PG8_SA(1, 1), a1 + hstepA, voffA);
;             PG8_WAIT_L(8); PG8_BAR; PG8_WAIT_L(0); PG8_MMA(0, 0, At, B0); PG8_BAR; PG8_SCHED;
;             PG8_LDB(B1, 0, 1); PG8_STAGE(PG8_SB(0, 0), b2, voffB);
;             PG8_BAR; PG8_WAIT_L(0); PG8_MMA(0, 1, At, B1); PG8_BAR;
;             PG8_LDA(At, 0, 1); PG8_STAGE(PG8_SA(0, 0), a2, voffA);
;             PG8_BAR; PG8_WAIT_L(0); if (!chalf) PG8_MMA(1, 0, At, B0); PG8_BAR; PG8_SCHED;
.LBB0_736:
	s_add_u32 s22, s18, s20
	ds_read_b128 v[148:151], v143
	ds_read_b128 v[152:155], v143 offset:1024
	ds_read_b128 v[156:159], v143 offset:2048
	ds_read_b128 v[160:163], v143 offset:3072
	s_addc_u32 s23, s19, s21
	s_add_u32 s22, s22, 0x294d8100
	s_addc_u32 s23, s23, 0
	s_add_u32 s41, s26, s20
	s_addc_u32 s42, s27, s21
	s_cmpk_eq_i32 s20, 0xf00
	s_cselect_b32 s25, s13, s23
	s_cselect_b32 s24, s12, s22
	s_cselect_b32 s23, s15, s42
	s_cselect_b32 s22, s14, s41
	s_mov_b32 m0, s29
	v_lshl_add_u64 v[196:197], v[140:141], 0, s[20:21]
	ds_read_b128 v[164:167], v144
	ds_read_b128 v[168:171], v144 offset:1024
	ds_read_b128 v[172:175], v144 offset:2048
	ds_read_b128 v[176:179], v144 offset:3072
	ds_read_b128 v[180:183], v144 offset:4096
	ds_read_b128 v[184:187], v144 offset:5120
	ds_read_b128 v[188:191], v144 offset:6144
	ds_read_b128 v[192:195], v144 offset:7168
	global_load_lds_dwordx4 v[196:197], off
	v_lshl_add_u64 v[196:197], v[138:139], 0, s[20:21]
	s_mov_b32 m0, s30
	s_nop 0
	global_load_lds_dwordx4 v[196:197], off
	s_waitcnt lgkmcnt(8)
	s_barrier
	s_waitcnt lgkmcnt(0)
	s_setprio 1
	s_waitcnt lgkmcnt(0)
	v_mfma_f32_16x16x32_bf16 v[126:129], v[148:151], v[164:167], v[126:129]
	v_mfma_f32_16x16x32_bf16 v[122:125], v[156:159], v[164:167], v[122:125]
	v_mfma_f32_16x16x32_bf16 v[110:113], v[148:151], v[172:175], v[110:113]
	v_mfma_f32_16x16x32_bf16 v[106:109], v[156:159], v[172:175], v[106:109]
	v_mfma_f32_16x16x32_bf16 v[94:97], v[148:151], v[180:183], v[94:97]
	v_mfma_f32_16x16x32_bf16 v[90:93], v[156:159], v[180:183], v[90:93]
	v_mfma_f32_16x16x32_bf16 v[78:81], v[148:151], v[188:191], v[78:81]
	v_mfma_f32_16x16x32_bf16 v[74:77], v[156:159], v[188:191], v[74:77]
	v_mfma_f32_16x16x32_bf16 v[126:129], v[152:155], v[168:171], v[126:129]
	v_mfma_f32_16x16x32_bf16 v[122:125], v[160:163], v[168:171], v[122:125]
	v_mfma_f32_16x16x32_bf16 v[110:113], v[152:155], v[176:179], v[110:113]
	v_mfma_f32_16x16x32_bf16 v[106:109], v[160:163], v[176:179], v[106:109]
	v_mfma_f32_16x16x32_bf16 v[94:97], v[152:155], v[184:187], v[94:97]
	v_mfma_f32_16x16x32_bf16 v[90:93], v[160:163], v[184:187], v[90:93]
	v_mfma_f32_16x16x32_bf16 v[78:81], v[152:155], v[192:195], v[78:81]
	v_mfma_f32_16x16x32_bf16 v[74:77], v[160:163], v[192:195], v[74:77]
	s_setprio 0
	s_barrier
	s_mov_b32 m0, s31
	s_add_u32 s54, s22, s16
	s_addc_u32 s55, s23, s17
	ds_read_b128 v[196:199], v145
	ds_read_b128 v[200:203], v145 offset:1024
	ds_read_b128 v[204:207], v145 offset:2048
	ds_read_b128 v[208:211], v145 offset:3072
	global_load_lds_dwordx4 v132, s[22:23]
	s_add_u32 s56, s22, s16
	s_addc_u32 s57, s23, s17
	s_mov_b32 m0, s34
	s_nop 0
	global_load_lds_dwordx4 v136, s[22:23]
	s_barrier
	s_waitcnt lgkmcnt(0)
	s_setprio 1
	s_waitcnt lgkmcnt(0)
	v_mfma_f32_16x16x32_bf16 v[118:121], v[196:199], v[164:167], v[118:121]
	v_mfma_f32_16x16x32_bf16 v[114:117], v[204:207], v[164:167], v[114:117]
	v_mfma_f32_16x16x32_bf16 v[102:105], v[196:199], v[172:175], v[102:105]
	v_mfma_f32_16x16x32_bf16 v[98:101], v[204:207], v[172:175], v[98:101]
	v_mfma_f32_16x16x32_bf16 v[86:89], v[196:199], v[180:183], v[86:89]
	v_mfma_f32_16x16x32_bf16 v[82:85], v[204:207], v[180:183], v[82:85]
	v_mfma_f32_16x16x32_bf16 v[70:73], v[196:199], v[188:191], v[70:73]
	v_mfma_f32_16x16x32_bf16 v[66:69], v[204:207], v[188:191], v[66:69]
	v_mfma_f32_16x16x32_bf16 v[118:121], v[200:203], v[168:171], v[118:121]
	v_mfma_f32_16x16x32_bf16 v[114:117], v[208:211], v[168:171], v[114:117]
	v_mfma_f32_16x16x32_bf16 v[102:105], v[200:203], v[176:179], v[102:105]
	v_mfma_f32_16x16x32_bf16 v[98:101], v[208:211], v[176:179], v[98:101]
	v_mfma_f32_16x16x32_bf16 v[86:89], v[200:203], v[184:187], v[86:89]
	v_mfma_f32_16x16x32_bf16 v[82:85], v[208:211], v[184:187], v[82:85]
	v_mfma_f32_16x16x32_bf16 v[70:73], v[200:203], v[192:195], v[70:73]
	v_mfma_f32_16x16x32_bf16 v[66:69], v[208:211], v[192:195], v[66:69]
	s_setprio 0
	s_mov_b32 m0, s1
	s_add_u32 s58, s24, s16
	s_addc_u32 s59, s25, s17
	s_barrier
	ds_read_b128 v[164:167], v144 offset:16384
	ds_read_b128 v[168:171], v144 offset:17408
	ds_read_b128 v[172:175], v144 offset:18432
	ds_read_b128 v[176:179], v144 offset:19456
	ds_read_b128 v[180:183], v144 offset:20480
	ds_read_b128 v[184:187], v144 offset:21504
	ds_read_b128 v[188:191], v144 offset:22528
	ds_read_b128 v[192:195], v144 offset:23552
	global_load_lds_dwordx4 v130, s[24:25]
	s_add_u32 s60, s24, s16
	s_addc_u32 s61, s25, s17
	s_mov_b32 m0, s2
	s_nop 0
	global_load_lds_dwordx4 v134, s[24:25]
	s_barrier
	s_waitcnt lgkmcnt(0)
	s_setprio 1
	s_waitcnt lgkmcnt(0)
	v_mfma_f32_16x16x32_bf16 v[62:65], v[148:151], v[164:167], v[62:65]
	v_mfma_f32_16x16x32_bf16 v[58:61], v[156:159], v[164:167], v[58:61]
	v_mfma_f32_16x16x32_bf16 v[46:49], v[148:151], v[172:175], v[46:49]
	v_mfma_f32_16x16x32_bf16 v[42:45], v[156:159], v[172:175], v[42:45]
	v_mfma_f32_16x16x32_bf16 v[30:33], v[148:151], v[180:183], v[30:33]
	v_mfma_f32_16x16x32_bf16 v[26:29], v[156:159], v[180:183], v[26:29]
	v_mfma_f32_16x16x32_bf16 v[14:17], v[148:151], v[188:191], v[14:17]
	v_mfma_f32_16x16x32_bf16 v[10:13], v[156:159], v[188:191], v[10:13]
	v_mfma_f32_16x16x32_bf16 v[62:65], v[152:155], v[168:171], v[62:65]
	v_mfma_f32_16x16x32_bf16 v[58:61], v[160:163], v[168:171], v[58:61]
	v_mfma_f32_16x16x32_bf16 v[46:49], v[152:155], v[176:179], v[46:49]
	v_mfma_f32_16x16x32_bf16 v[42:45], v[160:163], v[176:179], v[42:45]
	v_mfma_f32_16x16x32_bf16 v[30:33], v[152:155], v[184:187], v[30:33]
	v_mfma_f32_16x16x32_bf16 v[26:29], v[160:163], v[184:187], v[26:29]
	v_mfma_f32_16x16x32_bf16 v[14:17], v[152:155], v[192:195], v[14:17]
	v_mfma_f32_16x16x32_bf16 v[10:13], v[160:163], v[192:195], v[10:13]
	s_setprio 0
	s_barrier
; #define PG8_STAGE(bufoff, gbase, voff) do { _Pragma("unroll") for (int _i = 0; _i < 2; ++_i) \
;         __builtin_amdgcn_global_load_lds((const unsigned*)((const char*)(gbase) + (voff)[_i]), (LAS unsigned*)(lds + (bufoff) + ldsw + _i * 8192), 16, 0, 0); } while (0)
; #define PG8_LDA(dst, b, h) do { _Pragma("unroll") for (int m = 0; m < 4; ++m) _Pragma("unroll") for (int k = 0; k < 2; ++k) dst[m][k] = *(const LAS bf16x8*)(lds + PG8_SA(b, h) + aoff + m * 2048 + k * 1024); } while (0)
; #define PG8_LDB(dst, b, h) do { _Pragma("unroll") for (int n = 0; n < 2; ++n) _Pragma("unroll") for (int k = 0; k < 2; ++k) dst[n][k] = *(const LAS bf16x8*)(lds + PG8_SB(b, h) + boff + n * 2048 + k * 1024); } while (0)
; #define PG8_MMA(ai, bj, At, Bt) do { __builtin_amdgcn_s_setprio(1); _Pragma("unroll") for (int m = 0; m < 4; ++m) _Pragma("unroll") for (int n = 0; n < 2; ++n) _Pragma("unroll") for (int k = 0; k < 2; ++k) \
;         acc[ai][bj][m][n] = __builtin_amdgcn_mfma_f32_16x16x32_bf16(Bt[n][k], At[m][k], acc[ai][bj][m][n], 0, 0, 0); __builtin_amdgcn_s_setprio(0); } while (0)
; #define PG8_WAIT_V(n) asm volatile("s_waitcnt vmcnt(" #n ")" ::: "memory")
; #define PG8_WAIT_L(n) asm volatile("s_waitcnt lgkmcnt(" #n ")" ::: "memory")
; #define PG8_BAR __builtin_amdgcn_s_barrier()
; #define PG8_SCHED __builtin_amdgcn_sched_barrier(0)
; template <class Sched, class Epi>
; __device__ __forceinline__ void gemm_phase(LAS unsigned char* lds, const Sched& S, const Epi& E, const int K, const int lda, const int ldb) {
;     ...
;             PG8_STAGE(PG8_SB(0, 1), b2 + hstepB, voffB);
;             PG8_WAIT_V(6); PG8_BAR; if (!chalf) PG8_MMA(1, 1, At, B1); PG8_BAR;
;             PG8_LDB(B0, 1, 0); PG8_SCHED; PG8_LDA(At, 1, 0); PG8_STAGE(PG8_SA(0, 1), a2 + hstepA, voffA);
;             PG8_WAIT_L(8); PG8_BAR; PG8_WAIT_L(0); PG8_MMA(0, 0, At, B0); PG8_BAR; PG8_SCHED;
;             PG8_LDB(B1, 1, 1); PG8_STAGE(PG8_SB(1, 0), b3, voffB);
;             PG8_BAR; PG8_WAIT_L(0); PG8_MMA(0, 1, At, B1); PG8_BAR;
;             PG8_LDA(At, 1, 1); PG8_STAGE(PG8_SA(1, 0), a3, voffA);
	s_add_u32 s42, s22, 0x80000
	s_addc_u32 s43, s23, 0
	s_mov_b32 m0, s35
	s_nop 0
	global_load_lds_dwordx4 v132, s[42:43]
	s_mov_b32 m0, s36
	s_nop 0
	global_load_lds_dwordx4 v136, s[42:43]
	s_waitcnt vmcnt(6)
	s_barrier
	s_setprio 1
	v_mfma_f32_16x16x32_bf16 v[54:57], v[196:199], v[164:167], v[54:57]
	v_mfma_f32_16x16x32_bf16 v[50:53], v[204:207], v[164:167], v[50:53]
	v_mfma_f32_16x16x32_bf16 v[38:41], v[196:199], v[172:175], v[38:41]
	v_mfma_f32_16x16x32_bf16 v[34:37], v[204:207], v[172:175], v[34:37]
	v_mfma_f32_16x16x32_bf16 v[22:25], v[196:199], v[180:183], v[22:25]
	v_mfma_f32_16x16x32_bf16 v[18:21], v[204:207], v[180:183], v[18:21]
	v_mfma_f32_16x16x32_bf16 v[6:9], v[196:199], v[188:191], v[6:9]
	v_mfma_f32_16x16x32_bf16 v[2:5], v[204:207], v[188:191], v[2:5]
	v_mfma_f32_16x16x32_bf16 v[54:57], v[200:203], v[168:171], v[54:57]
	v_mfma_f32_16x16x32_bf16 v[50:53], v[208:211], v[168:171], v[50:53]
	v_mfma_f32_16x16x32_bf16 v[38:41], v[200:203], v[176:179], v[38:41]
	v_mfma_f32_16x16x32_bf16 v[34:37], v[208:211], v[176:179], v[34:37]
	v_mfma_f32_16x16x32_bf16 v[22:25], v[200:203], v[184:187], v[22:25]
	v_mfma_f32_16x16x32_bf16 v[18:21], v[208:211], v[184:187], v[18:21]
	v_mfma_f32_16x16x32_bf16 v[6:9], v[200:203], v[192:195], v[6:9]
	v_mfma_f32_16x16x32_bf16 v[2:5], v[208:211], v[192:195], v[2:5]
	s_setprio 0
	s_barrier
	ds_read_b128 v[148:151], v146
	ds_read_b128 v[152:155], v146 offset:1024
	ds_read_b128 v[156:159], v146 offset:2048
	ds_read_b128 v[160:163], v146 offset:3072
	s_add_u32 s24, s24, 0x80000
	s_addc_u32 s25, s25, 0
	s_mov_b32 m0, s3
	ds_read_b128 v[164:167], v144 offset:32768
	ds_read_b128 v[168:171], v144 offset:33792
	ds_read_b128 v[172:175], v144 offset:34816
	ds_read_b128 v[176:179], v144 offset:35840
	ds_read_b128 v[180:183], v144 offset:36864
	ds_read_b128 v[184:187], v144 offset:37888
	ds_read_b128 v[188:191], v144 offset:38912
	ds_read_b128 v[192:195], v144 offset:39936
	global_load_lds_dwordx4 v130, s[24:25]
	s_mov_b32 m0, s5
	s_nop 0
	global_load_lds_dwordx4 v134, s[24:25]
	s_waitcnt lgkmcnt(8)
	s_barrier
	s_waitcnt lgkmcnt(0)
	s_setprio 1
	s_waitcnt lgkmcnt(0)
	v_mfma_f32_16x16x32_bf16 v[126:129], v[148:151], v[164:167], v[126:129]
	v_mfma_f32_16x16x32_bf16 v[122:125], v[156:159], v[164:167], v[122:125]
	v_mfma_f32_16x16x32_bf16 v[110:113], v[148:151], v[172:175], v[110:113]
	v_mfma_f32_16x16x32_bf16 v[106:109], v[156:159], v[172:175], v[106:109]
	v_mfma_f32_16x16x32_bf16 v[94:97], v[148:151], v[180:183], v[94:97]
	v_mfma_f32_16x16x32_bf16 v[90:93], v[156:159], v[180:183], v[90:93]
	v_mfma_f32_16x16x32_bf16 v[78:81], v[148:151], v[188:191], v[78:81]
	v_mfma_f32_16x16x32_bf16 v[74:77], v[156:159], v[188:191], v[74:77]
	v_mfma_f32_16x16x32_bf16 v[126:129], v[152:155], v[168:171], v[126:129]
	v_mfma_f32_16x16x32_bf16 v[122:125], v[160:163], v[168:171], v[122:125]
	v_mfma_f32_16x16x32_bf16 v[110:113], v[152:155], v[176:179], v[110:113]
	v_mfma_f32_16x16x32_bf16 v[106:109], v[160:163], v[176:179], v[106:109]
	v_mfma_f32_16x16x32_bf16 v[94:97], v[152:155], v[184:187], v[94:97]
	v_mfma_f32_16x16x32_bf16 v[90:93], v[160:163], v[184:187], v[90:93]
	v_mfma_f32_16x16x32_bf16 v[78:81], v[152:155], v[192:195], v[78:81]
	v_mfma_f32_16x16x32_bf16 v[74:77], v[160:163], v[192:195], v[74:77]
	s_setprio 0
	s_barrier
	s_mov_b32 m0, s37
	ds_read_b128 v[196:199], v147
	ds_read_b128 v[200:203], v147 offset:1024
	ds_read_b128 v[204:207], v147 offset:2048
	ds_read_b128 v[208:211], v147 offset:3072
	global_load_lds_dwordx4 v132, s[54:55]
	s_mov_b32 m0, s38
	s_nop 0
	global_load_lds_dwordx4 v136, s[56:57]
	s_barrier
	s_waitcnt lgkmcnt(0)
	s_setprio 1
	s_waitcnt lgkmcnt(0)
	v_mfma_f32_16x16x32_bf16 v[118:121], v[196:199], v[164:167], v[118:121]
	v_mfma_f32_16x16x32_bf16 v[114:117], v[204:207], v[164:167], v[114:117]
	v_mfma_f32_16x16x32_bf16 v[102:105], v[196:199], v[172:175], v[102:105]
	v_mfma_f32_16x16x32_bf16 v[98:101], v[204:207], v[172:175], v[98:101]
	v_mfma_f32_16x16x32_bf16 v[86:89], v[196:199], v[180:183], v[86:89]
	v_mfma_f32_16x16x32_bf16 v[82:85], v[204:207], v[180:183], v[82:85]
	v_mfma_f32_16x16x32_bf16 v[70:73], v[196:199], v[188:191], v[70:73]
	v_mfma_f32_16x16x32_bf16 v[66:69], v[204:207], v[188:191], v[66:69]
	v_mfma_f32_16x16x32_bf16 v[118:121], v[200:203], v[168:171], v[118:121]
	v_mfma_f32_16x16x32_bf16 v[114:117], v[208:211], v[168:171], v[114:117]
	v_mfma_f32_16x16x32_bf16 v[102:105], v[200:203], v[176:179], v[102:105]
	v_mfma_f32_16x16x32_bf16 v[98:101], v[208:211], v[176:179], v[98:101]
	v_mfma_f32_16x16x32_bf16 v[86:89], v[200:203], v[184:187], v[86:89]
	v_mfma_f32_16x16x32_bf16 v[82:85], v[208:211], v[184:187], v[82:85]
	v_mfma_f32_16x16x32_bf16 v[70:73], v[200:203], v[192:195], v[70:73]
	v_mfma_f32_16x16x32_bf16 v[66:69], v[208:211], v[192:195], v[66:69]
	s_setprio 0
	s_mov_b32 m0, s10
	s_barrier
	ds_read_b128 v[164:167], v144 offset:49152
	ds_read_b128 v[168:171], v144 offset:50176
	ds_read_b128 v[172:175], v144 offset:51200
	ds_read_b128 v[176:179], v144 offset:52224
	ds_read_b128 v[180:183], v144 offset:53248
	ds_read_b128 v[184:187], v144 offset:54272
	ds_read_b128 v[188:191], v144 offset:55296
	ds_read_b128 v[192:195], v144 offset:56320
	global_load_lds_dwordx4 v130, s[58:59]
	s_mov_b32 m0, s11
	s_nop 0
	global_load_lds_dwordx4 v134, s[60:61]
	s_barrier
; #define PG8_STAGE(bufoff, gbase, voff) do { _Pragma("unroll") for (int _i = 0; _i < 2; ++_i) \
;         __builtin_amdgcn_global_load_lds((const unsigned*)((const char*)(gbase) + (voff)[_i]), (LAS unsigned*)(lds + (bufoff) + ldsw + _i * 8192), 16, 0, 0); } while (0)
; #define PG8_MMA(ai, bj, At, Bt) do { __builtin_amdgcn_s_setprio(1); _Pragma("unroll") for (int m = 0; m < 4; ++m) _Pragma("unroll") for (int n = 0; n < 2; ++n) _Pragma("unroll") for (int k = 0; k < 2; ++k) \
;         acc[ai][bj][m][n] = __builtin_amdgcn_mfma_f32_16x16x32_bf16(Bt[n][k], At[m][k], acc[ai][bj][m][n], 0, 0, 0); __builtin_amdgcn_s_setprio(0); } while (0)
; #define PG8_WAIT_V(n) asm volatile("s_waitcnt vmcnt(" #n ")" ::: "memory")
; #define PG8_WAIT_L(n) asm volatile("s_waitcnt lgkmcnt(" #n ")" ::: "memory")
; #define PG8_BAR __builtin_amdgcn_s_barrier()
; #define PG8_SCHED __builtin_amdgcn_sched_barrier(0)
; template <class Sched, class Epi>
; __device__ __forceinline__ void gemm_phase(LAS unsigned char* lds, const Sched& S, const Epi& E, const int K, const int lda, const int ldb) {
;     ...
;             PG8_BAR; PG8_WAIT_L(0); if (!chalf) PG8_MMA(1, 0, At, B0); PG8_BAR; PG8_SCHED;
;             PG8_STAGE(PG8_SB(1, 1), b3 + hstepB, voffB);
;             PG8_WAIT_V(6); PG8_BAR; if (!chalf) PG8_MMA(1, 1, At, B1); PG8_BAR;
;         }
;     __device__ __forceinline__ void operator()(EPI_ARGS) const {
; #pragma unroll
;         for (int ai = 0; ai < 2; ++ai) if (ai == 0 || !u.half) { u32x4 zz[4][2];
; #pragma unroll
;             for (int m = 0; m < 4; ++m)
; #pragma unroll
;                 for (int bj = 0; bj < 2; ++bj) zz[m][bj] = *(const u32x4*)(parts + E_PZC + (size_t)EPI_ROW * 1024 + EPI_COL(bj));
	s_waitcnt lgkmcnt(0)
	s_setprio 1
	s_waitcnt lgkmcnt(0)
	v_mfma_f32_16x16x32_bf16 v[62:65], v[148:151], v[164:167], v[62:65]
	v_mfma_f32_16x16x32_bf16 v[58:61], v[156:159], v[164:167], v[58:61]
	v_mfma_f32_16x16x32_bf16 v[46:49], v[148:151], v[172:175], v[46:49]
	v_mfma_f32_16x16x32_bf16 v[42:45], v[156:159], v[172:175], v[42:45]
	v_mfma_f32_16x16x32_bf16 v[30:33], v[148:151], v[180:183], v[30:33]
	v_mfma_f32_16x16x32_bf16 v[26:29], v[156:159], v[180:183], v[26:29]
	v_mfma_f32_16x16x32_bf16 v[14:17], v[148:151], v[188:191], v[14:17]
	v_mfma_f32_16x16x32_bf16 v[10:13], v[156:159], v[188:191], v[10:13]
	v_mfma_f32_16x16x32_bf16 v[62:65], v[152:155], v[168:171], v[62:65]
	v_mfma_f32_16x16x32_bf16 v[58:61], v[160:163], v[168:171], v[58:61]
	v_mfma_f32_16x16x32_bf16 v[46:49], v[152:155], v[176:179], v[46:49]
	v_mfma_f32_16x16x32_bf16 v[42:45], v[160:163], v[176:179], v[42:45]
	v_mfma_f32_16x16x32_bf16 v[30:33], v[152:155], v[184:187], v[30:33]
	v_mfma_f32_16x16x32_bf16 v[26:29], v[160:163], v[184:187], v[26:29]
	v_mfma_f32_16x16x32_bf16 v[14:17], v[152:155], v[192:195], v[14:17]
	v_mfma_f32_16x16x32_bf16 v[10:13], v[160:163], v[192:195], v[10:13]
	s_setprio 0
	s_barrier
	s_add_u32 s22, s22, 0x80080
	s_addc_u32 s23, s23, 0
	s_mov_b32 m0, s39
	s_nop 0
	global_load_lds_dwordx4 v132, s[22:23]
	s_mov_b32 m0, s40
	s_nop 0
	global_load_lds_dwordx4 v136, s[22:23]
	s_waitcnt vmcnt(6)
	s_barrier
	s_setprio 1
	v_mfma_f32_16x16x32_bf16 v[54:57], v[196:199], v[164:167], v[54:57]
	v_mfma_f32_16x16x32_bf16 v[50:53], v[204:207], v[164:167], v[50:53]
	v_mfma_f32_16x16x32_bf16 v[38:41], v[196:199], v[172:175], v[38:41]
	v_mfma_f32_16x16x32_bf16 v[34:37], v[204:207], v[172:175], v[34:37]
	v_mfma_f32_16x16x32_bf16 v[22:25], v[196:199], v[180:183], v[22:25]
	v_mfma_f32_16x16x32_bf16 v[18:21], v[204:207], v[180:183], v[18:21]
	v_mfma_f32_16x16x32_bf16 v[6:9], v[196:199], v[188:191], v[6:9]
	v_mfma_f32_16x16x32_bf16 v[2:5], v[204:207], v[188:191], v[2:5]
	v_mfma_f32_16x16x32_bf16 v[54:57], v[200:203], v[168:171], v[54:57]
	v_mfma_f32_16x16x32_bf16 v[50:53], v[208:211], v[168:171], v[50:53]
	v_mfma_f32_16x16x32_bf16 v[38:41], v[200:203], v[176:179], v[38:41]
	v_mfma_f32_16x16x32_bf16 v[34:37], v[208:211], v[176:179], v[34:37]
	v_mfma_f32_16x16x32_bf16 v[22:25], v[200:203], v[184:187], v[22:25]
	v_mfma_f32_16x16x32_bf16 v[18:21], v[208:211], v[184:187], v[18:21]
	v_mfma_f32_16x16x32_bf16 v[6:9], v[200:203], v[192:195], v[6:9]
	v_mfma_f32_16x16x32_bf16 v[2:5], v[208:211], v[192:195], v[2:5]
	s_setprio 0
	s_add_i32 s28, s28, 2
	s_add_u32 s20, s20, 0x100
	s_addc_u32 s21, s21, 0
	s_cmp_gt_u32 s28, 29
	s_barrier
	s_cbranch_scc0 .LBB0_736
	s_sext_i32_i8 s1, s4
	v_add_u32_e32 v152, s8, v1
	v_lshl_or_b32 v1, s1, 8, v142
	s_add_u32 s12, s6, 0x1b9d8000
	v_or_b32_e32 v130, s9, v1
	v_ashrrev_i32_e32 v153, 31, v152
	s_addc_u32 s13, s7, 0
	v_ashrrev_i32_e32 v131, 31, v130
	v_lshlrev_b64 v[132:133], 11, v[152:153]
	v_lshl_add_u64 v[134:135], s[12:13], 0, v[132:133]
	v_lshlrev_b64 v[150:151], 1, v[130:131]
	v_lshl_add_u64 v[130:131], v[134:135], 0, v[150:151]
	global_load_dwordx4 v[154:157], v[130:131], off
	global_load_dwordx4 v[158:161], v[130:131], off offset:256
	v_or_b32_e32 v130, 16, v152
	v_or_b32_e32 v134, 32, v152
	v_or_b32_e32 v136, 48, v152
	v_ashrrev_i32_e32 v131, 31, v130
	v_ashrrev_i32_e32 v135, 31, v134
	s_add_u32 s4, s6, 0x252d8000
	v_ashrrev_i32_e32 v137, 31, v136
	v_lshlrev_b64 v[130:131], 11, v[130:131]
	v_lshlrev_b64 v[134:135], 11, v[134:135]
	s_addc_u32 s5, s7, 0
	v_lshlrev_b64 v[136:137], 11, v[136:137]
	v_lshl_add_u64 v[130:131], s[12:13], 0, v[130:131]
	v_lshl_add_u64 v[134:135], s[12:13], 0, v[134:135]
	v_lshl_add_u64 v[136:137], s[12:13], 0, v[136:137]
	v_lshl_add_u64 v[132:133], s[4:5], 0, v[132:133]
	v_lshl_add_u64 v[130:131], v[130:131], 0, v[150:151]
	v_lshl_add_u64 v[134:135], v[134:135], 0, v[150:151]
	v_lshl_add_u64 v[166:167], v[136:137], 0, v[150:151]
	v_lshl_add_u64 v[168:169], v[132:133], 0, v[150:151]
	global_load_dwordx4 v[162:165], v[130:131], off
	global_load_dwordx4 v[146:149], v[130:131], off offset:256
	global_load_dwordx4 v[142:145], v[134:135], off
	global_load_dwordx4 v[138:141], v[134:135], off offset:256
	s_nop 0
	global_load_dwordx4 v[134:137], v[166:167], off
	global_load_dwordx4 v[130:133], v[166:167], off offset:256
	s_cmpk_lt_u32 s0, 0x100
	s_waitcnt vmcnt(0)
; __device__ __forceinline__ u32x4 pack8(const float (&f)[8]) { u32x4 r; r[0] = cvt_pk_bf16(f[0], f[1]); r[1] = cvt_pk_bf16(f[2], f[3]); r[2] = cvt_pk_bf16(f[4], f[5]); r[3] = cvt_pk_bf16(f[6], f[7]); return r; }
; __device__ __forceinline__ float siluf_(float x) { return x * __builtin_amdgcn_rcpf(1.0f + __expf(-x)); }
;     __device__ __forceinline__ void operator()(EPI_ARGS) const {
; #pragma unroll
;         for (int ai = 0; ai < 2; ++ai) if (ai == 0 || !u.half) { u32x4 zz[4][2];
; #pragma unroll
;             for (int m = 0; m < 4; ++m)
; #pragma unroll
;                 for (int bj = 0; bj < 2; ++bj) zz[m][bj] = *(const u32x4*)(parts + E_PZC + (size_t)EPI_ROW * 1024 + EPI_COL(bj));
; #pragma unroll
;             for (int m = 0; m < 4; ++m)
; #pragma unroll
;                 for (int bj = 0; bj < 2; ++bj) { const f32x4 v0 = acc[ai][bj][m][0], v1 = acc[ai][bj][m][1]; float z[8]; unpack8(zz[m][bj], z); float o[8];
; #pragma unroll
;                     for (int j = 0; j < 4; ++j) { o[j] = v0[j] * siluf_(z[j]); o[4 + j] = v1[j] * siluf_(z[4 + j]); }
;                     *(u32x4*)(O + (size_t)EPI_ROW * 1024 + EPI_COL(bj)) = pack8(o); } }
	v_lshlrev_b32_e32 v1, 16, v154
	v_and_b32_e32 v153, 0xffff0000, v154
	v_lshlrev_b32_e32 v154, 16, v155
	v_and_b32_e32 v155, 0xffff0000, v155
	v_lshlrev_b32_e32 v166, 16, v156
	v_and_b32_e32 v156, 0xffff0000, v156
	v_lshlrev_b32_e32 v167, 16, v157
	v_and_b32_e32 v157, 0xffff0000, v157
	v_mul_f32_e32 v171, 0xbfb8aa3b, v1
	v_mul_f32_e32 v172, 0xbfb8aa3b, v166
	v_mul_f32_e32 v173, 0xbfb8aa3b, v153
	v_mul_f32_e32 v174, 0xbfb8aa3b, v156
	v_mul_f32_e32 v175, 0xbfb8aa3b, v154
	v_mul_f32_e32 v176, 0xbfb8aa3b, v167
	v_mul_f32_e32 v177, 0xbfb8aa3b, v155
	v_mul_f32_e32 v178, 0xbfb8aa3b, v157
	v_exp_f32_e32 v171, v171
	v_exp_f32_e32 v172, v172
	v_exp_f32_e32 v173, v173
	v_exp_f32_e32 v174, v174
	v_exp_f32_e32 v175, v175
	v_exp_f32_e32 v176, v176
	v_exp_f32_e32 v177, v177
	v_exp_f32_e32 v178, v178
	v_add_f32_e32 v171, 1.0, v171
	v_add_f32_e32 v172, 1.0, v172
	v_add_f32_e32 v173, 1.0, v173
	v_add_f32_e32 v174, 1.0, v174
	v_add_f32_e32 v175, 1.0, v175
	v_add_f32_e32 v176, 1.0, v176
	v_add_f32_e32 v177, 1.0, v177
	v_add_f32_e32 v178, 1.0, v178
	v_rcp_f32_e32 v171, v171
	v_rcp_f32_e32 v172, v172
	v_rcp_f32_e32 v173, v173
	v_rcp_f32_e32 v174, v174
	v_rcp_f32_e32 v175, v175
	v_rcp_f32_e32 v176, v176
	v_rcp_f32_e32 v177, v177
	v_rcp_f32_e32 v178, v178
	v_mul_f32_e32 v1, v171, v1
	v_mul_f32_e32 v166, v172, v166
	v_mul_f32_e32 v153, v173, v153
	v_mul_f32_e32 v156, v174, v156
	v_mul_f32_e32 v154, v175, v154
	v_mul_f32_e32 v167, v176, v167
	v_mul_f32_e32 v155, v177, v155
	v_lshlrev_b32_e32 v170, 16, v158
	v_mul_f32_e32 v157, v178, v157
	v_mul_f32_e32 v1, v126, v1
	v_mul_f32_e32 v126, v122, v166
	v_mul_f32_e32 v122, v127, v153
	v_mul_f32_e32 v127, v123, v156
	v_mul_f32_e32 v123, v128, v154
	v_mul_f32_e32 v128, v124, v167
	v_mul_f32_e32 v124, v129, v155
	v_mul_f32_e32 v125, v125, v157
	v_cvt_pk_bf16_f32 v122, v1, v122
	v_cvt_pk_bf16_f32 v123, v123, v124
	v_cvt_pk_bf16_f32 v124, v126, v127
	v_mul_f32_e32 v126, 0xbfb8aa3b, v170
	v_cvt_pk_bf16_f32 v125, v128, v125
	global_store_dwordx4 v[168:169], v[122:125], off
	v_exp_f32_e32 v126, v126
	v_and_b32_e32 v1, 0xffff0000, v158
	v_lshlrev_b32_e32 v124, 16, v160
	v_mul_f32_e32 v127, 0xbfb8aa3b, v124
	v_exp_f32_e32 v127, v127
	v_add_f32_e32 v126, 1.0, v126
	v_rcp_f32_e32 v126, v126
	v_and_b32_e32 v125, 0xffff0000, v160
	v_add_f32_e32 v127, 1.0, v127
	v_rcp_f32_e32 v127, v127
	v_mul_f32_e32 v126, v126, v170
	v_mul_f32_e32 v118, v118, v126
	v_mul_f32_e32 v126, 0xbfb8aa3b, v1
	v_mul_f32_e32 v124, v127, v124
	v_exp_f32_e32 v126, v126
	v_mul_f32_e32 v127, 0xbfb8aa3b, v125
	v_exp_f32_e32 v127, v127
	v_lshlrev_b32_e32 v122, 16, v159
	v_mul_f32_e32 v124, v114, v124
	v_add_f32_e32 v114, 1.0, v126
	v_rcp_f32_e32 v114, v114
	v_add_f32_e32 v126, 1.0, v127
	v_mul_f32_e32 v127, 0xbfb8aa3b, v122
	v_exp_f32_e32 v127, v127
	v_mul_f32_e32 v1, v114, v1
	v_rcp_f32_e32 v126, v126
	v_mul_f32_e32 v1, v119, v1
	v_add_f32_e32 v119, 1.0, v127
	v_rcp_f32_e32 v119, v119
	v_lshlrev_b32_e32 v128, 16, v161
	v_and_b32_e32 v123, 0xffff0000, v159
	v_mul_f32_e32 v114, v126, v125
	v_mul_f32_e32 v125, 0xbfb8aa3b, v128
	v_and_b32_e32 v129, 0xffff0000, v161
	v_exp_f32_e32 v125, v125
	v_mul_f32_e32 v126, v115, v114
	v_mul_f32_e32 v114, v119, v122
	v_mul_f32_e32 v119, 0xbfb8aa3b, v123
	v_mul_f32_e32 v115, v120, v114
	v_exp_f32_e32 v119, v119
	v_mul_f32_e32 v120, 0xbfb8aa3b, v129
	v_exp_f32_e32 v120, v120
	v_add_f32_e32 v114, 1.0, v125
	v_rcp_f32_e32 v114, v114
	v_add_f32_e32 v119, 1.0, v119
	v_rcp_f32_e32 v119, v119
	v_add_f32_e32 v120, 1.0, v120
	v_rcp_f32_e32 v120, v120
	v_mul_f32_e32 v114, v114, v128
	v_mul_f32_e32 v122, v116, v114
	v_mul_f32_e32 v114, v119, v123
	v_mul_f32_e32 v116, v121, v114
	v_mul_f32_e32 v114, v120, v129
	v_mul_f32_e32 v117, v117, v114
	v_cvt_pk_bf16_f32 v114, v118, v1
	v_cvt_pk_bf16_f32 v115, v115, v116
	v_cvt_pk_bf16_f32 v116, v124, v126
	v_cvt_pk_bf16_f32 v117, v122, v117
	v_lshlrev_b32_e32 v1, 16, v162
	global_store_dwordx4 v[168:169], v[114:117], off offset:256
	v_mul_f32_e32 v119, 0xbfb8aa3b, v1
	v_exp_f32_e32 v119, v119
	v_lshlrev_b32_e32 v117, 16, v164
	v_mul_f32_e32 v120, 0xbfb8aa3b, v117
	v_exp_f32_e32 v120, v120
	v_add_f32_e32 v119, 1.0, v119
	v_rcp_f32_e32 v119, v119
	v_and_b32_e32 v114, 0xffff0000, v162
	v_add_f32_e32 v120, 1.0, v120
	v_rcp_f32_e32 v120, v120
	v_and_b32_e32 v118, 0xffff0000, v164
	v_mul_f32_e32 v1, v119, v1
	v_mul_f32_e32 v1, v110, v1
	v_mul_f32_e32 v110, v120, v117
	v_mul_f32_e32 v117, 0xbfb8aa3b, v114
	v_mul_f32_e32 v119, 0xbfb8aa3b, v118
	v_exp_f32_e32 v117, v117
	v_exp_f32_e32 v119, v119
	v_lshlrev_b32_e32 v115, 16, v163
	v_mul_f32_e32 v110, v106, v110
	v_add_f32_e32 v106, 1.0, v117
	v_add_f32_e32 v117, 1.0, v119
	v_mul_f32_e32 v119, 0xbfb8aa3b, v115
	v_rcp_f32_e32 v106, v106
	v_exp_f32_e32 v119, v119
	v_rcp_f32_e32 v117, v117
	v_lshlrev_b32_e32 v121, 16, v165
	v_mul_f32_e32 v106, v106, v114
	v_add_f32_e32 v114, 1.0, v119
	v_rcp_f32_e32 v114, v114
	v_and_b32_e32 v116, 0xffff0000, v163
	v_mul_f32_e32 v106, v111, v106
	v_mul_f32_e32 v111, v117, v118
	v_mul_f32_e32 v117, 0xbfb8aa3b, v121
	v_exp_f32_e32 v117, v117
	v_mul_f32_e32 v111, v107, v111
	v_mul_f32_e32 v107, v114, v115
	v_mul_f32_e32 v114, 0xbfb8aa3b, v116
	v_exp_f32_e32 v114, v114
	v_and_b32_e32 v122, 0xffff0000, v165
	v_mul_f32_e32 v107, v112, v107
	v_add_f32_e32 v112, 1.0, v117
	v_mul_f32_e32 v115, 0xbfb8aa3b, v122
	v_rcp_f32_e32 v112, v112
	v_exp_f32_e32 v115, v115
	v_add_f32_e32 v114, 1.0, v114
	v_rcp_f32_e32 v114, v114
	v_mul_f32_e32 v112, v112, v121
	v_add_f32_e32 v115, 1.0, v115
	v_rcp_f32_e32 v115, v115
	v_mul_f32_e32 v112, v108, v112
	v_mul_f32_e32 v108, v114, v116
	v_mul_f32_e32 v108, v113, v108
	v_cvt_pk_bf16_f32 v106, v1, v106
; __device__ __forceinline__ u32x4 pack8(const float (&f)[8]) { u32x4 r; r[0] = cvt_pk_bf16(f[0], f[1]); r[1] = cvt_pk_bf16(f[2], f[3]); r[2] = cvt_pk_bf16(f[4], f[5]); r[3] = cvt_pk_bf16(f[6], f[7]); return r; }
; __device__ __forceinline__ float siluf_(float x) { return x * __builtin_amdgcn_rcpf(1.0f + __expf(-x)); }
;     __device__ __forceinline__ void operator()(EPI_ARGS) const {
;     ...
;                 for (int bj = 0; bj < 2; ++bj) zz[m][bj] = *(const u32x4*)(parts + E_PZC + (size_t)EPI_ROW * 1024 + EPI_COL(bj));
; #pragma unroll
;             for (int m = 0; m < 4; ++m)
; #pragma unroll
;                 for (int bj = 0; bj < 2; ++bj) { const f32x4 v0 = acc[ai][bj][m][0], v1 = acc[ai][bj][m][1]; float z[8]; unpack8(zz[m][bj], z); float o[8];
; #pragma unroll
;                     for (int j = 0; j < 4; ++j) { o[j] = v0[j] * siluf_(z[j]); o[4 + j] = v1[j] * siluf_(z[4 + j]); }
;                     *(u32x4*)(O + (size_t)EPI_ROW * 1024 + EPI_COL(bj)) = pack8(o); } }
	v_cvt_pk_bf16_f32 v107, v107, v108
	v_cvt_pk_bf16_f32 v108, v110, v111
	v_add_u32_e32 v110, 16, v152
	v_ashrrev_i32_e32 v111, 31, v110
	v_mul_f32_e32 v113, v115, v122
	v_lshlrev_b64 v[110:111], 11, v[110:111]
	v_mul_f32_e32 v109, v109, v113
	v_lshl_add_u64 v[110:111], s[4:5], 0, v[110:111]
	v_cvt_pk_bf16_f32 v109, v112, v109
	v_lshl_add_u64 v[110:111], v[110:111], 0, v[150:151]
	v_lshlrev_b32_e32 v1, 16, v146
	global_store_dwordx4 v[110:111], v[106:109], off
	v_mul_f32_e32 v113, 0xbfb8aa3b, v1
	v_exp_f32_e32 v113, v113
	v_lshlrev_b32_e32 v109, 16, v148
	v_mul_f32_e32 v114, 0xbfb8aa3b, v109
	v_exp_f32_e32 v114, v114
	v_add_f32_e32 v113, 1.0, v113
	v_rcp_f32_e32 v113, v113
	v_and_b32_e32 v106, 0xffff0000, v146
	v_add_f32_e32 v114, 1.0, v114
	v_rcp_f32_e32 v114, v114
	v_and_b32_e32 v112, 0xffff0000, v148
	v_mul_f32_e32 v1, v113, v1
	v_mul_f32_e32 v1, v102, v1
	v_mul_f32_e32 v102, v114, v109
	v_mul_f32_e32 v109, 0xbfb8aa3b, v106
	v_mul_f32_e32 v113, 0xbfb8aa3b, v112
	v_exp_f32_e32 v109, v109
	v_exp_f32_e32 v113, v113
	v_lshlrev_b32_e32 v107, 16, v147
	v_mul_f32_e32 v102, v98, v102
	v_add_f32_e32 v98, 1.0, v109
	v_add_f32_e32 v109, 1.0, v113
	v_mul_f32_e32 v113, 0xbfb8aa3b, v107
	v_rcp_f32_e32 v98, v98
	v_exp_f32_e32 v113, v113
	v_rcp_f32_e32 v109, v109
	v_lshlrev_b32_e32 v115, 16, v149
	v_mul_f32_e32 v98, v98, v106
	v_add_f32_e32 v106, 1.0, v113
	v_rcp_f32_e32 v106, v106
	v_and_b32_e32 v108, 0xffff0000, v147
	v_mul_f32_e32 v98, v103, v98
	v_mul_f32_e32 v103, v109, v112
	v_mul_f32_e32 v109, 0xbfb8aa3b, v115
	v_and_b32_e32 v116, 0xffff0000, v149
	v_exp_f32_e32 v109, v109
	v_mul_f32_e32 v103, v99, v103
	v_mul_f32_e32 v99, v106, v107
	v_mul_f32_e32 v106, 0xbfb8aa3b, v108
	v_exp_f32_e32 v106, v106
	v_mul_f32_e32 v107, 0xbfb8aa3b, v116
	v_exp_f32_e32 v107, v107
	v_mul_f32_e32 v99, v104, v99
	v_add_f32_e32 v104, 1.0, v109
	v_rcp_f32_e32 v104, v104
	v_add_f32_e32 v106, 1.0, v106
	v_rcp_f32_e32 v106, v106
	v_add_f32_e32 v107, 1.0, v107
	v_rcp_f32_e32 v107, v107
	v_mul_f32_e32 v104, v104, v115
	v_mul_f32_e32 v104, v100, v104
	v_mul_f32_e32 v100, v106, v108
	v_mul_f32_e32 v100, v105, v100
	v_mul_f32_e32 v105, v107, v116
	v_mul_f32_e32 v101, v101, v105
	v_cvt_pk_bf16_f32 v98, v1, v98
	v_cvt_pk_bf16_f32 v99, v99, v100
	v_cvt_pk_bf16_f32 v100, v102, v103
	v_cvt_pk_bf16_f32 v101, v104, v101
	v_lshlrev_b32_e32 v1, 16, v142
	global_store_dwordx4 v[110:111], v[98:101], off offset:256
	v_mul_f32_e32 v103, 0xbfb8aa3b, v1
	v_exp_f32_e32 v103, v103
	v_lshlrev_b32_e32 v101, 16, v144
	v_mul_f32_e32 v104, 0xbfb8aa3b, v101
	v_exp_f32_e32 v104, v104
	v_add_f32_e32 v103, 1.0, v103
	v_rcp_f32_e32 v103, v103
	v_and_b32_e32 v98, 0xffff0000, v142
	v_add_f32_e32 v104, 1.0, v104
	v_rcp_f32_e32 v104, v104
	v_and_b32_e32 v102, 0xffff0000, v144
	v_mul_f32_e32 v1, v103, v1
	v_mul_f32_e32 v1, v94, v1
	v_mul_f32_e32 v94, v104, v101
	v_mul_f32_e32 v101, 0xbfb8aa3b, v98
	v_mul_f32_e32 v103, 0xbfb8aa3b, v102
	v_exp_f32_e32 v101, v101
	v_exp_f32_e32 v103, v103
	v_lshlrev_b32_e32 v99, 16, v143
	v_mul_f32_e32 v94, v90, v94
	v_add_f32_e32 v90, 1.0, v101
	v_add_f32_e32 v101, 1.0, v103
	v_mul_f32_e32 v103, 0xbfb8aa3b, v99
	v_rcp_f32_e32 v90, v90
	v_exp_f32_e32 v103, v103
	v_rcp_f32_e32 v101, v101
	v_lshlrev_b32_e32 v105, 16, v145
	v_mul_f32_e32 v90, v90, v98
	v_add_f32_e32 v98, 1.0, v103
	v_rcp_f32_e32 v98, v98
	v_and_b32_e32 v100, 0xffff0000, v143
	v_mul_f32_e32 v90, v95, v90
	v_mul_f32_e32 v95, v101, v102
	v_mul_f32_e32 v101, 0xbfb8aa3b, v105
	v_exp_f32_e32 v101, v101
	v_mul_f32_e32 v95, v91, v95
	v_mul_f32_e32 v91, v98, v99
	v_mul_f32_e32 v98, 0xbfb8aa3b, v100
	v_exp_f32_e32 v98, v98
	v_and_b32_e32 v106, 0xffff0000, v145
	v_mul_f32_e32 v91, v96, v91
	v_add_f32_e32 v96, 1.0, v101
	v_mul_f32_e32 v99, 0xbfb8aa3b, v106
	v_rcp_f32_e32 v96, v96
	v_exp_f32_e32 v99, v99
	v_add_f32_e32 v98, 1.0, v98
	v_rcp_f32_e32 v98, v98
	v_mul_f32_e32 v96, v96, v105
	v_add_f32_e32 v99, 1.0, v99
	v_rcp_f32_e32 v99, v99
	v_mul_f32_e32 v96, v92, v96
	v_mul_f32_e32 v92, v98, v100
	v_mul_f32_e32 v92, v97, v92
	v_cvt_pk_bf16_f32 v90, v1, v90
	v_cvt_pk_bf16_f32 v91, v91, v92
	v_cvt_pk_bf16_f32 v92, v94, v95
	v_add_u32_e32 v94, 32, v152
	v_ashrrev_i32_e32 v95, 31, v94
	v_mul_f32_e32 v97, v99, v106
	v_lshlrev_b64 v[94:95], 11, v[94:95]
	v_mul_f32_e32 v93, v93, v97
	v_lshl_add_u64 v[94:95], s[4:5], 0, v[94:95]
	v_cvt_pk_bf16_f32 v93, v96, v93
	v_lshl_add_u64 v[94:95], v[94:95], 0, v[150:151]
	v_lshlrev_b32_e32 v1, 16, v138
	global_store_dwordx4 v[94:95], v[90:93], off
	v_mul_f32_e32 v97, 0xbfb8aa3b, v1
	v_exp_f32_e32 v97, v97
	v_lshlrev_b32_e32 v93, 16, v140
	v_mul_f32_e32 v98, 0xbfb8aa3b, v93
	v_exp_f32_e32 v98, v98
	v_add_f32_e32 v97, 1.0, v97
	v_rcp_f32_e32 v97, v97
	v_and_b32_e32 v90, 0xffff0000, v138
	v_add_f32_e32 v98, 1.0, v98
	v_rcp_f32_e32 v98, v98
	v_and_b32_e32 v96, 0xffff0000, v140
	v_mul_f32_e32 v1, v97, v1
	v_mul_f32_e32 v1, v86, v1
	v_mul_f32_e32 v86, v98, v93
	v_mul_f32_e32 v93, 0xbfb8aa3b, v90
	v_mul_f32_e32 v97, 0xbfb8aa3b, v96
	v_exp_f32_e32 v93, v93
	v_exp_f32_e32 v97, v97
	v_lshlrev_b32_e32 v91, 16, v139
	v_mul_f32_e32 v86, v82, v86
	v_add_f32_e32 v82, 1.0, v93
	v_add_f32_e32 v93, 1.0, v97
	v_mul_f32_e32 v97, 0xbfb8aa3b, v91
	v_rcp_f32_e32 v82, v82
	v_exp_f32_e32 v97, v97
	v_rcp_f32_e32 v93, v93
	v_lshlrev_b32_e32 v99, 16, v141
	v_mul_f32_e32 v82, v82, v90
	v_add_f32_e32 v90, 1.0, v97
	v_rcp_f32_e32 v90, v90
	v_and_b32_e32 v92, 0xffff0000, v139
	v_mul_f32_e32 v82, v87, v82
	v_mul_f32_e32 v87, v93, v96
	v_mul_f32_e32 v93, 0xbfb8aa3b, v99
	v_and_b32_e32 v100, 0xffff0000, v141
	v_exp_f32_e32 v93, v93
	v_mul_f32_e32 v87, v83, v87
	v_mul_f32_e32 v83, v90, v91
	v_mul_f32_e32 v90, 0xbfb8aa3b, v92
; __device__ __forceinline__ u32x4 pack8(const float (&f)[8]) { u32x4 r; r[0] = cvt_pk_bf16(f[0], f[1]); r[1] = cvt_pk_bf16(f[2], f[3]); r[2] = cvt_pk_bf16(f[4], f[5]); r[3] = cvt_pk_bf16(f[6], f[7]); return r; }
; __device__ __forceinline__ float siluf_(float x) { return x * __builtin_amdgcn_rcpf(1.0f + __expf(-x)); }
;     __device__ __forceinline__ void operator()(EPI_ARGS) const {
;     ...
;                 for (int bj = 0; bj < 2; ++bj) zz[m][bj] = *(const u32x4*)(parts + E_PZC + (size_t)EPI_ROW * 1024 + EPI_COL(bj));
; #pragma unroll
;             for (int m = 0; m < 4; ++m)
; #pragma unroll
;                 for (int bj = 0; bj < 2; ++bj) { const f32x4 v0 = acc[ai][bj][m][0], v1 = acc[ai][bj][m][1]; float z[8]; unpack8(zz[m][bj], z); float o[8];
; #pragma unroll
;                     for (int j = 0; j < 4; ++j) { o[j] = v0[j] * siluf_(z[j]); o[4 + j] = v1[j] * siluf_(z[4 + j]); }
;                     *(u32x4*)(O + (size_t)EPI_ROW * 1024 + EPI_COL(bj)) = pack8(o); } }
	v_exp_f32_e32 v90, v90
	v_mul_f32_e32 v91, 0xbfb8aa3b, v100
	v_exp_f32_e32 v91, v91
	v_mul_f32_e32 v83, v88, v83
	v_add_f32_e32 v88, 1.0, v93
	v_rcp_f32_e32 v88, v88
	v_add_f32_e32 v90, 1.0, v90
	v_rcp_f32_e32 v90, v90
	v_add_f32_e32 v91, 1.0, v91
	v_rcp_f32_e32 v91, v91
	v_mul_f32_e32 v88, v88, v99
	v_mul_f32_e32 v88, v84, v88
	v_mul_f32_e32 v84, v90, v92
	v_mul_f32_e32 v84, v89, v84
	v_mul_f32_e32 v89, v91, v100
	v_mul_f32_e32 v85, v85, v89
	v_cvt_pk_bf16_f32 v82, v1, v82
	v_cvt_pk_bf16_f32 v83, v83, v84
	v_cvt_pk_bf16_f32 v84, v86, v87
	v_cvt_pk_bf16_f32 v85, v88, v85
	v_lshlrev_b32_e32 v1, 16, v134
	global_store_dwordx4 v[94:95], v[82:85], off offset:256
	v_mul_f32_e32 v87, 0xbfb8aa3b, v1
	v_exp_f32_e32 v87, v87
	v_lshlrev_b32_e32 v85, 16, v136
	v_mul_f32_e32 v88, 0xbfb8aa3b, v85
	v_exp_f32_e32 v88, v88
	v_add_f32_e32 v87, 1.0, v87
	v_rcp_f32_e32 v87, v87
	v_and_b32_e32 v82, 0xffff0000, v134
	v_add_f32_e32 v88, 1.0, v88
	v_rcp_f32_e32 v88, v88
	v_and_b32_e32 v86, 0xffff0000, v136
	v_mul_f32_e32 v1, v87, v1
	v_mul_f32_e32 v1, v78, v1
	v_mul_f32_e32 v78, v88, v85
	v_mul_f32_e32 v85, 0xbfb8aa3b, v82
	v_mul_f32_e32 v87, 0xbfb8aa3b, v86
	v_exp_f32_e32 v85, v85
	v_exp_f32_e32 v87, v87
	v_lshlrev_b32_e32 v83, 16, v135
	v_mul_f32_e32 v78, v74, v78
	v_add_f32_e32 v74, 1.0, v85
	v_add_f32_e32 v85, 1.0, v87
	v_mul_f32_e32 v87, 0xbfb8aa3b, v83
	v_rcp_f32_e32 v74, v74
	v_exp_f32_e32 v87, v87
	v_rcp_f32_e32 v85, v85
	v_lshlrev_b32_e32 v89, 16, v137
	v_mul_f32_e32 v74, v74, v82
	v_add_f32_e32 v82, 1.0, v87
	v_rcp_f32_e32 v82, v82
	v_and_b32_e32 v84, 0xffff0000, v135
	v_mul_f32_e32 v74, v79, v74
	v_mul_f32_e32 v79, v85, v86
	v_mul_f32_e32 v85, 0xbfb8aa3b, v89
	v_exp_f32_e32 v85, v85
	v_mul_f32_e32 v79, v75, v79
	v_mul_f32_e32 v75, v82, v83
	v_mul_f32_e32 v82, 0xbfb8aa3b, v84
	v_exp_f32_e32 v82, v82
	v_and_b32_e32 v90, 0xffff0000, v137
	v_mul_f32_e32 v75, v80, v75
	v_add_f32_e32 v80, 1.0, v85
	v_mul_f32_e32 v83, 0xbfb8aa3b, v90
	v_rcp_f32_e32 v80, v80
	v_exp_f32_e32 v83, v83
	v_add_f32_e32 v82, 1.0, v82
	v_rcp_f32_e32 v82, v82
	v_mul_f32_e32 v80, v80, v89
	v_add_f32_e32 v83, 1.0, v83
	v_rcp_f32_e32 v83, v83
	v_mul_f32_e32 v80, v76, v80
	v_mul_f32_e32 v76, v82, v84
	v_mul_f32_e32 v76, v81, v76
	v_cvt_pk_bf16_f32 v74, v1, v74
	v_cvt_pk_bf16_f32 v75, v75, v76
	v_cvt_pk_bf16_f32 v76, v78, v79
	v_add_u32_e32 v78, 48, v152
	v_ashrrev_i32_e32 v79, 31, v78
	v_mul_f32_e32 v81, v83, v90
	v_lshlrev_b64 v[78:79], 11, v[78:79]
	v_mul_f32_e32 v77, v77, v81
	v_lshl_add_u64 v[78:79], s[4:5], 0, v[78:79]
	v_cvt_pk_bf16_f32 v77, v80, v77
	v_lshl_add_u64 v[78:79], v[78:79], 0, v[150:151]
	v_lshlrev_b32_e32 v1, 16, v130
	global_store_dwordx4 v[78:79], v[74:77], off
	v_mul_f32_e32 v81, 0xbfb8aa3b, v1
	v_exp_f32_e32 v81, v81
	v_lshlrev_b32_e32 v77, 16, v132
	v_mul_f32_e32 v82, 0xbfb8aa3b, v77
	v_exp_f32_e32 v82, v82
	v_add_f32_e32 v81, 1.0, v81
	v_rcp_f32_e32 v81, v81
	v_and_b32_e32 v74, 0xffff0000, v130
	v_add_f32_e32 v82, 1.0, v82
	v_rcp_f32_e32 v82, v82
	v_and_b32_e32 v80, 0xffff0000, v132
	v_mul_f32_e32 v1, v81, v1
	v_mul_f32_e32 v1, v70, v1
	v_mul_f32_e32 v70, v82, v77
	v_mul_f32_e32 v77, 0xbfb8aa3b, v74
	v_mul_f32_e32 v81, 0xbfb8aa3b, v80
	v_exp_f32_e32 v77, v77
	v_exp_f32_e32 v81, v81
	v_lshlrev_b32_e32 v75, 16, v131
	v_mul_f32_e32 v70, v66, v70
	v_add_f32_e32 v66, 1.0, v77
	v_add_f32_e32 v77, 1.0, v81
	v_mul_f32_e32 v81, 0xbfb8aa3b, v75
	v_rcp_f32_e32 v66, v66
	v_exp_f32_e32 v81, v81
	v_rcp_f32_e32 v77, v77
	v_lshlrev_b32_e32 v83, 16, v133
	v_mul_f32_e32 v66, v66, v74
	v_add_f32_e32 v74, 1.0, v81
	v_rcp_f32_e32 v74, v74
	v_and_b32_e32 v76, 0xffff0000, v131
	v_mul_f32_e32 v66, v71, v66
	v_mul_f32_e32 v71, v77, v80
	v_mul_f32_e32 v77, 0xbfb8aa3b, v83
	v_exp_f32_e32 v77, v77
	v_mul_f32_e32 v71, v67, v71
	v_mul_f32_e32 v67, v74, v75
	v_mul_f32_e32 v74, 0xbfb8aa3b, v76
	v_exp_f32_e32 v74, v74
	v_and_b32_e32 v84, 0xffff0000, v133
	v_mul_f32_e32 v67, v72, v67
	v_add_f32_e32 v72, 1.0, v77
	v_rcp_f32_e32 v72, v72
	v_mul_f32_e32 v75, 0xbfb8aa3b, v84
	v_add_f32_e32 v74, 1.0, v74
	v_exp_f32_e32 v75, v75
	v_rcp_f32_e32 v74, v74
	v_mul_f32_e32 v72, v72, v83
	v_mul_f32_e32 v72, v68, v72
	v_add_f32_e32 v75, 1.0, v75
	v_mul_f32_e32 v68, v74, v76
	v_rcp_f32_e32 v75, v75
	v_mul_f32_e32 v68, v73, v68
	v_cvt_pk_bf16_f32 v66, v1, v66
	v_cvt_pk_bf16_f32 v67, v67, v68
	v_cvt_pk_bf16_f32 v68, v70, v71
	v_add_u32_e32 v70, 0x80, v152
	v_ashrrev_i32_e32 v71, 31, v70
	v_lshlrev_b64 v[104:105], 11, v[70:71]
	v_mul_f32_e32 v73, v75, v84
	v_lshl_add_u64 v[70:71], s[12:13], 0, v[104:105]
	v_mul_f32_e32 v69, v69, v73
	v_lshl_add_u64 v[70:71], v[70:71], 0, v[150:151]
	v_cvt_pk_bf16_f32 v69, v72, v69
	global_load_dwordx4 v[92:95], v[70:71], off
	s_nop 0
	global_store_dwordx4 v[78:79], v[66:69], off offset:256
	global_load_dwordx4 v[96:99], v[70:71], off offset:256
	s_waitcnt vmcnt(0)
; __device__ __forceinline__ u32x4 pack8(const float (&f)[8]) { u32x4 r; r[0] = cvt_pk_bf16(f[0], f[1]); r[1] = cvt_pk_bf16(f[2], f[3]); r[2] = cvt_pk_bf16(f[4], f[5]); r[3] = cvt_pk_bf16(f[6], f[7]); return r; }
; __device__ __forceinline__ float siluf_(float x) { return x * __builtin_amdgcn_rcpf(1.0f + __expf(-x)); }
;     __device__ __forceinline__ void operator()(EPI_ARGS) const {
;     ...
;                 for (int bj = 0; bj < 2; ++bj) zz[m][bj] = *(const u32x4*)(parts + E_PZC + (size_t)EPI_ROW * 1024 + EPI_COL(bj));
; #pragma unroll
;             for (int m = 0; m < 4; ++m)
; #pragma unroll
;                 for (int bj = 0; bj < 2; ++bj) { const f32x4 v0 = acc[ai][bj][m][0], v1 = acc[ai][bj][m][1]; float z[8]; unpack8(zz[m][bj], z); float o[8];
; #pragma unroll
;                     for (int j = 0; j < 4; ++j) { o[j] = v0[j] * siluf_(z[j]); o[4 + j] = v1[j] * siluf_(z[4 + j]); }
;                     *(u32x4*)(O + (size_t)EPI_ROW * 1024 + EPI_COL(bj)) = pack8(o); } }
	v_lshlrev_b32_e32 v1, 16, v92
	v_add_u32_e32 v66, 0x90, v152
	v_ashrrev_i32_e32 v67, 31, v66
	v_lshlrev_b64 v[90:91], 11, v[66:67]
	v_lshl_add_u64 v[66:67], s[12:13], 0, v[90:91]
	v_lshl_add_u64 v[66:67], v[66:67], 0, v[150:151]
	global_load_dwordx4 v[100:103], v[66:67], off
	global_load_dwordx4 v[82:85], v[66:67], off offset:256
	v_add_u32_e32 v66, 0xa0, v152
	v_ashrrev_i32_e32 v67, 31, v66
	v_lshlrev_b64 v[88:89], 11, v[66:67]
	v_lshl_add_u64 v[66:67], s[12:13], 0, v[88:89]
	v_lshl_add_u64 v[66:67], v[66:67], 0, v[150:151]
	global_load_dwordx4 v[78:81], v[66:67], off
	global_load_dwordx4 v[74:77], v[66:67], off offset:256
	v_add_u32_e32 v66, 0xb0, v152
	v_ashrrev_i32_e32 v67, 31, v66
	v_lshlrev_b64 v[86:87], 11, v[66:67]
	v_lshl_add_u64 v[66:67], s[12:13], 0, v[86:87]
	v_lshl_add_u64 v[106:107], v[66:67], 0, v[150:151]
	global_load_dwordx4 v[70:73], v[106:107], off
	global_load_dwordx4 v[66:69], v[106:107], off offset:256
	v_lshlrev_b32_e32 v107, 16, v94
	v_mul_f32_e32 v108, 0xbfb8aa3b, v1
	v_exp_f32_e32 v108, v108
	v_mul_f32_e32 v109, 0xbfb8aa3b, v107
	v_exp_f32_e32 v109, v109
	v_and_b32_e32 v92, 0xffff0000, v92
	v_add_f32_e32 v108, 1.0, v108
	v_rcp_f32_e32 v108, v108
	v_add_f32_e32 v109, 1.0, v109
	v_rcp_f32_e32 v109, v109
	v_and_b32_e32 v94, 0xffff0000, v94
	v_mul_f32_e32 v1, v108, v1
	v_mul_f32_e32 v1, v62, v1
	v_mul_f32_e32 v62, v109, v107
	v_mul_f32_e32 v107, 0xbfb8aa3b, v92
	v_mul_f32_e32 v108, 0xbfb8aa3b, v94
	v_exp_f32_e32 v107, v107
	v_exp_f32_e32 v108, v108
	v_lshlrev_b32_e32 v106, 16, v93
	v_mul_f32_e32 v62, v58, v62
	v_add_f32_e32 v58, 1.0, v107
	v_add_f32_e32 v107, 1.0, v108
	v_mul_f32_e32 v108, 0xbfb8aa3b, v106
	v_rcp_f32_e32 v58, v58
	v_exp_f32_e32 v108, v108
	v_rcp_f32_e32 v107, v107
	v_lshlrev_b32_e32 v110, 16, v95
	v_mul_f32_e32 v58, v58, v92
	v_add_f32_e32 v92, 1.0, v108
	v_mul_f32_e32 v58, v63, v58
	v_mul_f32_e32 v63, v107, v94
	v_rcp_f32_e32 v92, v92
	v_mul_f32_e32 v94, 0xbfb8aa3b, v110
	v_exp_f32_e32 v94, v94
	v_and_b32_e32 v93, 0xffff0000, v93
	v_and_b32_e32 v95, 0xffff0000, v95
	v_mul_f32_e32 v63, v59, v63
	v_mul_f32_e32 v59, v92, v106
	v_mul_f32_e32 v92, 0xbfb8aa3b, v93
	v_mul_f32_e32 v59, v64, v59
	v_add_f32_e32 v64, 1.0, v94
	v_exp_f32_e32 v92, v92
	v_mul_f32_e32 v94, 0xbfb8aa3b, v95
	v_exp_f32_e32 v94, v94
	v_rcp_f32_e32 v64, v64
	v_add_f32_e32 v92, 1.0, v92
	v_rcp_f32_e32 v92, v92
	v_add_f32_e32 v94, 1.0, v94
	v_rcp_f32_e32 v94, v94
	v_mul_f32_e32 v64, v64, v110
	v_mul_f32_e32 v64, v60, v64
	v_mul_f32_e32 v60, v92, v93
	v_mul_f32_e32 v60, v65, v60
	v_mul_f32_e32 v65, v94, v95
	v_mul_f32_e32 v61, v61, v65
	v_cvt_pk_bf16_f32 v58, v1, v58
	v_cvt_pk_bf16_f32 v59, v59, v60
	v_cvt_pk_bf16_f32 v60, v62, v63
	v_lshl_add_u64 v[62:63], s[4:5], 0, v[104:105]
	v_cvt_pk_bf16_f32 v61, v64, v61
	v_lshl_add_u64 v[62:63], v[62:63], 0, v[150:151]
	v_lshlrev_b32_e32 v1, 16, v96
	global_store_dwordx4 v[62:63], v[58:61], off
	v_mul_f32_e32 v65, 0xbfb8aa3b, v1
	v_exp_f32_e32 v65, v65
	v_lshlrev_b32_e32 v61, 16, v98
	v_mul_f32_e32 v92, 0xbfb8aa3b, v61
	v_exp_f32_e32 v92, v92
	v_add_f32_e32 v65, 1.0, v65
	v_rcp_f32_e32 v65, v65
	v_and_b32_e32 v58, 0xffff0000, v96
	v_add_f32_e32 v92, 1.0, v92
	v_rcp_f32_e32 v92, v92
	v_and_b32_e32 v64, 0xffff0000, v98
	v_mul_f32_e32 v1, v65, v1
	v_mul_f32_e32 v1, v54, v1
	v_mul_f32_e32 v54, v92, v61
	v_mul_f32_e32 v61, 0xbfb8aa3b, v58
	v_mul_f32_e32 v65, 0xbfb8aa3b, v64
	v_exp_f32_e32 v61, v61
	v_exp_f32_e32 v65, v65
	v_lshlrev_b32_e32 v59, 16, v97
	v_mul_f32_e32 v54, v50, v54
	v_add_f32_e32 v50, 1.0, v61
	v_add_f32_e32 v61, 1.0, v65
	v_mul_f32_e32 v65, 0xbfb8aa3b, v59
	v_rcp_f32_e32 v50, v50
	v_exp_f32_e32 v65, v65
	v_rcp_f32_e32 v61, v61
	v_lshlrev_b32_e32 v93, 16, v99
	v_mul_f32_e32 v50, v50, v58
	v_add_f32_e32 v58, 1.0, v65
	v_rcp_f32_e32 v58, v58
	v_and_b32_e32 v60, 0xffff0000, v97
	v_mul_f32_e32 v50, v55, v50
	v_mul_f32_e32 v55, v61, v64
	v_mul_f32_e32 v61, 0xbfb8aa3b, v93
	v_and_b32_e32 v94, 0xffff0000, v99
	v_exp_f32_e32 v61, v61
	v_mul_f32_e32 v55, v51, v55
	v_mul_f32_e32 v51, v58, v59
	v_mul_f32_e32 v58, 0xbfb8aa3b, v60
	v_exp_f32_e32 v58, v58
	v_mul_f32_e32 v59, 0xbfb8aa3b, v94
	v_exp_f32_e32 v59, v59
	v_mul_f32_e32 v51, v56, v51
	v_add_f32_e32 v56, 1.0, v61
	v_rcp_f32_e32 v56, v56
	v_add_f32_e32 v58, 1.0, v58
	v_rcp_f32_e32 v58, v58
	v_add_f32_e32 v59, 1.0, v59
	v_rcp_f32_e32 v59, v59
	v_mul_f32_e32 v56, v56, v93
	v_mul_f32_e32 v56, v52, v56
	v_mul_f32_e32 v52, v58, v60
	v_mul_f32_e32 v52, v57, v52
	v_mul_f32_e32 v57, v59, v94
	v_mul_f32_e32 v53, v53, v57
	v_cvt_pk_bf16_f32 v50, v1, v50
	v_cvt_pk_bf16_f32 v51, v51, v52
	v_cvt_pk_bf16_f32 v52, v54, v55
	v_cvt_pk_bf16_f32 v53, v56, v53
	s_waitcnt vmcnt(0)
; __device__ __forceinline__ u32x4 pack8(const float (&f)[8]) { u32x4 r; r[0] = cvt_pk_bf16(f[0], f[1]); r[1] = cvt_pk_bf16(f[2], f[3]); r[2] = cvt_pk_bf16(f[4], f[5]); r[3] = cvt_pk_bf16(f[6], f[7]); return r; }
; __device__ __forceinline__ float siluf_(float x) { return x * __builtin_amdgcn_rcpf(1.0f + __expf(-x)); }
;     __device__ __forceinline__ void operator()(EPI_ARGS) const {
;     ...
;                 for (int bj = 0; bj < 2; ++bj) zz[m][bj] = *(const u32x4*)(parts + E_PZC + (size_t)EPI_ROW * 1024 + EPI_COL(bj));
; #pragma unroll
;             for (int m = 0; m < 4; ++m)
; #pragma unroll
;                 for (int bj = 0; bj < 2; ++bj) { const f32x4 v0 = acc[ai][bj][m][0], v1 = acc[ai][bj][m][1]; float z[8]; unpack8(zz[m][bj], z); float o[8];
; #pragma unroll
;                     for (int j = 0; j < 4; ++j) { o[j] = v0[j] * siluf_(z[j]); o[4 + j] = v1[j] * siluf_(z[4 + j]); }
;                     *(u32x4*)(O + (size_t)EPI_ROW * 1024 + EPI_COL(bj)) = pack8(o); } }
	v_lshlrev_b32_e32 v1, 16, v100
	global_store_dwordx4 v[62:63], v[50:53], off offset:256
	v_mul_f32_e32 v55, 0xbfb8aa3b, v1
	v_exp_f32_e32 v55, v55
	v_lshlrev_b32_e32 v53, 16, v102
	v_mul_f32_e32 v56, 0xbfb8aa3b, v53
	v_exp_f32_e32 v56, v56
	v_add_f32_e32 v55, 1.0, v55
	v_rcp_f32_e32 v55, v55
	v_and_b32_e32 v50, 0xffff0000, v100
	v_add_f32_e32 v56, 1.0, v56
	v_rcp_f32_e32 v56, v56
	v_and_b32_e32 v54, 0xffff0000, v102
	v_mul_f32_e32 v1, v55, v1
	v_mul_f32_e32 v1, v46, v1
	v_mul_f32_e32 v46, v56, v53
	v_mul_f32_e32 v53, 0xbfb8aa3b, v50
	v_mul_f32_e32 v55, 0xbfb8aa3b, v54
	v_exp_f32_e32 v53, v53
	v_exp_f32_e32 v55, v55
	v_lshlrev_b32_e32 v51, 16, v101
	v_mul_f32_e32 v46, v42, v46
	v_add_f32_e32 v42, 1.0, v53
	v_add_f32_e32 v53, 1.0, v55
	v_mul_f32_e32 v55, 0xbfb8aa3b, v51
	v_rcp_f32_e32 v42, v42
	v_exp_f32_e32 v55, v55
	v_rcp_f32_e32 v53, v53
	v_lshlrev_b32_e32 v57, 16, v103
	v_mul_f32_e32 v42, v42, v50
	v_add_f32_e32 v50, 1.0, v55
	v_rcp_f32_e32 v50, v50
	v_and_b32_e32 v52, 0xffff0000, v101
	v_mul_f32_e32 v42, v47, v42
	v_mul_f32_e32 v47, v53, v54
	v_mul_f32_e32 v53, 0xbfb8aa3b, v57
	v_and_b32_e32 v58, 0xffff0000, v103
	v_exp_f32_e32 v53, v53
	v_mul_f32_e32 v47, v43, v47
	v_mul_f32_e32 v43, v50, v51
	v_mul_f32_e32 v50, 0xbfb8aa3b, v52
	v_exp_f32_e32 v50, v50
	v_mul_f32_e32 v51, 0xbfb8aa3b, v58
	v_exp_f32_e32 v51, v51
	v_mul_f32_e32 v43, v48, v43
	v_add_f32_e32 v48, 1.0, v53
	v_rcp_f32_e32 v48, v48
	v_add_f32_e32 v50, 1.0, v50
	v_rcp_f32_e32 v50, v50
	v_add_f32_e32 v51, 1.0, v51
	v_rcp_f32_e32 v51, v51
	v_mul_f32_e32 v48, v48, v57
	v_mul_f32_e32 v48, v44, v48
	v_mul_f32_e32 v44, v50, v52
	v_mul_f32_e32 v44, v49, v44
	v_mul_f32_e32 v49, v51, v58
	v_mul_f32_e32 v45, v45, v49
	v_cvt_pk_bf16_f32 v42, v1, v42
	v_cvt_pk_bf16_f32 v43, v43, v44
	v_cvt_pk_bf16_f32 v44, v46, v47
	v_lshl_add_u64 v[46:47], s[4:5], 0, v[90:91]
	v_cvt_pk_bf16_f32 v45, v48, v45
	v_lshl_add_u64 v[46:47], v[46:47], 0, v[150:151]
	v_lshlrev_b32_e32 v1, 16, v82
	global_store_dwordx4 v[46:47], v[42:45], off
	v_mul_f32_e32 v49, 0xbfb8aa3b, v1
	v_exp_f32_e32 v49, v49
	v_lshlrev_b32_e32 v45, 16, v84
	v_mul_f32_e32 v50, 0xbfb8aa3b, v45
	v_exp_f32_e32 v50, v50
	v_add_f32_e32 v49, 1.0, v49
	v_rcp_f32_e32 v49, v49
	v_and_b32_e32 v42, 0xffff0000, v82
	v_add_f32_e32 v50, 1.0, v50
	v_rcp_f32_e32 v50, v50
	v_and_b32_e32 v48, 0xffff0000, v84
	v_mul_f32_e32 v1, v49, v1
	v_mul_f32_e32 v1, v38, v1
	v_mul_f32_e32 v38, v50, v45
	v_mul_f32_e32 v45, 0xbfb8aa3b, v42
	v_mul_f32_e32 v49, 0xbfb8aa3b, v48
	v_exp_f32_e32 v45, v45
	v_exp_f32_e32 v49, v49
	v_lshlrev_b32_e32 v43, 16, v83
	v_mul_f32_e32 v38, v34, v38
	v_add_f32_e32 v34, 1.0, v45
	v_add_f32_e32 v45, 1.0, v49
	v_mul_f32_e32 v49, 0xbfb8aa3b, v43
	v_rcp_f32_e32 v34, v34
	v_exp_f32_e32 v49, v49
	v_rcp_f32_e32 v45, v45
	v_lshlrev_b32_e32 v51, 16, v85
	v_mul_f32_e32 v34, v34, v42
	v_add_f32_e32 v42, 1.0, v49
	v_rcp_f32_e32 v42, v42
	v_and_b32_e32 v44, 0xffff0000, v83
	v_mul_f32_e32 v34, v39, v34
	v_mul_f32_e32 v39, v45, v48
	v_mul_f32_e32 v45, 0xbfb8aa3b, v51
	v_and_b32_e32 v52, 0xffff0000, v85
	v_exp_f32_e32 v45, v45
	v_mul_f32_e32 v39, v35, v39
	v_mul_f32_e32 v35, v42, v43
	v_mul_f32_e32 v42, 0xbfb8aa3b, v44
	v_exp_f32_e32 v42, v42
	v_mul_f32_e32 v43, 0xbfb8aa3b, v52
	v_exp_f32_e32 v43, v43
	v_mul_f32_e32 v35, v40, v35
	v_add_f32_e32 v40, 1.0, v45
	v_rcp_f32_e32 v40, v40
	v_add_f32_e32 v42, 1.0, v42
	v_rcp_f32_e32 v42, v42
	v_add_f32_e32 v43, 1.0, v43
	v_rcp_f32_e32 v43, v43
	v_mul_f32_e32 v40, v40, v51
	v_mul_f32_e32 v40, v36, v40
	v_mul_f32_e32 v36, v42, v44
	v_mul_f32_e32 v36, v41, v36
	v_mul_f32_e32 v41, v43, v52
	v_mul_f32_e32 v37, v37, v41
	v_cvt_pk_bf16_f32 v34, v1, v34
	v_cvt_pk_bf16_f32 v35, v35, v36
	v_cvt_pk_bf16_f32 v36, v38, v39
	v_cvt_pk_bf16_f32 v37, v40, v37
	v_lshlrev_b32_e32 v1, 16, v78
	global_store_dwordx4 v[46:47], v[34:37], off offset:256
	v_mul_f32_e32 v39, 0xbfb8aa3b, v1
	v_exp_f32_e32 v39, v39
	v_lshlrev_b32_e32 v37, 16, v80
	v_mul_f32_e32 v40, 0xbfb8aa3b, v37
	v_exp_f32_e32 v40, v40
	v_add_f32_e32 v39, 1.0, v39
	v_rcp_f32_e32 v39, v39
	v_and_b32_e32 v34, 0xffff0000, v78
	v_add_f32_e32 v40, 1.0, v40
	v_rcp_f32_e32 v40, v40
	v_and_b32_e32 v38, 0xffff0000, v80
	v_mul_f32_e32 v1, v39, v1
	v_mul_f32_e32 v1, v30, v1
	v_mul_f32_e32 v30, v40, v37
	v_mul_f32_e32 v37, 0xbfb8aa3b, v34
	v_mul_f32_e32 v39, 0xbfb8aa3b, v38
	v_exp_f32_e32 v37, v37
	v_exp_f32_e32 v39, v39
	v_lshlrev_b32_e32 v35, 16, v79
	v_mul_f32_e32 v30, v26, v30
	v_add_f32_e32 v26, 1.0, v37
	v_add_f32_e32 v37, 1.0, v39
	v_mul_f32_e32 v39, 0xbfb8aa3b, v35
	v_rcp_f32_e32 v26, v26
	v_exp_f32_e32 v39, v39
	v_rcp_f32_e32 v37, v37
	v_lshlrev_b32_e32 v41, 16, v81
	v_mul_f32_e32 v26, v26, v34
	v_add_f32_e32 v34, 1.0, v39
	v_rcp_f32_e32 v34, v34
	v_and_b32_e32 v36, 0xffff0000, v79
	v_mul_f32_e32 v26, v31, v26
	v_mul_f32_e32 v31, v37, v38
	v_mul_f32_e32 v37, 0xbfb8aa3b, v41
	v_and_b32_e32 v42, 0xffff0000, v81
	v_exp_f32_e32 v37, v37
	v_mul_f32_e32 v31, v27, v31
	v_mul_f32_e32 v27, v34, v35
	v_mul_f32_e32 v34, 0xbfb8aa3b, v36
	v_exp_f32_e32 v34, v34
	v_mul_f32_e32 v35, 0xbfb8aa3b, v42
	v_exp_f32_e32 v35, v35
	v_mul_f32_e32 v27, v32, v27
	v_add_f32_e32 v32, 1.0, v37
	v_rcp_f32_e32 v32, v32
	v_add_f32_e32 v34, 1.0, v34
	v_rcp_f32_e32 v34, v34
	v_add_f32_e32 v35, 1.0, v35
	v_rcp_f32_e32 v35, v35
	v_mul_f32_e32 v32, v32, v41
	v_mul_f32_e32 v32, v28, v32
	v_mul_f32_e32 v28, v34, v36
	v_mul_f32_e32 v28, v33, v28
	v_mul_f32_e32 v33, v35, v42
	v_mul_f32_e32 v29, v29, v33
	v_cvt_pk_bf16_f32 v26, v1, v26
	v_cvt_pk_bf16_f32 v27, v27, v28
	v_cvt_pk_bf16_f32 v28, v30, v31
	v_lshl_add_u64 v[30:31], s[4:5], 0, v[88:89]
	v_cvt_pk_bf16_f32 v29, v32, v29
; __device__ __forceinline__ float siluf_(float x) { return x * __builtin_amdgcn_rcpf(1.0f + __expf(-x)); }
; __device__ __forceinline__ u32x4 pack8(const float (&f)[8]) { u32x4 r; r[0] = cvt_pk_bf16(f[0], f[1]); r[1] = cvt_pk_bf16(f[2], f[3]); r[2] = cvt_pk_bf16(f[4], f[5]); r[3] = cvt_pk_bf16(f[6], f[7]); return r; }
; #define PG8_WAIT_V(n) asm volatile("s_waitcnt vmcnt(" #n ")" ::: "memory")
; #define PG8_BAR __builtin_amdgcn_s_barrier()
; template <class Sched, class Epi>
; __device__ __forceinline__ void gemm_phase(LAS unsigned char* lds, const Sched& S, const Epi& E, const int K, const int lda, const int ldb) {
;     ...
;     PG8_WAIT_V(0);
;     if (wr == 0) PG8_BAR;
;     __device__ __forceinline__ void operator()(EPI_ARGS) const {
;     ...
;                 for (int bj = 0; bj < 2; ++bj) zz[m][bj] = *(const u32x4*)(parts + E_PZC + (size_t)EPI_ROW * 1024 + EPI_COL(bj));
; #pragma unroll
;             for (int m = 0; m < 4; ++m)
; #pragma unroll
;                 for (int bj = 0; bj < 2; ++bj) { const f32x4 v0 = acc[ai][bj][m][0], v1 = acc[ai][bj][m][1]; float z[8]; unpack8(zz[m][bj], z); float o[8];
; #pragma unroll
;                     for (int j = 0; j < 4; ++j) { o[j] = v0[j] * siluf_(z[j]); o[4 + j] = v1[j] * siluf_(z[4 + j]); }
;                     *(u32x4*)(O + (size_t)EPI_ROW * 1024 + EPI_COL(bj)) = pack8(o); } }
	v_lshl_add_u64 v[30:31], v[30:31], 0, v[150:151]
	v_lshlrev_b32_e32 v1, 16, v74
	global_store_dwordx4 v[30:31], v[26:29], off
	v_mul_f32_e32 v33, 0xbfb8aa3b, v1
	v_exp_f32_e32 v33, v33
	v_lshlrev_b32_e32 v29, 16, v76
	v_mul_f32_e32 v34, 0xbfb8aa3b, v29
	v_exp_f32_e32 v34, v34
	v_add_f32_e32 v33, 1.0, v33
	v_rcp_f32_e32 v33, v33
	v_and_b32_e32 v26, 0xffff0000, v74
	v_add_f32_e32 v34, 1.0, v34
	v_rcp_f32_e32 v34, v34
	v_and_b32_e32 v32, 0xffff0000, v76
	v_mul_f32_e32 v1, v33, v1
	v_mul_f32_e32 v1, v22, v1
	v_mul_f32_e32 v22, v34, v29
	v_mul_f32_e32 v29, 0xbfb8aa3b, v26
	v_mul_f32_e32 v33, 0xbfb8aa3b, v32
	v_exp_f32_e32 v29, v29
	v_exp_f32_e32 v33, v33
	v_lshlrev_b32_e32 v27, 16, v75
	v_mul_f32_e32 v22, v18, v22
	v_add_f32_e32 v18, 1.0, v29
	v_add_f32_e32 v29, 1.0, v33
	v_mul_f32_e32 v33, 0xbfb8aa3b, v27
	v_rcp_f32_e32 v18, v18
	v_exp_f32_e32 v33, v33
	v_rcp_f32_e32 v29, v29
	v_lshlrev_b32_e32 v35, 16, v77
	v_mul_f32_e32 v18, v18, v26
	v_add_f32_e32 v26, 1.0, v33
	v_rcp_f32_e32 v26, v26
	v_and_b32_e32 v28, 0xffff0000, v75
	v_mul_f32_e32 v18, v23, v18
	v_mul_f32_e32 v23, v29, v32
	v_mul_f32_e32 v29, 0xbfb8aa3b, v35
	v_and_b32_e32 v36, 0xffff0000, v77
	v_exp_f32_e32 v29, v29
	v_mul_f32_e32 v23, v19, v23
	v_mul_f32_e32 v19, v26, v27
	v_mul_f32_e32 v26, 0xbfb8aa3b, v28
	v_exp_f32_e32 v26, v26
	v_mul_f32_e32 v27, 0xbfb8aa3b, v36
	v_exp_f32_e32 v27, v27
	v_mul_f32_e32 v19, v24, v19
	v_add_f32_e32 v24, 1.0, v29
	v_rcp_f32_e32 v24, v24
	v_add_f32_e32 v26, 1.0, v26
	v_rcp_f32_e32 v26, v26
	v_add_f32_e32 v27, 1.0, v27
	v_rcp_f32_e32 v27, v27
	v_mul_f32_e32 v24, v24, v35
	v_mul_f32_e32 v24, v20, v24
	v_mul_f32_e32 v20, v26, v28
	v_mul_f32_e32 v20, v25, v20
	v_mul_f32_e32 v25, v27, v36
	v_mul_f32_e32 v21, v21, v25
	v_cvt_pk_bf16_f32 v18, v1, v18
	v_cvt_pk_bf16_f32 v19, v19, v20
	v_cvt_pk_bf16_f32 v20, v22, v23
	v_cvt_pk_bf16_f32 v21, v24, v21
	v_lshlrev_b32_e32 v1, 16, v70
	global_store_dwordx4 v[30:31], v[18:21], off offset:256
	v_mul_f32_e32 v23, 0xbfb8aa3b, v1
	v_exp_f32_e32 v23, v23
	v_lshlrev_b32_e32 v21, 16, v72
	v_mul_f32_e32 v24, 0xbfb8aa3b, v21
	v_exp_f32_e32 v24, v24
	v_add_f32_e32 v23, 1.0, v23
	v_rcp_f32_e32 v23, v23
	v_and_b32_e32 v18, 0xffff0000, v70
	v_add_f32_e32 v24, 1.0, v24
	v_rcp_f32_e32 v24, v24
	v_and_b32_e32 v22, 0xffff0000, v72
	v_mul_f32_e32 v1, v23, v1
	v_mul_f32_e32 v1, v14, v1
	v_mul_f32_e32 v14, v24, v21
	v_mul_f32_e32 v21, 0xbfb8aa3b, v18
	v_mul_f32_e32 v23, 0xbfb8aa3b, v22
	v_exp_f32_e32 v21, v21
	v_exp_f32_e32 v23, v23
	v_lshlrev_b32_e32 v19, 16, v71
	v_mul_f32_e32 v14, v10, v14
	v_add_f32_e32 v10, 1.0, v21
	v_add_f32_e32 v21, 1.0, v23
	v_mul_f32_e32 v23, 0xbfb8aa3b, v19
	v_rcp_f32_e32 v10, v10
	v_exp_f32_e32 v23, v23
	v_rcp_f32_e32 v21, v21
	v_lshlrev_b32_e32 v25, 16, v73
	v_mul_f32_e32 v10, v10, v18
	v_add_f32_e32 v18, 1.0, v23
	v_rcp_f32_e32 v18, v18
	v_and_b32_e32 v20, 0xffff0000, v71
	v_mul_f32_e32 v10, v15, v10
	v_mul_f32_e32 v15, v21, v22
	v_mul_f32_e32 v21, 0xbfb8aa3b, v25
	v_and_b32_e32 v26, 0xffff0000, v73
	v_exp_f32_e32 v21, v21
	v_mul_f32_e32 v15, v11, v15
	v_mul_f32_e32 v11, v18, v19
	v_mul_f32_e32 v18, 0xbfb8aa3b, v20
	v_exp_f32_e32 v18, v18
	v_mul_f32_e32 v19, 0xbfb8aa3b, v26
	v_exp_f32_e32 v19, v19
	v_mul_f32_e32 v11, v16, v11
	v_add_f32_e32 v16, 1.0, v21
	v_rcp_f32_e32 v16, v16
	v_add_f32_e32 v18, 1.0, v18
	v_rcp_f32_e32 v18, v18
	v_add_f32_e32 v19, 1.0, v19
	v_rcp_f32_e32 v19, v19
	v_mul_f32_e32 v16, v16, v25
	v_mul_f32_e32 v16, v12, v16
	v_mul_f32_e32 v12, v18, v20
	v_mul_f32_e32 v12, v17, v12
	v_mul_f32_e32 v17, v19, v26
	v_mul_f32_e32 v13, v13, v17
	v_cvt_pk_bf16_f32 v10, v1, v10
	v_cvt_pk_bf16_f32 v11, v11, v12
	v_cvt_pk_bf16_f32 v12, v14, v15
	v_lshl_add_u64 v[14:15], s[4:5], 0, v[86:87]
	v_cvt_pk_bf16_f32 v13, v16, v13
	v_lshl_add_u64 v[14:15], v[14:15], 0, v[150:151]
	v_lshlrev_b32_e32 v1, 16, v66
	global_store_dwordx4 v[14:15], v[10:13], off
	v_mul_f32_e32 v17, 0xbfb8aa3b, v1
	v_exp_f32_e32 v17, v17
	v_lshlrev_b32_e32 v13, 16, v68
	v_mul_f32_e32 v18, 0xbfb8aa3b, v13
	v_exp_f32_e32 v18, v18
	v_add_f32_e32 v17, 1.0, v17
	v_rcp_f32_e32 v17, v17
	v_and_b32_e32 v10, 0xffff0000, v66
	v_add_f32_e32 v18, 1.0, v18
	v_rcp_f32_e32 v18, v18
	v_and_b32_e32 v16, 0xffff0000, v68
	v_mul_f32_e32 v1, v17, v1
	v_mul_f32_e32 v1, v6, v1
	v_mul_f32_e32 v6, v18, v13
	v_mul_f32_e32 v13, 0xbfb8aa3b, v10
	v_mul_f32_e32 v17, 0xbfb8aa3b, v16
	v_exp_f32_e32 v13, v13
	v_exp_f32_e32 v17, v17
	v_lshlrev_b32_e32 v11, 16, v67
	v_mul_f32_e32 v6, v2, v6
	v_add_f32_e32 v2, 1.0, v13
	v_add_f32_e32 v13, 1.0, v17
	v_mul_f32_e32 v17, 0xbfb8aa3b, v11
	v_rcp_f32_e32 v2, v2
	v_exp_f32_e32 v17, v17
	v_rcp_f32_e32 v13, v13
	v_lshlrev_b32_e32 v19, 16, v69
	v_mul_f32_e32 v2, v2, v10
	v_add_f32_e32 v10, 1.0, v17
	v_rcp_f32_e32 v10, v10
	v_and_b32_e32 v12, 0xffff0000, v67
	v_mul_f32_e32 v2, v7, v2
	v_mul_f32_e32 v7, v13, v16
	v_mul_f32_e32 v13, 0xbfb8aa3b, v19
	v_and_b32_e32 v20, 0xffff0000, v69
	v_exp_f32_e32 v13, v13
	v_mul_f32_e32 v7, v3, v7
	v_mul_f32_e32 v3, v10, v11
	v_mul_f32_e32 v10, 0xbfb8aa3b, v12
	v_exp_f32_e32 v10, v10
	v_mul_f32_e32 v11, 0xbfb8aa3b, v20
	v_exp_f32_e32 v11, v11
	v_mul_f32_e32 v3, v8, v3
	v_add_f32_e32 v8, 1.0, v13
	v_rcp_f32_e32 v8, v8
	v_add_f32_e32 v10, 1.0, v10
	v_rcp_f32_e32 v10, v10
	v_add_f32_e32 v11, 1.0, v11
	v_rcp_f32_e32 v11, v11
	v_mul_f32_e32 v8, v8, v19
	v_mul_f32_e32 v8, v4, v8
	v_mul_f32_e32 v4, v10, v12
	v_mul_f32_e32 v4, v9, v4
	v_mul_f32_e32 v9, v11, v20
	v_mul_f32_e32 v5, v5, v9
	v_cvt_pk_bf16_f32 v2, v1, v2
	v_cvt_pk_bf16_f32 v3, v3, v4
	v_cvt_pk_bf16_f32 v4, v6, v7
	v_cvt_pk_bf16_f32 v5, v8, v5
	global_store_dwordx4 v[14:15], v[2:5], off offset:256
	s_waitcnt vmcnt(0)
	s_cbranch_scc0 .LBB0_739
	s_barrier

; #define PG8_STAGE(bufoff, gbase, voff) do { _Pragma("unroll") for (int _i = 0; _i < 2; ++_i) \
;         __builtin_amdgcn_global_load_lds((const unsigned*)((const char*)(gbase) + (voff)[_i]), (LAS unsigned*)(lds + (bufoff) + ldsw + _i * 8192), 16, 0, 0); } while (0)
; #define PG8_LDA(dst, b, h) do { _Pragma("unroll") for (int m = 0; m < 4; ++m) _Pragma("unroll") for (int k = 0; k < 2; ++k) dst[m][k] = *(const LAS bf16x8*)(lds + PG8_SA(b, h) + aoff + m * 2048 + k * 1024); } while (0)
; #define PG8_LDB(dst, b, h) do { _Pragma("unroll") for (int n = 0; n < 2; ++n) _Pragma("unroll") for (int k = 0; k < 2; ++k) dst[n][k] = *(const LAS bf16x8*)(lds + PG8_SB(b, h) + boff + n * 2048 + k * 1024); } while (0)
; #define PG8_MMA(ai, bj, At, Bt) do { __builtin_amdgcn_s_setprio(1); _Pragma("unroll") for (int m = 0; m < 4; ++m) _Pragma("unroll") for (int n = 0; n < 2; ++n) _Pragma("unroll") for (int k = 0; k < 2; ++k) \
;         acc[ai][bj][m][n] = __builtin_amdgcn_mfma_f32_16x16x32_bf16(Bt[n][k], At[m][k], acc[ai][bj][m][n], 0, 0, 0); __builtin_amdgcn_s_setprio(0); } while (0)
; #define PG8_WAIT_V(n) asm volatile("s_waitcnt vmcnt(" #n ")" ::: "memory")
; #define PG8_WAIT_L(n) asm volatile("s_waitcnt lgkmcnt(" #n ")" ::: "memory")
; #define PG8_BAR __builtin_amdgcn_s_barrier()
; #define PG8_SCHED __builtin_amdgcn_sched_barrier(0)
; template <class Sched, class Epi>
; __device__ __forceinline__ void gemm_phase(LAS unsigned char* lds, const Sched& S, const Epi& E, const int K, const int lda, const int ldb) {
;     ...
;             PG8_LDB(B0, 0, 0); PG8_SCHED; PG8_LDA(At, 0, 0); PG8_STAGE(PG8_SA(1, 1), a1 + hstepA, voffA);
;             PG8_WAIT_L(8); PG8_BAR; PG8_WAIT_L(0); PG8_MMA(0, 0, At, B0); PG8_BAR; PG8_SCHED;
;             PG8_LDB(B1, 0, 1); PG8_STAGE(PG8_SB(0, 0), b2, voffB);
;             PG8_BAR; PG8_WAIT_L(0); PG8_MMA(0, 1, At, B1); PG8_BAR;
;             PG8_LDA(At, 0, 1); PG8_STAGE(PG8_SA(0, 0), a2, voffA);
;             PG8_BAR; PG8_WAIT_L(0); if (!chalf) PG8_MMA(1, 0, At, B0); PG8_BAR; PG8_SCHED;
;             PG8_STAGE(PG8_SB(0, 1), b2 + hstepB, voffB);
;             PG8_WAIT_V(6); PG8_BAR; if (!chalf) PG8_MMA(1, 1, At, B1); PG8_BAR;
.LBB0_761:
	ds_read_b128 v[144:147], v155
	ds_read_b128 v[158:161], v155 offset:1024
	ds_read_b128 v[162:165], v155 offset:2048
	ds_read_b128 v[166:169], v155 offset:3072
	s_add_u32 s34, s28, 0xfffc0080
	s_addc_u32 s35, s29, -1
	s_cmp_eq_u32 s49, 12
	s_cselect_b32 s37, s25, s35
	s_cselect_b32 s36, s24, s34
	s_cselect_b32 s35, s27, s17
	s_cselect_b32 s34, s26, s15
	s_add_i32 m0, s23, 0xc000
	ds_read_b128 v[170:173], v156
	ds_read_b128 v[174:177], v156 offset:1024
	ds_read_b128 v[178:181], v156 offset:2048
	ds_read_b128 v[182:185], v156 offset:3072
	ds_read_b128 v[186:189], v156 offset:4096
	ds_read_b128 v[190:193], v156 offset:5120
	ds_read_b128 v[194:197], v156 offset:6144
	ds_read_b128 v[198:201], v156 offset:7168
	global_load_lds_dwordx4 v140, s[28:29]
	s_add_i32 m0, s23, 0xe000
	s_nop 0
	global_load_lds_dwordx4 v138, s[28:29]
	s_waitcnt lgkmcnt(8)
	s_barrier
	s_waitcnt lgkmcnt(0)
	s_setprio 1
	s_waitcnt lgkmcnt(0)
	v_mfma_f32_16x16x32_bf16 v[118:121], v[144:147], v[170:173], v[118:121]
	v_mfma_f32_16x16x32_bf16 v[114:117], v[162:165], v[170:173], v[114:117]
	v_mfma_f32_16x16x32_bf16 v[110:113], v[144:147], v[178:181], v[110:113]
	v_mfma_f32_16x16x32_bf16 v[106:109], v[162:165], v[178:181], v[106:109]
	v_mfma_f32_16x16x32_bf16 v[94:97], v[144:147], v[186:189], v[94:97]
	v_mfma_f32_16x16x32_bf16 v[90:93], v[162:165], v[186:189], v[90:93]
	v_mfma_f32_16x16x32_bf16 v[78:81], v[144:147], v[194:197], v[78:81]
	v_mfma_f32_16x16x32_bf16 v[74:77], v[162:165], v[194:197], v[74:77]
	v_mfma_f32_16x16x32_bf16 v[118:121], v[158:161], v[174:177], v[118:121]
	v_mfma_f32_16x16x32_bf16 v[114:117], v[166:169], v[174:177], v[114:117]
	v_mfma_f32_16x16x32_bf16 v[110:113], v[158:161], v[182:185], v[110:113]
	v_mfma_f32_16x16x32_bf16 v[106:109], v[166:169], v[182:185], v[106:109]
	v_mfma_f32_16x16x32_bf16 v[94:97], v[158:161], v[190:193], v[94:97]
	v_mfma_f32_16x16x32_bf16 v[90:93], v[166:169], v[190:193], v[90:93]
	v_mfma_f32_16x16x32_bf16 v[78:81], v[158:161], v[198:201], v[78:81]
	v_mfma_f32_16x16x32_bf16 v[74:77], v[166:169], v[198:201], v[74:77]
	s_setprio 0
	s_barrier
	s_add_i32 s50, s46, s38
	s_add_u32 s62, s34, s8
	s_addc_u32 s63, s35, s9
	s_mov_b32 m0, s50
	ds_read_b128 v[202:205], v157
	ds_read_b128 v[206:209], v157 offset:1024
	ds_read_b128 v[210:213], v157 offset:2048
	ds_read_b128 v[214:217], v157 offset:3072
	global_load_lds_dwordx4 v132, s[34:35]
	s_add_u32 s64, s34, s8
	s_addc_u32 s65, s35, s9
	s_add_i32 m0, s50, 0x2000
	s_nop 0
	global_load_lds_dwordx4 v136, s[34:35]
	s_barrier
	s_waitcnt lgkmcnt(0)
	s_setprio 1
	s_waitcnt lgkmcnt(0)
	v_mfma_f32_16x16x32_bf16 v[126:129], v[202:205], v[170:173], v[126:129]
	v_mfma_f32_16x16x32_bf16 v[122:125], v[210:213], v[170:173], v[122:125]
	v_mfma_f32_16x16x32_bf16 v[102:105], v[202:205], v[178:181], v[102:105]
	v_mfma_f32_16x16x32_bf16 v[98:101], v[210:213], v[178:181], v[98:101]
	v_mfma_f32_16x16x32_bf16 v[86:89], v[202:205], v[186:189], v[86:89]
	v_mfma_f32_16x16x32_bf16 v[82:85], v[210:213], v[186:189], v[82:85]
	v_mfma_f32_16x16x32_bf16 v[70:73], v[202:205], v[194:197], v[70:73]
	v_mfma_f32_16x16x32_bf16 v[66:69], v[210:213], v[194:197], v[66:69]
	v_mfma_f32_16x16x32_bf16 v[126:129], v[206:209], v[174:177], v[126:129]
	v_mfma_f32_16x16x32_bf16 v[122:125], v[214:217], v[174:177], v[122:125]
	v_mfma_f32_16x16x32_bf16 v[102:105], v[206:209], v[182:185], v[102:105]
	v_mfma_f32_16x16x32_bf16 v[98:101], v[214:217], v[182:185], v[98:101]
	v_mfma_f32_16x16x32_bf16 v[86:89], v[206:209], v[190:193], v[86:89]
	v_mfma_f32_16x16x32_bf16 v[82:85], v[214:217], v[190:193], v[82:85]
	v_mfma_f32_16x16x32_bf16 v[70:73], v[206:209], v[198:201], v[70:73]
	v_mfma_f32_16x16x32_bf16 v[66:69], v[214:217], v[198:201], v[66:69]
	s_setprio 0
	s_mov_b32 m0, s23
	s_add_u32 s66, s36, s8
	s_addc_u32 s67, s37, s9
	s_barrier
	ds_read_b128 v[170:173], v156 offset:16384
	ds_read_b128 v[174:177], v156 offset:17408
	ds_read_b128 v[178:181], v156 offset:18432
	ds_read_b128 v[182:185], v156 offset:19456
	ds_read_b128 v[186:189], v156 offset:20480
	ds_read_b128 v[190:193], v156 offset:21504
	ds_read_b128 v[194:197], v156 offset:22528
	ds_read_b128 v[198:201], v156 offset:23552
	global_load_lds_dwordx4 v130, s[36:37]
	s_add_u32 s68, s36, s8
	s_addc_u32 s69, s37, s9
	s_mov_b32 m0, s39
	s_nop 0
	global_load_lds_dwordx4 v134, s[36:37]
	s_barrier
	s_waitcnt lgkmcnt(0)
	s_setprio 1
	s_waitcnt lgkmcnt(0)
	v_mfma_f32_16x16x32_bf16 v[62:65], v[144:147], v[170:173], v[62:65]
	v_mfma_f32_16x16x32_bf16 v[58:61], v[162:165], v[170:173], v[58:61]
	v_mfma_f32_16x16x32_bf16 v[46:49], v[144:147], v[178:181], v[46:49]
	v_mfma_f32_16x16x32_bf16 v[42:45], v[162:165], v[178:181], v[42:45]
	v_mfma_f32_16x16x32_bf16 v[30:33], v[144:147], v[186:189], v[30:33]
	v_mfma_f32_16x16x32_bf16 v[26:29], v[162:165], v[186:189], v[26:29]
	v_mfma_f32_16x16x32_bf16 v[14:17], v[144:147], v[194:197], v[14:17]
	v_mfma_f32_16x16x32_bf16 v[10:13], v[162:165], v[194:197], v[10:13]
	v_mfma_f32_16x16x32_bf16 v[62:65], v[158:161], v[174:177], v[62:65]
	v_mfma_f32_16x16x32_bf16 v[58:61], v[166:169], v[174:177], v[58:61]
	v_mfma_f32_16x16x32_bf16 v[46:49], v[158:161], v[182:185], v[46:49]
	v_mfma_f32_16x16x32_bf16 v[42:45], v[166:169], v[182:185], v[42:45]
	v_mfma_f32_16x16x32_bf16 v[30:33], v[158:161], v[190:193], v[30:33]
	v_mfma_f32_16x16x32_bf16 v[26:29], v[166:169], v[190:193], v[26:29]
	v_mfma_f32_16x16x32_bf16 v[14:17], v[158:161], v[198:201], v[14:17]
	v_mfma_f32_16x16x32_bf16 v[10:13], v[166:169], v[198:201], v[10:13]
	s_setprio 0
	s_barrier
	s_add_u32 s50, s34, 0x40000
	s_addc_u32 s51, s35, 0
	s_add_i32 s52, s47, s38
	s_mov_b32 m0, s52
	s_nop 0
	global_load_lds_dwordx4 v132, s[50:51]
	s_add_i32 m0, s52, 0x2000
	s_nop 0
	global_load_lds_dwordx4 v136, s[50:51]
	s_waitcnt vmcnt(6)
	s_barrier
; #define PG8_STAGE(bufoff, gbase, voff) do { _Pragma("unroll") for (int _i = 0; _i < 2; ++_i) \
;         __builtin_amdgcn_global_load_lds((const unsigned*)((const char*)(gbase) + (voff)[_i]), (LAS unsigned*)(lds + (bufoff) + ldsw + _i * 8192), 16, 0, 0); } while (0)
; #define PG8_LDA(dst, b, h) do { _Pragma("unroll") for (int m = 0; m < 4; ++m) _Pragma("unroll") for (int k = 0; k < 2; ++k) dst[m][k] = *(const LAS bf16x8*)(lds + PG8_SA(b, h) + aoff + m * 2048 + k * 1024); } while (0)
; #define PG8_LDB(dst, b, h) do { _Pragma("unroll") for (int n = 0; n < 2; ++n) _Pragma("unroll") for (int k = 0; k < 2; ++k) dst[n][k] = *(const LAS bf16x8*)(lds + PG8_SB(b, h) + boff + n * 2048 + k * 1024); } while (0)
; #define PG8_MMA(ai, bj, At, Bt) do { __builtin_amdgcn_s_setprio(1); _Pragma("unroll") for (int m = 0; m < 4; ++m) _Pragma("unroll") for (int n = 0; n < 2; ++n) _Pragma("unroll") for (int k = 0; k < 2; ++k) \
;         acc[ai][bj][m][n] = __builtin_amdgcn_mfma_f32_16x16x32_bf16(Bt[n][k], At[m][k], acc[ai][bj][m][n], 0, 0, 0); __builtin_amdgcn_s_setprio(0); } while (0)
; #define PG8_WAIT_V(n) asm volatile("s_waitcnt vmcnt(" #n ")" ::: "memory")
; #define PG8_WAIT_L(n) asm volatile("s_waitcnt lgkmcnt(" #n ")" ::: "memory")
; #define PG8_BAR __builtin_amdgcn_s_barrier()
; #define PG8_SCHED __builtin_amdgcn_sched_barrier(0)
; template <class Sched, class Epi>
; __device__ __forceinline__ void gemm_phase(LAS unsigned char* lds, const Sched& S, const Epi& E, const int K, const int lda, const int ldb) {
;     ...
;             PG8_WAIT_V(6); PG8_BAR; if (!chalf) PG8_MMA(1, 1, At, B1); PG8_BAR;
;             PG8_LDB(B0, 1, 0); PG8_SCHED; PG8_LDA(At, 1, 0); PG8_STAGE(PG8_SA(0, 1), a2 + hstepA, voffA);
;             PG8_WAIT_L(8); PG8_BAR; PG8_WAIT_L(0); PG8_MMA(0, 0, At, B0); PG8_BAR; PG8_SCHED;
;             PG8_LDB(B1, 1, 1); PG8_STAGE(PG8_SB(1, 0), b3, voffB);
;             PG8_BAR; PG8_WAIT_L(0); PG8_MMA(0, 1, At, B1); PG8_BAR;
;             PG8_LDA(At, 1, 1); PG8_STAGE(PG8_SA(1, 0), a3, voffA);
	s_setprio 1
	v_mfma_f32_16x16x32_bf16 v[54:57], v[202:205], v[170:173], v[54:57]
	v_mfma_f32_16x16x32_bf16 v[50:53], v[210:213], v[170:173], v[50:53]
	v_mfma_f32_16x16x32_bf16 v[38:41], v[202:205], v[178:181], v[38:41]
	v_mfma_f32_16x16x32_bf16 v[34:37], v[210:213], v[178:181], v[34:37]
	v_mfma_f32_16x16x32_bf16 v[22:25], v[202:205], v[186:189], v[22:25]
	v_mfma_f32_16x16x32_bf16 v[18:21], v[210:213], v[186:189], v[18:21]
	v_mfma_f32_16x16x32_bf16 v[6:9], v[202:205], v[194:197], v[6:9]
	v_mfma_f32_16x16x32_bf16 v[2:5], v[210:213], v[194:197], v[2:5]
	v_mfma_f32_16x16x32_bf16 v[54:57], v[206:209], v[174:177], v[54:57]
	v_mfma_f32_16x16x32_bf16 v[50:53], v[214:217], v[174:177], v[50:53]
	v_mfma_f32_16x16x32_bf16 v[38:41], v[206:209], v[182:185], v[38:41]
	v_mfma_f32_16x16x32_bf16 v[34:37], v[214:217], v[182:185], v[34:37]
	v_mfma_f32_16x16x32_bf16 v[22:25], v[206:209], v[190:193], v[22:25]
	v_mfma_f32_16x16x32_bf16 v[18:21], v[214:217], v[190:193], v[18:21]
	v_mfma_f32_16x16x32_bf16 v[6:9], v[206:209], v[198:201], v[6:9]
	v_mfma_f32_16x16x32_bf16 v[2:5], v[214:217], v[198:201], v[2:5]
	s_setprio 0
	s_add_i32 s50, 16, 0x18000
	v_add_u32_e32 v166, s50, v150
	s_barrier
	ds_read_b128 v[144:147], v166
	ds_read_b128 v[158:161], v166 offset:1024
	ds_read_b128 v[162:165], v166 offset:2048
	ds_read_b128 v[166:169], v166 offset:3072
	s_add_u32 s36, s36, 0x40000
	s_addc_u32 s37, s37, 0
	s_mov_b32 m0, s40
	ds_read_b128 v[170:173], v156 offset:32768
	ds_read_b128 v[174:177], v156 offset:33792
	ds_read_b128 v[178:181], v156 offset:34816
	ds_read_b128 v[182:185], v156 offset:35840
	ds_read_b128 v[186:189], v156 offset:36864
	ds_read_b128 v[190:193], v156 offset:37888
	ds_read_b128 v[194:197], v156 offset:38912
	ds_read_b128 v[198:201], v156 offset:39936
	global_load_lds_dwordx4 v130, s[36:37]
	s_mov_b32 m0, s41
	s_nop 0
	global_load_lds_dwordx4 v134, s[36:37]
	s_waitcnt lgkmcnt(8)
	s_barrier
	s_waitcnt lgkmcnt(0)
	s_setprio 1
	s_waitcnt lgkmcnt(0)
	v_mfma_f32_16x16x32_bf16 v[118:121], v[144:147], v[170:173], v[118:121]
	v_mfma_f32_16x16x32_bf16 v[114:117], v[162:165], v[170:173], v[114:117]
	v_mfma_f32_16x16x32_bf16 v[110:113], v[144:147], v[178:181], v[110:113]
	v_mfma_f32_16x16x32_bf16 v[106:109], v[162:165], v[178:181], v[106:109]
	v_mfma_f32_16x16x32_bf16 v[94:97], v[144:147], v[186:189], v[94:97]
	v_mfma_f32_16x16x32_bf16 v[90:93], v[162:165], v[186:189], v[90:93]
	v_mfma_f32_16x16x32_bf16 v[78:81], v[144:147], v[194:197], v[78:81]
	v_mfma_f32_16x16x32_bf16 v[74:77], v[162:165], v[194:197], v[74:77]
	v_mfma_f32_16x16x32_bf16 v[118:121], v[158:161], v[174:177], v[118:121]
	v_mfma_f32_16x16x32_bf16 v[114:117], v[166:169], v[174:177], v[114:117]
	v_mfma_f32_16x16x32_bf16 v[110:113], v[158:161], v[182:185], v[110:113]
	v_mfma_f32_16x16x32_bf16 v[106:109], v[166:169], v[182:185], v[106:109]
	v_mfma_f32_16x16x32_bf16 v[94:97], v[158:161], v[190:193], v[94:97]
	v_mfma_f32_16x16x32_bf16 v[90:93], v[166:169], v[190:193], v[90:93]
	v_mfma_f32_16x16x32_bf16 v[78:81], v[158:161], v[198:201], v[78:81]
	v_mfma_f32_16x16x32_bf16 v[74:77], v[166:169], v[198:201], v[74:77]
	s_setprio 0
	s_barrier
	s_add_i32 s36, 16, 0x1c000
	s_add_i32 s37, s50, s38
	v_add_u32_e32 v214, s36, v150
	s_mov_b32 m0, s37
	ds_read_b128 v[202:205], v214
	ds_read_b128 v[206:209], v214 offset:1024
	ds_read_b128 v[210:213], v214 offset:2048
	ds_read_b128 v[214:217], v214 offset:3072
	global_load_lds_dwordx4 v132, s[62:63]
	s_add_i32 m0, s37, 0x2000
	s_nop 0
	global_load_lds_dwordx4 v136, s[64:65]
	s_barrier
	s_waitcnt lgkmcnt(0)
	s_setprio 1
	s_waitcnt lgkmcnt(0)
	v_mfma_f32_16x16x32_bf16 v[126:129], v[202:205], v[170:173], v[126:129]
	v_mfma_f32_16x16x32_bf16 v[122:125], v[210:213], v[170:173], v[122:125]
	v_mfma_f32_16x16x32_bf16 v[102:105], v[202:205], v[178:181], v[102:105]
	v_mfma_f32_16x16x32_bf16 v[98:101], v[210:213], v[178:181], v[98:101]
	v_mfma_f32_16x16x32_bf16 v[86:89], v[202:205], v[186:189], v[86:89]
	v_mfma_f32_16x16x32_bf16 v[82:85], v[210:213], v[186:189], v[82:85]
	v_mfma_f32_16x16x32_bf16 v[70:73], v[202:205], v[194:197], v[70:73]
	v_mfma_f32_16x16x32_bf16 v[66:69], v[210:213], v[194:197], v[66:69]
	v_mfma_f32_16x16x32_bf16 v[126:129], v[206:209], v[174:177], v[126:129]
	v_mfma_f32_16x16x32_bf16 v[122:125], v[214:217], v[174:177], v[122:125]
	v_mfma_f32_16x16x32_bf16 v[102:105], v[206:209], v[182:185], v[102:105]
	v_mfma_f32_16x16x32_bf16 v[98:101], v[214:217], v[182:185], v[98:101]
	v_mfma_f32_16x16x32_bf16 v[86:89], v[206:209], v[190:193], v[86:89]
	v_mfma_f32_16x16x32_bf16 v[82:85], v[214:217], v[190:193], v[82:85]
	v_mfma_f32_16x16x32_bf16 v[70:73], v[206:209], v[198:201], v[70:73]
	v_mfma_f32_16x16x32_bf16 v[66:69], v[214:217], v[198:201], v[66:69]
	s_setprio 0
	s_mov_b32 m0, s42
	s_barrier
	ds_read_b128 v[170:173], v156 offset:49152
	ds_read_b128 v[174:177], v156 offset:50176
	ds_read_b128 v[178:181], v156 offset:51200
	ds_read_b128 v[182:185], v156 offset:52224
	ds_read_b128 v[186:189], v156 offset:53248
	ds_read_b128 v[190:193], v156 offset:54272
	ds_read_b128 v[194:197], v156 offset:55296
	ds_read_b128 v[198:201], v156 offset:56320
	global_load_lds_dwordx4 v130, s[66:67]
	s_mov_b32 m0, s43
	s_nop 0
	global_load_lds_dwordx4 v134, s[68:69]
	s_barrier
; #define PG8_STAGE(bufoff, gbase, voff) do { _Pragma("unroll") for (int _i = 0; _i < 2; ++_i) \
;         __builtin_amdgcn_global_load_lds((const unsigned*)((const char*)(gbase) + (voff)[_i]), (LAS unsigned*)(lds + (bufoff) + ldsw + _i * 8192), 16, 0, 0); } while (0)
; #define PG8_MMA(ai, bj, At, Bt) do { __builtin_amdgcn_s_setprio(1); _Pragma("unroll") for (int m = 0; m < 4; ++m) _Pragma("unroll") for (int n = 0; n < 2; ++n) _Pragma("unroll") for (int k = 0; k < 2; ++k) \
;         acc[ai][bj][m][n] = __builtin_amdgcn_mfma_f32_16x16x32_bf16(Bt[n][k], At[m][k], acc[ai][bj][m][n], 0, 0, 0); __builtin_amdgcn_s_setprio(0); } while (0)
; #define PG8_WAIT_V(n) asm volatile("s_waitcnt vmcnt(" #n ")" ::: "memory")
; #define PG8_WAIT_L(n) asm volatile("s_waitcnt lgkmcnt(" #n ")" ::: "memory")
; #define PG8_BAR __builtin_amdgcn_s_barrier()
; #define PG8_SCHED __builtin_amdgcn_sched_barrier(0)
; template <class Sched, class Epi>
; __device__ __forceinline__ void gemm_phase(LAS unsigned char* lds, const Sched& S, const Epi& E, const int K, const int lda, const int ldb) {
;     ...
;             PG8_BAR; PG8_WAIT_L(0); if (!chalf) PG8_MMA(1, 0, At, B0); PG8_BAR; PG8_SCHED;
;             PG8_STAGE(PG8_SB(1, 1), b3 + hstepB, voffB);
;             PG8_WAIT_V(6); PG8_BAR; if (!chalf) PG8_MMA(1, 1, At, B1); PG8_BAR;
;         }
;     __device__ __forceinline__ void operator()(EPI_ARGS) const {
;         const int col = u.pn * 128 + wc * 32 + 8 * fq;
; #pragma unroll
;         for (int ai = 0; ai < 2; ++ai) if (ai == 0 || !u.half) { u32x4 zz[4];
; #pragma unroll
;             for (int m = 0; m < 4; ++m) zz[m] = *(const u32x4*)(parts + E_PZB + (size_t)EPI_ROW * 1024 + col);
	s_waitcnt lgkmcnt(0)
	s_setprio 1
	s_waitcnt lgkmcnt(0)
	v_mfma_f32_16x16x32_bf16 v[62:65], v[144:147], v[170:173], v[62:65]
	v_mfma_f32_16x16x32_bf16 v[58:61], v[162:165], v[170:173], v[58:61]
	v_mfma_f32_16x16x32_bf16 v[46:49], v[144:147], v[178:181], v[46:49]
	v_mfma_f32_16x16x32_bf16 v[42:45], v[162:165], v[178:181], v[42:45]
	v_mfma_f32_16x16x32_bf16 v[30:33], v[144:147], v[186:189], v[30:33]
	v_mfma_f32_16x16x32_bf16 v[26:29], v[162:165], v[186:189], v[26:29]
	v_mfma_f32_16x16x32_bf16 v[14:17], v[144:147], v[194:197], v[14:17]
	v_mfma_f32_16x16x32_bf16 v[10:13], v[162:165], v[194:197], v[10:13]
	v_mfma_f32_16x16x32_bf16 v[62:65], v[158:161], v[174:177], v[62:65]
	v_mfma_f32_16x16x32_bf16 v[58:61], v[166:169], v[174:177], v[58:61]
	v_mfma_f32_16x16x32_bf16 v[46:49], v[158:161], v[182:185], v[46:49]
	v_mfma_f32_16x16x32_bf16 v[42:45], v[166:169], v[182:185], v[42:45]
	v_mfma_f32_16x16x32_bf16 v[30:33], v[158:161], v[190:193], v[30:33]
	v_mfma_f32_16x16x32_bf16 v[26:29], v[166:169], v[190:193], v[26:29]
	v_mfma_f32_16x16x32_bf16 v[14:17], v[158:161], v[198:201], v[14:17]
	v_mfma_f32_16x16x32_bf16 v[10:13], v[166:169], v[198:201], v[10:13]
	s_setprio 0
	s_barrier
	s_add_u32 s34, s34, 0x40080
	s_addc_u32 s35, s35, 0
	s_add_i32 s36, s36, s38
	s_mov_b32 m0, s36
	s_nop 0
	global_load_lds_dwordx4 v132, s[34:35]
	s_add_i32 m0, s36, 0x2000
	s_nop 0
	global_load_lds_dwordx4 v136, s[34:35]
	s_waitcnt vmcnt(6)
	s_barrier
	s_setprio 1
	v_mfma_f32_16x16x32_bf16 v[54:57], v[202:205], v[170:173], v[54:57]
	v_mfma_f32_16x16x32_bf16 v[50:53], v[210:213], v[170:173], v[50:53]
	v_mfma_f32_16x16x32_bf16 v[38:41], v[202:205], v[178:181], v[38:41]
	v_mfma_f32_16x16x32_bf16 v[34:37], v[210:213], v[178:181], v[34:37]
	v_mfma_f32_16x16x32_bf16 v[22:25], v[202:205], v[186:189], v[22:25]
	v_mfma_f32_16x16x32_bf16 v[18:21], v[210:213], v[186:189], v[18:21]
	v_mfma_f32_16x16x32_bf16 v[6:9], v[202:205], v[194:197], v[6:9]
	v_mfma_f32_16x16x32_bf16 v[2:5], v[210:213], v[194:197], v[2:5]
	v_mfma_f32_16x16x32_bf16 v[54:57], v[206:209], v[174:177], v[54:57]
	v_mfma_f32_16x16x32_bf16 v[50:53], v[214:217], v[174:177], v[50:53]
	v_mfma_f32_16x16x32_bf16 v[38:41], v[206:209], v[182:185], v[38:41]
	v_mfma_f32_16x16x32_bf16 v[34:37], v[214:217], v[182:185], v[34:37]
	v_mfma_f32_16x16x32_bf16 v[22:25], v[206:209], v[190:193], v[22:25]
	v_mfma_f32_16x16x32_bf16 v[18:21], v[214:217], v[190:193], v[18:21]
	v_mfma_f32_16x16x32_bf16 v[6:9], v[206:209], v[198:201], v[6:9]
	v_mfma_f32_16x16x32_bf16 v[2:5], v[214:217], v[198:201], v[2:5]
	s_setprio 0
	s_add_i32 s49, s49, 2
	s_add_u32 s15, s15, 0x100
	s_addc_u32 s17, s17, 0
	s_add_u32 s28, s28, 0x100
	s_addc_u32 s29, s29, 0
	s_cmp_gt_u32 s49, 13
	s_barrier
	s_cbranch_scc0 .LBB0_761
	v_lshl_or_b32 v144, s48, 7, v154
	v_ashrrev_i32_e32 v145, 31, v144
	v_add_u32_e32 v148, s22, v1
	v_lshlrev_b64 v[144:145], 1, v[144:145]
	v_ashrrev_i32_e32 v149, 31, v148
	v_lshl_add_u64 v[146:147], s[6:7], 0, v[144:145]
	v_lshlrev_b64 v[166:167], 11, v[148:149]
	v_lshl_add_u64 v[158:159], v[146:147], 0, v[166:167]
	global_load_dwordx4 v[158:161], v[158:159], off
	v_mul_f32_e32 v149, 0xbfb8aa3b, v122
	v_mul_f32_e32 v123, 0xbfb8aa3b, v123
	v_add_u32_e32 v122, 16, v148
	v_exp_f32_e32 v174, v123
	v_ashrrev_i32_e32 v123, 31, v122
	v_lshlrev_b64 v[122:123], 11, v[122:123]
	v_mul_f32_e32 v126, 0xbfb8aa3b, v126
	v_mul_f32_e32 v127, 0xbfb8aa3b, v127
	v_mul_f32_e32 v128, 0xbfb8aa3b, v128
	v_mul_f32_e32 v129, 0xbfb8aa3b, v129
	v_lshl_add_u64 v[122:123], v[146:147], 0, v[122:123]
	v_exp_f32_e32 v168, v126
	v_exp_f32_e32 v172, v127
	v_exp_f32_e32 v176, v128
	v_exp_f32_e32 v180, v129
	global_load_dwordx4 v[126:129], v[122:123], off
	v_mul_f32_e32 v163, 0xbfb8aa3b, v124
	v_mul_f32_e32 v125, 0xbfb8aa3b, v125
	v_add_u32_e32 v124, 32, v148
	v_add_u32_e32 v162, 48, v148
	v_exp_f32_e32 v178, v163
	v_exp_f32_e32 v182, v125
	v_ashrrev_i32_e32 v125, 31, v124
	v_ashrrev_i32_e32 v163, 31, v162
	v_lshlrev_b64 v[122:123], 11, v[124:125]
	v_lshlrev_b64 v[124:125], 11, v[162:163]
	v_lshl_add_u64 v[122:123], v[146:147], 0, v[122:123]
	v_lshl_add_u64 v[124:125], v[146:147], 0, v[124:125]
	global_load_dwordx4 v[162:165], v[122:123], off
	s_nop 0
	global_load_dwordx4 v[122:125], v[124:125], off
	v_exp_f32_e32 v170, v149
	v_mul_f32_e32 v102, 0xbfb8aa3b, v102
	v_mul_f32_e32 v98, 0xbfb8aa3b, v98
	v_mul_f32_e32 v100, 0xbfb8aa3b, v100
	v_mul_f32_e32 v86, 0xbfb8aa3b, v86
	v_mul_f32_e32 v82, 0xbfb8aa3b, v82
	v_mul_f32_e32 v84, 0xbfb8aa3b, v84
	v_mul_f32_e32 v70, 0xbfb8aa3b, v70
	v_mul_f32_e32 v66, 0xbfb8aa3b, v66
	v_mul_f32_e32 v68, 0xbfb8aa3b, v68
	v_mul_f32_e32 v54, 0xbfb8aa3b, v54
	v_mul_f32_e32 v50, 0xbfb8aa3b, v50
	v_mul_f32_e32 v52, 0xbfb8aa3b, v52
	v_mul_f32_e32 v38, 0xbfb8aa3b, v38
	v_mul_f32_e32 v34, 0xbfb8aa3b, v34
	v_mul_f32_e32 v36, 0xbfb8aa3b, v36
	v_mul_f32_e32 v22, 0xbfb8aa3b, v22
	v_mul_f32_e32 v18, 0xbfb8aa3b, v18
	v_mul_f32_e32 v20, 0xbfb8aa3b, v20
	v_mul_f32_e32 v6, 0xbfb8aa3b, v6
	v_mul_f32_e32 v2, 0xbfb8aa3b, v2
	v_mul_f32_e32 v4, 0xbfb8aa3b, v4
	s_and_b64 vcc, exec, s[12:13]
	s_mov_b32 s48, s14
	s_mov_b64 s[34:35], s[20:21]
	s_mov_b64 s[28:29], s[18:19]
	s_waitcnt vmcnt(0)
; __device__ __forceinline__ u32x4 pack8(const float (&f)[8]) { u32x4 r; r[0] = cvt_pk_bf16(f[0], f[1]); r[1] = cvt_pk_bf16(f[2], f[3]); r[2] = cvt_pk_bf16(f[4], f[5]); r[3] = cvt_pk_bf16(f[6], f[7]); return r; }
;     __device__ __forceinline__ void operator()(EPI_ARGS) const {
;         const int col = u.pn * 128 + wc * 32 + 8 * fq;
; #pragma unroll
;         for (int ai = 0; ai < 2; ++ai) if (ai == 0 || !u.half) { u32x4 zz[4];
; #pragma unroll
;             for (int m = 0; m < 4; ++m) zz[m] = *(const u32x4*)(parts + E_PZB + (size_t)EPI_ROW * 1024 + col);
; #pragma unroll
;             for (int m = 0; m < 4; ++m) { float z[8]; unpack8(zz[m], z);
;                 const f32x4 a0 = acc[ai][0][m][0], a1 = acc[ai][0][m][1], b0 = acc[ai][1][m][0], b1 = acc[ai][1][m][1]; float o[8];
; #pragma unroll
;                 for (int j = 0; j < 4; ++j) { o[j] = a0[j] * z[j] * __builtin_amdgcn_rcpf((1.0f + __expf(-b0[j])) * (1.0f + __expf(-z[j]))); o[4 + j] = a1[j] * z[4 + j] * __builtin_amdgcn_rcpf((1.0f + __expf(-b1[j])) * (1.0f + __expf(-z[4 + j]))); }
;                 *(u32x4*)(O + (size_t)EPI_ROW * 1024 + col) = pack8(o); } }
	v_lshlrev_b32_e32 v149, 16, v158
	v_and_b32_e32 v158, 0xffff0000, v158
	v_lshlrev_b32_e32 v169, 16, v159
	v_and_b32_e32 v184, 0xffff0000, v159
	v_lshlrev_b32_e32 v159, 16, v160
	v_and_b32_e32 v160, 0xffff0000, v160
	v_lshlrev_b32_e32 v171, 16, v161
	v_mul_f32_e32 v186, v118, v149
	v_mul_f32_e32 v118, 0xbfb8aa3b, v149
	v_mul_f32_e32 v149, v114, v159
	v_mul_f32_e32 v114, 0xbfb8aa3b, v159
	v_mul_f32_e32 v187, v119, v158
	v_mul_f32_e32 v119, 0xbfb8aa3b, v158
	v_mul_f32_e32 v188, v115, v160
	v_mul_f32_e32 v115, 0xbfb8aa3b, v160
	v_mul_f32_e32 v158, 0xbfb8aa3b, v169
	v_mul_f32_e32 v159, 0xbfb8aa3b, v171
	v_mul_f32_e32 v120, v120, v169
	v_mul_f32_e32 v116, v116, v171
	v_exp_f32_e32 v169, v118
	v_exp_f32_e32 v171, v114
	v_exp_f32_e32 v173, v119
	v_exp_f32_e32 v175, v115
	v_exp_f32_e32 v177, v158
	v_exp_f32_e32 v179, v159
	v_and_b32_e32 v185, 0xffff0000, v161
	v_mul_f32_e32 v160, 0xbfb8aa3b, v184
	v_mul_f32_e32 v161, 0xbfb8aa3b, v185
	v_exp_f32_e32 v181, v160
	v_exp_f32_e32 v183, v161
	v_pk_add_f32 v[114:115], v[168:169], 1.0 op_sel_hi:[1,0]
	v_pk_add_f32 v[118:119], v[170:171], 1.0 op_sel_hi:[1,0]
	v_pk_add_f32 v[158:159], v[172:173], 1.0 op_sel_hi:[1,0]
	v_pk_add_f32 v[160:161], v[174:175], 1.0 op_sel_hi:[1,0]
	v_pk_add_f32 v[168:169], v[176:177], 1.0 op_sel_hi:[1,0]
	v_pk_add_f32 v[170:171], v[178:179], 1.0 op_sel_hi:[1,0]
	v_mul_f32_e32 v114, v114, v115
	v_mul_f32_e32 v115, v118, v119
	v_mul_f32_e32 v118, v158, v159
	v_mul_f32_e32 v119, v160, v161
	v_mul_f32_e32 v158, v168, v169
	v_mul_f32_e32 v159, v170, v171
	v_rcp_f32_e32 v115, v115
	v_rcp_f32_e32 v118, v118
	v_rcp_f32_e32 v119, v119
	v_rcp_f32_e32 v158, v158
	v_rcp_f32_e32 v159, v159
	v_pk_add_f32 v[172:173], v[180:181], 1.0 op_sel_hi:[1,0]
	v_pk_add_f32 v[174:175], v[182:183], 1.0 op_sel_hi:[1,0]
	v_mul_f32_e32 v160, v172, v173
	v_rcp_f32_e32 v114, v114
	v_mul_f32_e32 v149, v149, v115
	v_mul_f32_e32 v115, v187, v118
	v_mul_f32_e32 v118, v188, v119
	v_mul_f32_e32 v119, v120, v158
	v_mul_f32_e32 v120, v116, v159
	v_mul_f32_e32 v116, v174, v175
	v_rcp_f32_e32 v160, v160
	v_rcp_f32_e32 v116, v116
	v_mul_f32_e32 v114, v186, v114
	v_mul_f32_e32 v121, v121, v184
	v_mul_f32_e32 v117, v117, v185
	v_mul_f32_e32 v121, v121, v160
	v_mul_f32_e32 v117, v117, v116
	v_cvt_pk_bf16_f32 v114, v114, v115
	v_cvt_pk_bf16_f32 v115, v119, v121
	v_cvt_pk_bf16_f32 v116, v149, v118
	v_lshl_add_u64 v[118:119], s[4:5], 0, v[166:167]
	v_lshl_add_u64 v[118:119], v[118:119], 0, v[144:145]
	v_cvt_pk_bf16_f32 v117, v120, v117
	global_store_dwordx4 v[118:119], v[114:117], off
	v_lshlrev_b32_e32 v118, 16, v126
	v_and_b32_e32 v119, 0xffff0000, v126
	v_lshlrev_b32_e32 v126, 16, v128
	v_exp_f32_e32 v114, v102
	v_mul_f32_e32 v102, 0xbfb8aa3b, v118
	v_exp_f32_e32 v115, v102
	v_exp_f32_e32 v116, v98
	v_mul_f32_e32 v98, 0xbfb8aa3b, v126
	v_exp_f32_e32 v117, v98
	v_pk_add_f32 v[114:115], v[114:115], 1.0 op_sel_hi:[1,0]
	v_mul_f32_e32 v110, v110, v118
	v_mul_f32_e32 v98, v114, v115
	v_pk_add_f32 v[114:115], v[116:117], 1.0 op_sel_hi:[1,0]
	v_rcp_f32_e32 v98, v98
	v_mul_f32_e32 v102, v114, v115
	v_rcp_f32_e32 v102, v102
	v_lshlrev_b32_e32 v120, 16, v127
	v_mul_f32_e32 v110, v110, v98
	v_mul_f32_e32 v98, v106, v126
	v_mul_f32_e32 v106, v98, v102
	v_mul_f32_e32 v98, 0xbfb8aa3b, v103
	v_and_b32_e32 v121, 0xffff0000, v127
	v_and_b32_e32 v127, 0xffff0000, v128
	v_exp_f32_e32 v102, v98
	v_mul_f32_e32 v98, 0xbfb8aa3b, v119
	v_exp_f32_e32 v103, v98
	v_mul_f32_e32 v98, 0xbfb8aa3b, v99
	v_mul_f32_e32 v99, 0xbfb8aa3b, v127
	v_exp_f32_e32 v98, v98
	v_exp_f32_e32 v99, v99
	v_pk_add_f32 v[102:103], v[102:103], 1.0 op_sel_hi:[1,0]
	v_lshlrev_b32_e32 v128, 16, v129
	v_mul_f32_e32 v102, v102, v103
	v_pk_add_f32 v[98:99], v[98:99], 1.0 op_sel_hi:[1,0]
	v_rcp_f32_e32 v102, v102
	v_mul_f32_e32 v98, v98, v99
	v_rcp_f32_e32 v98, v98
	v_mul_f32_e32 v99, v111, v119
	v_mul_f32_e32 v111, v99, v102
	v_mul_f32_e32 v99, v107, v127
	v_mul_f32_e32 v107, v99, v98
	v_mul_f32_e32 v98, 0xbfb8aa3b, v104
	v_mul_f32_e32 v99, 0xbfb8aa3b, v120
	v_exp_f32_e32 v98, v98
	v_exp_f32_e32 v99, v99
	v_exp_f32_e32 v102, v100
	v_mul_f32_e32 v100, 0xbfb8aa3b, v128
	v_exp_f32_e32 v103, v100
	v_pk_add_f32 v[98:99], v[98:99], 1.0 op_sel_hi:[1,0]
	v_and_b32_e32 v129, 0xffff0000, v129
	v_mul_f32_e32 v98, v98, v99
	v_rcp_f32_e32 v100, v98
	v_pk_add_f32 v[98:99], v[102:103], 1.0 op_sel_hi:[1,0]
	s_nop 0
	v_mul_f32_e32 v98, v98, v99
	v_rcp_f32_e32 v98, v98
	v_mul_f32_e32 v99, v112, v120
	v_mul_f32_e32 v102, v99, v100
	v_mul_f32_e32 v99, v108, v128
	v_mul_f32_e32 v103, v99, v98
	v_mul_f32_e32 v98, 0xbfb8aa3b, v105
	v_mul_f32_e32 v99, 0xbfb8aa3b, v121
	v_exp_f32_e32 v98, v98
	v_exp_f32_e32 v99, v99
	v_mul_f32_e32 v100, 0xbfb8aa3b, v101
	v_mul_f32_e32 v101, 0xbfb8aa3b, v129
	v_exp_f32_e32 v100, v100
	v_exp_f32_e32 v101, v101
	v_pk_add_f32 v[98:99], v[98:99], 1.0 op_sel_hi:[1,0]
	v_lshlrev_b32_e32 v108, 16, v165
	v_mul_f32_e32 v98, v98, v99
	v_rcp_f32_e32 v104, v98
	v_pk_add_f32 v[98:99], v[100:101], 1.0 op_sel_hi:[1,0]
	v_mul_f32_e32 v100, v109, v129
	v_mul_f32_e32 v98, v98, v99
	v_rcp_f32_e32 v98, v98
	v_mul_f32_e32 v99, v113, v121
	v_mul_f32_e32 v99, v99, v104
	v_lshlrev_b32_e32 v104, 16, v163
	v_mul_f32_e32 v101, v100, v98
	v_cvt_pk_bf16_f32 v98, v110, v111
	v_cvt_pk_bf16_f32 v99, v102, v99
	v_add_u32_e32 v102, s22, v151
	v_cvt_pk_bf16_f32 v100, v106, v107
	v_cvt_pk_bf16_f32 v101, v103, v101
	v_ashrrev_i32_e32 v103, 31, v102
	v_lshlrev_b64 v[102:103], 11, v[102:103]
	v_lshl_add_u64 v[102:103], s[4:5], 0, v[102:103]
	v_lshl_add_u64 v[102:103], v[102:103], 0, v[144:145]
	global_store_dwordx4 v[102:103], v[98:101], off
	v_lshlrev_b32_e32 v102, 16, v162
	v_lshlrev_b32_e32 v106, 16, v164
; __device__ __forceinline__ u32x4 pack8(const float (&f)[8]) { u32x4 r; r[0] = cvt_pk_bf16(f[0], f[1]); r[1] = cvt_pk_bf16(f[2], f[3]); r[2] = cvt_pk_bf16(f[4], f[5]); r[3] = cvt_pk_bf16(f[6], f[7]); return r; }
;     __device__ __forceinline__ void operator()(EPI_ARGS) const {
;         const int col = u.pn * 128 + wc * 32 + 8 * fq;
; #pragma unroll
;         for (int ai = 0; ai < 2; ++ai) if (ai == 0 || !u.half) { u32x4 zz[4];
; #pragma unroll
;             for (int m = 0; m < 4; ++m) zz[m] = *(const u32x4*)(parts + E_PZB + (size_t)EPI_ROW * 1024 + col);
; #pragma unroll
;             for (int m = 0; m < 4; ++m) { float z[8]; unpack8(zz[m], z);
;                 const f32x4 a0 = acc[ai][0][m][0], a1 = acc[ai][0][m][1], b0 = acc[ai][1][m][0], b1 = acc[ai][1][m][1]; float o[8];
; #pragma unroll
;                 for (int j = 0; j < 4; ++j) { o[j] = a0[j] * z[j] * __builtin_amdgcn_rcpf((1.0f + __expf(-b0[j])) * (1.0f + __expf(-z[j]))); o[4 + j] = a1[j] * z[4 + j] * __builtin_amdgcn_rcpf((1.0f + __expf(-b1[j])) * (1.0f + __expf(-z[4 + j]))); }
;                 *(u32x4*)(O + (size_t)EPI_ROW * 1024 + col) = pack8(o); } }
	v_exp_f32_e32 v98, v86
	v_mul_f32_e32 v86, 0xbfb8aa3b, v102
	v_exp_f32_e32 v99, v86
	v_exp_f32_e32 v100, v82
	v_mul_f32_e32 v82, 0xbfb8aa3b, v106
	v_exp_f32_e32 v101, v82
	v_pk_add_f32 v[98:99], v[98:99], 1.0 op_sel_hi:[1,0]
	v_mul_f32_e32 v94, v94, v102
	v_mul_f32_e32 v82, v98, v99
	v_pk_add_f32 v[98:99], v[100:101], 1.0 op_sel_hi:[1,0]
	v_rcp_f32_e32 v82, v82
	v_mul_f32_e32 v86, v98, v99
	v_rcp_f32_e32 v86, v86
	v_and_b32_e32 v103, 0xffff0000, v162
	v_mul_f32_e32 v94, v94, v82
	v_mul_f32_e32 v82, v90, v106
	v_mul_f32_e32 v90, v82, v86
	v_mul_f32_e32 v82, 0xbfb8aa3b, v87
	v_and_b32_e32 v107, 0xffff0000, v164
	v_exp_f32_e32 v86, v82
	v_mul_f32_e32 v82, 0xbfb8aa3b, v103
	v_exp_f32_e32 v87, v82
	v_mul_f32_e32 v82, 0xbfb8aa3b, v83
	v_mul_f32_e32 v83, 0xbfb8aa3b, v107
	v_exp_f32_e32 v82, v82
	v_exp_f32_e32 v83, v83
	v_pk_add_f32 v[86:87], v[86:87], 1.0 op_sel_hi:[1,0]
	v_and_b32_e32 v105, 0xffff0000, v163
	v_mul_f32_e32 v86, v86, v87
	v_pk_add_f32 v[82:83], v[82:83], 1.0 op_sel_hi:[1,0]
	v_rcp_f32_e32 v86, v86
	v_mul_f32_e32 v82, v82, v83
	v_rcp_f32_e32 v82, v82
	v_mul_f32_e32 v83, v95, v103
	v_mul_f32_e32 v95, v83, v86
	v_mul_f32_e32 v83, v91, v107
	v_mul_f32_e32 v91, v83, v82
	v_mul_f32_e32 v82, 0xbfb8aa3b, v88
	v_mul_f32_e32 v83, 0xbfb8aa3b, v104
	v_exp_f32_e32 v82, v82
	v_exp_f32_e32 v83, v83
	v_exp_f32_e32 v86, v84
	v_mul_f32_e32 v84, 0xbfb8aa3b, v108
	v_exp_f32_e32 v87, v84
	v_pk_add_f32 v[82:83], v[82:83], 1.0 op_sel_hi:[1,0]
	v_and_b32_e32 v109, 0xffff0000, v165
	v_mul_f32_e32 v82, v82, v83
	v_rcp_f32_e32 v84, v82
	v_pk_add_f32 v[82:83], v[86:87], 1.0 op_sel_hi:[1,0]
	s_nop 0
	v_mul_f32_e32 v82, v82, v83
	v_rcp_f32_e32 v82, v82
	v_mul_f32_e32 v83, v96, v104
	v_mul_f32_e32 v86, v83, v84
	v_mul_f32_e32 v83, v92, v108
	v_mul_f32_e32 v87, v83, v82
	v_mul_f32_e32 v82, 0xbfb8aa3b, v89
	v_mul_f32_e32 v83, 0xbfb8aa3b, v105
	v_exp_f32_e32 v82, v82
	v_exp_f32_e32 v83, v83
	v_mul_f32_e32 v84, 0xbfb8aa3b, v85
	v_mul_f32_e32 v85, 0xbfb8aa3b, v109
	v_exp_f32_e32 v84, v84
	v_exp_f32_e32 v85, v85
	v_pk_add_f32 v[82:83], v[82:83], 1.0 op_sel_hi:[1,0]
	v_lshlrev_b32_e32 v92, 16, v125
	v_mul_f32_e32 v82, v82, v83
	v_rcp_f32_e32 v88, v82
	v_pk_add_f32 v[82:83], v[84:85], 1.0 op_sel_hi:[1,0]
	v_mul_f32_e32 v84, v93, v109
	v_mul_f32_e32 v82, v82, v83
	v_rcp_f32_e32 v82, v82
	v_mul_f32_e32 v83, v97, v105
	v_mul_f32_e32 v83, v83, v88
	v_lshlrev_b32_e32 v88, 16, v123
	v_mul_f32_e32 v85, v84, v82
	v_cvt_pk_bf16_f32 v82, v94, v95
	v_cvt_pk_bf16_f32 v83, v86, v83
	v_add_u32_e32 v86, s22, v152
	v_cvt_pk_bf16_f32 v84, v90, v91
	v_cvt_pk_bf16_f32 v85, v87, v85
	v_ashrrev_i32_e32 v87, 31, v86
	v_lshlrev_b64 v[86:87], 11, v[86:87]
	v_lshl_add_u64 v[86:87], s[4:5], 0, v[86:87]
	v_lshl_add_u64 v[86:87], v[86:87], 0, v[144:145]
	global_store_dwordx4 v[86:87], v[82:85], off
	v_lshlrev_b32_e32 v86, 16, v122
	v_lshlrev_b32_e32 v90, 16, v124
	v_exp_f32_e32 v82, v70
	v_mul_f32_e32 v70, 0xbfb8aa3b, v86
	v_exp_f32_e32 v83, v70
	v_exp_f32_e32 v84, v66
	v_mul_f32_e32 v66, 0xbfb8aa3b, v90
	v_exp_f32_e32 v85, v66
	v_pk_add_f32 v[82:83], v[82:83], 1.0 op_sel_hi:[1,0]
	v_mul_f32_e32 v78, v78, v86
	v_mul_f32_e32 v66, v82, v83
	v_pk_add_f32 v[82:83], v[84:85], 1.0 op_sel_hi:[1,0]
	v_rcp_f32_e32 v66, v66
	v_mul_f32_e32 v70, v82, v83
	v_rcp_f32_e32 v70, v70
	v_and_b32_e32 v87, 0xffff0000, v122
	v_mul_f32_e32 v78, v78, v66
	v_mul_f32_e32 v66, v74, v90
	v_mul_f32_e32 v74, v66, v70
	v_mul_f32_e32 v66, 0xbfb8aa3b, v71
	v_and_b32_e32 v91, 0xffff0000, v124
	v_exp_f32_e32 v70, v66
	v_mul_f32_e32 v66, 0xbfb8aa3b, v87
	v_exp_f32_e32 v71, v66
	v_mul_f32_e32 v66, 0xbfb8aa3b, v67
	v_mul_f32_e32 v67, 0xbfb8aa3b, v91
	v_exp_f32_e32 v66, v66
	v_exp_f32_e32 v67, v67
	v_pk_add_f32 v[70:71], v[70:71], 1.0 op_sel_hi:[1,0]
	v_and_b32_e32 v89, 0xffff0000, v123
	v_mul_f32_e32 v70, v70, v71
	v_pk_add_f32 v[66:67], v[66:67], 1.0 op_sel_hi:[1,0]
	v_rcp_f32_e32 v70, v70
	v_mul_f32_e32 v66, v66, v67
	v_rcp_f32_e32 v66, v66
	v_mul_f32_e32 v67, v79, v87
	v_mul_f32_e32 v79, v67, v70
	v_mul_f32_e32 v67, v75, v91
	v_mul_f32_e32 v75, v67, v66
	v_mul_f32_e32 v66, 0xbfb8aa3b, v72
	v_mul_f32_e32 v67, 0xbfb8aa3b, v88
	v_exp_f32_e32 v66, v66
	v_exp_f32_e32 v67, v67
	v_exp_f32_e32 v70, v68
	v_mul_f32_e32 v68, 0xbfb8aa3b, v92
	v_exp_f32_e32 v71, v68
	v_pk_add_f32 v[66:67], v[66:67], 1.0 op_sel_hi:[1,0]
	v_and_b32_e32 v93, 0xffff0000, v125
	v_mul_f32_e32 v66, v66, v67
	v_rcp_f32_e32 v68, v66
	v_pk_add_f32 v[66:67], v[70:71], 1.0 op_sel_hi:[1,0]
	s_nop 0
	v_mul_f32_e32 v66, v66, v67
	v_rcp_f32_e32 v66, v66
	v_mul_f32_e32 v67, v80, v88
	v_mul_f32_e32 v70, v67, v68
	v_mul_f32_e32 v67, v76, v92
	v_mul_f32_e32 v71, v67, v66
	v_mul_f32_e32 v66, 0xbfb8aa3b, v73
	v_mul_f32_e32 v67, 0xbfb8aa3b, v89
	v_exp_f32_e32 v66, v66
	v_exp_f32_e32 v67, v67
	v_mul_f32_e32 v68, 0xbfb8aa3b, v69
	v_mul_f32_e32 v69, 0xbfb8aa3b, v93
	v_exp_f32_e32 v68, v68
	v_exp_f32_e32 v69, v69
	v_pk_add_f32 v[66:67], v[66:67], 1.0 op_sel_hi:[1,0]
	s_nop 0
	v_mul_f32_e32 v66, v66, v67
	v_rcp_f32_e32 v72, v66
	v_pk_add_f32 v[66:67], v[68:69], 1.0 op_sel_hi:[1,0]
	v_mul_f32_e32 v68, v77, v93
	v_mul_f32_e32 v66, v66, v67
	v_rcp_f32_e32 v66, v66
	v_mul_f32_e32 v67, v81, v89
	v_mul_f32_e32 v67, v67, v72
	v_mul_f32_e32 v69, v68, v66
	v_cvt_pk_bf16_f32 v66, v78, v79
	v_cvt_pk_bf16_f32 v67, v70, v67
	v_add_u32_e32 v70, s22, v153
	v_cvt_pk_bf16_f32 v68, v74, v75
	v_cvt_pk_bf16_f32 v69, v71, v69
	v_ashrrev_i32_e32 v71, 31, v70
	v_lshlrev_b64 v[70:71], 11, v[70:71]
	v_lshl_add_u64 v[70:71], s[4:5], 0, v[70:71]
	v_lshl_add_u64 v[70:71], v[70:71], 0, v[144:145]
	global_store_dwordx4 v[70:71], v[66:69], off
	s_mov_b32 s22, s16
	s_nop 0
	v_add_u32_e32 v66, 0x80, v148
	v_ashrrev_i32_e32 v67, 31, v66
	v_lshlrev_b64 v[88:89], 11, v[66:67]
	v_lshl_add_u64 v[66:67], v[146:147], 0, v[88:89]
	global_load_dwordx4 v[80:83], v[66:67], off
	v_add_u32_e32 v66, 0x90, v148
	v_ashrrev_i32_e32 v67, 31, v66
	v_lshlrev_b64 v[78:79], 11, v[66:67]
	v_lshl_add_u64 v[66:67], v[146:147], 0, v[78:79]
	global_load_dwordx4 v[84:87], v[66:67], off
	v_add_u32_e32 v66, 0xa0, v148
	v_ashrrev_i32_e32 v67, 31, v66
	v_lshlrev_b64 v[76:77], 11, v[66:67]
	v_add_u32_e32 v66, 0xb0, v148
	v_ashrrev_i32_e32 v67, 31, v66
	v_lshl_add_u64 v[90:91], v[146:147], 0, v[76:77]
	v_lshlrev_b64 v[74:75], 11, v[66:67]
	v_lshl_add_u64 v[92:93], v[146:147], 0, v[74:75]
	global_load_dwordx4 v[70:73], v[90:91], off
	global_load_dwordx4 v[66:69], v[92:93], off
	s_waitcnt vmcnt(0)
; __device__ __forceinline__ u32x4 pack8(const float (&f)[8]) { u32x4 r; r[0] = cvt_pk_bf16(f[0], f[1]); r[1] = cvt_pk_bf16(f[2], f[3]); r[2] = cvt_pk_bf16(f[4], f[5]); r[3] = cvt_pk_bf16(f[6], f[7]); return r; }
;     __device__ __forceinline__ void operator()(EPI_ARGS) const {
;         const int col = u.pn * 128 + wc * 32 + 8 * fq;
; #pragma unroll
;         for (int ai = 0; ai < 2; ++ai) if (ai == 0 || !u.half) { u32x4 zz[4];
; #pragma unroll
;             for (int m = 0; m < 4; ++m) zz[m] = *(const u32x4*)(parts + E_PZB + (size_t)EPI_ROW * 1024 + col);
; #pragma unroll
;             for (int m = 0; m < 4; ++m) { float z[8]; unpack8(zz[m], z);
;                 const f32x4 a0 = acc[ai][0][m][0], a1 = acc[ai][0][m][1], b0 = acc[ai][1][m][0], b1 = acc[ai][1][m][1]; float o[8];
; #pragma unroll
;                 for (int j = 0; j < 4; ++j) { o[j] = a0[j] * z[j] * __builtin_amdgcn_rcpf((1.0f + __expf(-b0[j])) * (1.0f + __expf(-z[j]))); o[4 + j] = a1[j] * z[4 + j] * __builtin_amdgcn_rcpf((1.0f + __expf(-b1[j])) * (1.0f + __expf(-z[4 + j]))); }
;                 *(u32x4*)(O + (size_t)EPI_ROW * 1024 + col) = pack8(o); } }
	v_lshlrev_b32_e32 v90, 16, v80
	v_and_b32_e32 v91, 0xffff0000, v80
	v_lshlrev_b32_e32 v94, 16, v82
	v_exp_f32_e32 v80, v54
	v_mul_f32_e32 v54, 0xbfb8aa3b, v90
	v_lshlrev_b32_e32 v92, 16, v81
	v_and_b32_e32 v93, 0xffff0000, v81
	v_and_b32_e32 v95, 0xffff0000, v82
	v_exp_f32_e32 v81, v54
	v_exp_f32_e32 v82, v50
	v_mul_f32_e32 v50, 0xbfb8aa3b, v94
	v_lshlrev_b32_e32 v96, 16, v83
	v_and_b32_e32 v97, 0xffff0000, v83
	v_exp_f32_e32 v83, v50
	v_pk_add_f32 v[80:81], v[80:81], 1.0 op_sel_hi:[1,0]
	v_mul_f32_e32 v62, v62, v90
	v_mul_f32_e32 v50, v80, v81
	v_pk_add_f32 v[80:81], v[82:83], 1.0 op_sel_hi:[1,0]
	v_rcp_f32_e32 v50, v50
	v_mul_f32_e32 v54, v80, v81
	v_rcp_f32_e32 v54, v54
	v_mul_f32_e32 v62, v62, v50
	v_mul_f32_e32 v50, v58, v94
	v_mul_f32_e32 v58, v50, v54
	v_mul_f32_e32 v50, 0xbfb8aa3b, v55
	v_exp_f32_e32 v54, v50
	v_mul_f32_e32 v50, 0xbfb8aa3b, v91
	v_exp_f32_e32 v55, v50
	v_mul_f32_e32 v50, 0xbfb8aa3b, v51
	v_mul_f32_e32 v51, 0xbfb8aa3b, v95
	v_exp_f32_e32 v50, v50
	v_exp_f32_e32 v51, v51
	v_pk_add_f32 v[54:55], v[54:55], 1.0 op_sel_hi:[1,0]
	v_pk_add_f32 v[50:51], v[50:51], 1.0 op_sel_hi:[1,0]
	v_mul_f32_e32 v54, v54, v55
	v_rcp_f32_e32 v54, v54
	v_mul_f32_e32 v50, v50, v51
	v_rcp_f32_e32 v50, v50
	v_mul_f32_e32 v51, v63, v91
	v_mul_f32_e32 v63, v51, v54
	v_mul_f32_e32 v51, v59, v95
	v_mul_f32_e32 v59, v51, v50
	v_mul_f32_e32 v50, 0xbfb8aa3b, v56
	v_mul_f32_e32 v51, 0xbfb8aa3b, v92
	v_exp_f32_e32 v50, v50
	v_exp_f32_e32 v51, v51
	v_exp_f32_e32 v54, v52
	v_mul_f32_e32 v52, 0xbfb8aa3b, v96
	v_exp_f32_e32 v55, v52
	v_pk_add_f32 v[50:51], v[50:51], 1.0 op_sel_hi:[1,0]
	s_nop 0
	v_mul_f32_e32 v50, v50, v51
	v_rcp_f32_e32 v52, v50
	v_pk_add_f32 v[50:51], v[54:55], 1.0 op_sel_hi:[1,0]
	s_nop 0
	v_mul_f32_e32 v50, v50, v51
	v_rcp_f32_e32 v50, v50
	v_mul_f32_e32 v51, v64, v92
	v_mul_f32_e32 v54, v51, v52
	v_mul_f32_e32 v51, v60, v96
	v_mul_f32_e32 v55, v51, v50
	v_mul_f32_e32 v50, 0xbfb8aa3b, v57
	v_mul_f32_e32 v51, 0xbfb8aa3b, v93
	v_exp_f32_e32 v50, v50
	v_exp_f32_e32 v51, v51
	v_mul_f32_e32 v52, 0xbfb8aa3b, v53
	v_mul_f32_e32 v53, 0xbfb8aa3b, v97
	v_exp_f32_e32 v52, v52
	v_exp_f32_e32 v53, v53
	v_pk_add_f32 v[50:51], v[50:51], 1.0 op_sel_hi:[1,0]
	v_lshlrev_b32_e32 v60, 16, v87
	v_mul_f32_e32 v50, v50, v51
	v_rcp_f32_e32 v56, v50
	v_pk_add_f32 v[50:51], v[52:53], 1.0 op_sel_hi:[1,0]
	v_mul_f32_e32 v52, v61, v97
	v_mul_f32_e32 v50, v50, v51
	v_rcp_f32_e32 v50, v50
	v_mul_f32_e32 v51, v65, v93
	v_mul_f32_e32 v51, v51, v56
	v_lshlrev_b32_e32 v56, 16, v85
	v_mul_f32_e32 v53, v52, v50
	v_cvt_pk_bf16_f32 v50, v62, v63
	v_cvt_pk_bf16_f32 v51, v54, v51
	v_cvt_pk_bf16_f32 v52, v58, v59
	v_cvt_pk_bf16_f32 v53, v55, v53
	v_lshl_add_u64 v[54:55], s[4:5], 0, v[88:89]
	v_lshl_add_u64 v[54:55], v[54:55], 0, v[144:145]
	global_store_dwordx4 v[54:55], v[50:53], off
	v_lshlrev_b32_e32 v54, 16, v84
	v_lshlrev_b32_e32 v58, 16, v86
	v_exp_f32_e32 v50, v38
	v_mul_f32_e32 v38, 0xbfb8aa3b, v54
	v_exp_f32_e32 v51, v38
	v_exp_f32_e32 v52, v34
	v_mul_f32_e32 v34, 0xbfb8aa3b, v58
	v_exp_f32_e32 v53, v34
	v_pk_add_f32 v[50:51], v[50:51], 1.0 op_sel_hi:[1,0]
	v_mul_f32_e32 v46, v46, v54
	v_mul_f32_e32 v34, v50, v51
	v_pk_add_f32 v[50:51], v[52:53], 1.0 op_sel_hi:[1,0]
	v_rcp_f32_e32 v34, v34
	v_mul_f32_e32 v38, v50, v51
	v_rcp_f32_e32 v38, v38
	v_and_b32_e32 v55, 0xffff0000, v84
	v_mul_f32_e32 v46, v46, v34
	v_mul_f32_e32 v34, v42, v58
	v_mul_f32_e32 v42, v34, v38
	v_mul_f32_e32 v34, 0xbfb8aa3b, v39
	v_and_b32_e32 v59, 0xffff0000, v86
	v_exp_f32_e32 v38, v34
	v_mul_f32_e32 v34, 0xbfb8aa3b, v55
	v_exp_f32_e32 v39, v34
	v_mul_f32_e32 v34, 0xbfb8aa3b, v35
	v_mul_f32_e32 v35, 0xbfb8aa3b, v59
	v_exp_f32_e32 v34, v34
	v_exp_f32_e32 v35, v35
	v_pk_add_f32 v[38:39], v[38:39], 1.0 op_sel_hi:[1,0]
	v_and_b32_e32 v57, 0xffff0000, v85
	v_mul_f32_e32 v38, v38, v39
	v_pk_add_f32 v[34:35], v[34:35], 1.0 op_sel_hi:[1,0]
	v_rcp_f32_e32 v38, v38
	v_mul_f32_e32 v34, v34, v35
	v_rcp_f32_e32 v34, v34
	v_mul_f32_e32 v35, v47, v55
	v_mul_f32_e32 v47, v35, v38
	v_mul_f32_e32 v35, v43, v59
	v_mul_f32_e32 v43, v35, v34
	v_mul_f32_e32 v34, 0xbfb8aa3b, v40
	v_mul_f32_e32 v35, 0xbfb8aa3b, v56
	v_exp_f32_e32 v34, v34
	v_exp_f32_e32 v35, v35
	v_exp_f32_e32 v38, v36
	v_mul_f32_e32 v36, 0xbfb8aa3b, v60
	v_exp_f32_e32 v39, v36
	v_pk_add_f32 v[34:35], v[34:35], 1.0 op_sel_hi:[1,0]
	v_and_b32_e32 v61, 0xffff0000, v87
	v_mul_f32_e32 v34, v34, v35
	v_rcp_f32_e32 v36, v34
	v_pk_add_f32 v[34:35], v[38:39], 1.0 op_sel_hi:[1,0]
	s_nop 0
	v_mul_f32_e32 v34, v34, v35
	v_rcp_f32_e32 v34, v34
	v_mul_f32_e32 v35, v48, v56
	v_mul_f32_e32 v38, v35, v36
	v_mul_f32_e32 v35, v44, v60
	v_mul_f32_e32 v39, v35, v34
	v_mul_f32_e32 v34, 0xbfb8aa3b, v41
	v_mul_f32_e32 v35, 0xbfb8aa3b, v57
	v_exp_f32_e32 v34, v34
	v_exp_f32_e32 v35, v35
	v_mul_f32_e32 v36, 0xbfb8aa3b, v37
	v_mul_f32_e32 v37, 0xbfb8aa3b, v61
	v_exp_f32_e32 v36, v36
	v_exp_f32_e32 v37, v37
	v_pk_add_f32 v[34:35], v[34:35], 1.0 op_sel_hi:[1,0]
	v_lshlrev_b32_e32 v44, 16, v73
	v_mul_f32_e32 v34, v34, v35
	v_rcp_f32_e32 v40, v34
	v_pk_add_f32 v[34:35], v[36:37], 1.0 op_sel_hi:[1,0]
	v_mul_f32_e32 v36, v45, v61
	v_mul_f32_e32 v34, v34, v35
	v_rcp_f32_e32 v34, v34
	v_mul_f32_e32 v35, v49, v57
	v_mul_f32_e32 v35, v35, v40
	v_lshlrev_b32_e32 v40, 16, v71
	v_mul_f32_e32 v37, v36, v34
	v_cvt_pk_bf16_f32 v34, v46, v47
	v_cvt_pk_bf16_f32 v35, v38, v35
	v_cvt_pk_bf16_f32 v36, v42, v43
	v_cvt_pk_bf16_f32 v37, v39, v37
	v_lshl_add_u64 v[38:39], s[4:5], 0, v[78:79]
; __device__ __forceinline__ u32x4 pack8(const float (&f)[8]) { u32x4 r; r[0] = cvt_pk_bf16(f[0], f[1]); r[1] = cvt_pk_bf16(f[2], f[3]); r[2] = cvt_pk_bf16(f[4], f[5]); r[3] = cvt_pk_bf16(f[6], f[7]); return r; }
; #define PG8_WAIT_V(n) asm volatile("s_waitcnt vmcnt(" #n ")" ::: "memory")
; #define PG8_BAR __builtin_amdgcn_s_barrier()
; template <class Sched, class Epi>
; __device__ __forceinline__ void gemm_phase(LAS unsigned char* lds, const Sched& S, const Epi& E, const int K, const int lda, const int ldb) {
;     ...
;         if (!has_next) break;
; #pragma unroll
;         for (int a = 0; a < 2; ++a)
; #pragma unroll
;             for (int b = 0; b < 2; ++b)
; #pragma unroll
;                 for (int m = 0; m < 4; ++m)
; #pragma unroll
;                     for (int n = 0; n < 2; ++n) acc[a][b][m][n] = (f32x4){0.f, 0.f, 0.f, 0.f};
;         cur = nxt; cA = nA; cB = nB; ++ui;
;     }
;     PG8_WAIT_V(0);
;     if (wr == 0) PG8_BAR;
;     __device__ __forceinline__ void operator()(EPI_ARGS) const {
;         const int col = u.pn * 128 + wc * 32 + 8 * fq;
; #pragma unroll
;         for (int ai = 0; ai < 2; ++ai) if (ai == 0 || !u.half) { u32x4 zz[4];
; #pragma unroll
;             for (int m = 0; m < 4; ++m) zz[m] = *(const u32x4*)(parts + E_PZB + (size_t)EPI_ROW * 1024 + col);
; #pragma unroll
;             for (int m = 0; m < 4; ++m) { float z[8]; unpack8(zz[m], z);
;                 const f32x4 a0 = acc[ai][0][m][0], a1 = acc[ai][0][m][1], b0 = acc[ai][1][m][0], b1 = acc[ai][1][m][1]; float o[8];
; #pragma unroll
;                 for (int j = 0; j < 4; ++j) { o[j] = a0[j] * z[j] * __builtin_amdgcn_rcpf((1.0f + __expf(-b0[j])) * (1.0f + __expf(-z[j]))); o[4 + j] = a1[j] * z[4 + j] * __builtin_amdgcn_rcpf((1.0f + __expf(-b1[j])) * (1.0f + __expf(-z[4 + j]))); }
;                 *(u32x4*)(O + (size_t)EPI_ROW * 1024 + col) = pack8(o); } }
	v_lshl_add_u64 v[38:39], v[38:39], 0, v[144:145]
	global_store_dwordx4 v[38:39], v[34:37], off
	v_lshlrev_b32_e32 v38, 16, v70
	v_lshlrev_b32_e32 v42, 16, v72
	v_exp_f32_e32 v34, v22
	v_mul_f32_e32 v22, 0xbfb8aa3b, v38
	v_exp_f32_e32 v35, v22
	v_exp_f32_e32 v36, v18
	v_mul_f32_e32 v18, 0xbfb8aa3b, v42
	v_exp_f32_e32 v37, v18
	v_pk_add_f32 v[34:35], v[34:35], 1.0 op_sel_hi:[1,0]
	v_mul_f32_e32 v30, v30, v38
	v_mul_f32_e32 v18, v34, v35
	v_pk_add_f32 v[34:35], v[36:37], 1.0 op_sel_hi:[1,0]
	v_rcp_f32_e32 v18, v18
	v_mul_f32_e32 v22, v34, v35
	v_rcp_f32_e32 v22, v22
	v_and_b32_e32 v39, 0xffff0000, v70
	v_mul_f32_e32 v30, v30, v18
	v_mul_f32_e32 v18, v26, v42
	v_mul_f32_e32 v26, v18, v22
	v_mul_f32_e32 v18, 0xbfb8aa3b, v23
	v_and_b32_e32 v43, 0xffff0000, v72
	v_exp_f32_e32 v22, v18
	v_mul_f32_e32 v18, 0xbfb8aa3b, v39
	v_exp_f32_e32 v23, v18
	v_mul_f32_e32 v18, 0xbfb8aa3b, v19
	v_mul_f32_e32 v19, 0xbfb8aa3b, v43
	v_exp_f32_e32 v18, v18
	v_exp_f32_e32 v19, v19
	v_pk_add_f32 v[22:23], v[22:23], 1.0 op_sel_hi:[1,0]
	v_and_b32_e32 v41, 0xffff0000, v71
	v_mul_f32_e32 v22, v22, v23
	v_pk_add_f32 v[18:19], v[18:19], 1.0 op_sel_hi:[1,0]
	v_rcp_f32_e32 v22, v22
	v_mul_f32_e32 v18, v18, v19
	v_rcp_f32_e32 v18, v18
	v_mul_f32_e32 v19, v31, v39
	v_mul_f32_e32 v31, v19, v22
	v_mul_f32_e32 v19, v27, v43
	v_mul_f32_e32 v27, v19, v18
	v_mul_f32_e32 v18, 0xbfb8aa3b, v24
	v_mul_f32_e32 v19, 0xbfb8aa3b, v40
	v_exp_f32_e32 v18, v18
	v_exp_f32_e32 v19, v19
	v_exp_f32_e32 v22, v20
	v_mul_f32_e32 v20, 0xbfb8aa3b, v44
	v_exp_f32_e32 v23, v20
	v_pk_add_f32 v[18:19], v[18:19], 1.0 op_sel_hi:[1,0]
	v_and_b32_e32 v45, 0xffff0000, v73
	v_mul_f32_e32 v18, v18, v19
	v_rcp_f32_e32 v20, v18
	v_pk_add_f32 v[18:19], v[22:23], 1.0 op_sel_hi:[1,0]
	s_nop 0
	v_mul_f32_e32 v18, v18, v19
	v_rcp_f32_e32 v18, v18
	v_mul_f32_e32 v19, v32, v40
	v_mul_f32_e32 v22, v19, v20
	v_mul_f32_e32 v19, v28, v44
	v_mul_f32_e32 v23, v19, v18
	v_mul_f32_e32 v18, 0xbfb8aa3b, v25
	v_mul_f32_e32 v19, 0xbfb8aa3b, v41
	v_exp_f32_e32 v18, v18
	v_exp_f32_e32 v19, v19
	v_mul_f32_e32 v20, 0xbfb8aa3b, v21
	v_mul_f32_e32 v21, 0xbfb8aa3b, v45
	v_exp_f32_e32 v20, v20
	v_exp_f32_e32 v21, v21
	v_pk_add_f32 v[18:19], v[18:19], 1.0 op_sel_hi:[1,0]
	v_lshlrev_b32_e32 v28, 16, v69
	v_mul_f32_e32 v18, v18, v19
	v_rcp_f32_e32 v24, v18
	v_pk_add_f32 v[18:19], v[20:21], 1.0 op_sel_hi:[1,0]
	v_mul_f32_e32 v20, v29, v45
	v_mul_f32_e32 v18, v18, v19
	v_rcp_f32_e32 v18, v18
	v_mul_f32_e32 v19, v33, v41
	v_mul_f32_e32 v19, v19, v24
	v_lshlrev_b32_e32 v24, 16, v67
	v_mul_f32_e32 v21, v20, v18
	v_cvt_pk_bf16_f32 v18, v30, v31
	v_cvt_pk_bf16_f32 v19, v22, v19
	v_cvt_pk_bf16_f32 v20, v26, v27
	v_cvt_pk_bf16_f32 v21, v23, v21
	v_lshl_add_u64 v[22:23], s[4:5], 0, v[76:77]
	v_lshl_add_u64 v[22:23], v[22:23], 0, v[144:145]
	global_store_dwordx4 v[22:23], v[18:21], off
	v_lshlrev_b32_e32 v22, 16, v66
	v_lshlrev_b32_e32 v26, 16, v68
	v_exp_f32_e32 v18, v6
	v_mul_f32_e32 v6, 0xbfb8aa3b, v22
	v_exp_f32_e32 v19, v6
	v_exp_f32_e32 v20, v2
	v_mul_f32_e32 v2, 0xbfb8aa3b, v26
	v_exp_f32_e32 v21, v2
	v_pk_add_f32 v[18:19], v[18:19], 1.0 op_sel_hi:[1,0]
	v_mul_f32_e32 v14, v14, v22
	v_mul_f32_e32 v2, v18, v19
	v_pk_add_f32 v[18:19], v[20:21], 1.0 op_sel_hi:[1,0]
	v_rcp_f32_e32 v2, v2
	v_mul_f32_e32 v6, v18, v19
	v_rcp_f32_e32 v6, v6
	v_and_b32_e32 v23, 0xffff0000, v66
	v_mul_f32_e32 v14, v14, v2
	v_mul_f32_e32 v2, v10, v26
	v_mul_f32_e32 v10, v2, v6
	v_mul_f32_e32 v2, 0xbfb8aa3b, v7
	v_and_b32_e32 v27, 0xffff0000, v68
	v_exp_f32_e32 v6, v2
	v_mul_f32_e32 v2, 0xbfb8aa3b, v23
	v_exp_f32_e32 v7, v2
	v_mul_f32_e32 v2, 0xbfb8aa3b, v3
	v_mul_f32_e32 v3, 0xbfb8aa3b, v27
	v_exp_f32_e32 v2, v2
	v_exp_f32_e32 v3, v3
	v_pk_add_f32 v[6:7], v[6:7], 1.0 op_sel_hi:[1,0]
	v_and_b32_e32 v25, 0xffff0000, v67
	v_mul_f32_e32 v6, v6, v7
	v_pk_add_f32 v[2:3], v[2:3], 1.0 op_sel_hi:[1,0]
	v_rcp_f32_e32 v6, v6
	v_mul_f32_e32 v2, v2, v3
	v_rcp_f32_e32 v2, v2
	v_mul_f32_e32 v3, v15, v23
	v_mul_f32_e32 v15, v3, v6
	v_mul_f32_e32 v3, v11, v27
	v_mul_f32_e32 v11, v3, v2
	v_mul_f32_e32 v2, 0xbfb8aa3b, v8
	v_mul_f32_e32 v3, 0xbfb8aa3b, v24
	v_exp_f32_e32 v2, v2
	v_exp_f32_e32 v3, v3
	v_exp_f32_e32 v6, v4
	v_mul_f32_e32 v4, 0xbfb8aa3b, v28
	v_exp_f32_e32 v7, v4
	v_pk_add_f32 v[2:3], v[2:3], 1.0 op_sel_hi:[1,0]
	v_and_b32_e32 v29, 0xffff0000, v69
	v_mul_f32_e32 v2, v2, v3
	v_rcp_f32_e32 v4, v2
	v_pk_add_f32 v[2:3], v[6:7], 1.0 op_sel_hi:[1,0]
	s_nop 0
	v_mul_f32_e32 v2, v2, v3
	v_rcp_f32_e32 v2, v2
	v_mul_f32_e32 v3, v16, v24
	v_mul_f32_e32 v6, v3, v4
	v_mul_f32_e32 v3, v12, v28
	v_mul_f32_e32 v7, v3, v2
	v_mul_f32_e32 v2, 0xbfb8aa3b, v9
	v_mul_f32_e32 v3, 0xbfb8aa3b, v25
	v_exp_f32_e32 v2, v2
	v_exp_f32_e32 v3, v3
	v_mul_f32_e32 v4, 0xbfb8aa3b, v5
	v_mul_f32_e32 v5, 0xbfb8aa3b, v29
	v_exp_f32_e32 v4, v4
	v_exp_f32_e32 v5, v5
	v_pk_add_f32 v[2:3], v[2:3], 1.0 op_sel_hi:[1,0]
	s_nop 0
	v_mul_f32_e32 v2, v2, v3
	v_rcp_f32_e32 v8, v2
	v_pk_add_f32 v[2:3], v[4:5], 1.0 op_sel_hi:[1,0]
	v_mul_f32_e32 v4, v13, v29
	v_mul_f32_e32 v2, v2, v3
	v_rcp_f32_e32 v2, v2
	v_mul_f32_e32 v3, v17, v25
	v_mul_f32_e32 v3, v3, v8
	v_mul_f32_e32 v5, v4, v2
	v_cvt_pk_bf16_f32 v2, v14, v15
	v_cvt_pk_bf16_f32 v3, v6, v3
	v_cvt_pk_bf16_f32 v4, v10, v11
	v_cvt_pk_bf16_f32 v5, v7, v5
	v_lshl_add_u64 v[6:7], s[4:5], 0, v[74:75]
	v_lshl_add_u64 v[6:7], v[6:7], 0, v[144:145]
	global_store_dwordx4 v[6:7], v[2:5], off
	s_cbranch_vccz .LBB0_754
	s_waitcnt vmcnt(0)
	s_cmpk_gt_u32 s2, 0xff
	s_cbranch_scc1 .LBB0_765
	s_barrier

; #define PG8_STAGE(bufoff, gbase, voff) do { _Pragma("unroll") for (int _i = 0; _i < 2; ++_i) \
;         __builtin_amdgcn_global_load_lds((const unsigned*)((const char*)(gbase) + (voff)[_i]), (LAS unsigned*)(lds + (bufoff) + ldsw + _i * 8192), 16, 0, 0); } while (0)
; #define PG8_LDA(dst, b, h) do { _Pragma("unroll") for (int m = 0; m < 4; ++m) _Pragma("unroll") for (int k = 0; k < 2; ++k) dst[m][k] = *(const LAS bf16x8*)(lds + PG8_SA(b, h) + aoff + m * 2048 + k * 1024); } while (0)
; #define PG8_LDB(dst, b, h) do { _Pragma("unroll") for (int n = 0; n < 2; ++n) _Pragma("unroll") for (int k = 0; k < 2; ++k) dst[n][k] = *(const LAS bf16x8*)(lds + PG8_SB(b, h) + boff + n * 2048 + k * 1024); } while (0)
; #define PG8_MMA(ai, bj, At, Bt) do { __builtin_amdgcn_s_setprio(1); _Pragma("unroll") for (int m = 0; m < 4; ++m) _Pragma("unroll") for (int n = 0; n < 2; ++n) _Pragma("unroll") for (int k = 0; k < 2; ++k) \
;         acc[ai][bj][m][n] = __builtin_amdgcn_mfma_f32_16x16x32_bf16(Bt[n][k], At[m][k], acc[ai][bj][m][n], 0, 0, 0); __builtin_amdgcn_s_setprio(0); } while (0)
; #define PG8_WAIT_V(n) asm volatile("s_waitcnt vmcnt(" #n ")" ::: "memory")
; #define PG8_WAIT_L(n) asm volatile("s_waitcnt lgkmcnt(" #n ")" ::: "memory")
; #define PG8_BAR __builtin_amdgcn_s_barrier()
; #define PG8_SCHED __builtin_amdgcn_sched_barrier(0)
; template <class Sched, class Epi>
; __device__ __forceinline__ void gemm_phase(LAS unsigned char* lds, const Sched& S, const Epi& E, const int K, const int lda, const int ldb) {
;     ...
;             PG8_LDB(B0, 0, 0); PG8_SCHED; PG8_LDA(At, 0, 0); PG8_STAGE(PG8_SA(1, 1), a1 + hstepA, voffA);
;             PG8_WAIT_L(8); PG8_BAR; PG8_WAIT_L(0); PG8_MMA(0, 0, At, B0); PG8_BAR; PG8_SCHED;
;             PG8_LDB(B1, 0, 1); PG8_STAGE(PG8_SB(0, 0), b2, voffB);
;             PG8_BAR; PG8_WAIT_L(0); PG8_MMA(0, 1, At, B1); PG8_BAR;
;             PG8_LDA(At, 0, 1); PG8_STAGE(PG8_SA(0, 0), a2, voffA);
;             PG8_BAR; PG8_WAIT_L(0); if (!chalf) PG8_MMA(1, 0, At, B0); PG8_BAR; PG8_SCHED;
;             PG8_STAGE(PG8_SB(0, 1), b2 + hstepB, voffB);
;             PG8_WAIT_V(6); PG8_BAR; if (!chalf) PG8_MMA(1, 1, At, B1); PG8_BAR;
.LBB0_842:
	ds_read_b128 v[130:133], v233
	ds_read_b128 v[134:137], v233 offset:1024
	ds_read_b128 v[138:141], v233 offset:2048
	ds_read_b128 v[142:145], v233 offset:3072
	s_add_u32 s28, s6, 0xfffc0080
	s_addc_u32 s29, s7, -1
	s_cmp_eq_u32 s21, 12
	s_cselect_b32 s35, s23, s29
	s_cselect_b32 s34, s22, s28
	s_cselect_b32 s29, s25, s19
	s_cselect_b32 s28, s24, s17
	s_add_i32 m0, s31, 0xc000
	ds_read_b128 v[146:149], v234
	ds_read_b128 v[150:153], v234 offset:1024
	ds_read_b128 v[154:157], v234 offset:2048
	ds_read_b128 v[158:161], v234 offset:3072
	ds_read_b128 v[162:165], v234 offset:4096
	ds_read_b128 v[166:169], v234 offset:5120
	ds_read_b128 v[170:173], v234 offset:6144
	ds_read_b128 v[174:177], v234 offset:7168
	global_load_lds_dwordx4 v208, s[6:7]
	s_add_i32 m0, s31, 0xe000
	s_nop 0
	global_load_lds_dwordx4 v206, s[6:7]
	s_waitcnt lgkmcnt(8)
	s_barrier
	s_waitcnt lgkmcnt(0)
	s_setprio 1
	s_waitcnt lgkmcnt(0)
	v_mfma_f32_16x16x32_bf16 v[126:129], v[130:133], v[146:149], v[126:129]
	v_mfma_f32_16x16x32_bf16 v[122:125], v[138:141], v[146:149], v[122:125]
	v_mfma_f32_16x16x32_bf16 v[118:121], v[130:133], v[154:157], v[118:121]
	v_mfma_f32_16x16x32_bf16 v[114:117], v[138:141], v[154:157], v[114:117]
	v_mfma_f32_16x16x32_bf16 v[110:113], v[130:133], v[162:165], v[110:113]
	v_mfma_f32_16x16x32_bf16 v[106:109], v[138:141], v[162:165], v[106:109]
	v_mfma_f32_16x16x32_bf16 v[102:105], v[130:133], v[170:173], v[102:105]
	v_mfma_f32_16x16x32_bf16 v[98:101], v[138:141], v[170:173], v[98:101]
	v_mfma_f32_16x16x32_bf16 v[126:129], v[134:137], v[150:153], v[126:129]
	v_mfma_f32_16x16x32_bf16 v[122:125], v[142:145], v[150:153], v[122:125]
	v_mfma_f32_16x16x32_bf16 v[118:121], v[134:137], v[158:161], v[118:121]
	v_mfma_f32_16x16x32_bf16 v[114:117], v[142:145], v[158:161], v[114:117]
	v_mfma_f32_16x16x32_bf16 v[110:113], v[134:137], v[166:169], v[110:113]
	v_mfma_f32_16x16x32_bf16 v[106:109], v[142:145], v[166:169], v[106:109]
	v_mfma_f32_16x16x32_bf16 v[102:105], v[134:137], v[174:177], v[102:105]
	v_mfma_f32_16x16x32_bf16 v[98:101], v[142:145], v[174:177], v[98:101]
	s_setprio 0
	s_barrier
	s_add_i32 s49, s43, s27
	s_add_u32 s52, s28, s14
	s_addc_u32 s53, s29, s15
	s_mov_b32 m0, s49
	ds_read_b128 v[178:181], v235
	ds_read_b128 v[182:185], v235 offset:1024
	ds_read_b128 v[186:189], v235 offset:2048
	ds_read_b128 v[190:193], v235 offset:3072
	global_load_lds_dwordx4 v200, s[28:29]
	s_add_u32 s54, s28, s14
	s_addc_u32 s55, s29, s15
	s_add_i32 m0, s49, 0x2000
	s_nop 0
	global_load_lds_dwordx4 v204, s[28:29]
	s_barrier
	s_waitcnt lgkmcnt(0)
	s_setprio 1
	s_waitcnt lgkmcnt(0)
	v_mfma_f32_16x16x32_bf16 v[94:97], v[178:181], v[146:149], v[94:97]
	v_mfma_f32_16x16x32_bf16 v[90:93], v[186:189], v[146:149], v[90:93]
	v_mfma_f32_16x16x32_bf16 v[86:89], v[178:181], v[154:157], v[86:89]
	v_mfma_f32_16x16x32_bf16 v[82:85], v[186:189], v[154:157], v[82:85]
	v_mfma_f32_16x16x32_bf16 v[78:81], v[178:181], v[162:165], v[78:81]
	v_mfma_f32_16x16x32_bf16 v[74:77], v[186:189], v[162:165], v[74:77]
	v_mfma_f32_16x16x32_bf16 v[70:73], v[178:181], v[170:173], v[70:73]
	v_mfma_f32_16x16x32_bf16 v[66:69], v[186:189], v[170:173], v[66:69]
	v_mfma_f32_16x16x32_bf16 v[94:97], v[182:185], v[150:153], v[94:97]
	v_mfma_f32_16x16x32_bf16 v[90:93], v[190:193], v[150:153], v[90:93]
	v_mfma_f32_16x16x32_bf16 v[86:89], v[182:185], v[158:161], v[86:89]
	v_mfma_f32_16x16x32_bf16 v[82:85], v[190:193], v[158:161], v[82:85]
	v_mfma_f32_16x16x32_bf16 v[78:81], v[182:185], v[166:169], v[78:81]
	v_mfma_f32_16x16x32_bf16 v[74:77], v[190:193], v[166:169], v[74:77]
	v_mfma_f32_16x16x32_bf16 v[70:73], v[182:185], v[174:177], v[70:73]
	v_mfma_f32_16x16x32_bf16 v[66:69], v[190:193], v[174:177], v[66:69]
	s_setprio 0
	s_mov_b32 m0, s31
	s_add_u32 s56, s34, s14
	s_addc_u32 s57, s35, s15
	s_barrier
	ds_read_b128 v[146:149], v234 offset:16384
	ds_read_b128 v[150:153], v234 offset:17408
	ds_read_b128 v[154:157], v234 offset:18432
	ds_read_b128 v[158:161], v234 offset:19456
	ds_read_b128 v[162:165], v234 offset:20480
	ds_read_b128 v[166:169], v234 offset:21504
	ds_read_b128 v[170:173], v234 offset:22528
	ds_read_b128 v[174:177], v234 offset:23552
	global_load_lds_dwordx4 v198, s[34:35]
	s_add_u32 s58, s34, s14
	s_addc_u32 s59, s35, s15
	s_mov_b32 m0, s33
	s_nop 0
	global_load_lds_dwordx4 v202, s[34:35]
	s_barrier
	s_waitcnt lgkmcnt(0)
	s_setprio 1
	s_waitcnt lgkmcnt(0)
	v_mfma_f32_16x16x32_bf16 v[62:65], v[130:133], v[146:149], v[62:65]
	v_mfma_f32_16x16x32_bf16 v[58:61], v[138:141], v[146:149], v[58:61]
	v_mfma_f32_16x16x32_bf16 v[54:57], v[130:133], v[154:157], v[54:57]
	v_mfma_f32_16x16x32_bf16 v[50:53], v[138:141], v[154:157], v[50:53]
	v_mfma_f32_16x16x32_bf16 v[46:49], v[130:133], v[162:165], v[46:49]
	v_mfma_f32_16x16x32_bf16 v[42:45], v[138:141], v[162:165], v[42:45]
	v_mfma_f32_16x16x32_bf16 v[38:41], v[130:133], v[170:173], v[38:41]
	v_mfma_f32_16x16x32_bf16 v[34:37], v[138:141], v[170:173], v[34:37]
	v_mfma_f32_16x16x32_bf16 v[62:65], v[134:137], v[150:153], v[62:65]
	v_mfma_f32_16x16x32_bf16 v[58:61], v[142:145], v[150:153], v[58:61]
	v_mfma_f32_16x16x32_bf16 v[54:57], v[134:137], v[158:161], v[54:57]
	v_mfma_f32_16x16x32_bf16 v[50:53], v[142:145], v[158:161], v[50:53]
	v_mfma_f32_16x16x32_bf16 v[46:49], v[134:137], v[166:169], v[46:49]
	v_mfma_f32_16x16x32_bf16 v[42:45], v[142:145], v[166:169], v[42:45]
	v_mfma_f32_16x16x32_bf16 v[38:41], v[134:137], v[174:177], v[38:41]
	v_mfma_f32_16x16x32_bf16 v[34:37], v[142:145], v[174:177], v[34:37]
	s_setprio 0
	s_barrier
	s_add_u32 s50, s28, 0x40000
	s_addc_u32 s51, s29, 0
	s_add_i32 s49, s44, s27
	s_mov_b32 m0, s49
	s_nop 0
	global_load_lds_dwordx4 v200, s[50:51]
	s_add_i32 m0, s49, 0x2000
	s_nop 0
	global_load_lds_dwordx4 v204, s[50:51]
	s_waitcnt vmcnt(6)
	s_barrier
; #define PG8_STAGE(bufoff, gbase, voff) do { _Pragma("unroll") for (int _i = 0; _i < 2; ++_i) \
;         __builtin_amdgcn_global_load_lds((const unsigned*)((const char*)(gbase) + (voff)[_i]), (LAS unsigned*)(lds + (bufoff) + ldsw + _i * 8192), 16, 0, 0); } while (0)
; #define PG8_LDA(dst, b, h) do { _Pragma("unroll") for (int m = 0; m < 4; ++m) _Pragma("unroll") for (int k = 0; k < 2; ++k) dst[m][k] = *(const LAS bf16x8*)(lds + PG8_SA(b, h) + aoff + m * 2048 + k * 1024); } while (0)
; #define PG8_LDB(dst, b, h) do { _Pragma("unroll") for (int n = 0; n < 2; ++n) _Pragma("unroll") for (int k = 0; k < 2; ++k) dst[n][k] = *(const LAS bf16x8*)(lds + PG8_SB(b, h) + boff + n * 2048 + k * 1024); } while (0)
; #define PG8_MMA(ai, bj, At, Bt) do { __builtin_amdgcn_s_setprio(1); _Pragma("unroll") for (int m = 0; m < 4; ++m) _Pragma("unroll") for (int n = 0; n < 2; ++n) _Pragma("unroll") for (int k = 0; k < 2; ++k) \
;         acc[ai][bj][m][n] = __builtin_amdgcn_mfma_f32_16x16x32_bf16(Bt[n][k], At[m][k], acc[ai][bj][m][n], 0, 0, 0); __builtin_amdgcn_s_setprio(0); } while (0)
; #define PG8_WAIT_V(n) asm volatile("s_waitcnt vmcnt(" #n ")" ::: "memory")
; #define PG8_WAIT_L(n) asm volatile("s_waitcnt lgkmcnt(" #n ")" ::: "memory")
; #define PG8_BAR __builtin_amdgcn_s_barrier()
; #define PG8_SCHED __builtin_amdgcn_sched_barrier(0)
; template <class Sched, class Epi>
; __device__ __forceinline__ void gemm_phase(LAS unsigned char* lds, const Sched& S, const Epi& E, const int K, const int lda, const int ldb) {
;     ...
;             PG8_WAIT_V(6); PG8_BAR; if (!chalf) PG8_MMA(1, 1, At, B1); PG8_BAR;
;             PG8_LDB(B0, 1, 0); PG8_SCHED; PG8_LDA(At, 1, 0); PG8_STAGE(PG8_SA(0, 1), a2 + hstepA, voffA);
;             PG8_WAIT_L(8); PG8_BAR; PG8_WAIT_L(0); PG8_MMA(0, 0, At, B0); PG8_BAR; PG8_SCHED;
;             PG8_LDB(B1, 1, 1); PG8_STAGE(PG8_SB(1, 0), b3, voffB);
;             PG8_BAR; PG8_WAIT_L(0); PG8_MMA(0, 1, At, B1); PG8_BAR;
;             PG8_LDA(At, 1, 1); PG8_STAGE(PG8_SA(1, 0), a3, voffA);
	s_setprio 1
	v_mfma_f32_16x16x32_bf16 v[30:33], v[178:181], v[146:149], v[30:33]
	v_mfma_f32_16x16x32_bf16 v[26:29], v[186:189], v[146:149], v[26:29]
	v_mfma_f32_16x16x32_bf16 v[22:25], v[178:181], v[154:157], v[22:25]
	v_mfma_f32_16x16x32_bf16 v[18:21], v[186:189], v[154:157], v[18:21]
	v_mfma_f32_16x16x32_bf16 v[14:17], v[178:181], v[162:165], v[14:17]
	v_mfma_f32_16x16x32_bf16 v[10:13], v[186:189], v[162:165], v[10:13]
	v_mfma_f32_16x16x32_bf16 v[6:9], v[178:181], v[170:173], v[6:9]
	v_mfma_f32_16x16x32_bf16 v[2:5], v[186:189], v[170:173], v[2:5]
	v_mfma_f32_16x16x32_bf16 v[30:33], v[182:185], v[150:153], v[30:33]
	v_mfma_f32_16x16x32_bf16 v[26:29], v[190:193], v[150:153], v[26:29]
	v_mfma_f32_16x16x32_bf16 v[22:25], v[182:185], v[158:161], v[22:25]
	v_mfma_f32_16x16x32_bf16 v[18:21], v[190:193], v[158:161], v[18:21]
	v_mfma_f32_16x16x32_bf16 v[14:17], v[182:185], v[166:169], v[14:17]
	v_mfma_f32_16x16x32_bf16 v[10:13], v[190:193], v[166:169], v[10:13]
	v_mfma_f32_16x16x32_bf16 v[6:9], v[182:185], v[174:177], v[6:9]
	v_mfma_f32_16x16x32_bf16 v[2:5], v[190:193], v[174:177], v[2:5]
	s_setprio 0
	s_add_i32 s49, 16, 0x18000
	v_add_u32_e32 v142, s49, v224
	s_barrier
	ds_read_b128 v[130:133], v142
	ds_read_b128 v[134:137], v142 offset:1024
	ds_read_b128 v[138:141], v142 offset:2048
	ds_read_b128 v[142:145], v142 offset:3072
	s_add_u32 s34, s34, 0x40000
	s_addc_u32 s35, s35, 0
	s_mov_b32 m0, s36
	ds_read_b128 v[146:149], v234 offset:32768
	ds_read_b128 v[150:153], v234 offset:33792
	ds_read_b128 v[154:157], v234 offset:34816
	ds_read_b128 v[158:161], v234 offset:35840
	ds_read_b128 v[162:165], v234 offset:36864
	ds_read_b128 v[166:169], v234 offset:37888
	ds_read_b128 v[170:173], v234 offset:38912
	ds_read_b128 v[174:177], v234 offset:39936
	global_load_lds_dwordx4 v198, s[34:35]
	s_mov_b32 m0, s37
	s_nop 0
	global_load_lds_dwordx4 v202, s[34:35]
	s_waitcnt lgkmcnt(8)
	s_barrier
	s_waitcnt lgkmcnt(0)
	s_setprio 1
	s_waitcnt lgkmcnt(0)
	v_mfma_f32_16x16x32_bf16 v[126:129], v[130:133], v[146:149], v[126:129]
	v_mfma_f32_16x16x32_bf16 v[122:125], v[138:141], v[146:149], v[122:125]
	v_mfma_f32_16x16x32_bf16 v[118:121], v[130:133], v[154:157], v[118:121]
	v_mfma_f32_16x16x32_bf16 v[114:117], v[138:141], v[154:157], v[114:117]
	v_mfma_f32_16x16x32_bf16 v[110:113], v[130:133], v[162:165], v[110:113]
	v_mfma_f32_16x16x32_bf16 v[106:109], v[138:141], v[162:165], v[106:109]
	v_mfma_f32_16x16x32_bf16 v[102:105], v[130:133], v[170:173], v[102:105]
	v_mfma_f32_16x16x32_bf16 v[98:101], v[138:141], v[170:173], v[98:101]
	v_mfma_f32_16x16x32_bf16 v[126:129], v[134:137], v[150:153], v[126:129]
	v_mfma_f32_16x16x32_bf16 v[122:125], v[142:145], v[150:153], v[122:125]
	v_mfma_f32_16x16x32_bf16 v[118:121], v[134:137], v[158:161], v[118:121]
	v_mfma_f32_16x16x32_bf16 v[114:117], v[142:145], v[158:161], v[114:117]
	v_mfma_f32_16x16x32_bf16 v[110:113], v[134:137], v[166:169], v[110:113]
	v_mfma_f32_16x16x32_bf16 v[106:109], v[142:145], v[166:169], v[106:109]
	v_mfma_f32_16x16x32_bf16 v[102:105], v[134:137], v[174:177], v[102:105]
	v_mfma_f32_16x16x32_bf16 v[98:101], v[142:145], v[174:177], v[98:101]
	s_setprio 0
	s_barrier
	s_add_i32 s34, 16, 0x1c000
	s_add_i32 s35, s49, s27
	v_add_u32_e32 v190, s34, v224
	s_mov_b32 m0, s35
	ds_read_b128 v[178:181], v190
	ds_read_b128 v[182:185], v190 offset:1024
	ds_read_b128 v[186:189], v190 offset:2048
	ds_read_b128 v[190:193], v190 offset:3072
	global_load_lds_dwordx4 v200, s[52:53]
	s_add_i32 m0, s35, 0x2000
	s_nop 0
	global_load_lds_dwordx4 v204, s[54:55]
	s_barrier
	s_waitcnt lgkmcnt(0)
	s_setprio 1
	s_waitcnt lgkmcnt(0)
	v_mfma_f32_16x16x32_bf16 v[94:97], v[178:181], v[146:149], v[94:97]
	v_mfma_f32_16x16x32_bf16 v[90:93], v[186:189], v[146:149], v[90:93]
	v_mfma_f32_16x16x32_bf16 v[86:89], v[178:181], v[154:157], v[86:89]
	v_mfma_f32_16x16x32_bf16 v[82:85], v[186:189], v[154:157], v[82:85]
	v_mfma_f32_16x16x32_bf16 v[78:81], v[178:181], v[162:165], v[78:81]
	v_mfma_f32_16x16x32_bf16 v[74:77], v[186:189], v[162:165], v[74:77]
	v_mfma_f32_16x16x32_bf16 v[70:73], v[178:181], v[170:173], v[70:73]
	v_mfma_f32_16x16x32_bf16 v[66:69], v[186:189], v[170:173], v[66:69]
	v_mfma_f32_16x16x32_bf16 v[94:97], v[182:185], v[150:153], v[94:97]
	v_mfma_f32_16x16x32_bf16 v[90:93], v[190:193], v[150:153], v[90:93]
	v_mfma_f32_16x16x32_bf16 v[86:89], v[182:185], v[158:161], v[86:89]
	v_mfma_f32_16x16x32_bf16 v[82:85], v[190:193], v[158:161], v[82:85]
	v_mfma_f32_16x16x32_bf16 v[78:81], v[182:185], v[166:169], v[78:81]
	v_mfma_f32_16x16x32_bf16 v[74:77], v[190:193], v[166:169], v[74:77]
	v_mfma_f32_16x16x32_bf16 v[70:73], v[182:185], v[174:177], v[70:73]
	v_mfma_f32_16x16x32_bf16 v[66:69], v[190:193], v[174:177], v[66:69]
	s_setprio 0
	s_mov_b32 m0, s39
	s_barrier
; #define PG8_STAGE(bufoff, gbase, voff) do { _Pragma("unroll") for (int _i = 0; _i < 2; ++_i) \
;         __builtin_amdgcn_global_load_lds((const unsigned*)((const char*)(gbase) + (voff)[_i]), (LAS unsigned*)(lds + (bufoff) + ldsw + _i * 8192), 16, 0, 0); } while (0)
; #define PG8_LDA(dst, b, h) do { _Pragma("unroll") for (int m = 0; m < 4; ++m) _Pragma("unroll") for (int k = 0; k < 2; ++k) dst[m][k] = *(const LAS bf16x8*)(lds + PG8_SA(b, h) + aoff + m * 2048 + k * 1024); } while (0)
; #define PG8_MMA(ai, bj, At, Bt) do { __builtin_amdgcn_s_setprio(1); _Pragma("unroll") for (int m = 0; m < 4; ++m) _Pragma("unroll") for (int n = 0; n < 2; ++n) _Pragma("unroll") for (int k = 0; k < 2; ++k) \
;         acc[ai][bj][m][n] = __builtin_amdgcn_mfma_f32_16x16x32_bf16(Bt[n][k], At[m][k], acc[ai][bj][m][n], 0, 0, 0); __builtin_amdgcn_s_setprio(0); } while (0)
; #define PG8_WAIT_V(n) asm volatile("s_waitcnt vmcnt(" #n ")" ::: "memory")
; #define PG8_WAIT_L(n) asm volatile("s_waitcnt lgkmcnt(" #n ")" ::: "memory")
; #define PG8_BAR __builtin_amdgcn_s_barrier()
; #define PG8_SCHED __builtin_amdgcn_sched_barrier(0)
; template <class Sched, class Epi>
; __device__ __forceinline__ void gemm_phase(LAS unsigned char* lds, const Sched& S, const Epi& E, const int K, const int lda, const int ldb) {
;     ...
;             PG8_LDA(At, 1, 1); PG8_STAGE(PG8_SA(1, 0), a3, voffA);
;             PG8_BAR; PG8_WAIT_L(0); if (!chalf) PG8_MMA(1, 0, At, B0); PG8_BAR; PG8_SCHED;
;             PG8_STAGE(PG8_SB(1, 1), b3 + hstepB, voffB);
;             PG8_WAIT_V(6); PG8_BAR; if (!chalf) PG8_MMA(1, 1, At, B1); PG8_BAR;
;         }
;         E(acc, cur, wr, wc, fr, fq);
	ds_read_b128 v[146:149], v234 offset:49152
	ds_read_b128 v[150:153], v234 offset:50176
	ds_read_b128 v[154:157], v234 offset:51200
	ds_read_b128 v[158:161], v234 offset:52224
	ds_read_b128 v[162:165], v234 offset:53248
	ds_read_b128 v[166:169], v234 offset:54272
	ds_read_b128 v[170:173], v234 offset:55296
	ds_read_b128 v[174:177], v234 offset:56320
	global_load_lds_dwordx4 v198, s[56:57]
	s_mov_b32 m0, s40
	s_nop 0
	global_load_lds_dwordx4 v202, s[58:59]
	s_barrier
	s_waitcnt lgkmcnt(0)
	s_setprio 1
	s_waitcnt lgkmcnt(0)
	v_mfma_f32_16x16x32_bf16 v[62:65], v[130:133], v[146:149], v[62:65]
	v_mfma_f32_16x16x32_bf16 v[58:61], v[138:141], v[146:149], v[58:61]
	v_mfma_f32_16x16x32_bf16 v[54:57], v[130:133], v[154:157], v[54:57]
	v_mfma_f32_16x16x32_bf16 v[50:53], v[138:141], v[154:157], v[50:53]
	v_mfma_f32_16x16x32_bf16 v[46:49], v[130:133], v[162:165], v[46:49]
	v_mfma_f32_16x16x32_bf16 v[42:45], v[138:141], v[162:165], v[42:45]
	v_mfma_f32_16x16x32_bf16 v[38:41], v[130:133], v[170:173], v[38:41]
	v_mfma_f32_16x16x32_bf16 v[34:37], v[138:141], v[170:173], v[34:37]
	v_mfma_f32_16x16x32_bf16 v[62:65], v[134:137], v[150:153], v[62:65]
	v_mfma_f32_16x16x32_bf16 v[58:61], v[142:145], v[150:153], v[58:61]
	v_mfma_f32_16x16x32_bf16 v[54:57], v[134:137], v[158:161], v[54:57]
	v_mfma_f32_16x16x32_bf16 v[50:53], v[142:145], v[158:161], v[50:53]
	v_mfma_f32_16x16x32_bf16 v[46:49], v[134:137], v[166:169], v[46:49]
	v_mfma_f32_16x16x32_bf16 v[42:45], v[142:145], v[166:169], v[42:45]
	v_mfma_f32_16x16x32_bf16 v[38:41], v[134:137], v[174:177], v[38:41]
	v_mfma_f32_16x16x32_bf16 v[34:37], v[142:145], v[174:177], v[34:37]
	s_setprio 0
	s_barrier
	s_add_u32 s28, s28, 0x40080
	s_addc_u32 s29, s29, 0
	s_add_i32 s34, s34, s27
	s_mov_b32 m0, s34
	s_nop 0
	global_load_lds_dwordx4 v200, s[28:29]
	s_add_i32 m0, s34, 0x2000
	s_nop 0
	global_load_lds_dwordx4 v204, s[28:29]
	s_waitcnt vmcnt(6)
	s_barrier
	s_setprio 1
	v_mfma_f32_16x16x32_bf16 v[30:33], v[178:181], v[146:149], v[30:33]
	v_mfma_f32_16x16x32_bf16 v[26:29], v[186:189], v[146:149], v[26:29]
	v_mfma_f32_16x16x32_bf16 v[22:25], v[178:181], v[154:157], v[22:25]
	v_mfma_f32_16x16x32_bf16 v[18:21], v[186:189], v[154:157], v[18:21]
	v_mfma_f32_16x16x32_bf16 v[14:17], v[178:181], v[162:165], v[14:17]
	v_mfma_f32_16x16x32_bf16 v[10:13], v[186:189], v[162:165], v[10:13]
	v_mfma_f32_16x16x32_bf16 v[6:9], v[178:181], v[170:173], v[6:9]
	v_mfma_f32_16x16x32_bf16 v[2:5], v[186:189], v[170:173], v[2:5]
	v_mfma_f32_16x16x32_bf16 v[30:33], v[182:185], v[150:153], v[30:33]
	v_mfma_f32_16x16x32_bf16 v[26:29], v[190:193], v[150:153], v[26:29]
	v_mfma_f32_16x16x32_bf16 v[22:25], v[182:185], v[158:161], v[22:25]
	v_mfma_f32_16x16x32_bf16 v[18:21], v[190:193], v[158:161], v[18:21]
	v_mfma_f32_16x16x32_bf16 v[14:17], v[182:185], v[166:169], v[14:17]
	v_mfma_f32_16x16x32_bf16 v[10:13], v[190:193], v[166:169], v[10:13]
	v_mfma_f32_16x16x32_bf16 v[6:9], v[182:185], v[174:177], v[6:9]
	v_mfma_f32_16x16x32_bf16 v[2:5], v[190:193], v[174:177], v[2:5]
	s_setprio 0
	s_add_i32 s21, s21, 2
	s_add_u32 s17, s17, 0x100
	s_addc_u32 s19, s19, 0
	s_add_u32 s6, s6, 0x100
	s_addc_u32 s7, s7, 0
	s_cmp_gt_u32 s21, 13
	s_barrier
	s_cbranch_scc0 .LBB0_842
	s_lshl_b32 s6, s48, 11
	s_ashr_i32 s7, s6, 31
	s_lshl_b64 s[28:29], s[6:7], 1
	v_lshl_or_b32 v134, s47, 8, v232
	s_add_u32 s6, s41, s28
	v_ashrrev_i32_e32 v135, 31, v134
	s_addc_u32 s7, s42, s29
	v_lshlrev_b64 v[212:213], 1, v[134:135]
	v_add_u32_e32 v130, s26, v1
	v_lshl_add_u64 v[216:217], s[6:7], 0, v[212:213]
	v_mad_i64_i32 v[132:133], s[6:7], v130, s45, v[216:217]
	global_load_dwordx4 v[194:197], v[132:133], off
	v_ashrrev_i32_e32 v131, 31, v130
	s_cmp_gt_i32 s48, 0
	v_lshl_add_u64 v[218:219], s[12:13], 0, v[212:213]
	v_lshlrev_b64 v[132:133], 12, v[130:131]
	s_cselect_b64 s[34:35], -1, 0
	s_cmp_lt_i32 s48, 1
	v_lshl_add_u64 v[136:137], v[218:219], 0, v[132:133]
	s_cbranch_scc1 .LBB0_845
	global_load_dwordx4 v[190:193], v[136:137], off
	s_branch .LBB0_846

; #define PG8_STAGE(bufoff, gbase, voff) do { _Pragma("unroll") for (int _i = 0; _i < 2; ++_i) \
;         __builtin_amdgcn_global_load_lds((const unsigned*)((const char*)(gbase) + (voff)[_i]), (LAS unsigned*)(lds + (bufoff) + ldsw + _i * 8192), 16, 0, 0); } while (0)
; #define PG8_LDA(dst, b, h) do { _Pragma("unroll") for (int m = 0; m < 4; ++m) _Pragma("unroll") for (int k = 0; k < 2; ++k) dst[m][k] = *(const LAS bf16x8*)(lds + PG8_SA(b, h) + aoff + m * 2048 + k * 1024); } while (0)
; #define PG8_LDB(dst, b, h) do { _Pragma("unroll") for (int n = 0; n < 2; ++n) _Pragma("unroll") for (int k = 0; k < 2; ++k) dst[n][k] = *(const LAS bf16x8*)(lds + PG8_SB(b, h) + boff + n * 2048 + k * 1024); } while (0)
; #define PG8_MMA(ai, bj, At, Bt) do { __builtin_amdgcn_s_setprio(1); _Pragma("unroll") for (int m = 0; m < 4; ++m) _Pragma("unroll") for (int n = 0; n < 2; ++n) _Pragma("unroll") for (int k = 0; k < 2; ++k) \
;         acc[ai][bj][m][n] = __builtin_amdgcn_mfma_f32_16x16x32_bf16(Bt[n][k], At[m][k], acc[ai][bj][m][n], 0, 0, 0); __builtin_amdgcn_s_setprio(0); } while (0)
; #define PG8_WAIT_V(n) asm volatile("s_waitcnt vmcnt(" #n ")" ::: "memory")
; #define PG8_WAIT_L(n) asm volatile("s_waitcnt lgkmcnt(" #n ")" ::: "memory")
; #define PG8_BAR __builtin_amdgcn_s_barrier()
; #define PG8_SCHED __builtin_amdgcn_sched_barrier(0)
; template <class Sched, class Epi>
; __device__ __forceinline__ void gemm_phase(LAS unsigned char* lds, const Sched& S, const Epi& E, const int K, const int lda, const int ldb) {
;     ...
;             PG8_LDB(B0, 0, 0); PG8_SCHED; PG8_LDA(At, 0, 0); PG8_STAGE(PG8_SA(1, 1), a1 + hstepA, voffA);
;             PG8_WAIT_L(8); PG8_BAR; PG8_WAIT_L(0); PG8_MMA(0, 0, At, B0); PG8_BAR; PG8_SCHED;
;             PG8_LDB(B1, 0, 1); PG8_STAGE(PG8_SB(0, 0), b2, voffB);
;             PG8_BAR; PG8_WAIT_L(0); PG8_MMA(0, 1, At, B1); PG8_BAR;
;             PG8_LDA(At, 0, 1); PG8_STAGE(PG8_SA(0, 0), a2, voffA);
;             PG8_BAR; PG8_WAIT_L(0); if (!chalf) PG8_MMA(1, 0, At, B0); PG8_BAR; PG8_SCHED;
;             PG8_STAGE(PG8_SB(0, 1), b2 + hstepB, voffB);
;             PG8_WAIT_V(6); PG8_BAR; if (!chalf) PG8_MMA(1, 1, At, B1); PG8_BAR;
.LBB0_957:
	ds_read_b128 v[156:159], v153
	ds_read_b128 v[160:163], v153 offset:1024
	ds_read_b128 v[164:167], v153 offset:2048
	ds_read_b128 v[168:171], v153 offset:3072
	s_add_u32 s28, s26, 0xfff80080
	s_addc_u32 s29, s27, -1
	s_cmp_eq_u32 s46, 28
	s_cselect_b32 s35, s23, s29
	s_cselect_b32 s34, s22, s28
	s_cselect_b32 s29, s25, s17
	s_cselect_b32 s28, s24, s15
	s_add_i32 m0, s5, 0xc000
	ds_read_b128 v[172:175], v154
	ds_read_b128 v[176:179], v154 offset:1024
	ds_read_b128 v[180:183], v154 offset:2048
	ds_read_b128 v[184:187], v154 offset:3072
	ds_read_b128 v[188:191], v154 offset:4096
	ds_read_b128 v[192:195], v154 offset:5120
	ds_read_b128 v[196:199], v154 offset:6144
	ds_read_b128 v[200:203], v154 offset:7168
	global_load_lds_dwordx4 v140, s[26:27]
	s_add_i32 m0, s5, 0xe000
	s_nop 0
	global_load_lds_dwordx4 v138, s[26:27]
	s_waitcnt lgkmcnt(8)
	s_barrier
	s_waitcnt lgkmcnt(0)
	s_setprio 1
	s_waitcnt lgkmcnt(0)
	v_mfma_f32_16x16x32_bf16 v[126:129], v[156:159], v[172:175], v[126:129]
	v_mfma_f32_16x16x32_bf16 v[122:125], v[164:167], v[172:175], v[122:125]
	v_mfma_f32_16x16x32_bf16 v[114:117], v[156:159], v[180:183], v[114:117]
	v_mfma_f32_16x16x32_bf16 v[106:109], v[164:167], v[180:183], v[106:109]
	v_mfma_f32_16x16x32_bf16 v[98:101], v[156:159], v[188:191], v[98:101]
	v_mfma_f32_16x16x32_bf16 v[90:93], v[164:167], v[188:191], v[90:93]
	v_mfma_f32_16x16x32_bf16 v[82:85], v[156:159], v[196:199], v[82:85]
	v_mfma_f32_16x16x32_bf16 v[74:77], v[164:167], v[196:199], v[74:77]
	v_mfma_f32_16x16x32_bf16 v[126:129], v[160:163], v[176:179], v[126:129]
	v_mfma_f32_16x16x32_bf16 v[122:125], v[168:171], v[176:179], v[122:125]
	v_mfma_f32_16x16x32_bf16 v[114:117], v[160:163], v[184:187], v[114:117]
	v_mfma_f32_16x16x32_bf16 v[106:109], v[168:171], v[184:187], v[106:109]
	v_mfma_f32_16x16x32_bf16 v[98:101], v[160:163], v[192:195], v[98:101]
	v_mfma_f32_16x16x32_bf16 v[90:93], v[168:171], v[192:195], v[90:93]
	v_mfma_f32_16x16x32_bf16 v[82:85], v[160:163], v[200:203], v[82:85]
	v_mfma_f32_16x16x32_bf16 v[74:77], v[168:171], v[200:203], v[74:77]
	s_setprio 0
	s_barrier
	s_add_i32 s47, s43, s33
	s_add_u32 s52, s28, s8
	s_addc_u32 s53, s29, s9
	s_mov_b32 m0, s47
	ds_read_b128 v[204:207], v155
	ds_read_b128 v[208:211], v155 offset:1024
	ds_read_b128 v[212:215], v155 offset:2048
	ds_read_b128 v[216:219], v155 offset:3072
	global_load_lds_dwordx4 v132, s[28:29]
	s_add_u32 s54, s28, s8
	s_addc_u32 s55, s29, s9
	s_add_i32 m0, s47, 0x2000
	s_nop 0
	global_load_lds_dwordx4 v136, s[28:29]
	s_barrier
	s_waitcnt lgkmcnt(0)
	s_setprio 1
	s_waitcnt lgkmcnt(0)
	v_mfma_f32_16x16x32_bf16 v[118:121], v[204:207], v[172:175], v[118:121]
	v_mfma_f32_16x16x32_bf16 v[110:113], v[212:215], v[172:175], v[110:113]
	v_mfma_f32_16x16x32_bf16 v[102:105], v[204:207], v[180:183], v[102:105]
	v_mfma_f32_16x16x32_bf16 v[94:97], v[212:215], v[180:183], v[94:97]
	v_mfma_f32_16x16x32_bf16 v[86:89], v[204:207], v[188:191], v[86:89]
	v_mfma_f32_16x16x32_bf16 v[78:81], v[212:215], v[188:191], v[78:81]
	v_mfma_f32_16x16x32_bf16 v[70:73], v[204:207], v[196:199], v[70:73]
	v_mfma_f32_16x16x32_bf16 v[66:69], v[212:215], v[196:199], v[66:69]
	v_mfma_f32_16x16x32_bf16 v[118:121], v[208:211], v[176:179], v[118:121]
	v_mfma_f32_16x16x32_bf16 v[110:113], v[216:219], v[176:179], v[110:113]
	v_mfma_f32_16x16x32_bf16 v[102:105], v[208:211], v[184:187], v[102:105]
	v_mfma_f32_16x16x32_bf16 v[94:97], v[216:219], v[184:187], v[94:97]
	v_mfma_f32_16x16x32_bf16 v[86:89], v[208:211], v[192:195], v[86:89]
	v_mfma_f32_16x16x32_bf16 v[78:81], v[216:219], v[192:195], v[78:81]
	v_mfma_f32_16x16x32_bf16 v[70:73], v[208:211], v[200:203], v[70:73]
	v_mfma_f32_16x16x32_bf16 v[66:69], v[216:219], v[200:203], v[66:69]
	s_setprio 0
	s_mov_b32 m0, s5
	s_add_u32 s56, s34, s8
	s_addc_u32 s57, s35, s9
	s_barrier
	ds_read_b128 v[172:175], v154 offset:16384
	ds_read_b128 v[176:179], v154 offset:17408
	ds_read_b128 v[180:183], v154 offset:18432
	ds_read_b128 v[184:187], v154 offset:19456
	ds_read_b128 v[188:191], v154 offset:20480
	ds_read_b128 v[192:195], v154 offset:21504
	ds_read_b128 v[196:199], v154 offset:22528
	ds_read_b128 v[200:203], v154 offset:23552
	global_load_lds_dwordx4 v130, s[34:35]
	s_add_u32 s58, s34, s8
	s_addc_u32 s59, s35, s9
	s_mov_b32 m0, s36
	s_nop 0
	global_load_lds_dwordx4 v134, s[34:35]
	s_barrier
	s_waitcnt lgkmcnt(0)
	s_setprio 1
	s_waitcnt lgkmcnt(0)
	v_mfma_f32_16x16x32_bf16 v[62:65], v[156:159], v[172:175], v[62:65]
	v_mfma_f32_16x16x32_bf16 v[58:61], v[164:167], v[172:175], v[58:61]
	v_mfma_f32_16x16x32_bf16 v[54:57], v[156:159], v[180:183], v[54:57]
	v_mfma_f32_16x16x32_bf16 v[46:49], v[164:167], v[180:183], v[46:49]
	v_mfma_f32_16x16x32_bf16 v[38:41], v[156:159], v[188:191], v[38:41]
	v_mfma_f32_16x16x32_bf16 v[30:33], v[164:167], v[188:191], v[30:33]
	v_mfma_f32_16x16x32_bf16 v[22:25], v[156:159], v[196:199], v[22:25]
	v_mfma_f32_16x16x32_bf16 v[14:17], v[164:167], v[196:199], v[14:17]
	v_mfma_f32_16x16x32_bf16 v[62:65], v[160:163], v[176:179], v[62:65]
	v_mfma_f32_16x16x32_bf16 v[58:61], v[168:171], v[176:179], v[58:61]
	v_mfma_f32_16x16x32_bf16 v[54:57], v[160:163], v[184:187], v[54:57]
	v_mfma_f32_16x16x32_bf16 v[46:49], v[168:171], v[184:187], v[46:49]
	v_mfma_f32_16x16x32_bf16 v[38:41], v[160:163], v[192:195], v[38:41]
	v_mfma_f32_16x16x32_bf16 v[30:33], v[168:171], v[192:195], v[30:33]
	v_mfma_f32_16x16x32_bf16 v[22:25], v[160:163], v[200:203], v[22:25]
	v_mfma_f32_16x16x32_bf16 v[14:17], v[168:171], v[200:203], v[14:17]
	s_setprio 0
	s_barrier
	s_add_u32 s48, s28, 0x80000
	s_addc_u32 s49, s29, 0
	s_add_i32 s47, s44, s33
	s_mov_b32 m0, s47
	s_nop 0
	global_load_lds_dwordx4 v132, s[48:49]
	s_add_i32 m0, s47, 0x2000
	s_nop 0
	global_load_lds_dwordx4 v136, s[48:49]
	s_waitcnt vmcnt(6)
	s_barrier
; #define PG8_STAGE(bufoff, gbase, voff) do { _Pragma("unroll") for (int _i = 0; _i < 2; ++_i) \
;         __builtin_amdgcn_global_load_lds((const unsigned*)((const char*)(gbase) + (voff)[_i]), (LAS unsigned*)(lds + (bufoff) + ldsw + _i * 8192), 16, 0, 0); } while (0)
; #define PG8_LDA(dst, b, h) do { _Pragma("unroll") for (int m = 0; m < 4; ++m) _Pragma("unroll") for (int k = 0; k < 2; ++k) dst[m][k] = *(const LAS bf16x8*)(lds + PG8_SA(b, h) + aoff + m * 2048 + k * 1024); } while (0)
; #define PG8_LDB(dst, b, h) do { _Pragma("unroll") for (int n = 0; n < 2; ++n) _Pragma("unroll") for (int k = 0; k < 2; ++k) dst[n][k] = *(const LAS bf16x8*)(lds + PG8_SB(b, h) + boff + n * 2048 + k * 1024); } while (0)
; #define PG8_MMA(ai, bj, At, Bt) do { __builtin_amdgcn_s_setprio(1); _Pragma("unroll") for (int m = 0; m < 4; ++m) _Pragma("unroll") for (int n = 0; n < 2; ++n) _Pragma("unroll") for (int k = 0; k < 2; ++k) \
;         acc[ai][bj][m][n] = __builtin_amdgcn_mfma_f32_16x16x32_bf16(Bt[n][k], At[m][k], acc[ai][bj][m][n], 0, 0, 0); __builtin_amdgcn_s_setprio(0); } while (0)
; #define PG8_WAIT_V(n) asm volatile("s_waitcnt vmcnt(" #n ")" ::: "memory")
; #define PG8_WAIT_L(n) asm volatile("s_waitcnt lgkmcnt(" #n ")" ::: "memory")
; #define PG8_BAR __builtin_amdgcn_s_barrier()
; #define PG8_SCHED __builtin_amdgcn_sched_barrier(0)
; template <class Sched, class Epi>
; __device__ __forceinline__ void gemm_phase(LAS unsigned char* lds, const Sched& S, const Epi& E, const int K, const int lda, const int ldb) {
;     ...
;             PG8_WAIT_V(6); PG8_BAR; if (!chalf) PG8_MMA(1, 1, At, B1); PG8_BAR;
;             PG8_LDB(B0, 1, 0); PG8_SCHED; PG8_LDA(At, 1, 0); PG8_STAGE(PG8_SA(0, 1), a2 + hstepA, voffA);
;             PG8_WAIT_L(8); PG8_BAR; PG8_WAIT_L(0); PG8_MMA(0, 0, At, B0); PG8_BAR; PG8_SCHED;
;             PG8_LDB(B1, 1, 1); PG8_STAGE(PG8_SB(1, 0), b3, voffB);
;             PG8_BAR; PG8_WAIT_L(0); PG8_MMA(0, 1, At, B1); PG8_BAR;
;             PG8_LDA(At, 1, 1); PG8_STAGE(PG8_SA(1, 0), a3, voffA);
	s_setprio 1
	v_mfma_f32_16x16x32_bf16 v[50:53], v[204:207], v[172:175], v[50:53]
	v_mfma_f32_16x16x32_bf16 v[42:45], v[212:215], v[172:175], v[42:45]
	v_mfma_f32_16x16x32_bf16 v[34:37], v[204:207], v[180:183], v[34:37]
	v_mfma_f32_16x16x32_bf16 v[26:29], v[212:215], v[180:183], v[26:29]
	v_mfma_f32_16x16x32_bf16 v[18:21], v[204:207], v[188:191], v[18:21]
	v_mfma_f32_16x16x32_bf16 v[10:13], v[212:215], v[188:191], v[10:13]
	v_mfma_f32_16x16x32_bf16 v[6:9], v[204:207], v[196:199], v[6:9]
	v_mfma_f32_16x16x32_bf16 v[2:5], v[212:215], v[196:199], v[2:5]
	v_mfma_f32_16x16x32_bf16 v[50:53], v[208:211], v[176:179], v[50:53]
	v_mfma_f32_16x16x32_bf16 v[42:45], v[216:219], v[176:179], v[42:45]
	v_mfma_f32_16x16x32_bf16 v[34:37], v[208:211], v[184:187], v[34:37]
	v_mfma_f32_16x16x32_bf16 v[26:29], v[216:219], v[184:187], v[26:29]
	v_mfma_f32_16x16x32_bf16 v[18:21], v[208:211], v[192:195], v[18:21]
	v_mfma_f32_16x16x32_bf16 v[10:13], v[216:219], v[192:195], v[10:13]
	v_mfma_f32_16x16x32_bf16 v[6:9], v[208:211], v[200:203], v[6:9]
	v_mfma_f32_16x16x32_bf16 v[2:5], v[216:219], v[200:203], v[2:5]
	s_setprio 0
	s_add_i32 s47, 16, 0x18000
	v_add_u32_e32 v168, s47, v144
	s_barrier
	ds_read_b128 v[156:159], v168
	ds_read_b128 v[160:163], v168 offset:1024
	ds_read_b128 v[164:167], v168 offset:2048
	ds_read_b128 v[168:171], v168 offset:3072
	s_add_u32 s34, s34, 0x80000
	s_addc_u32 s35, s35, 0
	s_mov_b32 m0, s37
	ds_read_b128 v[172:175], v154 offset:32768
	ds_read_b128 v[176:179], v154 offset:33792
	ds_read_b128 v[180:183], v154 offset:34816
	ds_read_b128 v[184:187], v154 offset:35840
	ds_read_b128 v[188:191], v154 offset:36864
	ds_read_b128 v[192:195], v154 offset:37888
	ds_read_b128 v[196:199], v154 offset:38912
	ds_read_b128 v[200:203], v154 offset:39936
	global_load_lds_dwordx4 v130, s[34:35]
	s_mov_b32 m0, s38
	s_nop 0
	global_load_lds_dwordx4 v134, s[34:35]
	s_waitcnt lgkmcnt(8)
	s_barrier
	s_waitcnt lgkmcnt(0)
	s_setprio 1
	s_waitcnt lgkmcnt(0)
	v_mfma_f32_16x16x32_bf16 v[126:129], v[156:159], v[172:175], v[126:129]
	v_mfma_f32_16x16x32_bf16 v[122:125], v[164:167], v[172:175], v[122:125]
	v_mfma_f32_16x16x32_bf16 v[114:117], v[156:159], v[180:183], v[114:117]
	v_mfma_f32_16x16x32_bf16 v[106:109], v[164:167], v[180:183], v[106:109]
	v_mfma_f32_16x16x32_bf16 v[98:101], v[156:159], v[188:191], v[98:101]
	v_mfma_f32_16x16x32_bf16 v[90:93], v[164:167], v[188:191], v[90:93]
	v_mfma_f32_16x16x32_bf16 v[82:85], v[156:159], v[196:199], v[82:85]
	v_mfma_f32_16x16x32_bf16 v[74:77], v[164:167], v[196:199], v[74:77]
	v_mfma_f32_16x16x32_bf16 v[126:129], v[160:163], v[176:179], v[126:129]
	v_mfma_f32_16x16x32_bf16 v[122:125], v[168:171], v[176:179], v[122:125]
	v_mfma_f32_16x16x32_bf16 v[114:117], v[160:163], v[184:187], v[114:117]
	v_mfma_f32_16x16x32_bf16 v[106:109], v[168:171], v[184:187], v[106:109]
	v_mfma_f32_16x16x32_bf16 v[98:101], v[160:163], v[192:195], v[98:101]
	v_mfma_f32_16x16x32_bf16 v[90:93], v[168:171], v[192:195], v[90:93]
	v_mfma_f32_16x16x32_bf16 v[82:85], v[160:163], v[200:203], v[82:85]
	v_mfma_f32_16x16x32_bf16 v[74:77], v[168:171], v[200:203], v[74:77]
	s_setprio 0
	s_barrier
	s_add_i32 s34, 16, 0x1c000
	s_add_i32 s35, s47, s33
	v_add_u32_e32 v216, s34, v144
	s_mov_b32 m0, s35
	ds_read_b128 v[204:207], v216
	ds_read_b128 v[208:211], v216 offset:1024
	ds_read_b128 v[212:215], v216 offset:2048
	ds_read_b128 v[216:219], v216 offset:3072
	global_load_lds_dwordx4 v132, s[52:53]
	s_add_i32 m0, s35, 0x2000
	s_nop 0
	global_load_lds_dwordx4 v136, s[54:55]
	s_barrier
	s_waitcnt lgkmcnt(0)
	s_setprio 1
	s_waitcnt lgkmcnt(0)
	v_mfma_f32_16x16x32_bf16 v[118:121], v[204:207], v[172:175], v[118:121]
	v_mfma_f32_16x16x32_bf16 v[110:113], v[212:215], v[172:175], v[110:113]
	v_mfma_f32_16x16x32_bf16 v[102:105], v[204:207], v[180:183], v[102:105]
	v_mfma_f32_16x16x32_bf16 v[94:97], v[212:215], v[180:183], v[94:97]
	v_mfma_f32_16x16x32_bf16 v[86:89], v[204:207], v[188:191], v[86:89]
	v_mfma_f32_16x16x32_bf16 v[78:81], v[212:215], v[188:191], v[78:81]
	v_mfma_f32_16x16x32_bf16 v[70:73], v[204:207], v[196:199], v[70:73]
	v_mfma_f32_16x16x32_bf16 v[66:69], v[212:215], v[196:199], v[66:69]
	v_mfma_f32_16x16x32_bf16 v[118:121], v[208:211], v[176:179], v[118:121]
	v_mfma_f32_16x16x32_bf16 v[110:113], v[216:219], v[176:179], v[110:113]
	v_mfma_f32_16x16x32_bf16 v[102:105], v[208:211], v[184:187], v[102:105]
	v_mfma_f32_16x16x32_bf16 v[94:97], v[216:219], v[184:187], v[94:97]
	v_mfma_f32_16x16x32_bf16 v[86:89], v[208:211], v[192:195], v[86:89]
	v_mfma_f32_16x16x32_bf16 v[78:81], v[216:219], v[192:195], v[78:81]
	v_mfma_f32_16x16x32_bf16 v[70:73], v[208:211], v[200:203], v[70:73]
	v_mfma_f32_16x16x32_bf16 v[66:69], v[216:219], v[200:203], v[66:69]
	s_setprio 0
	s_mov_b32 m0, s39
	s_barrier
	ds_read_b128 v[172:175], v154 offset:49152
	ds_read_b128 v[176:179], v154 offset:50176
	ds_read_b128 v[180:183], v154 offset:51200
	ds_read_b128 v[184:187], v154 offset:52224
	ds_read_b128 v[188:191], v154 offset:53248
	ds_read_b128 v[192:195], v154 offset:54272
	ds_read_b128 v[196:199], v154 offset:55296
	ds_read_b128 v[200:203], v154 offset:56320
	global_load_lds_dwordx4 v130, s[56:57]
	s_mov_b32 m0, s40
	s_nop 0
	global_load_lds_dwordx4 v134, s[58:59]
	s_barrier
; #define PG8_STAGE(bufoff, gbase, voff) do { _Pragma("unroll") for (int _i = 0; _i < 2; ++_i) \
;         __builtin_amdgcn_global_load_lds((const unsigned*)((const char*)(gbase) + (voff)[_i]), (LAS unsigned*)(lds + (bufoff) + ldsw + _i * 8192), 16, 0, 0); } while (0)
; #define PG8_MMA(ai, bj, At, Bt) do { __builtin_amdgcn_s_setprio(1); _Pragma("unroll") for (int m = 0; m < 4; ++m) _Pragma("unroll") for (int n = 0; n < 2; ++n) _Pragma("unroll") for (int k = 0; k < 2; ++k) \
;         acc[ai][bj][m][n] = __builtin_amdgcn_mfma_f32_16x16x32_bf16(Bt[n][k], At[m][k], acc[ai][bj][m][n], 0, 0, 0); __builtin_amdgcn_s_setprio(0); } while (0)
; #define PG8_WAIT_V(n) asm volatile("s_waitcnt vmcnt(" #n ")" ::: "memory")
; #define PG8_WAIT_L(n) asm volatile("s_waitcnt lgkmcnt(" #n ")" ::: "memory")
; #define PG8_BAR __builtin_amdgcn_s_barrier()
; #define PG8_SCHED __builtin_amdgcn_sched_barrier(0)
; template <class Sched, class Epi>
; __device__ __forceinline__ void gemm_phase(LAS unsigned char* lds, const Sched& S, const Epi& E, const int K, const int lda, const int ldb) {
;     ...
;             PG8_BAR; PG8_WAIT_L(0); if (!chalf) PG8_MMA(1, 0, At, B0); PG8_BAR; PG8_SCHED;
;             PG8_STAGE(PG8_SB(1, 1), b3 + hstepB, voffB);
;             PG8_WAIT_V(6); PG8_BAR; if (!chalf) PG8_MMA(1, 1, At, B1); PG8_BAR;
;         }
	s_waitcnt lgkmcnt(0)
	s_setprio 1
	s_waitcnt lgkmcnt(0)
	v_mfma_f32_16x16x32_bf16 v[62:65], v[156:159], v[172:175], v[62:65]
	v_mfma_f32_16x16x32_bf16 v[58:61], v[164:167], v[172:175], v[58:61]
	v_mfma_f32_16x16x32_bf16 v[54:57], v[156:159], v[180:183], v[54:57]
	v_mfma_f32_16x16x32_bf16 v[46:49], v[164:167], v[180:183], v[46:49]
	v_mfma_f32_16x16x32_bf16 v[38:41], v[156:159], v[188:191], v[38:41]
	v_mfma_f32_16x16x32_bf16 v[30:33], v[164:167], v[188:191], v[30:33]
	v_mfma_f32_16x16x32_bf16 v[22:25], v[156:159], v[196:199], v[22:25]
	v_mfma_f32_16x16x32_bf16 v[14:17], v[164:167], v[196:199], v[14:17]
	v_mfma_f32_16x16x32_bf16 v[62:65], v[160:163], v[176:179], v[62:65]
	v_mfma_f32_16x16x32_bf16 v[58:61], v[168:171], v[176:179], v[58:61]
	v_mfma_f32_16x16x32_bf16 v[54:57], v[160:163], v[184:187], v[54:57]
	v_mfma_f32_16x16x32_bf16 v[46:49], v[168:171], v[184:187], v[46:49]
	v_mfma_f32_16x16x32_bf16 v[38:41], v[160:163], v[192:195], v[38:41]
	v_mfma_f32_16x16x32_bf16 v[30:33], v[168:171], v[192:195], v[30:33]
	v_mfma_f32_16x16x32_bf16 v[22:25], v[160:163], v[200:203], v[22:25]
	v_mfma_f32_16x16x32_bf16 v[14:17], v[168:171], v[200:203], v[14:17]
	s_setprio 0
	s_barrier
	s_add_u32 s28, s28, 0x80080
	s_addc_u32 s29, s29, 0
	s_add_i32 s34, s34, s33
	s_mov_b32 m0, s34
	s_nop 0
	global_load_lds_dwordx4 v132, s[28:29]
	s_add_i32 m0, s34, 0x2000
	s_nop 0
	global_load_lds_dwordx4 v136, s[28:29]
	s_waitcnt vmcnt(6)
	s_barrier
	s_setprio 1
	v_mfma_f32_16x16x32_bf16 v[50:53], v[204:207], v[172:175], v[50:53]
	v_mfma_f32_16x16x32_bf16 v[42:45], v[212:215], v[172:175], v[42:45]
	v_mfma_f32_16x16x32_bf16 v[34:37], v[204:207], v[180:183], v[34:37]
	v_mfma_f32_16x16x32_bf16 v[26:29], v[212:215], v[180:183], v[26:29]
	v_mfma_f32_16x16x32_bf16 v[18:21], v[204:207], v[188:191], v[18:21]
	v_mfma_f32_16x16x32_bf16 v[10:13], v[212:215], v[188:191], v[10:13]
	v_mfma_f32_16x16x32_bf16 v[6:9], v[204:207], v[196:199], v[6:9]
	v_mfma_f32_16x16x32_bf16 v[2:5], v[212:215], v[196:199], v[2:5]
	v_mfma_f32_16x16x32_bf16 v[50:53], v[208:211], v[176:179], v[50:53]
	v_mfma_f32_16x16x32_bf16 v[42:45], v[216:219], v[176:179], v[42:45]
	v_mfma_f32_16x16x32_bf16 v[34:37], v[208:211], v[184:187], v[34:37]
	v_mfma_f32_16x16x32_bf16 v[26:29], v[216:219], v[184:187], v[26:29]
	v_mfma_f32_16x16x32_bf16 v[18:21], v[208:211], v[192:195], v[18:21]
	v_mfma_f32_16x16x32_bf16 v[10:13], v[216:219], v[192:195], v[10:13]
	v_mfma_f32_16x16x32_bf16 v[6:9], v[208:211], v[200:203], v[6:9]
	v_mfma_f32_16x16x32_bf16 v[2:5], v[216:219], v[200:203], v[2:5]
	s_setprio 0
	s_add_i32 s46, s46, 2
	s_add_u32 s15, s15, 0x100
	s_addc_u32 s17, s17, 0
	s_add_u32 s26, s26, 0x100
	s_addc_u32 s27, s27, 0
	s_cmp_gt_u32 s46, 29
	s_barrier
	s_cbranch_scc0 .LBB0_957
; __device__ __forceinline__ unsigned cvt_pk_bf16(float lo, float hi) { unsigned r; asm volatile("v_cvt_pk_bf16_f32 %0, %1, %2" : "=v"(r) : "v"(lo), "v"(hi)); return r; }
; #define PG8_WAIT_V(n) asm volatile("s_waitcnt vmcnt(" #n ")" ::: "memory")
; #define PG8_BAR __builtin_amdgcn_s_barrier()
; #define EPI_FOR_ROWS _Pragma("unroll") for (int ai = 0; ai < 2; ++ai) if (ai == 0 || !u.half) _Pragma("unroll") for (int m = 0; m < 4; ++m)
; template <class Sched, class Epi>
; __device__ __forceinline__ void gemm_phase(LAS unsigned char* lds, const Sched& S, const Epi& E, const int K, const int lda, const int ldb) {
;     ...
;         if (!has_next) break;
; #pragma unroll
;         for (int a = 0; a < 2; ++a)
; #pragma unroll
;             for (int b = 0; b < 2; ++b)
; #pragma unroll
;                 for (int m = 0; m < 4; ++m)
; #pragma unroll
;                     for (int n = 0; n < 2; ++n) acc[a][b][m][n] = (f32x4){0.f, 0.f, 0.f, 0.f};
;         cur = nxt; cA = nA; cB = nB; ++ui;
;     }
;     PG8_WAIT_V(0);
;     if (wr == 0) PG8_BAR;
;     __device__ __forceinline__ void operator()(EPI_ARGS) const {
;         EPI_FOR_ROWS { bf16_t* rp = O + (size_t)EPI_ROW * ldc;
; #pragma unroll
;             for (int bj = 0; bj < 2; ++bj) { const f32x4 v0 = acc[ai][bj][m][0], v1 = acc[ai][bj][m][1]; u32x4 o;
;                 o[0] = cvt_pk_bf16(v0[0], v0[1]); o[1] = cvt_pk_bf16(v0[2], v0[3]); o[2] = cvt_pk_bf16(v1[0], v1[1]); o[3] = cvt_pk_bf16(v1[2], v1[3]);
;                 *(u32x4*)(rp + EPI_COL(bj)) = o; } }
	v_add_u32_e32 v156, s4, v1
	v_ashrrev_i32_e32 v157, 31, v156
	v_cvt_pk_bf16_f32 v126, v126, v127
	v_cvt_pk_bf16_f32 v127, v128, v129
	v_cvt_pk_bf16_f32 v128, v122, v123
	v_lshl_or_b32 v122, s45, 8, v152
	v_lshlrev_b64 v[156:157], 12, v[156:157]
	v_ashrrev_i32_e32 v123, 31, v122
	v_lshl_add_u64 v[156:157], s[6:7], 0, v[156:157]
	v_lshlrev_b64 v[122:123], 1, v[122:123]
	v_cvt_pk_bf16_f32 v129, v124, v125
	v_lshl_add_u64 v[124:125], v[156:157], 0, v[122:123]
	global_store_dwordx4 v[124:125], v[126:129], off
	v_cvt_pk_bf16_f32 v118, v118, v119
	v_cvt_pk_bf16_f32 v119, v120, v121
	v_cvt_pk_bf16_f32 v120, v110, v111
	v_add_u32_e32 v110, s4, v145
	v_ashrrev_i32_e32 v111, 31, v110
	v_lshlrev_b64 v[110:111], 12, v[110:111]
	v_cvt_pk_bf16_f32 v121, v112, v113
	global_store_dwordx4 v[124:125], v[118:121], off offset:256
	s_and_b64 vcc, exec, s[12:13]
	s_mov_b32 s45, s14
	v_lshl_add_u64 v[118:119], s[6:7], 0, v[110:111]
	v_cvt_pk_bf16_f32 v110, v114, v115
	v_cvt_pk_bf16_f32 v111, v116, v117
	v_cvt_pk_bf16_f32 v112, v106, v107
	v_lshl_add_u64 v[106:107], v[118:119], 0, v[122:123]
	v_cvt_pk_bf16_f32 v113, v108, v109
	global_store_dwordx4 v[106:107], v[110:113], off
	v_cvt_pk_bf16_f32 v102, v102, v103
	v_cvt_pk_bf16_f32 v103, v104, v105
	v_cvt_pk_bf16_f32 v104, v94, v95
	v_add_u32_e32 v94, s4, v146
	v_ashrrev_i32_e32 v95, 31, v94
	v_lshlrev_b64 v[94:95], 12, v[94:95]
	v_cvt_pk_bf16_f32 v105, v96, v97
	global_store_dwordx4 v[106:107], v[102:105], off offset:256
	s_mov_b64 s[28:29], s[20:21]
	s_mov_b64 s[26:27], s[18:19]
	v_lshl_add_u64 v[102:103], s[6:7], 0, v[94:95]
	v_cvt_pk_bf16_f32 v94, v98, v99
	v_cvt_pk_bf16_f32 v95, v100, v101
	v_cvt_pk_bf16_f32 v96, v90, v91
	v_lshl_add_u64 v[90:91], v[102:103], 0, v[122:123]
	v_cvt_pk_bf16_f32 v97, v92, v93
	global_store_dwordx4 v[90:91], v[94:97], off
	v_cvt_pk_bf16_f32 v86, v86, v87
	v_cvt_pk_bf16_f32 v87, v88, v89
	v_cvt_pk_bf16_f32 v88, v78, v79
	v_add_u32_e32 v78, s4, v147
	v_ashrrev_i32_e32 v79, 31, v78
	v_lshlrev_b64 v[78:79], 12, v[78:79]
	v_cvt_pk_bf16_f32 v89, v80, v81
	global_store_dwordx4 v[90:91], v[86:89], off offset:256
	s_nop 1
	v_lshl_add_u64 v[86:87], s[6:7], 0, v[78:79]
	v_cvt_pk_bf16_f32 v78, v82, v83
	v_cvt_pk_bf16_f32 v79, v84, v85
	v_cvt_pk_bf16_f32 v80, v74, v75
	v_lshl_add_u64 v[74:75], v[86:87], 0, v[122:123]
	v_cvt_pk_bf16_f32 v81, v76, v77
	global_store_dwordx4 v[74:75], v[78:81], off
	v_cvt_pk_bf16_f32 v70, v70, v71
	v_cvt_pk_bf16_f32 v71, v72, v73
	v_cvt_pk_bf16_f32 v72, v66, v67
	v_add_u32_e32 v66, s4, v148
	v_ashrrev_i32_e32 v67, 31, v66
	v_lshlrev_b64 v[66:67], 12, v[66:67]
	v_lshl_add_u64 v[66:67], s[6:7], 0, v[66:67]
	v_cvt_pk_bf16_f32 v73, v68, v69
	global_store_dwordx4 v[74:75], v[70:73], off offset:256
	v_cvt_pk_bf16_f32 v62, v62, v63
	v_cvt_pk_bf16_f32 v63, v64, v65
	v_cvt_pk_bf16_f32 v64, v58, v59
	v_lshl_add_u64 v[58:59], v[66:67], 0, v[122:123]
	v_cvt_pk_bf16_f32 v65, v60, v61
	global_store_dwordx4 v[58:59], v[62:65], off
	v_cvt_pk_bf16_f32 v50, v50, v51
	v_cvt_pk_bf16_f32 v51, v52, v53
	v_cvt_pk_bf16_f32 v52, v42, v43
	v_add_u32_e32 v42, s4, v149
	v_ashrrev_i32_e32 v43, 31, v42
	v_lshlrev_b64 v[42:43], 12, v[42:43]
	v_cvt_pk_bf16_f32 v53, v44, v45
	global_store_dwordx4 v[58:59], v[50:53], off offset:256
	s_nop 1
	v_lshl_add_u64 v[50:51], s[6:7], 0, v[42:43]
	v_cvt_pk_bf16_f32 v42, v54, v55
	v_cvt_pk_bf16_f32 v43, v56, v57
	v_cvt_pk_bf16_f32 v44, v46, v47
	v_lshl_add_u64 v[46:47], v[50:51], 0, v[122:123]
	v_cvt_pk_bf16_f32 v45, v48, v49
	global_store_dwordx4 v[46:47], v[42:45], off
	v_cvt_pk_bf16_f32 v34, v34, v35
	v_cvt_pk_bf16_f32 v35, v36, v37
	v_cvt_pk_bf16_f32 v36, v26, v27
	v_add_u32_e32 v26, s4, v150
	v_ashrrev_i32_e32 v27, 31, v26
	v_lshlrev_b64 v[26:27], 12, v[26:27]
	v_cvt_pk_bf16_f32 v37, v28, v29
	global_store_dwordx4 v[46:47], v[34:37], off offset:256
	s_nop 1
	v_lshl_add_u64 v[34:35], s[6:7], 0, v[26:27]
	v_cvt_pk_bf16_f32 v26, v38, v39
	v_cvt_pk_bf16_f32 v27, v40, v41
	v_cvt_pk_bf16_f32 v28, v30, v31
	v_lshl_add_u64 v[30:31], v[34:35], 0, v[122:123]
	v_cvt_pk_bf16_f32 v29, v32, v33
	global_store_dwordx4 v[30:31], v[26:29], off
	v_cvt_pk_bf16_f32 v18, v18, v19
	v_cvt_pk_bf16_f32 v19, v20, v21
	v_cvt_pk_bf16_f32 v20, v10, v11
	v_add_u32_e32 v10, s4, v151
	v_ashrrev_i32_e32 v11, 31, v10
	v_lshlrev_b64 v[10:11], 12, v[10:11]
	v_cvt_pk_bf16_f32 v21, v12, v13
	global_store_dwordx4 v[30:31], v[18:21], off offset:256
	s_mov_b32 s4, s16
	s_nop 0
	v_lshl_add_u64 v[18:19], s[6:7], 0, v[10:11]
	v_cvt_pk_bf16_f32 v10, v22, v23
	v_cvt_pk_bf16_f32 v11, v24, v25
	v_cvt_pk_bf16_f32 v12, v14, v15
	v_lshl_add_u64 v[14:15], v[18:19], 0, v[122:123]
	v_cvt_pk_bf16_f32 v13, v16, v17
	global_store_dwordx4 v[14:15], v[10:13], off
	v_cvt_pk_bf16_f32 v6, v6, v7
	v_cvt_pk_bf16_f32 v7, v8, v9
	v_cvt_pk_bf16_f32 v8, v2, v3
	v_cvt_pk_bf16_f32 v9, v4, v5
	global_store_dwordx4 v[14:15], v[6:9], off offset:256
	s_cbranch_vccz .LBB0_950
	s_waitcnt vmcnt(0)
	s_cmpk_gt_u32 s2, 0xff
	s_cbranch_scc1 .LBB0_961
	s_barrier

; #define PG8_STAGE(bufoff, gbase, voff) do { _Pragma("unroll") for (int _i = 0; _i < 2; ++_i) \
;         __builtin_amdgcn_global_load_lds((const unsigned*)((const char*)(gbase) + (voff)[_i]), (LAS unsigned*)(lds + (bufoff) + ldsw + _i * 8192), 16, 0, 0); } while (0)
; #define PG8_LDA(dst, b, h) do { _Pragma("unroll") for (int m = 0; m < 4; ++m) _Pragma("unroll") for (int k = 0; k < 2; ++k) dst[m][k] = *(const LAS bf16x8*)(lds + PG8_SA(b, h) + aoff + m * 2048 + k * 1024); } while (0)
; #define PG8_LDB(dst, b, h) do { _Pragma("unroll") for (int n = 0; n < 2; ++n) _Pragma("unroll") for (int k = 0; k < 2; ++k) dst[n][k] = *(const LAS bf16x8*)(lds + PG8_SB(b, h) + boff + n * 2048 + k * 1024); } while (0)
; #define PG8_MMA(ai, bj, At, Bt) do { __builtin_amdgcn_s_setprio(1); _Pragma("unroll") for (int m = 0; m < 4; ++m) _Pragma("unroll") for (int n = 0; n < 2; ++n) _Pragma("unroll") for (int k = 0; k < 2; ++k) \
;         acc[ai][bj][m][n] = __builtin_amdgcn_mfma_f32_16x16x32_bf16(Bt[n][k], At[m][k], acc[ai][bj][m][n], 0, 0, 0); __builtin_amdgcn_s_setprio(0); } while (0)
; #define PG8_WAIT_V(n) asm volatile("s_waitcnt vmcnt(" #n ")" ::: "memory")
; #define PG8_WAIT_L(n) asm volatile("s_waitcnt lgkmcnt(" #n ")" ::: "memory")
; #define PG8_BAR __builtin_amdgcn_s_barrier()
; #define PG8_SCHED __builtin_amdgcn_sched_barrier(0)
; template <class Sched, class Epi>
; __device__ __forceinline__ void gemm_phase(LAS unsigned char* lds, const Sched& S, const Epi& E, const int K, const int lda, const int ldb) {
;     ...
;             PG8_LDB(B0, 0, 0); PG8_SCHED; PG8_LDA(At, 0, 0); PG8_STAGE(PG8_SA(1, 1), a1 + hstepA, voffA);
;             PG8_WAIT_L(8); PG8_BAR; PG8_WAIT_L(0); PG8_MMA(0, 0, At, B0); PG8_BAR; PG8_SCHED;
;             PG8_LDB(B1, 0, 1); PG8_STAGE(PG8_SB(0, 0), b2, voffB);
;             PG8_BAR; PG8_WAIT_L(0); PG8_MMA(0, 1, At, B1); PG8_BAR;
;             PG8_LDA(At, 0, 1); PG8_STAGE(PG8_SA(0, 0), a2, voffA);
;             PG8_BAR; PG8_WAIT_L(0); if (!chalf) PG8_MMA(1, 0, At, B0); PG8_BAR; PG8_SCHED;
;             PG8_STAGE(PG8_SB(0, 1), b2 + hstepB, voffB);
;             PG8_WAIT_V(6); PG8_BAR; if (!chalf) PG8_MMA(1, 1, At, B1); PG8_BAR;
.LBB0_1092:
	ds_read_b128 v[160:163], v156
	ds_read_b128 v[164:167], v156 offset:1024
	ds_read_b128 v[168:171], v156 offset:2048
	ds_read_b128 v[172:175], v156 offset:3072
	s_add_u32 s26, s24, 0xfff80080
	s_addc_u32 s27, s25, -1
	s_cmp_eq_u32 s48, 28
	s_cselect_b32 s29, s21, s27
	s_cselect_b32 s28, s20, s26
	s_cselect_b32 s27, s23, s15
	s_cselect_b32 s26, s22, s13
	s_add_i32 m0, s5, 0xc000
	ds_read_b128 v[176:179], v157
	ds_read_b128 v[180:183], v157 offset:1024
	ds_read_b128 v[184:187], v157 offset:2048
	ds_read_b128 v[188:191], v157 offset:3072
	ds_read_b128 v[192:195], v157 offset:4096
	ds_read_b128 v[196:199], v157 offset:5120
	ds_read_b128 v[200:203], v157 offset:6144
	ds_read_b128 v[204:207], v157 offset:7168
	global_load_lds_dwordx4 v142, s[24:25]
	s_add_i32 m0, s5, 0xe000
	s_nop 0
	global_load_lds_dwordx4 v140, s[24:25]
	s_waitcnt lgkmcnt(8)
	s_barrier
	s_waitcnt lgkmcnt(0)
	s_setprio 1
	s_waitcnt lgkmcnt(0)
	v_mfma_f32_16x16x32_bf16 v[126:129], v[160:163], v[176:179], v[126:129]
	v_mfma_f32_16x16x32_bf16 v[122:125], v[168:171], v[176:179], v[122:125]
	v_mfma_f32_16x16x32_bf16 v[114:117], v[160:163], v[184:187], v[114:117]
	v_mfma_f32_16x16x32_bf16 v[106:109], v[168:171], v[184:187], v[106:109]
	v_mfma_f32_16x16x32_bf16 v[98:101], v[160:163], v[192:195], v[98:101]
	v_mfma_f32_16x16x32_bf16 v[90:93], v[168:171], v[192:195], v[90:93]
	v_mfma_f32_16x16x32_bf16 v[82:85], v[160:163], v[200:203], v[82:85]
	v_mfma_f32_16x16x32_bf16 v[74:77], v[168:171], v[200:203], v[74:77]
	v_mfma_f32_16x16x32_bf16 v[126:129], v[164:167], v[180:183], v[126:129]
	v_mfma_f32_16x16x32_bf16 v[122:125], v[172:175], v[180:183], v[122:125]
	v_mfma_f32_16x16x32_bf16 v[114:117], v[164:167], v[188:191], v[114:117]
	v_mfma_f32_16x16x32_bf16 v[106:109], v[172:175], v[188:191], v[106:109]
	v_mfma_f32_16x16x32_bf16 v[98:101], v[164:167], v[196:199], v[98:101]
	v_mfma_f32_16x16x32_bf16 v[90:93], v[172:175], v[196:199], v[90:93]
	v_mfma_f32_16x16x32_bf16 v[82:85], v[164:167], v[204:207], v[82:85]
	v_mfma_f32_16x16x32_bf16 v[74:77], v[172:175], v[204:207], v[74:77]
	s_setprio 0
	s_barrier
	s_add_i32 s49, s44, s11
	s_add_u32 s52, s26, s6
	s_addc_u32 s53, s27, s7
	s_mov_b32 m0, s49
	ds_read_b128 v[208:211], v158
	ds_read_b128 v[212:215], v158 offset:1024
	ds_read_b128 v[216:219], v158 offset:2048
	ds_read_b128 v[220:223], v158 offset:3072
	global_load_lds_dwordx4 v134, s[26:27]
	s_add_u32 s54, s26, s6
	s_addc_u32 s55, s27, s7
	s_add_i32 m0, s49, 0x2000
	s_nop 0
	global_load_lds_dwordx4 v130, s[26:27]
	s_barrier
	s_waitcnt lgkmcnt(0)
	s_setprio 1
	s_waitcnt lgkmcnt(0)
	v_mfma_f32_16x16x32_bf16 v[118:121], v[208:211], v[176:179], v[118:121]
	v_mfma_f32_16x16x32_bf16 v[110:113], v[216:219], v[176:179], v[110:113]
	v_mfma_f32_16x16x32_bf16 v[102:105], v[208:211], v[184:187], v[102:105]
	v_mfma_f32_16x16x32_bf16 v[94:97], v[216:219], v[184:187], v[94:97]
	v_mfma_f32_16x16x32_bf16 v[86:89], v[208:211], v[192:195], v[86:89]
	v_mfma_f32_16x16x32_bf16 v[78:81], v[216:219], v[192:195], v[78:81]
	v_mfma_f32_16x16x32_bf16 v[70:73], v[208:211], v[200:203], v[70:73]
	v_mfma_f32_16x16x32_bf16 v[66:69], v[216:219], v[200:203], v[66:69]
	v_mfma_f32_16x16x32_bf16 v[118:121], v[212:215], v[180:183], v[118:121]
	v_mfma_f32_16x16x32_bf16 v[110:113], v[220:223], v[180:183], v[110:113]
	v_mfma_f32_16x16x32_bf16 v[102:105], v[212:215], v[188:191], v[102:105]
	v_mfma_f32_16x16x32_bf16 v[94:97], v[220:223], v[188:191], v[94:97]
	v_mfma_f32_16x16x32_bf16 v[86:89], v[212:215], v[196:199], v[86:89]
	v_mfma_f32_16x16x32_bf16 v[78:81], v[220:223], v[196:199], v[78:81]
	v_mfma_f32_16x16x32_bf16 v[70:73], v[212:215], v[204:207], v[70:73]
	v_mfma_f32_16x16x32_bf16 v[66:69], v[220:223], v[204:207], v[66:69]
	s_setprio 0
	s_mov_b32 m0, s5
	s_add_u32 s56, s28, s6
	s_addc_u32 s57, s29, s7
	s_barrier
	ds_read_b128 v[176:179], v157 offset:16384
	ds_read_b128 v[180:183], v157 offset:17408
	ds_read_b128 v[184:187], v157 offset:18432
	ds_read_b128 v[188:191], v157 offset:19456
	ds_read_b128 v[192:195], v157 offset:20480
	ds_read_b128 v[196:199], v157 offset:21504
	ds_read_b128 v[200:203], v157 offset:22528
	ds_read_b128 v[204:207], v157 offset:23552
	global_load_lds_dwordx4 v136, s[28:29]
	s_add_u32 s58, s28, s6
	s_addc_u32 s59, s29, s7
	s_mov_b32 m0, s35
	s_nop 0
	global_load_lds_dwordx4 v132, s[28:29]
	s_barrier
	s_waitcnt lgkmcnt(0)
	s_setprio 1
	s_waitcnt lgkmcnt(0)
	v_mfma_f32_16x16x32_bf16 v[62:65], v[160:163], v[176:179], v[62:65]
	v_mfma_f32_16x16x32_bf16 v[58:61], v[168:171], v[176:179], v[58:61]
	v_mfma_f32_16x16x32_bf16 v[50:53], v[160:163], v[184:187], v[50:53]
	v_mfma_f32_16x16x32_bf16 v[42:45], v[168:171], v[184:187], v[42:45]
	v_mfma_f32_16x16x32_bf16 v[34:37], v[160:163], v[192:195], v[34:37]
	v_mfma_f32_16x16x32_bf16 v[26:29], v[168:171], v[192:195], v[26:29]
	v_mfma_f32_16x16x32_bf16 v[18:21], v[160:163], v[200:203], v[18:21]
	v_mfma_f32_16x16x32_bf16 v[10:13], v[168:171], v[200:203], v[10:13]
	v_mfma_f32_16x16x32_bf16 v[62:65], v[164:167], v[180:183], v[62:65]
	v_mfma_f32_16x16x32_bf16 v[58:61], v[172:175], v[180:183], v[58:61]
	v_mfma_f32_16x16x32_bf16 v[50:53], v[164:167], v[188:191], v[50:53]
	v_mfma_f32_16x16x32_bf16 v[42:45], v[172:175], v[188:191], v[42:45]
	v_mfma_f32_16x16x32_bf16 v[34:37], v[164:167], v[196:199], v[34:37]
	v_mfma_f32_16x16x32_bf16 v[26:29], v[172:175], v[196:199], v[26:29]
	v_mfma_f32_16x16x32_bf16 v[18:21], v[164:167], v[204:207], v[18:21]
	v_mfma_f32_16x16x32_bf16 v[10:13], v[172:175], v[204:207], v[10:13]
	s_setprio 0
	s_barrier
	s_add_u32 s50, s26, 0x80000
	s_addc_u32 s51, s27, 0
	s_add_i32 s49, s45, s11
	s_mov_b32 m0, s49
	s_nop 0
	global_load_lds_dwordx4 v134, s[50:51]
	s_add_i32 m0, s49, 0x2000
	s_nop 0
	global_load_lds_dwordx4 v130, s[50:51]
	s_waitcnt vmcnt(6)
	s_barrier
; #define PG8_STAGE(bufoff, gbase, voff) do { _Pragma("unroll") for (int _i = 0; _i < 2; ++_i) \
;         __builtin_amdgcn_global_load_lds((const unsigned*)((const char*)(gbase) + (voff)[_i]), (LAS unsigned*)(lds + (bufoff) + ldsw + _i * 8192), 16, 0, 0); } while (0)
; #define PG8_LDA(dst, b, h) do { _Pragma("unroll") for (int m = 0; m < 4; ++m) _Pragma("unroll") for (int k = 0; k < 2; ++k) dst[m][k] = *(const LAS bf16x8*)(lds + PG8_SA(b, h) + aoff + m * 2048 + k * 1024); } while (0)
; #define PG8_LDB(dst, b, h) do { _Pragma("unroll") for (int n = 0; n < 2; ++n) _Pragma("unroll") for (int k = 0; k < 2; ++k) dst[n][k] = *(const LAS bf16x8*)(lds + PG8_SB(b, h) + boff + n * 2048 + k * 1024); } while (0)
; #define PG8_MMA(ai, bj, At, Bt) do { __builtin_amdgcn_s_setprio(1); _Pragma("unroll") for (int m = 0; m < 4; ++m) _Pragma("unroll") for (int n = 0; n < 2; ++n) _Pragma("unroll") for (int k = 0; k < 2; ++k) \
;         acc[ai][bj][m][n] = __builtin_amdgcn_mfma_f32_16x16x32_bf16(Bt[n][k], At[m][k], acc[ai][bj][m][n], 0, 0, 0); __builtin_amdgcn_s_setprio(0); } while (0)
; #define PG8_WAIT_V(n) asm volatile("s_waitcnt vmcnt(" #n ")" ::: "memory")
; #define PG8_WAIT_L(n) asm volatile("s_waitcnt lgkmcnt(" #n ")" ::: "memory")
; #define PG8_BAR __builtin_amdgcn_s_barrier()
; #define PG8_SCHED __builtin_amdgcn_sched_barrier(0)
; template <class Sched, class Epi>
; __device__ __forceinline__ void gemm_phase(LAS unsigned char* lds, const Sched& S, const Epi& E, const int K, const int lda, const int ldb) {
;     ...
;             PG8_WAIT_V(6); PG8_BAR; if (!chalf) PG8_MMA(1, 1, At, B1); PG8_BAR;
;             PG8_LDB(B0, 1, 0); PG8_SCHED; PG8_LDA(At, 1, 0); PG8_STAGE(PG8_SA(0, 1), a2 + hstepA, voffA);
;             PG8_WAIT_L(8); PG8_BAR; PG8_WAIT_L(0); PG8_MMA(0, 0, At, B0); PG8_BAR; PG8_SCHED;
;             PG8_LDB(B1, 1, 1); PG8_STAGE(PG8_SB(1, 0), b3, voffB);
;             PG8_BAR; PG8_WAIT_L(0); PG8_MMA(0, 1, At, B1); PG8_BAR;
;             PG8_LDA(At, 1, 1); PG8_STAGE(PG8_SA(1, 0), a3, voffA);
	s_setprio 1
	v_mfma_f32_16x16x32_bf16 v[54:57], v[208:211], v[176:179], v[54:57]
	v_mfma_f32_16x16x32_bf16 v[46:49], v[216:219], v[176:179], v[46:49]
	v_mfma_f32_16x16x32_bf16 v[38:41], v[208:211], v[184:187], v[38:41]
	v_mfma_f32_16x16x32_bf16 v[30:33], v[216:219], v[184:187], v[30:33]
	v_mfma_f32_16x16x32_bf16 v[22:25], v[208:211], v[192:195], v[22:25]
	v_mfma_f32_16x16x32_bf16 v[14:17], v[216:219], v[192:195], v[14:17]
	v_mfma_f32_16x16x32_bf16 v[6:9], v[208:211], v[200:203], v[6:9]
	v_mfma_f32_16x16x32_bf16 v[2:5], v[216:219], v[200:203], v[2:5]
	v_mfma_f32_16x16x32_bf16 v[54:57], v[212:215], v[180:183], v[54:57]
	v_mfma_f32_16x16x32_bf16 v[46:49], v[220:223], v[180:183], v[46:49]
	v_mfma_f32_16x16x32_bf16 v[38:41], v[212:215], v[188:191], v[38:41]
	v_mfma_f32_16x16x32_bf16 v[30:33], v[220:223], v[188:191], v[30:33]
	v_mfma_f32_16x16x32_bf16 v[22:25], v[212:215], v[196:199], v[22:25]
	v_mfma_f32_16x16x32_bf16 v[14:17], v[220:223], v[196:199], v[14:17]
	v_mfma_f32_16x16x32_bf16 v[6:9], v[212:215], v[204:207], v[6:9]
	v_mfma_f32_16x16x32_bf16 v[2:5], v[220:223], v[204:207], v[2:5]
	s_setprio 0
	s_add_i32 s49, 16, 0x18000
	v_add_u32_e32 v159, s49, v148
	s_barrier
	ds_read_b128 v[160:163], v159
	ds_read_b128 v[164:167], v159 offset:1024
	ds_read_b128 v[168:171], v159 offset:2048
	ds_read_b128 v[172:175], v159 offset:3072
	s_add_u32 s28, s28, 0x80000
	s_addc_u32 s29, s29, 0
	s_mov_b32 m0, s36
	ds_read_b128 v[176:179], v157 offset:32768
	ds_read_b128 v[180:183], v157 offset:33792
	ds_read_b128 v[184:187], v157 offset:34816
	ds_read_b128 v[188:191], v157 offset:35840
	ds_read_b128 v[192:195], v157 offset:36864
	ds_read_b128 v[196:199], v157 offset:37888
	ds_read_b128 v[200:203], v157 offset:38912
	ds_read_b128 v[204:207], v157 offset:39936
	global_load_lds_dwordx4 v136, s[28:29]
	s_mov_b32 m0, s37
	s_nop 0
	global_load_lds_dwordx4 v132, s[28:29]
	s_waitcnt lgkmcnt(8)
	s_barrier
	s_waitcnt lgkmcnt(0)
	s_setprio 1
	s_waitcnt lgkmcnt(0)
	v_mfma_f32_16x16x32_bf16 v[126:129], v[160:163], v[176:179], v[126:129]
	v_mfma_f32_16x16x32_bf16 v[122:125], v[168:171], v[176:179], v[122:125]
	v_mfma_f32_16x16x32_bf16 v[114:117], v[160:163], v[184:187], v[114:117]
	v_mfma_f32_16x16x32_bf16 v[106:109], v[168:171], v[184:187], v[106:109]
	v_mfma_f32_16x16x32_bf16 v[98:101], v[160:163], v[192:195], v[98:101]
	v_mfma_f32_16x16x32_bf16 v[90:93], v[168:171], v[192:195], v[90:93]
	v_mfma_f32_16x16x32_bf16 v[82:85], v[160:163], v[200:203], v[82:85]
	v_mfma_f32_16x16x32_bf16 v[74:77], v[168:171], v[200:203], v[74:77]
	v_mfma_f32_16x16x32_bf16 v[126:129], v[164:167], v[180:183], v[126:129]
	v_mfma_f32_16x16x32_bf16 v[122:125], v[172:175], v[180:183], v[122:125]
	v_mfma_f32_16x16x32_bf16 v[114:117], v[164:167], v[188:191], v[114:117]
	v_mfma_f32_16x16x32_bf16 v[106:109], v[172:175], v[188:191], v[106:109]
	v_mfma_f32_16x16x32_bf16 v[98:101], v[164:167], v[196:199], v[98:101]
	v_mfma_f32_16x16x32_bf16 v[90:93], v[172:175], v[196:199], v[90:93]
	v_mfma_f32_16x16x32_bf16 v[82:85], v[164:167], v[204:207], v[82:85]
	v_mfma_f32_16x16x32_bf16 v[74:77], v[172:175], v[204:207], v[74:77]
	s_setprio 0
	s_barrier
	s_add_i32 s28, 16, 0x1c000
	s_add_i32 s29, s49, s11
	v_add_u32_e32 v159, s28, v148
	s_mov_b32 m0, s29
	ds_read_b128 v[208:211], v159
	ds_read_b128 v[212:215], v159 offset:1024
	ds_read_b128 v[216:219], v159 offset:2048
	ds_read_b128 v[220:223], v159 offset:3072
	global_load_lds_dwordx4 v134, s[52:53]
	s_add_i32 m0, s29, 0x2000
	s_nop 0
	global_load_lds_dwordx4 v130, s[54:55]
	s_barrier
	s_waitcnt lgkmcnt(0)
	s_setprio 1
	s_waitcnt lgkmcnt(0)
	v_mfma_f32_16x16x32_bf16 v[118:121], v[208:211], v[176:179], v[118:121]
	v_mfma_f32_16x16x32_bf16 v[110:113], v[216:219], v[176:179], v[110:113]
	v_mfma_f32_16x16x32_bf16 v[102:105], v[208:211], v[184:187], v[102:105]
	v_mfma_f32_16x16x32_bf16 v[94:97], v[216:219], v[184:187], v[94:97]
	v_mfma_f32_16x16x32_bf16 v[86:89], v[208:211], v[192:195], v[86:89]
	v_mfma_f32_16x16x32_bf16 v[78:81], v[216:219], v[192:195], v[78:81]
	v_mfma_f32_16x16x32_bf16 v[70:73], v[208:211], v[200:203], v[70:73]
	v_mfma_f32_16x16x32_bf16 v[66:69], v[216:219], v[200:203], v[66:69]
	v_mfma_f32_16x16x32_bf16 v[118:121], v[212:215], v[180:183], v[118:121]
	v_mfma_f32_16x16x32_bf16 v[110:113], v[220:223], v[180:183], v[110:113]
	v_mfma_f32_16x16x32_bf16 v[102:105], v[212:215], v[188:191], v[102:105]
	v_mfma_f32_16x16x32_bf16 v[94:97], v[220:223], v[188:191], v[94:97]
	v_mfma_f32_16x16x32_bf16 v[86:89], v[212:215], v[196:199], v[86:89]
	v_mfma_f32_16x16x32_bf16 v[78:81], v[220:223], v[196:199], v[78:81]
	v_mfma_f32_16x16x32_bf16 v[70:73], v[212:215], v[204:207], v[70:73]
	v_mfma_f32_16x16x32_bf16 v[66:69], v[220:223], v[204:207], v[66:69]
	s_setprio 0
	s_mov_b32 m0, s41
	s_barrier
; #define PG8_STAGE(bufoff, gbase, voff) do { _Pragma("unroll") for (int _i = 0; _i < 2; ++_i) \
;         __builtin_amdgcn_global_load_lds((const unsigned*)((const char*)(gbase) + (voff)[_i]), (LAS unsigned*)(lds + (bufoff) + ldsw + _i * 8192), 16, 0, 0); } while (0)
; #define PG8_LDA(dst, b, h) do { _Pragma("unroll") for (int m = 0; m < 4; ++m) _Pragma("unroll") for (int k = 0; k < 2; ++k) dst[m][k] = *(const LAS bf16x8*)(lds + PG8_SA(b, h) + aoff + m * 2048 + k * 1024); } while (0)
; #define PG8_MMA(ai, bj, At, Bt) do { __builtin_amdgcn_s_setprio(1); _Pragma("unroll") for (int m = 0; m < 4; ++m) _Pragma("unroll") for (int n = 0; n < 2; ++n) _Pragma("unroll") for (int k = 0; k < 2; ++k) \
;         acc[ai][bj][m][n] = __builtin_amdgcn_mfma_f32_16x16x32_bf16(Bt[n][k], At[m][k], acc[ai][bj][m][n], 0, 0, 0); __builtin_amdgcn_s_setprio(0); } while (0)
; #define PG8_WAIT_V(n) asm volatile("s_waitcnt vmcnt(" #n ")" ::: "memory")
; #define PG8_WAIT_L(n) asm volatile("s_waitcnt lgkmcnt(" #n ")" ::: "memory")
; #define PG8_BAR __builtin_amdgcn_s_barrier()
; #define PG8_SCHED __builtin_amdgcn_sched_barrier(0)
; template <class Sched, class Epi>
; __device__ __forceinline__ void gemm_phase(LAS unsigned char* lds, const Sched& S, const Epi& E, const int K, const int lda, const int ldb) {
;     ...
;             PG8_LDA(At, 1, 1); PG8_STAGE(PG8_SA(1, 0), a3, voffA);
;             PG8_BAR; PG8_WAIT_L(0); if (!chalf) PG8_MMA(1, 0, At, B0); PG8_BAR; PG8_SCHED;
;             PG8_STAGE(PG8_SB(1, 1), b3 + hstepB, voffB);
;             PG8_WAIT_V(6); PG8_BAR; if (!chalf) PG8_MMA(1, 1, At, B1); PG8_BAR;
;         }
;     __device__ __forceinline__ void operator()(EPI_ARGS) const {
;         const int c0 = u.pn * 256; size_t eb; int pitch, cl;
;         if (c0 < C_U) { eb = E_PC; pitch = 4096; cl = c0; } else if (c0 < C_ZB) { eb = E_PU; pitch = 1024; cl = c0 - C_U; } else if (c0 < C_F) { eb = E_PZB; pitch = 1024; cl = c0 - C_ZB; }
;         else if (c0 < C_ZC) { eb = E_PF; pitch = 1024; cl = c0 - C_F; } else if (c0 < C_GL) { eb = E_PZC; pitch = 1024; cl = c0 - C_ZC; } else { eb = E_PGL; pitch = 6144; cl = c0 - C_GL; }
	ds_read_b128 v[176:179], v157 offset:49152
	ds_read_b128 v[180:183], v157 offset:50176
	ds_read_b128 v[184:187], v157 offset:51200
	ds_read_b128 v[188:191], v157 offset:52224
	ds_read_b128 v[192:195], v157 offset:53248
	ds_read_b128 v[196:199], v157 offset:54272
	ds_read_b128 v[200:203], v157 offset:55296
	ds_read_b128 v[204:207], v157 offset:56320
	global_load_lds_dwordx4 v136, s[56:57]
	s_mov_b32 m0, s42
	s_nop 0
	global_load_lds_dwordx4 v132, s[58:59]
	s_barrier
	s_waitcnt lgkmcnt(0)
	s_setprio 1
	s_waitcnt lgkmcnt(0)
	v_mfma_f32_16x16x32_bf16 v[62:65], v[160:163], v[176:179], v[62:65]
	v_mfma_f32_16x16x32_bf16 v[58:61], v[168:171], v[176:179], v[58:61]
	v_mfma_f32_16x16x32_bf16 v[50:53], v[160:163], v[184:187], v[50:53]
	v_mfma_f32_16x16x32_bf16 v[42:45], v[168:171], v[184:187], v[42:45]
	v_mfma_f32_16x16x32_bf16 v[34:37], v[160:163], v[192:195], v[34:37]
	v_mfma_f32_16x16x32_bf16 v[26:29], v[168:171], v[192:195], v[26:29]
	v_mfma_f32_16x16x32_bf16 v[18:21], v[160:163], v[200:203], v[18:21]
	v_mfma_f32_16x16x32_bf16 v[10:13], v[168:171], v[200:203], v[10:13]
	v_mfma_f32_16x16x32_bf16 v[62:65], v[164:167], v[180:183], v[62:65]
	v_mfma_f32_16x16x32_bf16 v[58:61], v[172:175], v[180:183], v[58:61]
	v_mfma_f32_16x16x32_bf16 v[50:53], v[164:167], v[188:191], v[50:53]
	v_mfma_f32_16x16x32_bf16 v[42:45], v[172:175], v[188:191], v[42:45]
	v_mfma_f32_16x16x32_bf16 v[34:37], v[164:167], v[196:199], v[34:37]
	v_mfma_f32_16x16x32_bf16 v[26:29], v[172:175], v[196:199], v[26:29]
	v_mfma_f32_16x16x32_bf16 v[18:21], v[164:167], v[204:207], v[18:21]
	v_mfma_f32_16x16x32_bf16 v[10:13], v[172:175], v[204:207], v[10:13]
	s_setprio 0
	s_barrier
	s_add_u32 s26, s26, 0x80080
	s_addc_u32 s27, s27, 0
	s_add_i32 s28, s28, s11
	s_mov_b32 m0, s28
	s_nop 0
	global_load_lds_dwordx4 v134, s[26:27]
	s_add_i32 m0, s28, 0x2000
	s_nop 0
	global_load_lds_dwordx4 v130, s[26:27]
	s_waitcnt vmcnt(6)
	s_barrier
	s_setprio 1
	v_mfma_f32_16x16x32_bf16 v[54:57], v[208:211], v[176:179], v[54:57]
	v_mfma_f32_16x16x32_bf16 v[46:49], v[216:219], v[176:179], v[46:49]
	v_mfma_f32_16x16x32_bf16 v[38:41], v[208:211], v[184:187], v[38:41]
	v_mfma_f32_16x16x32_bf16 v[30:33], v[216:219], v[184:187], v[30:33]
	v_mfma_f32_16x16x32_bf16 v[22:25], v[208:211], v[192:195], v[22:25]
	v_mfma_f32_16x16x32_bf16 v[14:17], v[216:219], v[192:195], v[14:17]
	v_mfma_f32_16x16x32_bf16 v[6:9], v[208:211], v[200:203], v[6:9]
	v_mfma_f32_16x16x32_bf16 v[2:5], v[216:219], v[200:203], v[2:5]
	v_mfma_f32_16x16x32_bf16 v[54:57], v[212:215], v[180:183], v[54:57]
	v_mfma_f32_16x16x32_bf16 v[46:49], v[220:223], v[180:183], v[46:49]
	v_mfma_f32_16x16x32_bf16 v[38:41], v[212:215], v[188:191], v[38:41]
	v_mfma_f32_16x16x32_bf16 v[30:33], v[220:223], v[188:191], v[30:33]
	v_mfma_f32_16x16x32_bf16 v[22:25], v[212:215], v[196:199], v[22:25]
	v_mfma_f32_16x16x32_bf16 v[14:17], v[220:223], v[196:199], v[14:17]
	v_mfma_f32_16x16x32_bf16 v[6:9], v[212:215], v[204:207], v[6:9]
	v_mfma_f32_16x16x32_bf16 v[2:5], v[220:223], v[204:207], v[2:5]
	s_setprio 0
	s_add_i32 s48, s48, 2
	s_add_u32 s13, s13, 0x100
	s_addc_u32 s15, s15, 0
	s_add_u32 s24, s24, 0x100
	s_addc_u32 s25, s25, 0
	s_cmp_gt_u32 s48, 29
	s_barrier
	s_cbranch_scc0 .LBB0_1092
	s_lshl_b32 s22, s47, 8
	s_cmp_lt_i32 s47, 16
	s_cbranch_scc1 .LBB0_1109
	s_cmp_gt_u32 s47, 19
	s_mov_b64 s[26:27], -1
	s_cbranch_scc0 .LBB0_1107
	s_cmp_gt_u32 s47, 23
	s_cbranch_scc0 .LBB0_1104
	s_cmp_gt_u32 s47, 27
	s_cbranch_scc0 .LBB0_1101
	s_cmp_gt_u32 s47, 31
	s_mov_b64 s[20:21], -1
	s_cbranch_scc0 .LBB0_1099
	s_add_i32 s13, s22, 0xffffe000
	s_mov_b64 s[20:21], 0

; #define PG8_STAGE(bufoff, gbase, voff) do { _Pragma("unroll") for (int _i = 0; _i < 2; ++_i) \
;         __builtin_amdgcn_global_load_lds((const unsigned*)((const char*)(gbase) + (voff)[_i]), (LAS unsigned*)(lds + (bufoff) + ldsw + _i * 8192), 16, 0, 0); } while (0)
; #define PG8_LDA(dst, b, h) do { _Pragma("unroll") for (int m = 0; m < 4; ++m) _Pragma("unroll") for (int k = 0; k < 2; ++k) dst[m][k] = *(const LAS bf16x8*)(lds + PG8_SA(b, h) + aoff + m * 2048 + k * 1024); } while (0)
; #define PG8_LDB(dst, b, h) do { _Pragma("unroll") for (int n = 0; n < 2; ++n) _Pragma("unroll") for (int k = 0; k < 2; ++k) dst[n][k] = *(const LAS bf16x8*)(lds + PG8_SB(b, h) + boff + n * 2048 + k * 1024); } while (0)
; #define PG8_MMA(ai, bj, At, Bt) do { __builtin_amdgcn_s_setprio(1); _Pragma("unroll") for (int m = 0; m < 4; ++m) _Pragma("unroll") for (int n = 0; n < 2; ++n) _Pragma("unroll") for (int k = 0; k < 2; ++k) \
;         acc[ai][bj][m][n] = __builtin_amdgcn_mfma_f32_16x16x32_bf16(Bt[n][k], At[m][k], acc[ai][bj][m][n], 0, 0, 0); __builtin_amdgcn_s_setprio(0); } while (0)
; #define PG8_WAIT_L(n) asm volatile("s_waitcnt lgkmcnt(" #n ")" ::: "memory")
; #define PG8_BAR __builtin_amdgcn_s_barrier()
; #define PG8_SCHED __builtin_amdgcn_sched_barrier(0)
; template <class Sched, class Epi>
; __device__ __forceinline__ void gemm_phase(LAS unsigned char* lds, const Sched& S, const Epi& E, const int K, const int lda, const int ldb) {
;     ...
;             PG8_LDB(B0, 0, 0); PG8_SCHED; PG8_LDA(At, 0, 0); PG8_STAGE(PG8_SA(1, 1), a1 + hstepA, voffA);
;             PG8_WAIT_L(8); PG8_BAR; PG8_WAIT_L(0); PG8_MMA(0, 0, At, B0); PG8_BAR; PG8_SCHED;
;             PG8_LDB(B1, 0, 1); PG8_STAGE(PG8_SB(0, 0), b2, voffB);
;             PG8_BAR; PG8_WAIT_L(0); PG8_MMA(0, 1, At, B1); PG8_BAR;
;             PG8_LDA(At, 0, 1); PG8_STAGE(PG8_SA(0, 0), a2, voffA);
;             PG8_BAR; PG8_WAIT_L(0); if (!chalf) PG8_MMA(1, 0, At, B0); PG8_BAR; PG8_SCHED;
.LBB0_1390:
	s_add_u32 s22, s18, s20
	ds_read_b128 v[148:151], v143
	ds_read_b128 v[152:155], v143 offset:1024
	ds_read_b128 v[156:159], v143 offset:2048
	ds_read_b128 v[160:163], v143 offset:3072
	s_addc_u32 s23, s19, s21
	s_add_u32 s22, s22, 0x294d8100
	s_addc_u32 s23, s23, 0
	s_add_u32 s41, s26, s20
	s_addc_u32 s42, s27, s21
	s_cmpk_eq_i32 s20, 0xf00
	s_cselect_b32 s25, s13, s23
	s_cselect_b32 s24, s12, s22
	s_cselect_b32 s23, s15, s42
	s_cselect_b32 s22, s14, s41
	s_mov_b32 m0, s29
	v_lshl_add_u64 v[196:197], v[140:141], 0, s[20:21]
	ds_read_b128 v[164:167], v144
	ds_read_b128 v[168:171], v144 offset:1024
	ds_read_b128 v[172:175], v144 offset:2048
	ds_read_b128 v[176:179], v144 offset:3072
	ds_read_b128 v[180:183], v144 offset:4096
	ds_read_b128 v[184:187], v144 offset:5120
	ds_read_b128 v[188:191], v144 offset:6144
	ds_read_b128 v[192:195], v144 offset:7168
	global_load_lds_dwordx4 v[196:197], off
	v_lshl_add_u64 v[196:197], v[138:139], 0, s[20:21]
	s_mov_b32 m0, s30
	s_nop 0
	global_load_lds_dwordx4 v[196:197], off
	s_waitcnt lgkmcnt(8)
	s_barrier
	s_waitcnt lgkmcnt(0)
	s_setprio 1
	s_waitcnt lgkmcnt(0)
	v_mfma_f32_16x16x32_bf16 v[126:129], v[148:151], v[164:167], v[126:129]
	v_mfma_f32_16x16x32_bf16 v[122:125], v[156:159], v[164:167], v[122:125]
	v_mfma_f32_16x16x32_bf16 v[110:113], v[148:151], v[172:175], v[110:113]
	v_mfma_f32_16x16x32_bf16 v[106:109], v[156:159], v[172:175], v[106:109]
	v_mfma_f32_16x16x32_bf16 v[94:97], v[148:151], v[180:183], v[94:97]
	v_mfma_f32_16x16x32_bf16 v[90:93], v[156:159], v[180:183], v[90:93]
	v_mfma_f32_16x16x32_bf16 v[78:81], v[148:151], v[188:191], v[78:81]
	v_mfma_f32_16x16x32_bf16 v[74:77], v[156:159], v[188:191], v[74:77]
	v_mfma_f32_16x16x32_bf16 v[126:129], v[152:155], v[168:171], v[126:129]
	v_mfma_f32_16x16x32_bf16 v[122:125], v[160:163], v[168:171], v[122:125]
	v_mfma_f32_16x16x32_bf16 v[110:113], v[152:155], v[176:179], v[110:113]
	v_mfma_f32_16x16x32_bf16 v[106:109], v[160:163], v[176:179], v[106:109]
	v_mfma_f32_16x16x32_bf16 v[94:97], v[152:155], v[184:187], v[94:97]
	v_mfma_f32_16x16x32_bf16 v[90:93], v[160:163], v[184:187], v[90:93]
	v_mfma_f32_16x16x32_bf16 v[78:81], v[152:155], v[192:195], v[78:81]
	v_mfma_f32_16x16x32_bf16 v[74:77], v[160:163], v[192:195], v[74:77]
	s_setprio 0
	s_barrier
	s_mov_b32 m0, s31
	s_add_u32 s54, s22, s16
	s_addc_u32 s55, s23, s17
	ds_read_b128 v[196:199], v145
	ds_read_b128 v[200:203], v145 offset:1024
	ds_read_b128 v[204:207], v145 offset:2048
	ds_read_b128 v[208:211], v145 offset:3072
	global_load_lds_dwordx4 v132, s[22:23]
	s_add_u32 s56, s22, s16
	s_addc_u32 s57, s23, s17
	s_mov_b32 m0, s34
	s_nop 0
	global_load_lds_dwordx4 v136, s[22:23]
	s_barrier
	s_waitcnt lgkmcnt(0)
	s_setprio 1
	s_waitcnt lgkmcnt(0)
	v_mfma_f32_16x16x32_bf16 v[118:121], v[196:199], v[164:167], v[118:121]
	v_mfma_f32_16x16x32_bf16 v[114:117], v[204:207], v[164:167], v[114:117]
	v_mfma_f32_16x16x32_bf16 v[102:105], v[196:199], v[172:175], v[102:105]
	v_mfma_f32_16x16x32_bf16 v[98:101], v[204:207], v[172:175], v[98:101]
	v_mfma_f32_16x16x32_bf16 v[86:89], v[196:199], v[180:183], v[86:89]
	v_mfma_f32_16x16x32_bf16 v[82:85], v[204:207], v[180:183], v[82:85]
	v_mfma_f32_16x16x32_bf16 v[70:73], v[196:199], v[188:191], v[70:73]
	v_mfma_f32_16x16x32_bf16 v[66:69], v[204:207], v[188:191], v[66:69]
	v_mfma_f32_16x16x32_bf16 v[118:121], v[200:203], v[168:171], v[118:121]
	v_mfma_f32_16x16x32_bf16 v[114:117], v[208:211], v[168:171], v[114:117]
	v_mfma_f32_16x16x32_bf16 v[102:105], v[200:203], v[176:179], v[102:105]
	v_mfma_f32_16x16x32_bf16 v[98:101], v[208:211], v[176:179], v[98:101]
	v_mfma_f32_16x16x32_bf16 v[86:89], v[200:203], v[184:187], v[86:89]
	v_mfma_f32_16x16x32_bf16 v[82:85], v[208:211], v[184:187], v[82:85]
	v_mfma_f32_16x16x32_bf16 v[70:73], v[200:203], v[192:195], v[70:73]
	v_mfma_f32_16x16x32_bf16 v[66:69], v[208:211], v[192:195], v[66:69]
	s_setprio 0
	s_mov_b32 m0, s1
	s_add_u32 s58, s24, s16
	s_addc_u32 s59, s25, s17
	s_barrier
	ds_read_b128 v[164:167], v144 offset:16384
	ds_read_b128 v[168:171], v144 offset:17408
	ds_read_b128 v[172:175], v144 offset:18432
	ds_read_b128 v[176:179], v144 offset:19456
	ds_read_b128 v[180:183], v144 offset:20480
	ds_read_b128 v[184:187], v144 offset:21504
	ds_read_b128 v[188:191], v144 offset:22528
	ds_read_b128 v[192:195], v144 offset:23552
	global_load_lds_dwordx4 v130, s[24:25]
	s_add_u32 s60, s24, s16
	s_addc_u32 s61, s25, s17
	s_mov_b32 m0, s2
	s_nop 0
	global_load_lds_dwordx4 v134, s[24:25]
	s_barrier
	s_waitcnt lgkmcnt(0)
	s_setprio 1
	s_waitcnt lgkmcnt(0)
	v_mfma_f32_16x16x32_bf16 v[62:65], v[148:151], v[164:167], v[62:65]
	v_mfma_f32_16x16x32_bf16 v[58:61], v[156:159], v[164:167], v[58:61]
	v_mfma_f32_16x16x32_bf16 v[46:49], v[148:151], v[172:175], v[46:49]
	v_mfma_f32_16x16x32_bf16 v[42:45], v[156:159], v[172:175], v[42:45]
	v_mfma_f32_16x16x32_bf16 v[30:33], v[148:151], v[180:183], v[30:33]
	v_mfma_f32_16x16x32_bf16 v[26:29], v[156:159], v[180:183], v[26:29]
	v_mfma_f32_16x16x32_bf16 v[14:17], v[148:151], v[188:191], v[14:17]
	v_mfma_f32_16x16x32_bf16 v[10:13], v[156:159], v[188:191], v[10:13]
	v_mfma_f32_16x16x32_bf16 v[62:65], v[152:155], v[168:171], v[62:65]
	v_mfma_f32_16x16x32_bf16 v[58:61], v[160:163], v[168:171], v[58:61]
	v_mfma_f32_16x16x32_bf16 v[46:49], v[152:155], v[176:179], v[46:49]
	v_mfma_f32_16x16x32_bf16 v[42:45], v[160:163], v[176:179], v[42:45]
	v_mfma_f32_16x16x32_bf16 v[30:33], v[152:155], v[184:187], v[30:33]
	v_mfma_f32_16x16x32_bf16 v[26:29], v[160:163], v[184:187], v[26:29]
	v_mfma_f32_16x16x32_bf16 v[14:17], v[152:155], v[192:195], v[14:17]
	v_mfma_f32_16x16x32_bf16 v[10:13], v[160:163], v[192:195], v[10:13]
	s_setprio 0
	s_barrier
; #define PG8_STAGE(bufoff, gbase, voff) do { _Pragma("unroll") for (int _i = 0; _i < 2; ++_i) \
;         __builtin_amdgcn_global_load_lds((const unsigned*)((const char*)(gbase) + (voff)[_i]), (LAS unsigned*)(lds + (bufoff) + ldsw + _i * 8192), 16, 0, 0); } while (0)
; #define PG8_LDA(dst, b, h) do { _Pragma("unroll") for (int m = 0; m < 4; ++m) _Pragma("unroll") for (int k = 0; k < 2; ++k) dst[m][k] = *(const LAS bf16x8*)(lds + PG8_SA(b, h) + aoff + m * 2048 + k * 1024); } while (0)
; #define PG8_LDB(dst, b, h) do { _Pragma("unroll") for (int n = 0; n < 2; ++n) _Pragma("unroll") for (int k = 0; k < 2; ++k) dst[n][k] = *(const LAS bf16x8*)(lds + PG8_SB(b, h) + boff + n * 2048 + k * 1024); } while (0)
; #define PG8_MMA(ai, bj, At, Bt) do { __builtin_amdgcn_s_setprio(1); _Pragma("unroll") for (int m = 0; m < 4; ++m) _Pragma("unroll") for (int n = 0; n < 2; ++n) _Pragma("unroll") for (int k = 0; k < 2; ++k) \
;         acc[ai][bj][m][n] = __builtin_amdgcn_mfma_f32_16x16x32_bf16(Bt[n][k], At[m][k], acc[ai][bj][m][n], 0, 0, 0); __builtin_amdgcn_s_setprio(0); } while (0)
; #define PG8_WAIT_V(n) asm volatile("s_waitcnt vmcnt(" #n ")" ::: "memory")
; #define PG8_WAIT_L(n) asm volatile("s_waitcnt lgkmcnt(" #n ")" ::: "memory")
; #define PG8_BAR __builtin_amdgcn_s_barrier()
; #define PG8_SCHED __builtin_amdgcn_sched_barrier(0)
; template <class Sched, class Epi>
; __device__ __forceinline__ void gemm_phase(LAS unsigned char* lds, const Sched& S, const Epi& E, const int K, const int lda, const int ldb) {
;     ...
;             PG8_BAR; PG8_WAIT_L(0); if (!chalf) PG8_MMA(1, 0, At, B0); PG8_BAR; PG8_SCHED;
;             PG8_STAGE(PG8_SB(0, 1), b2 + hstepB, voffB);
;             PG8_WAIT_V(6); PG8_BAR; if (!chalf) PG8_MMA(1, 1, At, B1); PG8_BAR;
;             PG8_LDB(B0, 1, 0); PG8_SCHED; PG8_LDA(At, 1, 0); PG8_STAGE(PG8_SA(0, 1), a2 + hstepA, voffA);
;             PG8_WAIT_L(8); PG8_BAR; PG8_WAIT_L(0); PG8_MMA(0, 0, At, B0); PG8_BAR; PG8_SCHED;
;             PG8_LDB(B1, 1, 1); PG8_STAGE(PG8_SB(1, 0), b3, voffB);
;             PG8_BAR; PG8_WAIT_L(0); PG8_MMA(0, 1, At, B1); PG8_BAR;
;             PG8_LDA(At, 1, 1); PG8_STAGE(PG8_SA(1, 0), a3, voffA);
	s_add_u32 s42, s22, 0x80000
	s_addc_u32 s43, s23, 0
	s_mov_b32 m0, s35
	s_nop 0
	global_load_lds_dwordx4 v132, s[42:43]
	s_mov_b32 m0, s36
	s_nop 0
	global_load_lds_dwordx4 v136, s[42:43]
	s_waitcnt vmcnt(6)
	s_barrier
	s_setprio 1
	v_mfma_f32_16x16x32_bf16 v[54:57], v[196:199], v[164:167], v[54:57]
	v_mfma_f32_16x16x32_bf16 v[50:53], v[204:207], v[164:167], v[50:53]
	v_mfma_f32_16x16x32_bf16 v[38:41], v[196:199], v[172:175], v[38:41]
	v_mfma_f32_16x16x32_bf16 v[34:37], v[204:207], v[172:175], v[34:37]
	v_mfma_f32_16x16x32_bf16 v[22:25], v[196:199], v[180:183], v[22:25]
	v_mfma_f32_16x16x32_bf16 v[18:21], v[204:207], v[180:183], v[18:21]
	v_mfma_f32_16x16x32_bf16 v[6:9], v[196:199], v[188:191], v[6:9]
	v_mfma_f32_16x16x32_bf16 v[2:5], v[204:207], v[188:191], v[2:5]
	v_mfma_f32_16x16x32_bf16 v[54:57], v[200:203], v[168:171], v[54:57]
	v_mfma_f32_16x16x32_bf16 v[50:53], v[208:211], v[168:171], v[50:53]
	v_mfma_f32_16x16x32_bf16 v[38:41], v[200:203], v[176:179], v[38:41]
	v_mfma_f32_16x16x32_bf16 v[34:37], v[208:211], v[176:179], v[34:37]
	v_mfma_f32_16x16x32_bf16 v[22:25], v[200:203], v[184:187], v[22:25]
	v_mfma_f32_16x16x32_bf16 v[18:21], v[208:211], v[184:187], v[18:21]
	v_mfma_f32_16x16x32_bf16 v[6:9], v[200:203], v[192:195], v[6:9]
	v_mfma_f32_16x16x32_bf16 v[2:5], v[208:211], v[192:195], v[2:5]
	s_setprio 0
	s_barrier
	ds_read_b128 v[148:151], v146
	ds_read_b128 v[152:155], v146 offset:1024
	ds_read_b128 v[156:159], v146 offset:2048
	ds_read_b128 v[160:163], v146 offset:3072
	s_add_u32 s24, s24, 0x80000
	s_addc_u32 s25, s25, 0
	s_mov_b32 m0, s3
	ds_read_b128 v[164:167], v144 offset:32768
	ds_read_b128 v[168:171], v144 offset:33792
	ds_read_b128 v[172:175], v144 offset:34816
	ds_read_b128 v[176:179], v144 offset:35840
	ds_read_b128 v[180:183], v144 offset:36864
	ds_read_b128 v[184:187], v144 offset:37888
	ds_read_b128 v[188:191], v144 offset:38912
	ds_read_b128 v[192:195], v144 offset:39936
	global_load_lds_dwordx4 v130, s[24:25]
	s_mov_b32 m0, s7
	s_nop 0
	global_load_lds_dwordx4 v134, s[24:25]
	s_waitcnt lgkmcnt(8)
	s_barrier
	s_waitcnt lgkmcnt(0)
	s_setprio 1
	s_waitcnt lgkmcnt(0)
	v_mfma_f32_16x16x32_bf16 v[126:129], v[148:151], v[164:167], v[126:129]
	v_mfma_f32_16x16x32_bf16 v[122:125], v[156:159], v[164:167], v[122:125]
	v_mfma_f32_16x16x32_bf16 v[110:113], v[148:151], v[172:175], v[110:113]
	v_mfma_f32_16x16x32_bf16 v[106:109], v[156:159], v[172:175], v[106:109]
	v_mfma_f32_16x16x32_bf16 v[94:97], v[148:151], v[180:183], v[94:97]
	v_mfma_f32_16x16x32_bf16 v[90:93], v[156:159], v[180:183], v[90:93]
	v_mfma_f32_16x16x32_bf16 v[78:81], v[148:151], v[188:191], v[78:81]
	v_mfma_f32_16x16x32_bf16 v[74:77], v[156:159], v[188:191], v[74:77]
	v_mfma_f32_16x16x32_bf16 v[126:129], v[152:155], v[168:171], v[126:129]
	v_mfma_f32_16x16x32_bf16 v[122:125], v[160:163], v[168:171], v[122:125]
	v_mfma_f32_16x16x32_bf16 v[110:113], v[152:155], v[176:179], v[110:113]
	v_mfma_f32_16x16x32_bf16 v[106:109], v[160:163], v[176:179], v[106:109]
	v_mfma_f32_16x16x32_bf16 v[94:97], v[152:155], v[184:187], v[94:97]
	v_mfma_f32_16x16x32_bf16 v[90:93], v[160:163], v[184:187], v[90:93]
	v_mfma_f32_16x16x32_bf16 v[78:81], v[152:155], v[192:195], v[78:81]
	v_mfma_f32_16x16x32_bf16 v[74:77], v[160:163], v[192:195], v[74:77]
	s_setprio 0
	s_barrier
	s_mov_b32 m0, s37
	ds_read_b128 v[196:199], v147
	ds_read_b128 v[200:203], v147 offset:1024
	ds_read_b128 v[204:207], v147 offset:2048
	ds_read_b128 v[208:211], v147 offset:3072
	global_load_lds_dwordx4 v132, s[54:55]
	s_mov_b32 m0, s38
	s_nop 0
	global_load_lds_dwordx4 v136, s[56:57]
	s_barrier
	s_waitcnt lgkmcnt(0)
	s_setprio 1
	s_waitcnt lgkmcnt(0)
	v_mfma_f32_16x16x32_bf16 v[118:121], v[196:199], v[164:167], v[118:121]
	v_mfma_f32_16x16x32_bf16 v[114:117], v[204:207], v[164:167], v[114:117]
	v_mfma_f32_16x16x32_bf16 v[102:105], v[196:199], v[172:175], v[102:105]
	v_mfma_f32_16x16x32_bf16 v[98:101], v[204:207], v[172:175], v[98:101]
	v_mfma_f32_16x16x32_bf16 v[86:89], v[196:199], v[180:183], v[86:89]
	v_mfma_f32_16x16x32_bf16 v[82:85], v[204:207], v[180:183], v[82:85]
	v_mfma_f32_16x16x32_bf16 v[70:73], v[196:199], v[188:191], v[70:73]
	v_mfma_f32_16x16x32_bf16 v[66:69], v[204:207], v[188:191], v[66:69]
	v_mfma_f32_16x16x32_bf16 v[118:121], v[200:203], v[168:171], v[118:121]
	v_mfma_f32_16x16x32_bf16 v[114:117], v[208:211], v[168:171], v[114:117]
	v_mfma_f32_16x16x32_bf16 v[102:105], v[200:203], v[176:179], v[102:105]
	v_mfma_f32_16x16x32_bf16 v[98:101], v[208:211], v[176:179], v[98:101]
	v_mfma_f32_16x16x32_bf16 v[86:89], v[200:203], v[184:187], v[86:89]
	v_mfma_f32_16x16x32_bf16 v[82:85], v[208:211], v[184:187], v[82:85]
	v_mfma_f32_16x16x32_bf16 v[70:73], v[200:203], v[192:195], v[70:73]
	v_mfma_f32_16x16x32_bf16 v[66:69], v[208:211], v[192:195], v[66:69]
	s_setprio 0
	s_mov_b32 m0, s10
	s_barrier
	ds_read_b128 v[164:167], v144 offset:49152
	ds_read_b128 v[168:171], v144 offset:50176
	ds_read_b128 v[172:175], v144 offset:51200
	ds_read_b128 v[176:179], v144 offset:52224
	ds_read_b128 v[180:183], v144 offset:53248
	ds_read_b128 v[184:187], v144 offset:54272
	ds_read_b128 v[188:191], v144 offset:55296
	ds_read_b128 v[192:195], v144 offset:56320
	global_load_lds_dwordx4 v130, s[58:59]
	s_mov_b32 m0, s11
	s_nop 0
	global_load_lds_dwordx4 v134, s[60:61]
	s_barrier
; #define PG8_STAGE(bufoff, gbase, voff) do { _Pragma("unroll") for (int _i = 0; _i < 2; ++_i) \
;         __builtin_amdgcn_global_load_lds((const unsigned*)((const char*)(gbase) + (voff)[_i]), (LAS unsigned*)(lds + (bufoff) + ldsw + _i * 8192), 16, 0, 0); } while (0)
; #define PG8_MMA(ai, bj, At, Bt) do { __builtin_amdgcn_s_setprio(1); _Pragma("unroll") for (int m = 0; m < 4; ++m) _Pragma("unroll") for (int n = 0; n < 2; ++n) _Pragma("unroll") for (int k = 0; k < 2; ++k) \
;         acc[ai][bj][m][n] = __builtin_amdgcn_mfma_f32_16x16x32_bf16(Bt[n][k], At[m][k], acc[ai][bj][m][n], 0, 0, 0); __builtin_amdgcn_s_setprio(0); } while (0)
; #define PG8_WAIT_V(n) asm volatile("s_waitcnt vmcnt(" #n ")" ::: "memory")
; #define PG8_WAIT_L(n) asm volatile("s_waitcnt lgkmcnt(" #n ")" ::: "memory")
; #define PG8_BAR __builtin_amdgcn_s_barrier()
; #define PG8_SCHED __builtin_amdgcn_sched_barrier(0)
; template <class Sched, class Epi>
; __device__ __forceinline__ void gemm_phase(LAS unsigned char* lds, const Sched& S, const Epi& E, const int K, const int lda, const int ldb) {
;     ...
;             PG8_BAR; PG8_WAIT_L(0); if (!chalf) PG8_MMA(1, 0, At, B0); PG8_BAR; PG8_SCHED;
;             PG8_STAGE(PG8_SB(1, 1), b3 + hstepB, voffB);
;             PG8_WAIT_V(6); PG8_BAR; if (!chalf) PG8_MMA(1, 1, At, B1); PG8_BAR;
;         }
;     __device__ __forceinline__ void operator()(EPI_ARGS) const {
;     ...
;         for (int ai = 0; ai < 2; ++ai) if (ai == 0 || !u.half) { u32x4 zz[4][2];
; #pragma unroll
;             for (int m = 0; m < 4; ++m)
; #pragma unroll
;                 for (int bj = 0; bj < 2; ++bj) zz[m][bj] = *(const u32x4*)(parts + E_PZC + (size_t)EPI_ROW * 1024 + EPI_COL(bj));
	s_waitcnt lgkmcnt(0)
	s_setprio 1
	s_waitcnt lgkmcnt(0)
	v_mfma_f32_16x16x32_bf16 v[62:65], v[148:151], v[164:167], v[62:65]
	v_mfma_f32_16x16x32_bf16 v[58:61], v[156:159], v[164:167], v[58:61]
	v_mfma_f32_16x16x32_bf16 v[46:49], v[148:151], v[172:175], v[46:49]
	v_mfma_f32_16x16x32_bf16 v[42:45], v[156:159], v[172:175], v[42:45]
	v_mfma_f32_16x16x32_bf16 v[30:33], v[148:151], v[180:183], v[30:33]
	v_mfma_f32_16x16x32_bf16 v[26:29], v[156:159], v[180:183], v[26:29]
	v_mfma_f32_16x16x32_bf16 v[14:17], v[148:151], v[188:191], v[14:17]
	v_mfma_f32_16x16x32_bf16 v[10:13], v[156:159], v[188:191], v[10:13]
	v_mfma_f32_16x16x32_bf16 v[62:65], v[152:155], v[168:171], v[62:65]
	v_mfma_f32_16x16x32_bf16 v[58:61], v[160:163], v[168:171], v[58:61]
	v_mfma_f32_16x16x32_bf16 v[46:49], v[152:155], v[176:179], v[46:49]
	v_mfma_f32_16x16x32_bf16 v[42:45], v[160:163], v[176:179], v[42:45]
	v_mfma_f32_16x16x32_bf16 v[30:33], v[152:155], v[184:187], v[30:33]
	v_mfma_f32_16x16x32_bf16 v[26:29], v[160:163], v[184:187], v[26:29]
	v_mfma_f32_16x16x32_bf16 v[14:17], v[152:155], v[192:195], v[14:17]
	v_mfma_f32_16x16x32_bf16 v[10:13], v[160:163], v[192:195], v[10:13]
	s_setprio 0
	s_barrier
	s_add_u32 s22, s22, 0x80080
	s_addc_u32 s23, s23, 0
	s_mov_b32 m0, s39
	s_nop 0
	global_load_lds_dwordx4 v132, s[22:23]
	s_mov_b32 m0, s40
	s_nop 0
	global_load_lds_dwordx4 v136, s[22:23]
	s_waitcnt vmcnt(6)
	s_barrier
	s_setprio 1
	v_mfma_f32_16x16x32_bf16 v[54:57], v[196:199], v[164:167], v[54:57]
	v_mfma_f32_16x16x32_bf16 v[50:53], v[204:207], v[164:167], v[50:53]
	v_mfma_f32_16x16x32_bf16 v[38:41], v[196:199], v[172:175], v[38:41]
	v_mfma_f32_16x16x32_bf16 v[34:37], v[204:207], v[172:175], v[34:37]
	v_mfma_f32_16x16x32_bf16 v[22:25], v[196:199], v[180:183], v[22:25]
	v_mfma_f32_16x16x32_bf16 v[18:21], v[204:207], v[180:183], v[18:21]
	v_mfma_f32_16x16x32_bf16 v[6:9], v[196:199], v[188:191], v[6:9]
	v_mfma_f32_16x16x32_bf16 v[2:5], v[204:207], v[188:191], v[2:5]
	v_mfma_f32_16x16x32_bf16 v[54:57], v[200:203], v[168:171], v[54:57]
	v_mfma_f32_16x16x32_bf16 v[50:53], v[208:211], v[168:171], v[50:53]
	v_mfma_f32_16x16x32_bf16 v[38:41], v[200:203], v[176:179], v[38:41]
	v_mfma_f32_16x16x32_bf16 v[34:37], v[208:211], v[176:179], v[34:37]
	v_mfma_f32_16x16x32_bf16 v[22:25], v[200:203], v[184:187], v[22:25]
	v_mfma_f32_16x16x32_bf16 v[18:21], v[208:211], v[184:187], v[18:21]
	v_mfma_f32_16x16x32_bf16 v[6:9], v[200:203], v[192:195], v[6:9]
	v_mfma_f32_16x16x32_bf16 v[2:5], v[208:211], v[192:195], v[2:5]
	s_setprio 0
	s_add_i32 s28, s28, 2
	s_add_u32 s20, s20, 0x100
	s_addc_u32 s21, s21, 0
	s_cmp_gt_u32 s28, 29
	s_barrier
	s_cbranch_scc0 .LBB0_1390
	s_sext_i32_i8 s1, s6
	v_add_u32_e32 v152, s8, v1
	v_lshl_or_b32 v1, s1, 8, v142
	s_add_u32 s12, s4, 0x1b9d8000
	v_or_b32_e32 v130, s9, v1
	v_ashrrev_i32_e32 v153, 31, v152
	s_addc_u32 s13, s5, 0
	v_ashrrev_i32_e32 v131, 31, v130
	v_lshlrev_b64 v[132:133], 11, v[152:153]
	v_lshl_add_u64 v[134:135], s[12:13], 0, v[132:133]
	v_lshlrev_b64 v[150:151], 1, v[130:131]
	v_lshl_add_u64 v[130:131], v[134:135], 0, v[150:151]
	global_load_dwordx4 v[154:157], v[130:131], off
	global_load_dwordx4 v[158:161], v[130:131], off offset:256
	v_or_b32_e32 v130, 16, v152
	v_or_b32_e32 v134, 32, v152
	v_or_b32_e32 v136, 48, v152
	v_ashrrev_i32_e32 v131, 31, v130
	v_ashrrev_i32_e32 v135, 31, v134
	s_add_u32 s6, s4, 0x252d8000
	v_ashrrev_i32_e32 v137, 31, v136
	v_lshlrev_b64 v[130:131], 11, v[130:131]
	v_lshlrev_b64 v[134:135], 11, v[134:135]
	s_addc_u32 s7, s5, 0
	v_lshlrev_b64 v[136:137], 11, v[136:137]
	v_lshl_add_u64 v[130:131], s[12:13], 0, v[130:131]
	v_lshl_add_u64 v[134:135], s[12:13], 0, v[134:135]
	v_lshl_add_u64 v[136:137], s[12:13], 0, v[136:137]
	v_lshl_add_u64 v[132:133], s[6:7], 0, v[132:133]
	v_lshl_add_u64 v[130:131], v[130:131], 0, v[150:151]
	v_lshl_add_u64 v[134:135], v[134:135], 0, v[150:151]
	v_lshl_add_u64 v[166:167], v[136:137], 0, v[150:151]
	v_lshl_add_u64 v[168:169], v[132:133], 0, v[150:151]
	global_load_dwordx4 v[162:165], v[130:131], off
	global_load_dwordx4 v[146:149], v[130:131], off offset:256
	global_load_dwordx4 v[142:145], v[134:135], off
	global_load_dwordx4 v[138:141], v[134:135], off offset:256
	s_nop 0
	global_load_dwordx4 v[134:137], v[166:167], off
	global_load_dwordx4 v[130:133], v[166:167], off offset:256
	s_cmpk_lt_u32 s0, 0x100
	s_waitcnt vmcnt(0)
; __device__ __forceinline__ float siluf_(float x) { return x * __builtin_amdgcn_rcpf(1.0f + __expf(-x)); }
; __device__ __forceinline__ u32x4 pack8(const float (&f)[8]) { u32x4 r; r[0] = cvt_pk_bf16(f[0], f[1]); r[1] = cvt_pk_bf16(f[2], f[3]); r[2] = cvt_pk_bf16(f[4], f[5]); r[3] = cvt_pk_bf16(f[6], f[7]); return r; }
;     __device__ __forceinline__ void operator()(EPI_ARGS) const {
;     ...
;             for (int m = 0; m < 4; ++m)
; #pragma unroll
;                 for (int bj = 0; bj < 2; ++bj) { const f32x4 v0 = acc[ai][bj][m][0], v1 = acc[ai][bj][m][1]; float z[8]; unpack8(zz[m][bj], z); float o[8];
; #pragma unroll
;                     for (int j = 0; j < 4; ++j) { o[j] = v0[j] * siluf_(z[j]); o[4 + j] = v1[j] * siluf_(z[4 + j]); }
;                     *(u32x4*)(O + (size_t)EPI_ROW * 1024 + EPI_COL(bj)) = pack8(o); } }
	v_lshlrev_b32_e32 v1, 16, v154
	v_and_b32_e32 v153, 0xffff0000, v154
	v_lshlrev_b32_e32 v154, 16, v155
	v_and_b32_e32 v155, 0xffff0000, v155
	v_lshlrev_b32_e32 v166, 16, v156
	v_and_b32_e32 v156, 0xffff0000, v156
	v_lshlrev_b32_e32 v167, 16, v157
	v_and_b32_e32 v157, 0xffff0000, v157
	v_mul_f32_e32 v171, 0xbfb8aa3b, v1
	v_mul_f32_e32 v172, 0xbfb8aa3b, v166
	v_mul_f32_e32 v173, 0xbfb8aa3b, v153
	v_mul_f32_e32 v174, 0xbfb8aa3b, v156
	v_mul_f32_e32 v175, 0xbfb8aa3b, v154
	v_mul_f32_e32 v176, 0xbfb8aa3b, v167
	v_mul_f32_e32 v177, 0xbfb8aa3b, v155
	v_mul_f32_e32 v178, 0xbfb8aa3b, v157
	v_exp_f32_e32 v171, v171
	v_exp_f32_e32 v172, v172
	v_exp_f32_e32 v173, v173
	v_exp_f32_e32 v174, v174
	v_exp_f32_e32 v175, v175
	v_exp_f32_e32 v176, v176
	v_exp_f32_e32 v177, v177
	v_exp_f32_e32 v178, v178
	v_add_f32_e32 v171, 1.0, v171
	v_add_f32_e32 v172, 1.0, v172
	v_add_f32_e32 v173, 1.0, v173
	v_add_f32_e32 v174, 1.0, v174
	v_add_f32_e32 v175, 1.0, v175
	v_add_f32_e32 v176, 1.0, v176
	v_add_f32_e32 v177, 1.0, v177
	v_add_f32_e32 v178, 1.0, v178
	v_rcp_f32_e32 v171, v171
	v_rcp_f32_e32 v172, v172
	v_rcp_f32_e32 v173, v173
	v_rcp_f32_e32 v174, v174
	v_rcp_f32_e32 v175, v175
	v_rcp_f32_e32 v176, v176
	v_rcp_f32_e32 v177, v177
	v_rcp_f32_e32 v178, v178
	v_mul_f32_e32 v1, v171, v1
	v_mul_f32_e32 v166, v172, v166
	v_mul_f32_e32 v153, v173, v153
	v_mul_f32_e32 v156, v174, v156
	v_mul_f32_e32 v154, v175, v154
	v_mul_f32_e32 v167, v176, v167
	v_mul_f32_e32 v155, v177, v155
	v_lshlrev_b32_e32 v170, 16, v158
	v_mul_f32_e32 v157, v178, v157
	v_mul_f32_e32 v1, v126, v1
	v_mul_f32_e32 v126, v122, v166
	v_mul_f32_e32 v122, v127, v153
	v_mul_f32_e32 v127, v123, v156
	v_mul_f32_e32 v123, v128, v154
	v_mul_f32_e32 v128, v124, v167
	v_mul_f32_e32 v124, v129, v155
	v_mul_f32_e32 v125, v125, v157
	v_cvt_pk_bf16_f32 v122, v1, v122
	v_cvt_pk_bf16_f32 v123, v123, v124
	v_cvt_pk_bf16_f32 v124, v126, v127
	v_mul_f32_e32 v126, 0xbfb8aa3b, v170
	v_cvt_pk_bf16_f32 v125, v128, v125
	global_store_dwordx4 v[168:169], v[122:125], off
	v_exp_f32_e32 v126, v126
	v_and_b32_e32 v1, 0xffff0000, v158
	v_lshlrev_b32_e32 v124, 16, v160
	v_mul_f32_e32 v127, 0xbfb8aa3b, v124
	v_exp_f32_e32 v127, v127
	v_add_f32_e32 v126, 1.0, v126
	v_rcp_f32_e32 v126, v126
	v_and_b32_e32 v125, 0xffff0000, v160
	v_add_f32_e32 v127, 1.0, v127
	v_rcp_f32_e32 v127, v127
	v_mul_f32_e32 v126, v126, v170
	v_mul_f32_e32 v118, v118, v126
	v_mul_f32_e32 v126, 0xbfb8aa3b, v1
	v_mul_f32_e32 v124, v127, v124
	v_exp_f32_e32 v126, v126
	v_mul_f32_e32 v127, 0xbfb8aa3b, v125
	v_exp_f32_e32 v127, v127
	v_lshlrev_b32_e32 v122, 16, v159
	v_mul_f32_e32 v124, v114, v124
	v_add_f32_e32 v114, 1.0, v126
	v_rcp_f32_e32 v114, v114
	v_add_f32_e32 v126, 1.0, v127
	v_mul_f32_e32 v127, 0xbfb8aa3b, v122
	v_exp_f32_e32 v127, v127
	v_mul_f32_e32 v1, v114, v1
	v_rcp_f32_e32 v126, v126
	v_mul_f32_e32 v1, v119, v1
	v_add_f32_e32 v119, 1.0, v127
	v_rcp_f32_e32 v119, v119
	v_lshlrev_b32_e32 v128, 16, v161
	v_and_b32_e32 v123, 0xffff0000, v159
	v_mul_f32_e32 v114, v126, v125
	v_mul_f32_e32 v125, 0xbfb8aa3b, v128
	v_and_b32_e32 v129, 0xffff0000, v161
	v_exp_f32_e32 v125, v125
	v_mul_f32_e32 v126, v115, v114
	v_mul_f32_e32 v114, v119, v122
	v_mul_f32_e32 v119, 0xbfb8aa3b, v123
	v_mul_f32_e32 v115, v120, v114
	v_exp_f32_e32 v119, v119
	v_mul_f32_e32 v120, 0xbfb8aa3b, v129
	v_exp_f32_e32 v120, v120
	v_add_f32_e32 v114, 1.0, v125
	v_rcp_f32_e32 v114, v114
	v_add_f32_e32 v119, 1.0, v119
	v_rcp_f32_e32 v119, v119
	v_add_f32_e32 v120, 1.0, v120
	v_rcp_f32_e32 v120, v120
	v_mul_f32_e32 v114, v114, v128
	v_mul_f32_e32 v122, v116, v114
	v_mul_f32_e32 v114, v119, v123
	v_mul_f32_e32 v116, v121, v114
	v_mul_f32_e32 v114, v120, v129
	v_mul_f32_e32 v117, v117, v114
	v_cvt_pk_bf16_f32 v114, v118, v1
	v_cvt_pk_bf16_f32 v115, v115, v116
	v_cvt_pk_bf16_f32 v116, v124, v126
	v_cvt_pk_bf16_f32 v117, v122, v117
	v_lshlrev_b32_e32 v1, 16, v162
	global_store_dwordx4 v[168:169], v[114:117], off offset:256
	v_mul_f32_e32 v119, 0xbfb8aa3b, v1
	v_exp_f32_e32 v119, v119
	v_lshlrev_b32_e32 v117, 16, v164
	v_mul_f32_e32 v120, 0xbfb8aa3b, v117
	v_exp_f32_e32 v120, v120
	v_add_f32_e32 v119, 1.0, v119
	v_rcp_f32_e32 v119, v119
	v_and_b32_e32 v114, 0xffff0000, v162
	v_add_f32_e32 v120, 1.0, v120
	v_rcp_f32_e32 v120, v120
	v_and_b32_e32 v118, 0xffff0000, v164
	v_mul_f32_e32 v1, v119, v1
	v_mul_f32_e32 v1, v110, v1
	v_mul_f32_e32 v110, v120, v117
	v_mul_f32_e32 v117, 0xbfb8aa3b, v114
	v_mul_f32_e32 v119, 0xbfb8aa3b, v118
	v_exp_f32_e32 v117, v117
	v_exp_f32_e32 v119, v119
	v_lshlrev_b32_e32 v115, 16, v163
	v_mul_f32_e32 v110, v106, v110
	v_add_f32_e32 v106, 1.0, v117
	v_add_f32_e32 v117, 1.0, v119
	v_mul_f32_e32 v119, 0xbfb8aa3b, v115
	v_rcp_f32_e32 v106, v106
	v_exp_f32_e32 v119, v119
	v_rcp_f32_e32 v117, v117
	v_lshlrev_b32_e32 v121, 16, v165
	v_mul_f32_e32 v106, v106, v114
	v_add_f32_e32 v114, 1.0, v119
	v_rcp_f32_e32 v114, v114
	v_and_b32_e32 v116, 0xffff0000, v163
	v_mul_f32_e32 v106, v111, v106
	v_mul_f32_e32 v111, v117, v118
	v_mul_f32_e32 v117, 0xbfb8aa3b, v121
	v_exp_f32_e32 v117, v117
	v_mul_f32_e32 v111, v107, v111
	v_mul_f32_e32 v107, v114, v115
	v_mul_f32_e32 v114, 0xbfb8aa3b, v116
	v_exp_f32_e32 v114, v114
	v_and_b32_e32 v122, 0xffff0000, v165
	v_mul_f32_e32 v107, v112, v107
	v_add_f32_e32 v112, 1.0, v117
	v_mul_f32_e32 v115, 0xbfb8aa3b, v122
	v_rcp_f32_e32 v112, v112
	v_exp_f32_e32 v115, v115
	v_add_f32_e32 v114, 1.0, v114
	v_rcp_f32_e32 v114, v114
	v_mul_f32_e32 v112, v112, v121
	v_add_f32_e32 v115, 1.0, v115
	v_rcp_f32_e32 v115, v115
	v_mul_f32_e32 v112, v108, v112
	v_mul_f32_e32 v108, v114, v116
	v_mul_f32_e32 v108, v113, v108
	v_cvt_pk_bf16_f32 v106, v1, v106
; __device__ __forceinline__ float siluf_(float x) { return x * __builtin_amdgcn_rcpf(1.0f + __expf(-x)); }
; __device__ __forceinline__ u32x4 pack8(const float (&f)[8]) { u32x4 r; r[0] = cvt_pk_bf16(f[0], f[1]); r[1] = cvt_pk_bf16(f[2], f[3]); r[2] = cvt_pk_bf16(f[4], f[5]); r[3] = cvt_pk_bf16(f[6], f[7]); return r; }
;     __device__ __forceinline__ void operator()(EPI_ARGS) const {
;     ...
;             for (int m = 0; m < 4; ++m)
; #pragma unroll
;                 for (int bj = 0; bj < 2; ++bj) { const f32x4 v0 = acc[ai][bj][m][0], v1 = acc[ai][bj][m][1]; float z[8]; unpack8(zz[m][bj], z); float o[8];
; #pragma unroll
;                     for (int j = 0; j < 4; ++j) { o[j] = v0[j] * siluf_(z[j]); o[4 + j] = v1[j] * siluf_(z[4 + j]); }
;                     *(u32x4*)(O + (size_t)EPI_ROW * 1024 + EPI_COL(bj)) = pack8(o); } }
	v_cvt_pk_bf16_f32 v107, v107, v108
	v_cvt_pk_bf16_f32 v108, v110, v111
	v_add_u32_e32 v110, 16, v152
	v_ashrrev_i32_e32 v111, 31, v110
	v_mul_f32_e32 v113, v115, v122
	v_lshlrev_b64 v[110:111], 11, v[110:111]
	v_mul_f32_e32 v109, v109, v113
	v_lshl_add_u64 v[110:111], s[6:7], 0, v[110:111]
	v_cvt_pk_bf16_f32 v109, v112, v109
	v_lshl_add_u64 v[110:111], v[110:111], 0, v[150:151]
	v_lshlrev_b32_e32 v1, 16, v146
	global_store_dwordx4 v[110:111], v[106:109], off
	v_mul_f32_e32 v113, 0xbfb8aa3b, v1
	v_exp_f32_e32 v113, v113
	v_lshlrev_b32_e32 v109, 16, v148
	v_mul_f32_e32 v114, 0xbfb8aa3b, v109
	v_exp_f32_e32 v114, v114
	v_add_f32_e32 v113, 1.0, v113
	v_rcp_f32_e32 v113, v113
	v_and_b32_e32 v106, 0xffff0000, v146
	v_add_f32_e32 v114, 1.0, v114
	v_rcp_f32_e32 v114, v114
	v_and_b32_e32 v112, 0xffff0000, v148
	v_mul_f32_e32 v1, v113, v1
	v_mul_f32_e32 v1, v102, v1
	v_mul_f32_e32 v102, v114, v109
	v_mul_f32_e32 v109, 0xbfb8aa3b, v106
	v_mul_f32_e32 v113, 0xbfb8aa3b, v112
	v_exp_f32_e32 v109, v109
	v_exp_f32_e32 v113, v113
	v_lshlrev_b32_e32 v107, 16, v147
	v_mul_f32_e32 v102, v98, v102
	v_add_f32_e32 v98, 1.0, v109
	v_add_f32_e32 v109, 1.0, v113
	v_mul_f32_e32 v113, 0xbfb8aa3b, v107
	v_rcp_f32_e32 v98, v98
	v_exp_f32_e32 v113, v113
	v_rcp_f32_e32 v109, v109
	v_lshlrev_b32_e32 v115, 16, v149
	v_mul_f32_e32 v98, v98, v106
	v_add_f32_e32 v106, 1.0, v113
	v_rcp_f32_e32 v106, v106
	v_and_b32_e32 v108, 0xffff0000, v147
	v_mul_f32_e32 v98, v103, v98
	v_mul_f32_e32 v103, v109, v112
	v_mul_f32_e32 v109, 0xbfb8aa3b, v115
	v_and_b32_e32 v116, 0xffff0000, v149
	v_exp_f32_e32 v109, v109
	v_mul_f32_e32 v103, v99, v103
	v_mul_f32_e32 v99, v106, v107
	v_mul_f32_e32 v106, 0xbfb8aa3b, v108
	v_exp_f32_e32 v106, v106
	v_mul_f32_e32 v107, 0xbfb8aa3b, v116
	v_exp_f32_e32 v107, v107
	v_mul_f32_e32 v99, v104, v99
	v_add_f32_e32 v104, 1.0, v109
	v_rcp_f32_e32 v104, v104
	v_add_f32_e32 v106, 1.0, v106
	v_rcp_f32_e32 v106, v106
	v_add_f32_e32 v107, 1.0, v107
	v_rcp_f32_e32 v107, v107
	v_mul_f32_e32 v104, v104, v115
	v_mul_f32_e32 v104, v100, v104
	v_mul_f32_e32 v100, v106, v108
	v_mul_f32_e32 v100, v105, v100
	v_mul_f32_e32 v105, v107, v116
	v_mul_f32_e32 v101, v101, v105
	v_cvt_pk_bf16_f32 v98, v1, v98
	v_cvt_pk_bf16_f32 v99, v99, v100
	v_cvt_pk_bf16_f32 v100, v102, v103
	v_cvt_pk_bf16_f32 v101, v104, v101
	v_lshlrev_b32_e32 v1, 16, v142
	global_store_dwordx4 v[110:111], v[98:101], off offset:256
	v_mul_f32_e32 v103, 0xbfb8aa3b, v1
	v_exp_f32_e32 v103, v103
	v_lshlrev_b32_e32 v101, 16, v144
	v_mul_f32_e32 v104, 0xbfb8aa3b, v101
	v_exp_f32_e32 v104, v104
	v_add_f32_e32 v103, 1.0, v103
	v_rcp_f32_e32 v103, v103
	v_and_b32_e32 v98, 0xffff0000, v142
	v_add_f32_e32 v104, 1.0, v104
	v_rcp_f32_e32 v104, v104
	v_and_b32_e32 v102, 0xffff0000, v144
	v_mul_f32_e32 v1, v103, v1
	v_mul_f32_e32 v1, v94, v1
	v_mul_f32_e32 v94, v104, v101
	v_mul_f32_e32 v101, 0xbfb8aa3b, v98
	v_mul_f32_e32 v103, 0xbfb8aa3b, v102
	v_exp_f32_e32 v101, v101
	v_exp_f32_e32 v103, v103
	v_lshlrev_b32_e32 v99, 16, v143
	v_mul_f32_e32 v94, v90, v94
	v_add_f32_e32 v90, 1.0, v101
	v_add_f32_e32 v101, 1.0, v103
	v_mul_f32_e32 v103, 0xbfb8aa3b, v99
	v_rcp_f32_e32 v90, v90
	v_exp_f32_e32 v103, v103
	v_rcp_f32_e32 v101, v101
	v_lshlrev_b32_e32 v105, 16, v145
	v_mul_f32_e32 v90, v90, v98
	v_add_f32_e32 v98, 1.0, v103
	v_rcp_f32_e32 v98, v98
	v_and_b32_e32 v100, 0xffff0000, v143
	v_mul_f32_e32 v90, v95, v90
	v_mul_f32_e32 v95, v101, v102
	v_mul_f32_e32 v101, 0xbfb8aa3b, v105
	v_exp_f32_e32 v101, v101
	v_mul_f32_e32 v95, v91, v95
	v_mul_f32_e32 v91, v98, v99
	v_mul_f32_e32 v98, 0xbfb8aa3b, v100
	v_exp_f32_e32 v98, v98
	v_and_b32_e32 v106, 0xffff0000, v145
	v_mul_f32_e32 v91, v96, v91
	v_add_f32_e32 v96, 1.0, v101
	v_mul_f32_e32 v99, 0xbfb8aa3b, v106
	v_rcp_f32_e32 v96, v96
	v_exp_f32_e32 v99, v99
	v_add_f32_e32 v98, 1.0, v98
	v_rcp_f32_e32 v98, v98
	v_mul_f32_e32 v96, v96, v105
	v_add_f32_e32 v99, 1.0, v99
	v_rcp_f32_e32 v99, v99
	v_mul_f32_e32 v96, v92, v96
	v_mul_f32_e32 v92, v98, v100
	v_mul_f32_e32 v92, v97, v92
	v_cvt_pk_bf16_f32 v90, v1, v90
	v_cvt_pk_bf16_f32 v91, v91, v92
	v_cvt_pk_bf16_f32 v92, v94, v95
	v_add_u32_e32 v94, 32, v152
	v_ashrrev_i32_e32 v95, 31, v94
	v_mul_f32_e32 v97, v99, v106
	v_lshlrev_b64 v[94:95], 11, v[94:95]
	v_mul_f32_e32 v93, v93, v97
	v_lshl_add_u64 v[94:95], s[6:7], 0, v[94:95]
	v_cvt_pk_bf16_f32 v93, v96, v93
	v_lshl_add_u64 v[94:95], v[94:95], 0, v[150:151]
	v_lshlrev_b32_e32 v1, 16, v138
	global_store_dwordx4 v[94:95], v[90:93], off
	v_mul_f32_e32 v97, 0xbfb8aa3b, v1
	v_exp_f32_e32 v97, v97
	v_lshlrev_b32_e32 v93, 16, v140
	v_mul_f32_e32 v98, 0xbfb8aa3b, v93
	v_exp_f32_e32 v98, v98
	v_add_f32_e32 v97, 1.0, v97
	v_rcp_f32_e32 v97, v97
	v_and_b32_e32 v90, 0xffff0000, v138
	v_add_f32_e32 v98, 1.0, v98
	v_rcp_f32_e32 v98, v98
	v_and_b32_e32 v96, 0xffff0000, v140
	v_mul_f32_e32 v1, v97, v1
	v_mul_f32_e32 v1, v86, v1
	v_mul_f32_e32 v86, v98, v93
	v_mul_f32_e32 v93, 0xbfb8aa3b, v90
	v_mul_f32_e32 v97, 0xbfb8aa3b, v96
	v_exp_f32_e32 v93, v93
	v_exp_f32_e32 v97, v97
	v_lshlrev_b32_e32 v91, 16, v139
	v_mul_f32_e32 v86, v82, v86
	v_add_f32_e32 v82, 1.0, v93
	v_add_f32_e32 v93, 1.0, v97
	v_mul_f32_e32 v97, 0xbfb8aa3b, v91
	v_rcp_f32_e32 v82, v82
	v_exp_f32_e32 v97, v97
	v_rcp_f32_e32 v93, v93
	v_lshlrev_b32_e32 v99, 16, v141
	v_mul_f32_e32 v82, v82, v90
	v_add_f32_e32 v90, 1.0, v97
	v_rcp_f32_e32 v90, v90
	v_and_b32_e32 v92, 0xffff0000, v139
	v_mul_f32_e32 v82, v87, v82
	v_mul_f32_e32 v87, v93, v96
	v_mul_f32_e32 v93, 0xbfb8aa3b, v99
	v_and_b32_e32 v100, 0xffff0000, v141
	v_exp_f32_e32 v93, v93
	v_mul_f32_e32 v87, v83, v87
	v_mul_f32_e32 v83, v90, v91
	v_mul_f32_e32 v90, 0xbfb8aa3b, v92
; __device__ __forceinline__ float siluf_(float x) { return x * __builtin_amdgcn_rcpf(1.0f + __expf(-x)); }
; __device__ __forceinline__ u32x4 pack8(const float (&f)[8]) { u32x4 r; r[0] = cvt_pk_bf16(f[0], f[1]); r[1] = cvt_pk_bf16(f[2], f[3]); r[2] = cvt_pk_bf16(f[4], f[5]); r[3] = cvt_pk_bf16(f[6], f[7]); return r; }
;     __device__ __forceinline__ void operator()(EPI_ARGS) const {
;     ...
;         for (int ai = 0; ai < 2; ++ai) if (ai == 0 || !u.half) { u32x4 zz[4][2];
; #pragma unroll
;             for (int m = 0; m < 4; ++m)
; #pragma unroll
;                 for (int bj = 0; bj < 2; ++bj) zz[m][bj] = *(const u32x4*)(parts + E_PZC + (size_t)EPI_ROW * 1024 + EPI_COL(bj));
;     ...
;             for (int m = 0; m < 4; ++m)
; #pragma unroll
;                 for (int bj = 0; bj < 2; ++bj) { const f32x4 v0 = acc[ai][bj][m][0], v1 = acc[ai][bj][m][1]; float z[8]; unpack8(zz[m][bj], z); float o[8];
; #pragma unroll
;                     for (int j = 0; j < 4; ++j) { o[j] = v0[j] * siluf_(z[j]); o[4 + j] = v1[j] * siluf_(z[4 + j]); }
;                     *(u32x4*)(O + (size_t)EPI_ROW * 1024 + EPI_COL(bj)) = pack8(o); } }
	v_exp_f32_e32 v90, v90
	v_mul_f32_e32 v91, 0xbfb8aa3b, v100
	v_exp_f32_e32 v91, v91
	v_mul_f32_e32 v83, v88, v83
	v_add_f32_e32 v88, 1.0, v93
	v_rcp_f32_e32 v88, v88
	v_add_f32_e32 v90, 1.0, v90
	v_rcp_f32_e32 v90, v90
	v_add_f32_e32 v91, 1.0, v91
	v_rcp_f32_e32 v91, v91
	v_mul_f32_e32 v88, v88, v99
	v_mul_f32_e32 v88, v84, v88
	v_mul_f32_e32 v84, v90, v92
	v_mul_f32_e32 v84, v89, v84
	v_mul_f32_e32 v89, v91, v100
	v_mul_f32_e32 v85, v85, v89
	v_cvt_pk_bf16_f32 v82, v1, v82
	v_cvt_pk_bf16_f32 v83, v83, v84
	v_cvt_pk_bf16_f32 v84, v86, v87
	v_cvt_pk_bf16_f32 v85, v88, v85
	v_lshlrev_b32_e32 v1, 16, v134
	global_store_dwordx4 v[94:95], v[82:85], off offset:256
	v_mul_f32_e32 v87, 0xbfb8aa3b, v1
	v_exp_f32_e32 v87, v87
	v_lshlrev_b32_e32 v85, 16, v136
	v_mul_f32_e32 v88, 0xbfb8aa3b, v85
	v_exp_f32_e32 v88, v88
	v_add_f32_e32 v87, 1.0, v87
	v_rcp_f32_e32 v87, v87
	v_and_b32_e32 v82, 0xffff0000, v134
	v_add_f32_e32 v88, 1.0, v88
	v_rcp_f32_e32 v88, v88
	v_and_b32_e32 v86, 0xffff0000, v136
	v_mul_f32_e32 v1, v87, v1
	v_mul_f32_e32 v1, v78, v1
	v_mul_f32_e32 v78, v88, v85
	v_mul_f32_e32 v85, 0xbfb8aa3b, v82
	v_mul_f32_e32 v87, 0xbfb8aa3b, v86
	v_exp_f32_e32 v85, v85
	v_exp_f32_e32 v87, v87
	v_lshlrev_b32_e32 v83, 16, v135
	v_mul_f32_e32 v78, v74, v78
	v_add_f32_e32 v74, 1.0, v85
	v_add_f32_e32 v85, 1.0, v87
	v_mul_f32_e32 v87, 0xbfb8aa3b, v83
	v_rcp_f32_e32 v74, v74
	v_exp_f32_e32 v87, v87
	v_rcp_f32_e32 v85, v85
	v_lshlrev_b32_e32 v89, 16, v137
	v_mul_f32_e32 v74, v74, v82
	v_add_f32_e32 v82, 1.0, v87
	v_rcp_f32_e32 v82, v82
	v_and_b32_e32 v84, 0xffff0000, v135
	v_mul_f32_e32 v74, v79, v74
	v_mul_f32_e32 v79, v85, v86
	v_mul_f32_e32 v85, 0xbfb8aa3b, v89
	v_exp_f32_e32 v85, v85
	v_mul_f32_e32 v79, v75, v79
	v_mul_f32_e32 v75, v82, v83
	v_mul_f32_e32 v82, 0xbfb8aa3b, v84
	v_exp_f32_e32 v82, v82
	v_and_b32_e32 v90, 0xffff0000, v137
	v_mul_f32_e32 v75, v80, v75
	v_add_f32_e32 v80, 1.0, v85
	v_mul_f32_e32 v83, 0xbfb8aa3b, v90
	v_rcp_f32_e32 v80, v80
	v_exp_f32_e32 v83, v83
	v_add_f32_e32 v82, 1.0, v82
	v_rcp_f32_e32 v82, v82
	v_mul_f32_e32 v80, v80, v89
	v_add_f32_e32 v83, 1.0, v83
	v_rcp_f32_e32 v83, v83
	v_mul_f32_e32 v80, v76, v80
	v_mul_f32_e32 v76, v82, v84
	v_mul_f32_e32 v76, v81, v76
	v_cvt_pk_bf16_f32 v74, v1, v74
	v_cvt_pk_bf16_f32 v75, v75, v76
	v_cvt_pk_bf16_f32 v76, v78, v79
	v_add_u32_e32 v78, 48, v152
	v_ashrrev_i32_e32 v79, 31, v78
	v_mul_f32_e32 v81, v83, v90
	v_lshlrev_b64 v[78:79], 11, v[78:79]
	v_mul_f32_e32 v77, v77, v81
	v_lshl_add_u64 v[78:79], s[6:7], 0, v[78:79]
	v_cvt_pk_bf16_f32 v77, v80, v77
	v_lshl_add_u64 v[78:79], v[78:79], 0, v[150:151]
	v_lshlrev_b32_e32 v1, 16, v130
	global_store_dwordx4 v[78:79], v[74:77], off
	v_mul_f32_e32 v81, 0xbfb8aa3b, v1
	v_exp_f32_e32 v81, v81
	v_lshlrev_b32_e32 v77, 16, v132
	v_mul_f32_e32 v82, 0xbfb8aa3b, v77
	v_exp_f32_e32 v82, v82
	v_add_f32_e32 v81, 1.0, v81
	v_rcp_f32_e32 v81, v81
	v_and_b32_e32 v74, 0xffff0000, v130
	v_add_f32_e32 v82, 1.0, v82
	v_rcp_f32_e32 v82, v82
	v_and_b32_e32 v80, 0xffff0000, v132
	v_mul_f32_e32 v1, v81, v1
	v_mul_f32_e32 v1, v70, v1
	v_mul_f32_e32 v70, v82, v77
	v_mul_f32_e32 v77, 0xbfb8aa3b, v74
	v_mul_f32_e32 v81, 0xbfb8aa3b, v80
	v_exp_f32_e32 v77, v77
	v_exp_f32_e32 v81, v81
	v_lshlrev_b32_e32 v75, 16, v131
	v_mul_f32_e32 v70, v66, v70
	v_add_f32_e32 v66, 1.0, v77
	v_add_f32_e32 v77, 1.0, v81
	v_mul_f32_e32 v81, 0xbfb8aa3b, v75
	v_rcp_f32_e32 v66, v66
	v_exp_f32_e32 v81, v81
	v_rcp_f32_e32 v77, v77
	v_lshlrev_b32_e32 v83, 16, v133
	v_mul_f32_e32 v66, v66, v74
	v_add_f32_e32 v74, 1.0, v81
	v_rcp_f32_e32 v74, v74
	v_and_b32_e32 v76, 0xffff0000, v131
	v_mul_f32_e32 v66, v71, v66
	v_mul_f32_e32 v71, v77, v80
	v_mul_f32_e32 v77, 0xbfb8aa3b, v83
	v_exp_f32_e32 v77, v77
	v_mul_f32_e32 v71, v67, v71
	v_mul_f32_e32 v67, v74, v75
	v_mul_f32_e32 v74, 0xbfb8aa3b, v76
	v_exp_f32_e32 v74, v74
	v_and_b32_e32 v84, 0xffff0000, v133
	v_mul_f32_e32 v67, v72, v67
	v_add_f32_e32 v72, 1.0, v77
	v_rcp_f32_e32 v72, v72
	v_mul_f32_e32 v75, 0xbfb8aa3b, v84
	v_add_f32_e32 v74, 1.0, v74
	v_exp_f32_e32 v75, v75
	v_rcp_f32_e32 v74, v74
	v_mul_f32_e32 v72, v72, v83
	v_mul_f32_e32 v72, v68, v72
	v_add_f32_e32 v75, 1.0, v75
	v_mul_f32_e32 v68, v74, v76
	v_rcp_f32_e32 v75, v75
	v_mul_f32_e32 v68, v73, v68
	v_cvt_pk_bf16_f32 v66, v1, v66
	v_cvt_pk_bf16_f32 v67, v67, v68
	v_cvt_pk_bf16_f32 v68, v70, v71
	v_add_u32_e32 v70, 0x80, v152
	v_ashrrev_i32_e32 v71, 31, v70
	v_lshlrev_b64 v[104:105], 11, v[70:71]
	v_mul_f32_e32 v73, v75, v84
	v_lshl_add_u64 v[70:71], s[12:13], 0, v[104:105]
	v_mul_f32_e32 v69, v69, v73
	v_lshl_add_u64 v[70:71], v[70:71], 0, v[150:151]
	v_cvt_pk_bf16_f32 v69, v72, v69
	global_load_dwordx4 v[92:95], v[70:71], off
	s_nop 0
	global_store_dwordx4 v[78:79], v[66:69], off offset:256
	global_load_dwordx4 v[96:99], v[70:71], off offset:256
	s_waitcnt vmcnt(0)
; __device__ __forceinline__ float siluf_(float x) { return x * __builtin_amdgcn_rcpf(1.0f + __expf(-x)); }
; __device__ __forceinline__ u32x4 pack8(const float (&f)[8]) { u32x4 r; r[0] = cvt_pk_bf16(f[0], f[1]); r[1] = cvt_pk_bf16(f[2], f[3]); r[2] = cvt_pk_bf16(f[4], f[5]); r[3] = cvt_pk_bf16(f[6], f[7]); return r; }
;     __device__ __forceinline__ void operator()(EPI_ARGS) const {
;     ...
;         for (int ai = 0; ai < 2; ++ai) if (ai == 0 || !u.half) { u32x4 zz[4][2];
; #pragma unroll
;             for (int m = 0; m < 4; ++m)
; #pragma unroll
;                 for (int bj = 0; bj < 2; ++bj) zz[m][bj] = *(const u32x4*)(parts + E_PZC + (size_t)EPI_ROW * 1024 + EPI_COL(bj));
; #pragma unroll
;             for (int m = 0; m < 4; ++m)
; #pragma unroll
;                 for (int bj = 0; bj < 2; ++bj) { const f32x4 v0 = acc[ai][bj][m][0], v1 = acc[ai][bj][m][1]; float z[8]; unpack8(zz[m][bj], z); float o[8];
; #pragma unroll
;                     for (int j = 0; j < 4; ++j) { o[j] = v0[j] * siluf_(z[j]); o[4 + j] = v1[j] * siluf_(z[4 + j]); }
;                     *(u32x4*)(O + (size_t)EPI_ROW * 1024 + EPI_COL(bj)) = pack8(o); } }
	v_lshlrev_b32_e32 v1, 16, v92
	v_add_u32_e32 v66, 0x90, v152
	v_ashrrev_i32_e32 v67, 31, v66
	v_lshlrev_b64 v[90:91], 11, v[66:67]
	v_lshl_add_u64 v[66:67], s[12:13], 0, v[90:91]
	v_lshl_add_u64 v[66:67], v[66:67], 0, v[150:151]
	global_load_dwordx4 v[100:103], v[66:67], off
	global_load_dwordx4 v[82:85], v[66:67], off offset:256
	v_add_u32_e32 v66, 0xa0, v152
	v_ashrrev_i32_e32 v67, 31, v66
	v_lshlrev_b64 v[88:89], 11, v[66:67]
	v_lshl_add_u64 v[66:67], s[12:13], 0, v[88:89]
	v_lshl_add_u64 v[66:67], v[66:67], 0, v[150:151]
	global_load_dwordx4 v[78:81], v[66:67], off
	global_load_dwordx4 v[74:77], v[66:67], off offset:256
	v_add_u32_e32 v66, 0xb0, v152
	v_ashrrev_i32_e32 v67, 31, v66
	v_lshlrev_b64 v[86:87], 11, v[66:67]
	v_lshl_add_u64 v[66:67], s[12:13], 0, v[86:87]
	v_lshl_add_u64 v[106:107], v[66:67], 0, v[150:151]
	global_load_dwordx4 v[70:73], v[106:107], off
	global_load_dwordx4 v[66:69], v[106:107], off offset:256
	v_lshlrev_b32_e32 v107, 16, v94
	v_mul_f32_e32 v108, 0xbfb8aa3b, v1
	v_exp_f32_e32 v108, v108
	v_mul_f32_e32 v109, 0xbfb8aa3b, v107
	v_exp_f32_e32 v109, v109
	v_and_b32_e32 v92, 0xffff0000, v92
	v_add_f32_e32 v108, 1.0, v108
	v_rcp_f32_e32 v108, v108
	v_add_f32_e32 v109, 1.0, v109
	v_rcp_f32_e32 v109, v109
	v_and_b32_e32 v94, 0xffff0000, v94
	v_mul_f32_e32 v1, v108, v1
	v_mul_f32_e32 v1, v62, v1
	v_mul_f32_e32 v62, v109, v107
	v_mul_f32_e32 v107, 0xbfb8aa3b, v92
	v_mul_f32_e32 v108, 0xbfb8aa3b, v94
	v_exp_f32_e32 v107, v107
	v_exp_f32_e32 v108, v108
	v_lshlrev_b32_e32 v106, 16, v93
	v_mul_f32_e32 v62, v58, v62
	v_add_f32_e32 v58, 1.0, v107
	v_add_f32_e32 v107, 1.0, v108
	v_mul_f32_e32 v108, 0xbfb8aa3b, v106
	v_rcp_f32_e32 v58, v58
	v_exp_f32_e32 v108, v108
	v_rcp_f32_e32 v107, v107
	v_lshlrev_b32_e32 v110, 16, v95
	v_mul_f32_e32 v58, v58, v92
	v_add_f32_e32 v92, 1.0, v108
	v_mul_f32_e32 v58, v63, v58
	v_mul_f32_e32 v63, v107, v94
	v_rcp_f32_e32 v92, v92
	v_mul_f32_e32 v94, 0xbfb8aa3b, v110
	v_exp_f32_e32 v94, v94
	v_and_b32_e32 v93, 0xffff0000, v93
	v_and_b32_e32 v95, 0xffff0000, v95
	v_mul_f32_e32 v63, v59, v63
	v_mul_f32_e32 v59, v92, v106
	v_mul_f32_e32 v92, 0xbfb8aa3b, v93
	v_mul_f32_e32 v59, v64, v59
	v_add_f32_e32 v64, 1.0, v94
	v_exp_f32_e32 v92, v92
	v_mul_f32_e32 v94, 0xbfb8aa3b, v95
	v_exp_f32_e32 v94, v94
	v_rcp_f32_e32 v64, v64
	v_add_f32_e32 v92, 1.0, v92
	v_rcp_f32_e32 v92, v92
	v_add_f32_e32 v94, 1.0, v94
	v_rcp_f32_e32 v94, v94
	v_mul_f32_e32 v64, v64, v110
	v_mul_f32_e32 v64, v60, v64
	v_mul_f32_e32 v60, v92, v93
	v_mul_f32_e32 v60, v65, v60
	v_mul_f32_e32 v65, v94, v95
	v_mul_f32_e32 v61, v61, v65
	v_cvt_pk_bf16_f32 v58, v1, v58
	v_cvt_pk_bf16_f32 v59, v59, v60
	v_cvt_pk_bf16_f32 v60, v62, v63
	v_lshl_add_u64 v[62:63], s[6:7], 0, v[104:105]
	v_cvt_pk_bf16_f32 v61, v64, v61
	v_lshl_add_u64 v[62:63], v[62:63], 0, v[150:151]
	v_lshlrev_b32_e32 v1, 16, v96
	global_store_dwordx4 v[62:63], v[58:61], off
	v_mul_f32_e32 v65, 0xbfb8aa3b, v1
	v_exp_f32_e32 v65, v65
	v_lshlrev_b32_e32 v61, 16, v98
	v_mul_f32_e32 v92, 0xbfb8aa3b, v61
	v_exp_f32_e32 v92, v92
	v_add_f32_e32 v65, 1.0, v65
	v_rcp_f32_e32 v65, v65
	v_and_b32_e32 v58, 0xffff0000, v96
	v_add_f32_e32 v92, 1.0, v92
	v_rcp_f32_e32 v92, v92
	v_and_b32_e32 v64, 0xffff0000, v98
	v_mul_f32_e32 v1, v65, v1
	v_mul_f32_e32 v1, v54, v1
	v_mul_f32_e32 v54, v92, v61
	v_mul_f32_e32 v61, 0xbfb8aa3b, v58
	v_mul_f32_e32 v65, 0xbfb8aa3b, v64
	v_exp_f32_e32 v61, v61
	v_exp_f32_e32 v65, v65
	v_lshlrev_b32_e32 v59, 16, v97
	v_mul_f32_e32 v54, v50, v54
	v_add_f32_e32 v50, 1.0, v61
	v_add_f32_e32 v61, 1.0, v65
	v_mul_f32_e32 v65, 0xbfb8aa3b, v59
	v_rcp_f32_e32 v50, v50
	v_exp_f32_e32 v65, v65
	v_rcp_f32_e32 v61, v61
	v_lshlrev_b32_e32 v93, 16, v99
	v_mul_f32_e32 v50, v50, v58
	v_add_f32_e32 v58, 1.0, v65
	v_rcp_f32_e32 v58, v58
	v_and_b32_e32 v60, 0xffff0000, v97
	v_mul_f32_e32 v50, v55, v50
	v_mul_f32_e32 v55, v61, v64
	v_mul_f32_e32 v61, 0xbfb8aa3b, v93
	v_and_b32_e32 v94, 0xffff0000, v99
	v_exp_f32_e32 v61, v61
	v_mul_f32_e32 v55, v51, v55
	v_mul_f32_e32 v51, v58, v59
	v_mul_f32_e32 v58, 0xbfb8aa3b, v60
	v_exp_f32_e32 v58, v58
	v_mul_f32_e32 v59, 0xbfb8aa3b, v94
	v_exp_f32_e32 v59, v59
	v_mul_f32_e32 v51, v56, v51
	v_add_f32_e32 v56, 1.0, v61
	v_rcp_f32_e32 v56, v56
	v_add_f32_e32 v58, 1.0, v58
	v_rcp_f32_e32 v58, v58
	v_add_f32_e32 v59, 1.0, v59
	v_rcp_f32_e32 v59, v59
	v_mul_f32_e32 v56, v56, v93
	v_mul_f32_e32 v56, v52, v56
	v_mul_f32_e32 v52, v58, v60
	v_mul_f32_e32 v52, v57, v52
	v_mul_f32_e32 v57, v59, v94
	v_mul_f32_e32 v53, v53, v57
	v_cvt_pk_bf16_f32 v50, v1, v50
	v_cvt_pk_bf16_f32 v51, v51, v52
	v_cvt_pk_bf16_f32 v52, v54, v55
	v_cvt_pk_bf16_f32 v53, v56, v53
	s_waitcnt vmcnt(0)
; __device__ __forceinline__ float siluf_(float x) { return x * __builtin_amdgcn_rcpf(1.0f + __expf(-x)); }
; __device__ __forceinline__ u32x4 pack8(const float (&f)[8]) { u32x4 r; r[0] = cvt_pk_bf16(f[0], f[1]); r[1] = cvt_pk_bf16(f[2], f[3]); r[2] = cvt_pk_bf16(f[4], f[5]); r[3] = cvt_pk_bf16(f[6], f[7]); return r; }
;     __device__ __forceinline__ void operator()(EPI_ARGS) const {
;     ...
;             for (int m = 0; m < 4; ++m)
; #pragma unroll
;                 for (int bj = 0; bj < 2; ++bj) { const f32x4 v0 = acc[ai][bj][m][0], v1 = acc[ai][bj][m][1]; float z[8]; unpack8(zz[m][bj], z); float o[8];
; #pragma unroll
;                     for (int j = 0; j < 4; ++j) { o[j] = v0[j] * siluf_(z[j]); o[4 + j] = v1[j] * siluf_(z[4 + j]); }
;                     *(u32x4*)(O + (size_t)EPI_ROW * 1024 + EPI_COL(bj)) = pack8(o); } }
	v_lshlrev_b32_e32 v1, 16, v100
	global_store_dwordx4 v[62:63], v[50:53], off offset:256
	v_mul_f32_e32 v55, 0xbfb8aa3b, v1
	v_exp_f32_e32 v55, v55
	v_lshlrev_b32_e32 v53, 16, v102
	v_mul_f32_e32 v56, 0xbfb8aa3b, v53
	v_exp_f32_e32 v56, v56
	v_add_f32_e32 v55, 1.0, v55
	v_rcp_f32_e32 v55, v55
	v_and_b32_e32 v50, 0xffff0000, v100
	v_add_f32_e32 v56, 1.0, v56
	v_rcp_f32_e32 v56, v56
	v_and_b32_e32 v54, 0xffff0000, v102
	v_mul_f32_e32 v1, v55, v1
	v_mul_f32_e32 v1, v46, v1
	v_mul_f32_e32 v46, v56, v53
	v_mul_f32_e32 v53, 0xbfb8aa3b, v50
	v_mul_f32_e32 v55, 0xbfb8aa3b, v54
	v_exp_f32_e32 v53, v53
	v_exp_f32_e32 v55, v55
	v_lshlrev_b32_e32 v51, 16, v101
	v_mul_f32_e32 v46, v42, v46
	v_add_f32_e32 v42, 1.0, v53
	v_add_f32_e32 v53, 1.0, v55
	v_mul_f32_e32 v55, 0xbfb8aa3b, v51
	v_rcp_f32_e32 v42, v42
	v_exp_f32_e32 v55, v55
	v_rcp_f32_e32 v53, v53
	v_lshlrev_b32_e32 v57, 16, v103
	v_mul_f32_e32 v42, v42, v50
	v_add_f32_e32 v50, 1.0, v55
	v_rcp_f32_e32 v50, v50
	v_and_b32_e32 v52, 0xffff0000, v101
	v_mul_f32_e32 v42, v47, v42
	v_mul_f32_e32 v47, v53, v54
	v_mul_f32_e32 v53, 0xbfb8aa3b, v57
	v_and_b32_e32 v58, 0xffff0000, v103
	v_exp_f32_e32 v53, v53
	v_mul_f32_e32 v47, v43, v47
	v_mul_f32_e32 v43, v50, v51
	v_mul_f32_e32 v50, 0xbfb8aa3b, v52
	v_exp_f32_e32 v50, v50
	v_mul_f32_e32 v51, 0xbfb8aa3b, v58
	v_exp_f32_e32 v51, v51
	v_mul_f32_e32 v43, v48, v43
	v_add_f32_e32 v48, 1.0, v53
	v_rcp_f32_e32 v48, v48
	v_add_f32_e32 v50, 1.0, v50
	v_rcp_f32_e32 v50, v50
	v_add_f32_e32 v51, 1.0, v51
	v_rcp_f32_e32 v51, v51
	v_mul_f32_e32 v48, v48, v57
	v_mul_f32_e32 v48, v44, v48
	v_mul_f32_e32 v44, v50, v52
	v_mul_f32_e32 v44, v49, v44
	v_mul_f32_e32 v49, v51, v58
	v_mul_f32_e32 v45, v45, v49
	v_cvt_pk_bf16_f32 v42, v1, v42
	v_cvt_pk_bf16_f32 v43, v43, v44
	v_cvt_pk_bf16_f32 v44, v46, v47
	v_lshl_add_u64 v[46:47], s[6:7], 0, v[90:91]
	v_cvt_pk_bf16_f32 v45, v48, v45
	v_lshl_add_u64 v[46:47], v[46:47], 0, v[150:151]
	v_lshlrev_b32_e32 v1, 16, v82
	global_store_dwordx4 v[46:47], v[42:45], off
	v_mul_f32_e32 v49, 0xbfb8aa3b, v1
	v_exp_f32_e32 v49, v49
	v_lshlrev_b32_e32 v45, 16, v84
	v_mul_f32_e32 v50, 0xbfb8aa3b, v45
	v_exp_f32_e32 v50, v50
	v_add_f32_e32 v49, 1.0, v49
	v_rcp_f32_e32 v49, v49
	v_and_b32_e32 v42, 0xffff0000, v82
	v_add_f32_e32 v50, 1.0, v50
	v_rcp_f32_e32 v50, v50
	v_and_b32_e32 v48, 0xffff0000, v84
	v_mul_f32_e32 v1, v49, v1
	v_mul_f32_e32 v1, v38, v1
	v_mul_f32_e32 v38, v50, v45
	v_mul_f32_e32 v45, 0xbfb8aa3b, v42
	v_mul_f32_e32 v49, 0xbfb8aa3b, v48
	v_exp_f32_e32 v45, v45
	v_exp_f32_e32 v49, v49
	v_lshlrev_b32_e32 v43, 16, v83
	v_mul_f32_e32 v38, v34, v38
	v_add_f32_e32 v34, 1.0, v45
	v_add_f32_e32 v45, 1.0, v49
	v_mul_f32_e32 v49, 0xbfb8aa3b, v43
	v_rcp_f32_e32 v34, v34
	v_exp_f32_e32 v49, v49
	v_rcp_f32_e32 v45, v45
	v_lshlrev_b32_e32 v51, 16, v85
	v_mul_f32_e32 v34, v34, v42
	v_add_f32_e32 v42, 1.0, v49
	v_rcp_f32_e32 v42, v42
	v_and_b32_e32 v44, 0xffff0000, v83
	v_mul_f32_e32 v34, v39, v34
	v_mul_f32_e32 v39, v45, v48
	v_mul_f32_e32 v45, 0xbfb8aa3b, v51
	v_and_b32_e32 v52, 0xffff0000, v85
	v_exp_f32_e32 v45, v45
	v_mul_f32_e32 v39, v35, v39
	v_mul_f32_e32 v35, v42, v43
	v_mul_f32_e32 v42, 0xbfb8aa3b, v44
	v_exp_f32_e32 v42, v42
	v_mul_f32_e32 v43, 0xbfb8aa3b, v52
	v_exp_f32_e32 v43, v43
	v_mul_f32_e32 v35, v40, v35
	v_add_f32_e32 v40, 1.0, v45
	v_rcp_f32_e32 v40, v40
	v_add_f32_e32 v42, 1.0, v42
	v_rcp_f32_e32 v42, v42
	v_add_f32_e32 v43, 1.0, v43
	v_rcp_f32_e32 v43, v43
	v_mul_f32_e32 v40, v40, v51
	v_mul_f32_e32 v40, v36, v40
	v_mul_f32_e32 v36, v42, v44
	v_mul_f32_e32 v36, v41, v36
	v_mul_f32_e32 v41, v43, v52
	v_mul_f32_e32 v37, v37, v41
	v_cvt_pk_bf16_f32 v34, v1, v34
	v_cvt_pk_bf16_f32 v35, v35, v36
	v_cvt_pk_bf16_f32 v36, v38, v39
	v_cvt_pk_bf16_f32 v37, v40, v37
	v_lshlrev_b32_e32 v1, 16, v78
	global_store_dwordx4 v[46:47], v[34:37], off offset:256
	v_mul_f32_e32 v39, 0xbfb8aa3b, v1
	v_exp_f32_e32 v39, v39
	v_lshlrev_b32_e32 v37, 16, v80
	v_mul_f32_e32 v40, 0xbfb8aa3b, v37
	v_exp_f32_e32 v40, v40
	v_add_f32_e32 v39, 1.0, v39
	v_rcp_f32_e32 v39, v39
	v_and_b32_e32 v34, 0xffff0000, v78
	v_add_f32_e32 v40, 1.0, v40
	v_rcp_f32_e32 v40, v40
	v_and_b32_e32 v38, 0xffff0000, v80
	v_mul_f32_e32 v1, v39, v1
	v_mul_f32_e32 v1, v30, v1
	v_mul_f32_e32 v30, v40, v37
	v_mul_f32_e32 v37, 0xbfb8aa3b, v34
	v_mul_f32_e32 v39, 0xbfb8aa3b, v38
	v_exp_f32_e32 v37, v37
	v_exp_f32_e32 v39, v39
	v_lshlrev_b32_e32 v35, 16, v79
	v_mul_f32_e32 v30, v26, v30
	v_add_f32_e32 v26, 1.0, v37
	v_add_f32_e32 v37, 1.0, v39
	v_mul_f32_e32 v39, 0xbfb8aa3b, v35
	v_rcp_f32_e32 v26, v26
	v_exp_f32_e32 v39, v39
	v_rcp_f32_e32 v37, v37
	v_lshlrev_b32_e32 v41, 16, v81
	v_mul_f32_e32 v26, v26, v34
	v_add_f32_e32 v34, 1.0, v39
	v_rcp_f32_e32 v34, v34
	v_and_b32_e32 v36, 0xffff0000, v79
	v_mul_f32_e32 v26, v31, v26
	v_mul_f32_e32 v31, v37, v38
	v_mul_f32_e32 v37, 0xbfb8aa3b, v41
	v_and_b32_e32 v42, 0xffff0000, v81
	v_exp_f32_e32 v37, v37
	v_mul_f32_e32 v31, v27, v31
	v_mul_f32_e32 v27, v34, v35
	v_mul_f32_e32 v34, 0xbfb8aa3b, v36
	v_exp_f32_e32 v34, v34
	v_mul_f32_e32 v35, 0xbfb8aa3b, v42
	v_exp_f32_e32 v35, v35
	v_mul_f32_e32 v27, v32, v27
	v_add_f32_e32 v32, 1.0, v37
	v_rcp_f32_e32 v32, v32
	v_add_f32_e32 v34, 1.0, v34
	v_rcp_f32_e32 v34, v34
	v_add_f32_e32 v35, 1.0, v35
	v_rcp_f32_e32 v35, v35
	v_mul_f32_e32 v32, v32, v41
	v_mul_f32_e32 v32, v28, v32
	v_mul_f32_e32 v28, v34, v36
	v_mul_f32_e32 v28, v33, v28
	v_mul_f32_e32 v33, v35, v42
	v_mul_f32_e32 v29, v29, v33
	v_cvt_pk_bf16_f32 v26, v1, v26
	v_cvt_pk_bf16_f32 v27, v27, v28
	v_cvt_pk_bf16_f32 v28, v30, v31
	v_lshl_add_u64 v[30:31], s[6:7], 0, v[88:89]
	v_cvt_pk_bf16_f32 v29, v32, v29
; __device__ __forceinline__ float siluf_(float x) { return x * __builtin_amdgcn_rcpf(1.0f + __expf(-x)); }
; __device__ __forceinline__ u32x4 pack8(const float (&f)[8]) { u32x4 r; r[0] = cvt_pk_bf16(f[0], f[1]); r[1] = cvt_pk_bf16(f[2], f[3]); r[2] = cvt_pk_bf16(f[4], f[5]); r[3] = cvt_pk_bf16(f[6], f[7]); return r; }
; #define PG8_WAIT_V(n) asm volatile("s_waitcnt vmcnt(" #n ")" ::: "memory")
; #define PG8_BAR __builtin_amdgcn_s_barrier()
; template <class Sched, class Epi>
; __device__ __forceinline__ void gemm_phase(LAS unsigned char* lds, const Sched& S, const Epi& E, const int K, const int lda, const int ldb) {
;     ...
;     PG8_WAIT_V(0);
;     if (wr == 0) PG8_BAR;
;     __device__ __forceinline__ void operator()(EPI_ARGS) const {
;     ...
;             for (int m = 0; m < 4; ++m)
; #pragma unroll
;                 for (int bj = 0; bj < 2; ++bj) { const f32x4 v0 = acc[ai][bj][m][0], v1 = acc[ai][bj][m][1]; float z[8]; unpack8(zz[m][bj], z); float o[8];
; #pragma unroll
;                     for (int j = 0; j < 4; ++j) { o[j] = v0[j] * siluf_(z[j]); o[4 + j] = v1[j] * siluf_(z[4 + j]); }
;                     *(u32x4*)(O + (size_t)EPI_ROW * 1024 + EPI_COL(bj)) = pack8(o); } }
	v_lshl_add_u64 v[30:31], v[30:31], 0, v[150:151]
	v_lshlrev_b32_e32 v1, 16, v74
	global_store_dwordx4 v[30:31], v[26:29], off
	v_mul_f32_e32 v33, 0xbfb8aa3b, v1
	v_exp_f32_e32 v33, v33
	v_lshlrev_b32_e32 v29, 16, v76
	v_mul_f32_e32 v34, 0xbfb8aa3b, v29
	v_exp_f32_e32 v34, v34
	v_add_f32_e32 v33, 1.0, v33
	v_rcp_f32_e32 v33, v33
	v_and_b32_e32 v26, 0xffff0000, v74
	v_add_f32_e32 v34, 1.0, v34
	v_rcp_f32_e32 v34, v34
	v_and_b32_e32 v32, 0xffff0000, v76
	v_mul_f32_e32 v1, v33, v1
	v_mul_f32_e32 v1, v22, v1
	v_mul_f32_e32 v22, v34, v29
	v_mul_f32_e32 v29, 0xbfb8aa3b, v26
	v_mul_f32_e32 v33, 0xbfb8aa3b, v32
	v_exp_f32_e32 v29, v29
	v_exp_f32_e32 v33, v33
	v_lshlrev_b32_e32 v27, 16, v75
	v_mul_f32_e32 v22, v18, v22
	v_add_f32_e32 v18, 1.0, v29
	v_add_f32_e32 v29, 1.0, v33
	v_mul_f32_e32 v33, 0xbfb8aa3b, v27
	v_rcp_f32_e32 v18, v18
	v_exp_f32_e32 v33, v33
	v_rcp_f32_e32 v29, v29
	v_lshlrev_b32_e32 v35, 16, v77
	v_mul_f32_e32 v18, v18, v26
	v_add_f32_e32 v26, 1.0, v33
	v_rcp_f32_e32 v26, v26
	v_and_b32_e32 v28, 0xffff0000, v75
	v_mul_f32_e32 v18, v23, v18
	v_mul_f32_e32 v23, v29, v32
	v_mul_f32_e32 v29, 0xbfb8aa3b, v35
	v_and_b32_e32 v36, 0xffff0000, v77
	v_exp_f32_e32 v29, v29
	v_mul_f32_e32 v23, v19, v23
	v_mul_f32_e32 v19, v26, v27
	v_mul_f32_e32 v26, 0xbfb8aa3b, v28
	v_exp_f32_e32 v26, v26
	v_mul_f32_e32 v27, 0xbfb8aa3b, v36
	v_exp_f32_e32 v27, v27
	v_mul_f32_e32 v19, v24, v19
	v_add_f32_e32 v24, 1.0, v29
	v_rcp_f32_e32 v24, v24
	v_add_f32_e32 v26, 1.0, v26
	v_rcp_f32_e32 v26, v26
	v_add_f32_e32 v27, 1.0, v27
	v_rcp_f32_e32 v27, v27
	v_mul_f32_e32 v24, v24, v35
	v_mul_f32_e32 v24, v20, v24
	v_mul_f32_e32 v20, v26, v28
	v_mul_f32_e32 v20, v25, v20
	v_mul_f32_e32 v25, v27, v36
	v_mul_f32_e32 v21, v21, v25
	v_cvt_pk_bf16_f32 v18, v1, v18
	v_cvt_pk_bf16_f32 v19, v19, v20
	v_cvt_pk_bf16_f32 v20, v22, v23
	v_cvt_pk_bf16_f32 v21, v24, v21
	v_lshlrev_b32_e32 v1, 16, v70
	global_store_dwordx4 v[30:31], v[18:21], off offset:256
	v_mul_f32_e32 v23, 0xbfb8aa3b, v1
	v_exp_f32_e32 v23, v23
	v_lshlrev_b32_e32 v21, 16, v72
	v_mul_f32_e32 v24, 0xbfb8aa3b, v21
	v_exp_f32_e32 v24, v24
	v_add_f32_e32 v23, 1.0, v23
	v_rcp_f32_e32 v23, v23
	v_and_b32_e32 v18, 0xffff0000, v70
	v_add_f32_e32 v24, 1.0, v24
	v_rcp_f32_e32 v24, v24
	v_and_b32_e32 v22, 0xffff0000, v72
	v_mul_f32_e32 v1, v23, v1
	v_mul_f32_e32 v1, v14, v1
	v_mul_f32_e32 v14, v24, v21
	v_mul_f32_e32 v21, 0xbfb8aa3b, v18
	v_mul_f32_e32 v23, 0xbfb8aa3b, v22
	v_exp_f32_e32 v21, v21
	v_exp_f32_e32 v23, v23
	v_lshlrev_b32_e32 v19, 16, v71
	v_mul_f32_e32 v14, v10, v14
	v_add_f32_e32 v10, 1.0, v21
	v_add_f32_e32 v21, 1.0, v23
	v_mul_f32_e32 v23, 0xbfb8aa3b, v19
	v_rcp_f32_e32 v10, v10
	v_exp_f32_e32 v23, v23
	v_rcp_f32_e32 v21, v21
	v_lshlrev_b32_e32 v25, 16, v73
	v_mul_f32_e32 v10, v10, v18
	v_add_f32_e32 v18, 1.0, v23
	v_rcp_f32_e32 v18, v18
	v_and_b32_e32 v20, 0xffff0000, v71
	v_mul_f32_e32 v10, v15, v10
	v_mul_f32_e32 v15, v21, v22
	v_mul_f32_e32 v21, 0xbfb8aa3b, v25
	v_and_b32_e32 v26, 0xffff0000, v73
	v_exp_f32_e32 v21, v21
	v_mul_f32_e32 v15, v11, v15
	v_mul_f32_e32 v11, v18, v19
	v_mul_f32_e32 v18, 0xbfb8aa3b, v20
	v_exp_f32_e32 v18, v18
	v_mul_f32_e32 v19, 0xbfb8aa3b, v26
	v_exp_f32_e32 v19, v19
	v_mul_f32_e32 v11, v16, v11
	v_add_f32_e32 v16, 1.0, v21
	v_rcp_f32_e32 v16, v16
	v_add_f32_e32 v18, 1.0, v18
	v_rcp_f32_e32 v18, v18
	v_add_f32_e32 v19, 1.0, v19
	v_rcp_f32_e32 v19, v19
	v_mul_f32_e32 v16, v16, v25
	v_mul_f32_e32 v16, v12, v16
	v_mul_f32_e32 v12, v18, v20
	v_mul_f32_e32 v12, v17, v12
	v_mul_f32_e32 v17, v19, v26
	v_mul_f32_e32 v13, v13, v17
	v_cvt_pk_bf16_f32 v10, v1, v10
	v_cvt_pk_bf16_f32 v11, v11, v12
	v_cvt_pk_bf16_f32 v12, v14, v15
	v_lshl_add_u64 v[14:15], s[6:7], 0, v[86:87]
	v_cvt_pk_bf16_f32 v13, v16, v13
	v_lshl_add_u64 v[14:15], v[14:15], 0, v[150:151]
	v_lshlrev_b32_e32 v1, 16, v66
	global_store_dwordx4 v[14:15], v[10:13], off
	v_mul_f32_e32 v17, 0xbfb8aa3b, v1
	v_exp_f32_e32 v17, v17
	v_lshlrev_b32_e32 v13, 16, v68
	v_mul_f32_e32 v18, 0xbfb8aa3b, v13
	v_exp_f32_e32 v18, v18
	v_add_f32_e32 v17, 1.0, v17
	v_rcp_f32_e32 v17, v17
	v_and_b32_e32 v10, 0xffff0000, v66
	v_add_f32_e32 v18, 1.0, v18
	v_rcp_f32_e32 v18, v18
	v_and_b32_e32 v16, 0xffff0000, v68
	v_mul_f32_e32 v1, v17, v1
	v_mul_f32_e32 v1, v6, v1
	v_mul_f32_e32 v6, v18, v13
	v_mul_f32_e32 v13, 0xbfb8aa3b, v10
	v_mul_f32_e32 v17, 0xbfb8aa3b, v16
	v_exp_f32_e32 v13, v13
	v_exp_f32_e32 v17, v17
	v_lshlrev_b32_e32 v11, 16, v67
	v_mul_f32_e32 v6, v2, v6
	v_add_f32_e32 v2, 1.0, v13
	v_add_f32_e32 v13, 1.0, v17
	v_mul_f32_e32 v17, 0xbfb8aa3b, v11
	v_rcp_f32_e32 v2, v2
	v_exp_f32_e32 v17, v17
	v_rcp_f32_e32 v13, v13
	v_lshlrev_b32_e32 v19, 16, v69
	v_mul_f32_e32 v2, v2, v10
	v_add_f32_e32 v10, 1.0, v17
	v_rcp_f32_e32 v10, v10
	v_and_b32_e32 v12, 0xffff0000, v67
	v_mul_f32_e32 v2, v7, v2
	v_mul_f32_e32 v7, v13, v16
	v_mul_f32_e32 v13, 0xbfb8aa3b, v19
	v_and_b32_e32 v20, 0xffff0000, v69
	v_exp_f32_e32 v13, v13
	v_mul_f32_e32 v7, v3, v7
	v_mul_f32_e32 v3, v10, v11
	v_mul_f32_e32 v10, 0xbfb8aa3b, v12
	v_exp_f32_e32 v10, v10
	v_mul_f32_e32 v11, 0xbfb8aa3b, v20
	v_exp_f32_e32 v11, v11
	v_mul_f32_e32 v3, v8, v3
	v_add_f32_e32 v8, 1.0, v13
	v_rcp_f32_e32 v8, v8
	v_add_f32_e32 v10, 1.0, v10
	v_rcp_f32_e32 v10, v10
	v_add_f32_e32 v11, 1.0, v11
	v_rcp_f32_e32 v11, v11
	v_mul_f32_e32 v8, v8, v19
	v_mul_f32_e32 v8, v4, v8
	v_mul_f32_e32 v4, v10, v12
	v_mul_f32_e32 v4, v9, v4
	v_mul_f32_e32 v9, v11, v20
	v_mul_f32_e32 v5, v5, v9
	v_cvt_pk_bf16_f32 v2, v1, v2
	v_cvt_pk_bf16_f32 v3, v3, v4
	v_cvt_pk_bf16_f32 v4, v6, v7
	v_cvt_pk_bf16_f32 v5, v8, v5
	global_store_dwordx4 v[14:15], v[2:5], off offset:256
	s_waitcnt vmcnt(0)
	s_cbranch_scc0 .LBB0_1393
	s_barrier

; #define PG8_STAGE(bufoff, gbase, voff) do { _Pragma("unroll") for (int _i = 0; _i < 2; ++_i) \
;         __builtin_amdgcn_global_load_lds((const unsigned*)((const char*)(gbase) + (voff)[_i]), (LAS unsigned*)(lds + (bufoff) + ldsw + _i * 8192), 16, 0, 0); } while (0)
; #define PG8_LDA(dst, b, h) do { _Pragma("unroll") for (int m = 0; m < 4; ++m) _Pragma("unroll") for (int k = 0; k < 2; ++k) dst[m][k] = *(const LAS bf16x8*)(lds + PG8_SA(b, h) + aoff + m * 2048 + k * 1024); } while (0)
; #define PG8_LDB(dst, b, h) do { _Pragma("unroll") for (int n = 0; n < 2; ++n) _Pragma("unroll") for (int k = 0; k < 2; ++k) dst[n][k] = *(const LAS bf16x8*)(lds + PG8_SB(b, h) + boff + n * 2048 + k * 1024); } while (0)
; #define PG8_MMA(ai, bj, At, Bt) do { __builtin_amdgcn_s_setprio(1); _Pragma("unroll") for (int m = 0; m < 4; ++m) _Pragma("unroll") for (int n = 0; n < 2; ++n) _Pragma("unroll") for (int k = 0; k < 2; ++k) \
;         acc[ai][bj][m][n] = __builtin_amdgcn_mfma_f32_16x16x32_bf16(Bt[n][k], At[m][k], acc[ai][bj][m][n], 0, 0, 0); __builtin_amdgcn_s_setprio(0); } while (0)
; #define PG8_WAIT_V(n) asm volatile("s_waitcnt vmcnt(" #n ")" ::: "memory")
; #define PG8_WAIT_L(n) asm volatile("s_waitcnt lgkmcnt(" #n ")" ::: "memory")
; #define PG8_BAR __builtin_amdgcn_s_barrier()
; #define PG8_SCHED __builtin_amdgcn_sched_barrier(0)
; template <class Sched, class Epi>
; __device__ __forceinline__ void gemm_phase(LAS unsigned char* lds, const Sched& S, const Epi& E, const int K, const int lda, const int ldb) {
;     ...
;             PG8_LDB(B0, 0, 0); PG8_SCHED; PG8_LDA(At, 0, 0); PG8_STAGE(PG8_SA(1, 1), a1 + hstepA, voffA);
;             PG8_WAIT_L(8); PG8_BAR; PG8_WAIT_L(0); PG8_MMA(0, 0, At, B0); PG8_BAR; PG8_SCHED;
;             PG8_LDB(B1, 0, 1); PG8_STAGE(PG8_SB(0, 0), b2, voffB);
;             PG8_BAR; PG8_WAIT_L(0); PG8_MMA(0, 1, At, B1); PG8_BAR;
;             PG8_LDA(At, 0, 1); PG8_STAGE(PG8_SA(0, 0), a2, voffA);
;             PG8_BAR; PG8_WAIT_L(0); if (!chalf) PG8_MMA(1, 0, At, B0); PG8_BAR; PG8_SCHED;
;             PG8_STAGE(PG8_SB(0, 1), b2 + hstepB, voffB);
;             PG8_WAIT_V(6); PG8_BAR; if (!chalf) PG8_MMA(1, 1, At, B1); PG8_BAR;
.LBB0_1415:
	ds_read_b128 v[144:147], v155
	ds_read_b128 v[158:161], v155 offset:1024
	ds_read_b128 v[162:165], v155 offset:2048
	ds_read_b128 v[166:169], v155 offset:3072
	s_add_u32 s34, s28, 0xfffc0080
	s_addc_u32 s35, s29, -1
	s_cmp_eq_u32 s49, 12
	s_cselect_b32 s37, s25, s35
	s_cselect_b32 s36, s24, s34
	s_cselect_b32 s35, s27, s17
	s_cselect_b32 s34, s26, s15
	s_add_i32 m0, s23, 0xc000
	ds_read_b128 v[170:173], v156
	ds_read_b128 v[174:177], v156 offset:1024
	ds_read_b128 v[178:181], v156 offset:2048
	ds_read_b128 v[182:185], v156 offset:3072
	ds_read_b128 v[186:189], v156 offset:4096
	ds_read_b128 v[190:193], v156 offset:5120
	ds_read_b128 v[194:197], v156 offset:6144
	ds_read_b128 v[198:201], v156 offset:7168
	global_load_lds_dwordx4 v140, s[28:29]
	s_add_i32 m0, s23, 0xe000
	s_nop 0
	global_load_lds_dwordx4 v138, s[28:29]
	s_waitcnt lgkmcnt(8)
	s_barrier
	s_waitcnt lgkmcnt(0)
	s_setprio 1
	s_waitcnt lgkmcnt(0)
	v_mfma_f32_16x16x32_bf16 v[118:121], v[144:147], v[170:173], v[118:121]
	v_mfma_f32_16x16x32_bf16 v[114:117], v[162:165], v[170:173], v[114:117]
	v_mfma_f32_16x16x32_bf16 v[110:113], v[144:147], v[178:181], v[110:113]
	v_mfma_f32_16x16x32_bf16 v[106:109], v[162:165], v[178:181], v[106:109]
	v_mfma_f32_16x16x32_bf16 v[94:97], v[144:147], v[186:189], v[94:97]
	v_mfma_f32_16x16x32_bf16 v[90:93], v[162:165], v[186:189], v[90:93]
	v_mfma_f32_16x16x32_bf16 v[78:81], v[144:147], v[194:197], v[78:81]
	v_mfma_f32_16x16x32_bf16 v[74:77], v[162:165], v[194:197], v[74:77]
	v_mfma_f32_16x16x32_bf16 v[118:121], v[158:161], v[174:177], v[118:121]
	v_mfma_f32_16x16x32_bf16 v[114:117], v[166:169], v[174:177], v[114:117]
	v_mfma_f32_16x16x32_bf16 v[110:113], v[158:161], v[182:185], v[110:113]
	v_mfma_f32_16x16x32_bf16 v[106:109], v[166:169], v[182:185], v[106:109]
	v_mfma_f32_16x16x32_bf16 v[94:97], v[158:161], v[190:193], v[94:97]
	v_mfma_f32_16x16x32_bf16 v[90:93], v[166:169], v[190:193], v[90:93]
	v_mfma_f32_16x16x32_bf16 v[78:81], v[158:161], v[198:201], v[78:81]
	v_mfma_f32_16x16x32_bf16 v[74:77], v[166:169], v[198:201], v[74:77]
	s_setprio 0
	s_barrier
	s_add_i32 s50, s46, s38
	s_add_u32 s62, s34, s8
	s_addc_u32 s63, s35, s9
	s_mov_b32 m0, s50
	ds_read_b128 v[202:205], v157
	ds_read_b128 v[206:209], v157 offset:1024
	ds_read_b128 v[210:213], v157 offset:2048
	ds_read_b128 v[214:217], v157 offset:3072
	global_load_lds_dwordx4 v132, s[34:35]
	s_add_u32 s64, s34, s8
	s_addc_u32 s65, s35, s9
	s_add_i32 m0, s50, 0x2000
	s_nop 0
	global_load_lds_dwordx4 v136, s[34:35]
	s_barrier
	s_waitcnt lgkmcnt(0)
	s_setprio 1
	s_waitcnt lgkmcnt(0)
	v_mfma_f32_16x16x32_bf16 v[126:129], v[202:205], v[170:173], v[126:129]
	v_mfma_f32_16x16x32_bf16 v[122:125], v[210:213], v[170:173], v[122:125]
	v_mfma_f32_16x16x32_bf16 v[102:105], v[202:205], v[178:181], v[102:105]
	v_mfma_f32_16x16x32_bf16 v[98:101], v[210:213], v[178:181], v[98:101]
	v_mfma_f32_16x16x32_bf16 v[86:89], v[202:205], v[186:189], v[86:89]
	v_mfma_f32_16x16x32_bf16 v[82:85], v[210:213], v[186:189], v[82:85]
	v_mfma_f32_16x16x32_bf16 v[70:73], v[202:205], v[194:197], v[70:73]
	v_mfma_f32_16x16x32_bf16 v[66:69], v[210:213], v[194:197], v[66:69]
	v_mfma_f32_16x16x32_bf16 v[126:129], v[206:209], v[174:177], v[126:129]
	v_mfma_f32_16x16x32_bf16 v[122:125], v[214:217], v[174:177], v[122:125]
	v_mfma_f32_16x16x32_bf16 v[102:105], v[206:209], v[182:185], v[102:105]
	v_mfma_f32_16x16x32_bf16 v[98:101], v[214:217], v[182:185], v[98:101]
	v_mfma_f32_16x16x32_bf16 v[86:89], v[206:209], v[190:193], v[86:89]
	v_mfma_f32_16x16x32_bf16 v[82:85], v[214:217], v[190:193], v[82:85]
	v_mfma_f32_16x16x32_bf16 v[70:73], v[206:209], v[198:201], v[70:73]
	v_mfma_f32_16x16x32_bf16 v[66:69], v[214:217], v[198:201], v[66:69]
	s_setprio 0
	s_mov_b32 m0, s23
	s_add_u32 s66, s36, s8
	s_addc_u32 s67, s37, s9
	s_barrier
	ds_read_b128 v[170:173], v156 offset:16384
	ds_read_b128 v[174:177], v156 offset:17408
	ds_read_b128 v[178:181], v156 offset:18432
	ds_read_b128 v[182:185], v156 offset:19456
	ds_read_b128 v[186:189], v156 offset:20480
	ds_read_b128 v[190:193], v156 offset:21504
	ds_read_b128 v[194:197], v156 offset:22528
	ds_read_b128 v[198:201], v156 offset:23552
	global_load_lds_dwordx4 v130, s[36:37]
	s_add_u32 s68, s36, s8
	s_addc_u32 s69, s37, s9
	s_mov_b32 m0, s39
	s_nop 0
	global_load_lds_dwordx4 v134, s[36:37]
	s_barrier
	s_waitcnt lgkmcnt(0)
	s_setprio 1
	s_waitcnt lgkmcnt(0)
	v_mfma_f32_16x16x32_bf16 v[62:65], v[144:147], v[170:173], v[62:65]
	v_mfma_f32_16x16x32_bf16 v[58:61], v[162:165], v[170:173], v[58:61]
	v_mfma_f32_16x16x32_bf16 v[46:49], v[144:147], v[178:181], v[46:49]
	v_mfma_f32_16x16x32_bf16 v[42:45], v[162:165], v[178:181], v[42:45]
	v_mfma_f32_16x16x32_bf16 v[30:33], v[144:147], v[186:189], v[30:33]
	v_mfma_f32_16x16x32_bf16 v[26:29], v[162:165], v[186:189], v[26:29]
	v_mfma_f32_16x16x32_bf16 v[14:17], v[144:147], v[194:197], v[14:17]
	v_mfma_f32_16x16x32_bf16 v[10:13], v[162:165], v[194:197], v[10:13]
	v_mfma_f32_16x16x32_bf16 v[62:65], v[158:161], v[174:177], v[62:65]
	v_mfma_f32_16x16x32_bf16 v[58:61], v[166:169], v[174:177], v[58:61]
	v_mfma_f32_16x16x32_bf16 v[46:49], v[158:161], v[182:185], v[46:49]
	v_mfma_f32_16x16x32_bf16 v[42:45], v[166:169], v[182:185], v[42:45]
	v_mfma_f32_16x16x32_bf16 v[30:33], v[158:161], v[190:193], v[30:33]
	v_mfma_f32_16x16x32_bf16 v[26:29], v[166:169], v[190:193], v[26:29]
	v_mfma_f32_16x16x32_bf16 v[14:17], v[158:161], v[198:201], v[14:17]
	v_mfma_f32_16x16x32_bf16 v[10:13], v[166:169], v[198:201], v[10:13]
	s_setprio 0
	s_barrier
	s_add_u32 s50, s34, 0x40000
	s_addc_u32 s51, s35, 0
	s_add_i32 s52, s47, s38
	s_mov_b32 m0, s52
	s_nop 0
	global_load_lds_dwordx4 v132, s[50:51]
	s_add_i32 m0, s52, 0x2000
	s_nop 0
	global_load_lds_dwordx4 v136, s[50:51]
	s_waitcnt vmcnt(6)
	s_barrier
; #define PG8_STAGE(bufoff, gbase, voff) do { _Pragma("unroll") for (int _i = 0; _i < 2; ++_i) \
;         __builtin_amdgcn_global_load_lds((const unsigned*)((const char*)(gbase) + (voff)[_i]), (LAS unsigned*)(lds + (bufoff) + ldsw + _i * 8192), 16, 0, 0); } while (0)
; #define PG8_LDA(dst, b, h) do { _Pragma("unroll") for (int m = 0; m < 4; ++m) _Pragma("unroll") for (int k = 0; k < 2; ++k) dst[m][k] = *(const LAS bf16x8*)(lds + PG8_SA(b, h) + aoff + m * 2048 + k * 1024); } while (0)
; #define PG8_LDB(dst, b, h) do { _Pragma("unroll") for (int n = 0; n < 2; ++n) _Pragma("unroll") for (int k = 0; k < 2; ++k) dst[n][k] = *(const LAS bf16x8*)(lds + PG8_SB(b, h) + boff + n * 2048 + k * 1024); } while (0)
; #define PG8_MMA(ai, bj, At, Bt) do { __builtin_amdgcn_s_setprio(1); _Pragma("unroll") for (int m = 0; m < 4; ++m) _Pragma("unroll") for (int n = 0; n < 2; ++n) _Pragma("unroll") for (int k = 0; k < 2; ++k) \
;         acc[ai][bj][m][n] = __builtin_amdgcn_mfma_f32_16x16x32_bf16(Bt[n][k], At[m][k], acc[ai][bj][m][n], 0, 0, 0); __builtin_amdgcn_s_setprio(0); } while (0)
; #define PG8_WAIT_V(n) asm volatile("s_waitcnt vmcnt(" #n ")" ::: "memory")
; #define PG8_WAIT_L(n) asm volatile("s_waitcnt lgkmcnt(" #n ")" ::: "memory")
; #define PG8_BAR __builtin_amdgcn_s_barrier()
; #define PG8_SCHED __builtin_amdgcn_sched_barrier(0)
; template <class Sched, class Epi>
; __device__ __forceinline__ void gemm_phase(LAS unsigned char* lds, const Sched& S, const Epi& E, const int K, const int lda, const int ldb) {
;     ...
;             PG8_WAIT_V(6); PG8_BAR; if (!chalf) PG8_MMA(1, 1, At, B1); PG8_BAR;
;             PG8_LDB(B0, 1, 0); PG8_SCHED; PG8_LDA(At, 1, 0); PG8_STAGE(PG8_SA(0, 1), a2 + hstepA, voffA);
;             PG8_WAIT_L(8); PG8_BAR; PG8_WAIT_L(0); PG8_MMA(0, 0, At, B0); PG8_BAR; PG8_SCHED;
;             PG8_LDB(B1, 1, 1); PG8_STAGE(PG8_SB(1, 0), b3, voffB);
;             PG8_BAR; PG8_WAIT_L(0); PG8_MMA(0, 1, At, B1); PG8_BAR;
;             PG8_LDA(At, 1, 1); PG8_STAGE(PG8_SA(1, 0), a3, voffA);
	s_setprio 1
	v_mfma_f32_16x16x32_bf16 v[54:57], v[202:205], v[170:173], v[54:57]
	v_mfma_f32_16x16x32_bf16 v[50:53], v[210:213], v[170:173], v[50:53]
	v_mfma_f32_16x16x32_bf16 v[38:41], v[202:205], v[178:181], v[38:41]
	v_mfma_f32_16x16x32_bf16 v[34:37], v[210:213], v[178:181], v[34:37]
	v_mfma_f32_16x16x32_bf16 v[22:25], v[202:205], v[186:189], v[22:25]
	v_mfma_f32_16x16x32_bf16 v[18:21], v[210:213], v[186:189], v[18:21]
	v_mfma_f32_16x16x32_bf16 v[6:9], v[202:205], v[194:197], v[6:9]
	v_mfma_f32_16x16x32_bf16 v[2:5], v[210:213], v[194:197], v[2:5]
	v_mfma_f32_16x16x32_bf16 v[54:57], v[206:209], v[174:177], v[54:57]
	v_mfma_f32_16x16x32_bf16 v[50:53], v[214:217], v[174:177], v[50:53]
	v_mfma_f32_16x16x32_bf16 v[38:41], v[206:209], v[182:185], v[38:41]
	v_mfma_f32_16x16x32_bf16 v[34:37], v[214:217], v[182:185], v[34:37]
	v_mfma_f32_16x16x32_bf16 v[22:25], v[206:209], v[190:193], v[22:25]
	v_mfma_f32_16x16x32_bf16 v[18:21], v[214:217], v[190:193], v[18:21]
	v_mfma_f32_16x16x32_bf16 v[6:9], v[206:209], v[198:201], v[6:9]
	v_mfma_f32_16x16x32_bf16 v[2:5], v[214:217], v[198:201], v[2:5]
	s_setprio 0
	s_add_i32 s50, 16, 0x18000
	v_add_u32_e32 v166, s50, v150
	s_barrier
	ds_read_b128 v[144:147], v166
	ds_read_b128 v[158:161], v166 offset:1024
	ds_read_b128 v[162:165], v166 offset:2048
	ds_read_b128 v[166:169], v166 offset:3072
	s_add_u32 s36, s36, 0x40000
	s_addc_u32 s37, s37, 0
	s_mov_b32 m0, s40
	ds_read_b128 v[170:173], v156 offset:32768
	ds_read_b128 v[174:177], v156 offset:33792
	ds_read_b128 v[178:181], v156 offset:34816
	ds_read_b128 v[182:185], v156 offset:35840
	ds_read_b128 v[186:189], v156 offset:36864
	ds_read_b128 v[190:193], v156 offset:37888
	ds_read_b128 v[194:197], v156 offset:38912
	ds_read_b128 v[198:201], v156 offset:39936
	global_load_lds_dwordx4 v130, s[36:37]
	s_mov_b32 m0, s41
	s_nop 0
	global_load_lds_dwordx4 v134, s[36:37]
	s_waitcnt lgkmcnt(8)
	s_barrier
	s_waitcnt lgkmcnt(0)
	s_setprio 1
	s_waitcnt lgkmcnt(0)
	v_mfma_f32_16x16x32_bf16 v[118:121], v[144:147], v[170:173], v[118:121]
	v_mfma_f32_16x16x32_bf16 v[114:117], v[162:165], v[170:173], v[114:117]
	v_mfma_f32_16x16x32_bf16 v[110:113], v[144:147], v[178:181], v[110:113]
	v_mfma_f32_16x16x32_bf16 v[106:109], v[162:165], v[178:181], v[106:109]
	v_mfma_f32_16x16x32_bf16 v[94:97], v[144:147], v[186:189], v[94:97]
	v_mfma_f32_16x16x32_bf16 v[90:93], v[162:165], v[186:189], v[90:93]
	v_mfma_f32_16x16x32_bf16 v[78:81], v[144:147], v[194:197], v[78:81]
	v_mfma_f32_16x16x32_bf16 v[74:77], v[162:165], v[194:197], v[74:77]
	v_mfma_f32_16x16x32_bf16 v[118:121], v[158:161], v[174:177], v[118:121]
	v_mfma_f32_16x16x32_bf16 v[114:117], v[166:169], v[174:177], v[114:117]
	v_mfma_f32_16x16x32_bf16 v[110:113], v[158:161], v[182:185], v[110:113]
	v_mfma_f32_16x16x32_bf16 v[106:109], v[166:169], v[182:185], v[106:109]
	v_mfma_f32_16x16x32_bf16 v[94:97], v[158:161], v[190:193], v[94:97]
	v_mfma_f32_16x16x32_bf16 v[90:93], v[166:169], v[190:193], v[90:93]
	v_mfma_f32_16x16x32_bf16 v[78:81], v[158:161], v[198:201], v[78:81]
	v_mfma_f32_16x16x32_bf16 v[74:77], v[166:169], v[198:201], v[74:77]
	s_setprio 0
	s_barrier
	s_add_i32 s36, 16, 0x1c000
	s_add_i32 s37, s50, s38
	v_add_u32_e32 v214, s36, v150
	s_mov_b32 m0, s37
	ds_read_b128 v[202:205], v214
	ds_read_b128 v[206:209], v214 offset:1024
	ds_read_b128 v[210:213], v214 offset:2048
	ds_read_b128 v[214:217], v214 offset:3072
	global_load_lds_dwordx4 v132, s[62:63]
	s_add_i32 m0, s37, 0x2000
	s_nop 0
	global_load_lds_dwordx4 v136, s[64:65]
	s_barrier
	s_waitcnt lgkmcnt(0)
	s_setprio 1
	s_waitcnt lgkmcnt(0)
	v_mfma_f32_16x16x32_bf16 v[126:129], v[202:205], v[170:173], v[126:129]
	v_mfma_f32_16x16x32_bf16 v[122:125], v[210:213], v[170:173], v[122:125]
	v_mfma_f32_16x16x32_bf16 v[102:105], v[202:205], v[178:181], v[102:105]
	v_mfma_f32_16x16x32_bf16 v[98:101], v[210:213], v[178:181], v[98:101]
	v_mfma_f32_16x16x32_bf16 v[86:89], v[202:205], v[186:189], v[86:89]
	v_mfma_f32_16x16x32_bf16 v[82:85], v[210:213], v[186:189], v[82:85]
	v_mfma_f32_16x16x32_bf16 v[70:73], v[202:205], v[194:197], v[70:73]
	v_mfma_f32_16x16x32_bf16 v[66:69], v[210:213], v[194:197], v[66:69]
	v_mfma_f32_16x16x32_bf16 v[126:129], v[206:209], v[174:177], v[126:129]
	v_mfma_f32_16x16x32_bf16 v[122:125], v[214:217], v[174:177], v[122:125]
	v_mfma_f32_16x16x32_bf16 v[102:105], v[206:209], v[182:185], v[102:105]
	v_mfma_f32_16x16x32_bf16 v[98:101], v[214:217], v[182:185], v[98:101]
	v_mfma_f32_16x16x32_bf16 v[86:89], v[206:209], v[190:193], v[86:89]
	v_mfma_f32_16x16x32_bf16 v[82:85], v[214:217], v[190:193], v[82:85]
	v_mfma_f32_16x16x32_bf16 v[70:73], v[206:209], v[198:201], v[70:73]
	v_mfma_f32_16x16x32_bf16 v[66:69], v[214:217], v[198:201], v[66:69]
	s_setprio 0
	s_mov_b32 m0, s42
	s_barrier
	ds_read_b128 v[170:173], v156 offset:49152
	ds_read_b128 v[174:177], v156 offset:50176
	ds_read_b128 v[178:181], v156 offset:51200
	ds_read_b128 v[182:185], v156 offset:52224
	ds_read_b128 v[186:189], v156 offset:53248
	ds_read_b128 v[190:193], v156 offset:54272
	ds_read_b128 v[194:197], v156 offset:55296
	ds_read_b128 v[198:201], v156 offset:56320
	global_load_lds_dwordx4 v130, s[66:67]
	s_mov_b32 m0, s43
	s_nop 0
	global_load_lds_dwordx4 v134, s[68:69]
	s_barrier
; #define PG8_STAGE(bufoff, gbase, voff) do { _Pragma("unroll") for (int _i = 0; _i < 2; ++_i) \
;         __builtin_amdgcn_global_load_lds((const unsigned*)((const char*)(gbase) + (voff)[_i]), (LAS unsigned*)(lds + (bufoff) + ldsw + _i * 8192), 16, 0, 0); } while (0)
; #define PG8_MMA(ai, bj, At, Bt) do { __builtin_amdgcn_s_setprio(1); _Pragma("unroll") for (int m = 0; m < 4; ++m) _Pragma("unroll") for (int n = 0; n < 2; ++n) _Pragma("unroll") for (int k = 0; k < 2; ++k) \
;         acc[ai][bj][m][n] = __builtin_amdgcn_mfma_f32_16x16x32_bf16(Bt[n][k], At[m][k], acc[ai][bj][m][n], 0, 0, 0); __builtin_amdgcn_s_setprio(0); } while (0)
; #define PG8_WAIT_V(n) asm volatile("s_waitcnt vmcnt(" #n ")" ::: "memory")
; #define PG8_WAIT_L(n) asm volatile("s_waitcnt lgkmcnt(" #n ")" ::: "memory")
; #define PG8_BAR __builtin_amdgcn_s_barrier()
; #define PG8_SCHED __builtin_amdgcn_sched_barrier(0)
; template <class Sched, class Epi>
; __device__ __forceinline__ void gemm_phase(LAS unsigned char* lds, const Sched& S, const Epi& E, const int K, const int lda, const int ldb) {
;     ...
;             PG8_BAR; PG8_WAIT_L(0); if (!chalf) PG8_MMA(1, 0, At, B0); PG8_BAR; PG8_SCHED;
;             PG8_STAGE(PG8_SB(1, 1), b3 + hstepB, voffB);
;             PG8_WAIT_V(6); PG8_BAR; if (!chalf) PG8_MMA(1, 1, At, B1); PG8_BAR;
;         }
;     __device__ __forceinline__ void operator()(EPI_ARGS) const {
;         const int col = u.pn * 128 + wc * 32 + 8 * fq;
; #pragma unroll
;         for (int ai = 0; ai < 2; ++ai) if (ai == 0 || !u.half) { u32x4 zz[4];
; #pragma unroll
;             for (int m = 0; m < 4; ++m) zz[m] = *(const u32x4*)(parts + E_PZB + (size_t)EPI_ROW * 1024 + col);
	s_waitcnt lgkmcnt(0)
	s_setprio 1
	s_waitcnt lgkmcnt(0)
	v_mfma_f32_16x16x32_bf16 v[62:65], v[144:147], v[170:173], v[62:65]
	v_mfma_f32_16x16x32_bf16 v[58:61], v[162:165], v[170:173], v[58:61]
	v_mfma_f32_16x16x32_bf16 v[46:49], v[144:147], v[178:181], v[46:49]
	v_mfma_f32_16x16x32_bf16 v[42:45], v[162:165], v[178:181], v[42:45]
	v_mfma_f32_16x16x32_bf16 v[30:33], v[144:147], v[186:189], v[30:33]
	v_mfma_f32_16x16x32_bf16 v[26:29], v[162:165], v[186:189], v[26:29]
	v_mfma_f32_16x16x32_bf16 v[14:17], v[144:147], v[194:197], v[14:17]
	v_mfma_f32_16x16x32_bf16 v[10:13], v[162:165], v[194:197], v[10:13]
	v_mfma_f32_16x16x32_bf16 v[62:65], v[158:161], v[174:177], v[62:65]
	v_mfma_f32_16x16x32_bf16 v[58:61], v[166:169], v[174:177], v[58:61]
	v_mfma_f32_16x16x32_bf16 v[46:49], v[158:161], v[182:185], v[46:49]
	v_mfma_f32_16x16x32_bf16 v[42:45], v[166:169], v[182:185], v[42:45]
	v_mfma_f32_16x16x32_bf16 v[30:33], v[158:161], v[190:193], v[30:33]
	v_mfma_f32_16x16x32_bf16 v[26:29], v[166:169], v[190:193], v[26:29]
	v_mfma_f32_16x16x32_bf16 v[14:17], v[158:161], v[198:201], v[14:17]
	v_mfma_f32_16x16x32_bf16 v[10:13], v[166:169], v[198:201], v[10:13]
	s_setprio 0
	s_barrier
	s_add_u32 s34, s34, 0x40080
	s_addc_u32 s35, s35, 0
	s_add_i32 s36, s36, s38
	s_mov_b32 m0, s36
	s_nop 0
	global_load_lds_dwordx4 v132, s[34:35]
	s_add_i32 m0, s36, 0x2000
	s_nop 0
	global_load_lds_dwordx4 v136, s[34:35]
	s_waitcnt vmcnt(6)
	s_barrier
	s_setprio 1
	v_mfma_f32_16x16x32_bf16 v[54:57], v[202:205], v[170:173], v[54:57]
	v_mfma_f32_16x16x32_bf16 v[50:53], v[210:213], v[170:173], v[50:53]
	v_mfma_f32_16x16x32_bf16 v[38:41], v[202:205], v[178:181], v[38:41]
	v_mfma_f32_16x16x32_bf16 v[34:37], v[210:213], v[178:181], v[34:37]
	v_mfma_f32_16x16x32_bf16 v[22:25], v[202:205], v[186:189], v[22:25]
	v_mfma_f32_16x16x32_bf16 v[18:21], v[210:213], v[186:189], v[18:21]
	v_mfma_f32_16x16x32_bf16 v[6:9], v[202:205], v[194:197], v[6:9]
	v_mfma_f32_16x16x32_bf16 v[2:5], v[210:213], v[194:197], v[2:5]
	v_mfma_f32_16x16x32_bf16 v[54:57], v[206:209], v[174:177], v[54:57]
	v_mfma_f32_16x16x32_bf16 v[50:53], v[214:217], v[174:177], v[50:53]
	v_mfma_f32_16x16x32_bf16 v[38:41], v[206:209], v[182:185], v[38:41]
	v_mfma_f32_16x16x32_bf16 v[34:37], v[214:217], v[182:185], v[34:37]
	v_mfma_f32_16x16x32_bf16 v[22:25], v[206:209], v[190:193], v[22:25]
	v_mfma_f32_16x16x32_bf16 v[18:21], v[214:217], v[190:193], v[18:21]
	v_mfma_f32_16x16x32_bf16 v[6:9], v[206:209], v[198:201], v[6:9]
	v_mfma_f32_16x16x32_bf16 v[2:5], v[214:217], v[198:201], v[2:5]
	s_setprio 0
	s_add_i32 s49, s49, 2
	s_add_u32 s15, s15, 0x100
	s_addc_u32 s17, s17, 0
	s_add_u32 s28, s28, 0x100
	s_addc_u32 s29, s29, 0
	s_cmp_gt_u32 s49, 13
	s_barrier
	s_cbranch_scc0 .LBB0_1415
	v_lshl_or_b32 v144, s48, 7, v154
	v_ashrrev_i32_e32 v145, 31, v144
	v_add_u32_e32 v148, s22, v1
	v_lshlrev_b64 v[144:145], 1, v[144:145]
	v_ashrrev_i32_e32 v149, 31, v148
	v_lshl_add_u64 v[146:147], s[4:5], 0, v[144:145]
	v_lshlrev_b64 v[166:167], 11, v[148:149]
	v_lshl_add_u64 v[158:159], v[146:147], 0, v[166:167]
	global_load_dwordx4 v[158:161], v[158:159], off
	v_mul_f32_e32 v149, 0xbfb8aa3b, v122
	v_mul_f32_e32 v123, 0xbfb8aa3b, v123
	v_add_u32_e32 v122, 16, v148
	v_exp_f32_e32 v174, v123
	v_ashrrev_i32_e32 v123, 31, v122
	v_lshlrev_b64 v[122:123], 11, v[122:123]
	v_mul_f32_e32 v126, 0xbfb8aa3b, v126
	v_mul_f32_e32 v127, 0xbfb8aa3b, v127
	v_mul_f32_e32 v128, 0xbfb8aa3b, v128
	v_mul_f32_e32 v129, 0xbfb8aa3b, v129
	v_lshl_add_u64 v[122:123], v[146:147], 0, v[122:123]
	v_exp_f32_e32 v168, v126
	v_exp_f32_e32 v172, v127
	v_exp_f32_e32 v176, v128
	v_exp_f32_e32 v180, v129
	global_load_dwordx4 v[126:129], v[122:123], off
	v_mul_f32_e32 v163, 0xbfb8aa3b, v124
	v_mul_f32_e32 v125, 0xbfb8aa3b, v125
	v_add_u32_e32 v124, 32, v148
	v_add_u32_e32 v162, 48, v148
	v_exp_f32_e32 v178, v163
	v_exp_f32_e32 v182, v125
	v_ashrrev_i32_e32 v125, 31, v124
	v_ashrrev_i32_e32 v163, 31, v162
	v_lshlrev_b64 v[122:123], 11, v[124:125]
	v_lshlrev_b64 v[124:125], 11, v[162:163]
	v_lshl_add_u64 v[122:123], v[146:147], 0, v[122:123]
	v_lshl_add_u64 v[124:125], v[146:147], 0, v[124:125]
	global_load_dwordx4 v[162:165], v[122:123], off
	s_nop 0
	global_load_dwordx4 v[122:125], v[124:125], off
	v_exp_f32_e32 v170, v149
	v_mul_f32_e32 v102, 0xbfb8aa3b, v102
	v_mul_f32_e32 v98, 0xbfb8aa3b, v98
	v_mul_f32_e32 v100, 0xbfb8aa3b, v100
	v_mul_f32_e32 v86, 0xbfb8aa3b, v86
	v_mul_f32_e32 v82, 0xbfb8aa3b, v82
	v_mul_f32_e32 v84, 0xbfb8aa3b, v84
	v_mul_f32_e32 v70, 0xbfb8aa3b, v70
	v_mul_f32_e32 v66, 0xbfb8aa3b, v66
	v_mul_f32_e32 v68, 0xbfb8aa3b, v68
	v_mul_f32_e32 v54, 0xbfb8aa3b, v54
	v_mul_f32_e32 v50, 0xbfb8aa3b, v50
	v_mul_f32_e32 v52, 0xbfb8aa3b, v52
	v_mul_f32_e32 v38, 0xbfb8aa3b, v38
	v_mul_f32_e32 v34, 0xbfb8aa3b, v34
	v_mul_f32_e32 v36, 0xbfb8aa3b, v36
	v_mul_f32_e32 v22, 0xbfb8aa3b, v22
	v_mul_f32_e32 v18, 0xbfb8aa3b, v18
	v_mul_f32_e32 v20, 0xbfb8aa3b, v20
	v_mul_f32_e32 v6, 0xbfb8aa3b, v6
	v_mul_f32_e32 v2, 0xbfb8aa3b, v2
	v_mul_f32_e32 v4, 0xbfb8aa3b, v4
	s_and_b64 vcc, exec, s[12:13]
	s_mov_b32 s48, s14
	s_mov_b64 s[34:35], s[20:21]
	s_mov_b64 s[28:29], s[18:19]
	s_waitcnt vmcnt(0)
; __device__ __forceinline__ u32x4 pack8(const float (&f)[8]) { u32x4 r; r[0] = cvt_pk_bf16(f[0], f[1]); r[1] = cvt_pk_bf16(f[2], f[3]); r[2] = cvt_pk_bf16(f[4], f[5]); r[3] = cvt_pk_bf16(f[6], f[7]); return r; }
;     __device__ __forceinline__ void operator()(EPI_ARGS) const {
;     ...
;             for (int m = 0; m < 4; ++m) { float z[8]; unpack8(zz[m], z);
;                 const f32x4 a0 = acc[ai][0][m][0], a1 = acc[ai][0][m][1], b0 = acc[ai][1][m][0], b1 = acc[ai][1][m][1]; float o[8];
; #pragma unroll
;                 for (int j = 0; j < 4; ++j) { o[j] = a0[j] * z[j] * __builtin_amdgcn_rcpf((1.0f + __expf(-b0[j])) * (1.0f + __expf(-z[j]))); o[4 + j] = a1[j] * z[4 + j] * __builtin_amdgcn_rcpf((1.0f + __expf(-b1[j])) * (1.0f + __expf(-z[4 + j]))); }
;                 *(u32x4*)(O + (size_t)EPI_ROW * 1024 + col) = pack8(o); } }
	v_lshlrev_b32_e32 v149, 16, v158
	v_and_b32_e32 v158, 0xffff0000, v158
	v_lshlrev_b32_e32 v169, 16, v159
	v_and_b32_e32 v184, 0xffff0000, v159
	v_lshlrev_b32_e32 v159, 16, v160
	v_and_b32_e32 v160, 0xffff0000, v160
	v_lshlrev_b32_e32 v171, 16, v161
	v_mul_f32_e32 v186, v118, v149
	v_mul_f32_e32 v118, 0xbfb8aa3b, v149
	v_mul_f32_e32 v149, v114, v159
	v_mul_f32_e32 v114, 0xbfb8aa3b, v159
	v_mul_f32_e32 v187, v119, v158
	v_mul_f32_e32 v119, 0xbfb8aa3b, v158
	v_mul_f32_e32 v188, v115, v160
	v_mul_f32_e32 v115, 0xbfb8aa3b, v160
	v_mul_f32_e32 v158, 0xbfb8aa3b, v169
	v_mul_f32_e32 v159, 0xbfb8aa3b, v171
	v_mul_f32_e32 v120, v120, v169
	v_mul_f32_e32 v116, v116, v171
	v_exp_f32_e32 v169, v118
	v_exp_f32_e32 v171, v114
	v_exp_f32_e32 v173, v119
	v_exp_f32_e32 v175, v115
	v_exp_f32_e32 v177, v158
	v_exp_f32_e32 v179, v159
	v_and_b32_e32 v185, 0xffff0000, v161
	v_mul_f32_e32 v160, 0xbfb8aa3b, v184
	v_mul_f32_e32 v161, 0xbfb8aa3b, v185
	v_exp_f32_e32 v181, v160
	v_exp_f32_e32 v183, v161
	v_pk_add_f32 v[114:115], v[168:169], 1.0 op_sel_hi:[1,0]
	v_pk_add_f32 v[118:119], v[170:171], 1.0 op_sel_hi:[1,0]
	v_pk_add_f32 v[158:159], v[172:173], 1.0 op_sel_hi:[1,0]
	v_pk_add_f32 v[160:161], v[174:175], 1.0 op_sel_hi:[1,0]
	v_pk_add_f32 v[168:169], v[176:177], 1.0 op_sel_hi:[1,0]
	v_pk_add_f32 v[170:171], v[178:179], 1.0 op_sel_hi:[1,0]
	v_mul_f32_e32 v114, v114, v115
	v_mul_f32_e32 v115, v118, v119
	v_mul_f32_e32 v118, v158, v159
	v_mul_f32_e32 v119, v160, v161
	v_mul_f32_e32 v158, v168, v169
	v_mul_f32_e32 v159, v170, v171
	v_rcp_f32_e32 v115, v115
	v_rcp_f32_e32 v118, v118
	v_rcp_f32_e32 v119, v119
	v_rcp_f32_e32 v158, v158
	v_rcp_f32_e32 v159, v159
	v_pk_add_f32 v[172:173], v[180:181], 1.0 op_sel_hi:[1,0]
	v_pk_add_f32 v[174:175], v[182:183], 1.0 op_sel_hi:[1,0]
	v_mul_f32_e32 v160, v172, v173
	v_rcp_f32_e32 v114, v114
	v_mul_f32_e32 v149, v149, v115
	v_mul_f32_e32 v115, v187, v118
	v_mul_f32_e32 v118, v188, v119
	v_mul_f32_e32 v119, v120, v158
	v_mul_f32_e32 v120, v116, v159
	v_mul_f32_e32 v116, v174, v175
	v_rcp_f32_e32 v160, v160
	v_rcp_f32_e32 v116, v116
	v_mul_f32_e32 v114, v186, v114
	v_mul_f32_e32 v121, v121, v184
	v_mul_f32_e32 v117, v117, v185
	v_mul_f32_e32 v121, v121, v160
	v_mul_f32_e32 v117, v117, v116
	v_cvt_pk_bf16_f32 v114, v114, v115
	v_cvt_pk_bf16_f32 v115, v119, v121
	v_cvt_pk_bf16_f32 v116, v149, v118
	v_lshl_add_u64 v[118:119], s[6:7], 0, v[166:167]
	v_lshl_add_u64 v[118:119], v[118:119], 0, v[144:145]
	v_cvt_pk_bf16_f32 v117, v120, v117
	global_store_dwordx4 v[118:119], v[114:117], off
	v_lshlrev_b32_e32 v118, 16, v126
	v_and_b32_e32 v119, 0xffff0000, v126
	v_lshlrev_b32_e32 v126, 16, v128
	v_exp_f32_e32 v114, v102
	v_mul_f32_e32 v102, 0xbfb8aa3b, v118
	v_exp_f32_e32 v115, v102
	v_exp_f32_e32 v116, v98
	v_mul_f32_e32 v98, 0xbfb8aa3b, v126
	v_exp_f32_e32 v117, v98
	v_pk_add_f32 v[114:115], v[114:115], 1.0 op_sel_hi:[1,0]
	v_mul_f32_e32 v110, v110, v118
	v_mul_f32_e32 v98, v114, v115
	v_pk_add_f32 v[114:115], v[116:117], 1.0 op_sel_hi:[1,0]
	v_rcp_f32_e32 v98, v98
	v_mul_f32_e32 v102, v114, v115
	v_rcp_f32_e32 v102, v102
	v_lshlrev_b32_e32 v120, 16, v127
	v_mul_f32_e32 v110, v110, v98
	v_mul_f32_e32 v98, v106, v126
	v_mul_f32_e32 v106, v98, v102
	v_mul_f32_e32 v98, 0xbfb8aa3b, v103
	v_and_b32_e32 v121, 0xffff0000, v127
	v_and_b32_e32 v127, 0xffff0000, v128
	v_exp_f32_e32 v102, v98
	v_mul_f32_e32 v98, 0xbfb8aa3b, v119
	v_exp_f32_e32 v103, v98
	v_mul_f32_e32 v98, 0xbfb8aa3b, v99
	v_mul_f32_e32 v99, 0xbfb8aa3b, v127
	v_exp_f32_e32 v98, v98
	v_exp_f32_e32 v99, v99
	v_pk_add_f32 v[102:103], v[102:103], 1.0 op_sel_hi:[1,0]
	v_lshlrev_b32_e32 v128, 16, v129
	v_mul_f32_e32 v102, v102, v103
	v_pk_add_f32 v[98:99], v[98:99], 1.0 op_sel_hi:[1,0]
	v_rcp_f32_e32 v102, v102
	v_mul_f32_e32 v98, v98, v99
	v_rcp_f32_e32 v98, v98
	v_mul_f32_e32 v99, v111, v119
	v_mul_f32_e32 v111, v99, v102
	v_mul_f32_e32 v99, v107, v127
	v_mul_f32_e32 v107, v99, v98
	v_mul_f32_e32 v98, 0xbfb8aa3b, v104
	v_mul_f32_e32 v99, 0xbfb8aa3b, v120
	v_exp_f32_e32 v98, v98
	v_exp_f32_e32 v99, v99
	v_exp_f32_e32 v102, v100
	v_mul_f32_e32 v100, 0xbfb8aa3b, v128
	v_exp_f32_e32 v103, v100
	v_pk_add_f32 v[98:99], v[98:99], 1.0 op_sel_hi:[1,0]
	v_and_b32_e32 v129, 0xffff0000, v129
	v_mul_f32_e32 v98, v98, v99
	v_rcp_f32_e32 v100, v98
	v_pk_add_f32 v[98:99], v[102:103], 1.0 op_sel_hi:[1,0]
	s_nop 0
	v_mul_f32_e32 v98, v98, v99
	v_rcp_f32_e32 v98, v98
	v_mul_f32_e32 v99, v112, v120
	v_mul_f32_e32 v102, v99, v100
	v_mul_f32_e32 v99, v108, v128
	v_mul_f32_e32 v103, v99, v98
	v_mul_f32_e32 v98, 0xbfb8aa3b, v105
	v_mul_f32_e32 v99, 0xbfb8aa3b, v121
	v_exp_f32_e32 v98, v98
	v_exp_f32_e32 v99, v99
	v_mul_f32_e32 v100, 0xbfb8aa3b, v101
	v_mul_f32_e32 v101, 0xbfb8aa3b, v129
	v_exp_f32_e32 v100, v100
	v_exp_f32_e32 v101, v101
	v_pk_add_f32 v[98:99], v[98:99], 1.0 op_sel_hi:[1,0]
	v_lshlrev_b32_e32 v108, 16, v165
	v_mul_f32_e32 v98, v98, v99
	v_rcp_f32_e32 v104, v98
	v_pk_add_f32 v[98:99], v[100:101], 1.0 op_sel_hi:[1,0]
	v_mul_f32_e32 v100, v109, v129
	v_mul_f32_e32 v98, v98, v99
	v_rcp_f32_e32 v98, v98
	v_mul_f32_e32 v99, v113, v121
	v_mul_f32_e32 v99, v99, v104
	v_lshlrev_b32_e32 v104, 16, v163
	v_mul_f32_e32 v101, v100, v98
	v_cvt_pk_bf16_f32 v98, v110, v111
	v_cvt_pk_bf16_f32 v99, v102, v99
	v_add_u32_e32 v102, s22, v151
	v_cvt_pk_bf16_f32 v100, v106, v107
	v_cvt_pk_bf16_f32 v101, v103, v101
	v_ashrrev_i32_e32 v103, 31, v102
	v_lshlrev_b64 v[102:103], 11, v[102:103]
	v_lshl_add_u64 v[102:103], s[6:7], 0, v[102:103]
	v_lshl_add_u64 v[102:103], v[102:103], 0, v[144:145]
	global_store_dwordx4 v[102:103], v[98:101], off
	v_lshlrev_b32_e32 v102, 16, v162
	v_lshlrev_b32_e32 v106, 16, v164
; __device__ __forceinline__ u32x4 pack8(const float (&f)[8]) { u32x4 r; r[0] = cvt_pk_bf16(f[0], f[1]); r[1] = cvt_pk_bf16(f[2], f[3]); r[2] = cvt_pk_bf16(f[4], f[5]); r[3] = cvt_pk_bf16(f[6], f[7]); return r; }
;     __device__ __forceinline__ void operator()(EPI_ARGS) const {
;     ...
;         for (int ai = 0; ai < 2; ++ai) if (ai == 0 || !u.half) { u32x4 zz[4];
; #pragma unroll
;             for (int m = 0; m < 4; ++m) zz[m] = *(const u32x4*)(parts + E_PZB + (size_t)EPI_ROW * 1024 + col);
;     ...
;             for (int m = 0; m < 4; ++m) { float z[8]; unpack8(zz[m], z);
;                 const f32x4 a0 = acc[ai][0][m][0], a1 = acc[ai][0][m][1], b0 = acc[ai][1][m][0], b1 = acc[ai][1][m][1]; float o[8];
; #pragma unroll
;                 for (int j = 0; j < 4; ++j) { o[j] = a0[j] * z[j] * __builtin_amdgcn_rcpf((1.0f + __expf(-b0[j])) * (1.0f + __expf(-z[j]))); o[4 + j] = a1[j] * z[4 + j] * __builtin_amdgcn_rcpf((1.0f + __expf(-b1[j])) * (1.0f + __expf(-z[4 + j]))); }
;                 *(u32x4*)(O + (size_t)EPI_ROW * 1024 + col) = pack8(o); } }
	v_exp_f32_e32 v98, v86
	v_mul_f32_e32 v86, 0xbfb8aa3b, v102
	v_exp_f32_e32 v99, v86
	v_exp_f32_e32 v100, v82
	v_mul_f32_e32 v82, 0xbfb8aa3b, v106
	v_exp_f32_e32 v101, v82
	v_pk_add_f32 v[98:99], v[98:99], 1.0 op_sel_hi:[1,0]
	v_mul_f32_e32 v94, v94, v102
	v_mul_f32_e32 v82, v98, v99
	v_pk_add_f32 v[98:99], v[100:101], 1.0 op_sel_hi:[1,0]
	v_rcp_f32_e32 v82, v82
	v_mul_f32_e32 v86, v98, v99
	v_rcp_f32_e32 v86, v86
	v_and_b32_e32 v103, 0xffff0000, v162
	v_mul_f32_e32 v94, v94, v82
	v_mul_f32_e32 v82, v90, v106
	v_mul_f32_e32 v90, v82, v86
	v_mul_f32_e32 v82, 0xbfb8aa3b, v87
	v_and_b32_e32 v107, 0xffff0000, v164
	v_exp_f32_e32 v86, v82
	v_mul_f32_e32 v82, 0xbfb8aa3b, v103
	v_exp_f32_e32 v87, v82
	v_mul_f32_e32 v82, 0xbfb8aa3b, v83
	v_mul_f32_e32 v83, 0xbfb8aa3b, v107
	v_exp_f32_e32 v82, v82
	v_exp_f32_e32 v83, v83
	v_pk_add_f32 v[86:87], v[86:87], 1.0 op_sel_hi:[1,0]
	v_and_b32_e32 v105, 0xffff0000, v163
	v_mul_f32_e32 v86, v86, v87
	v_pk_add_f32 v[82:83], v[82:83], 1.0 op_sel_hi:[1,0]
	v_rcp_f32_e32 v86, v86
	v_mul_f32_e32 v82, v82, v83
	v_rcp_f32_e32 v82, v82
	v_mul_f32_e32 v83, v95, v103
	v_mul_f32_e32 v95, v83, v86
	v_mul_f32_e32 v83, v91, v107
	v_mul_f32_e32 v91, v83, v82
	v_mul_f32_e32 v82, 0xbfb8aa3b, v88
	v_mul_f32_e32 v83, 0xbfb8aa3b, v104
	v_exp_f32_e32 v82, v82
	v_exp_f32_e32 v83, v83
	v_exp_f32_e32 v86, v84
	v_mul_f32_e32 v84, 0xbfb8aa3b, v108
	v_exp_f32_e32 v87, v84
	v_pk_add_f32 v[82:83], v[82:83], 1.0 op_sel_hi:[1,0]
	v_and_b32_e32 v109, 0xffff0000, v165
	v_mul_f32_e32 v82, v82, v83
	v_rcp_f32_e32 v84, v82
	v_pk_add_f32 v[82:83], v[86:87], 1.0 op_sel_hi:[1,0]
	s_nop 0
	v_mul_f32_e32 v82, v82, v83
	v_rcp_f32_e32 v82, v82
	v_mul_f32_e32 v83, v96, v104
	v_mul_f32_e32 v86, v83, v84
	v_mul_f32_e32 v83, v92, v108
	v_mul_f32_e32 v87, v83, v82
	v_mul_f32_e32 v82, 0xbfb8aa3b, v89
	v_mul_f32_e32 v83, 0xbfb8aa3b, v105
	v_exp_f32_e32 v82, v82
	v_exp_f32_e32 v83, v83
	v_mul_f32_e32 v84, 0xbfb8aa3b, v85
	v_mul_f32_e32 v85, 0xbfb8aa3b, v109
	v_exp_f32_e32 v84, v84
	v_exp_f32_e32 v85, v85
	v_pk_add_f32 v[82:83], v[82:83], 1.0 op_sel_hi:[1,0]
	v_lshlrev_b32_e32 v92, 16, v125
	v_mul_f32_e32 v82, v82, v83
	v_rcp_f32_e32 v88, v82
	v_pk_add_f32 v[82:83], v[84:85], 1.0 op_sel_hi:[1,0]
	v_mul_f32_e32 v84, v93, v109
	v_mul_f32_e32 v82, v82, v83
	v_rcp_f32_e32 v82, v82
	v_mul_f32_e32 v83, v97, v105
	v_mul_f32_e32 v83, v83, v88
	v_lshlrev_b32_e32 v88, 16, v123
	v_mul_f32_e32 v85, v84, v82
	v_cvt_pk_bf16_f32 v82, v94, v95
	v_cvt_pk_bf16_f32 v83, v86, v83
	v_add_u32_e32 v86, s22, v152
	v_cvt_pk_bf16_f32 v84, v90, v91
	v_cvt_pk_bf16_f32 v85, v87, v85
	v_ashrrev_i32_e32 v87, 31, v86
	v_lshlrev_b64 v[86:87], 11, v[86:87]
	v_lshl_add_u64 v[86:87], s[6:7], 0, v[86:87]
	v_lshl_add_u64 v[86:87], v[86:87], 0, v[144:145]
	global_store_dwordx4 v[86:87], v[82:85], off
	v_lshlrev_b32_e32 v86, 16, v122
	v_lshlrev_b32_e32 v90, 16, v124
	v_exp_f32_e32 v82, v70
	v_mul_f32_e32 v70, 0xbfb8aa3b, v86
	v_exp_f32_e32 v83, v70
	v_exp_f32_e32 v84, v66
	v_mul_f32_e32 v66, 0xbfb8aa3b, v90
	v_exp_f32_e32 v85, v66
	v_pk_add_f32 v[82:83], v[82:83], 1.0 op_sel_hi:[1,0]
	v_mul_f32_e32 v78, v78, v86
	v_mul_f32_e32 v66, v82, v83
	v_pk_add_f32 v[82:83], v[84:85], 1.0 op_sel_hi:[1,0]
	v_rcp_f32_e32 v66, v66
	v_mul_f32_e32 v70, v82, v83
	v_rcp_f32_e32 v70, v70
	v_and_b32_e32 v87, 0xffff0000, v122
	v_mul_f32_e32 v78, v78, v66
	v_mul_f32_e32 v66, v74, v90
	v_mul_f32_e32 v74, v66, v70
	v_mul_f32_e32 v66, 0xbfb8aa3b, v71
	v_and_b32_e32 v91, 0xffff0000, v124
	v_exp_f32_e32 v70, v66
	v_mul_f32_e32 v66, 0xbfb8aa3b, v87
	v_exp_f32_e32 v71, v66
	v_mul_f32_e32 v66, 0xbfb8aa3b, v67
	v_mul_f32_e32 v67, 0xbfb8aa3b, v91
	v_exp_f32_e32 v66, v66
	v_exp_f32_e32 v67, v67
	v_pk_add_f32 v[70:71], v[70:71], 1.0 op_sel_hi:[1,0]
	v_and_b32_e32 v89, 0xffff0000, v123
	v_mul_f32_e32 v70, v70, v71
	v_pk_add_f32 v[66:67], v[66:67], 1.0 op_sel_hi:[1,0]
	v_rcp_f32_e32 v70, v70
	v_mul_f32_e32 v66, v66, v67
	v_rcp_f32_e32 v66, v66
	v_mul_f32_e32 v67, v79, v87
	v_mul_f32_e32 v79, v67, v70
	v_mul_f32_e32 v67, v75, v91
	v_mul_f32_e32 v75, v67, v66
	v_mul_f32_e32 v66, 0xbfb8aa3b, v72
	v_mul_f32_e32 v67, 0xbfb8aa3b, v88
	v_exp_f32_e32 v66, v66
	v_exp_f32_e32 v67, v67
	v_exp_f32_e32 v70, v68
	v_mul_f32_e32 v68, 0xbfb8aa3b, v92
	v_exp_f32_e32 v71, v68
	v_pk_add_f32 v[66:67], v[66:67], 1.0 op_sel_hi:[1,0]
	v_and_b32_e32 v93, 0xffff0000, v125
	v_mul_f32_e32 v66, v66, v67
	v_rcp_f32_e32 v68, v66
	v_pk_add_f32 v[66:67], v[70:71], 1.0 op_sel_hi:[1,0]
	s_nop 0
	v_mul_f32_e32 v66, v66, v67
	v_rcp_f32_e32 v66, v66
	v_mul_f32_e32 v67, v80, v88
	v_mul_f32_e32 v70, v67, v68
	v_mul_f32_e32 v67, v76, v92
	v_mul_f32_e32 v71, v67, v66
	v_mul_f32_e32 v66, 0xbfb8aa3b, v73
	v_mul_f32_e32 v67, 0xbfb8aa3b, v89
	v_exp_f32_e32 v66, v66
	v_exp_f32_e32 v67, v67
	v_mul_f32_e32 v68, 0xbfb8aa3b, v69
	v_mul_f32_e32 v69, 0xbfb8aa3b, v93
	v_exp_f32_e32 v68, v68
	v_exp_f32_e32 v69, v69
	v_pk_add_f32 v[66:67], v[66:67], 1.0 op_sel_hi:[1,0]
	s_nop 0
	v_mul_f32_e32 v66, v66, v67
	v_rcp_f32_e32 v72, v66
	v_pk_add_f32 v[66:67], v[68:69], 1.0 op_sel_hi:[1,0]
	v_mul_f32_e32 v68, v77, v93
	v_mul_f32_e32 v66, v66, v67
	v_rcp_f32_e32 v66, v66
	v_mul_f32_e32 v67, v81, v89
	v_mul_f32_e32 v67, v67, v72
	v_mul_f32_e32 v69, v68, v66
	v_cvt_pk_bf16_f32 v66, v78, v79
	v_cvt_pk_bf16_f32 v67, v70, v67
	v_add_u32_e32 v70, s22, v153
	v_cvt_pk_bf16_f32 v68, v74, v75
	v_cvt_pk_bf16_f32 v69, v71, v69
	v_ashrrev_i32_e32 v71, 31, v70
	v_lshlrev_b64 v[70:71], 11, v[70:71]
	v_lshl_add_u64 v[70:71], s[6:7], 0, v[70:71]
	v_lshl_add_u64 v[70:71], v[70:71], 0, v[144:145]
	global_store_dwordx4 v[70:71], v[66:69], off
	s_mov_b32 s22, s16
	s_nop 0
	v_add_u32_e32 v66, 0x80, v148
	v_ashrrev_i32_e32 v67, 31, v66
	v_lshlrev_b64 v[88:89], 11, v[66:67]
	v_lshl_add_u64 v[66:67], v[146:147], 0, v[88:89]
	global_load_dwordx4 v[80:83], v[66:67], off
	v_add_u32_e32 v66, 0x90, v148
	v_ashrrev_i32_e32 v67, 31, v66
	v_lshlrev_b64 v[78:79], 11, v[66:67]
	v_lshl_add_u64 v[66:67], v[146:147], 0, v[78:79]
	global_load_dwordx4 v[84:87], v[66:67], off
	v_add_u32_e32 v66, 0xa0, v148
	v_ashrrev_i32_e32 v67, 31, v66
	v_lshlrev_b64 v[76:77], 11, v[66:67]
	v_add_u32_e32 v66, 0xb0, v148
	v_ashrrev_i32_e32 v67, 31, v66
	v_lshl_add_u64 v[90:91], v[146:147], 0, v[76:77]
	v_lshlrev_b64 v[74:75], 11, v[66:67]
	v_lshl_add_u64 v[92:93], v[146:147], 0, v[74:75]
	global_load_dwordx4 v[70:73], v[90:91], off
	global_load_dwordx4 v[66:69], v[92:93], off
	s_waitcnt vmcnt(0)
; __device__ __forceinline__ u32x4 pack8(const float (&f)[8]) { u32x4 r; r[0] = cvt_pk_bf16(f[0], f[1]); r[1] = cvt_pk_bf16(f[2], f[3]); r[2] = cvt_pk_bf16(f[4], f[5]); r[3] = cvt_pk_bf16(f[6], f[7]); return r; }
;     __device__ __forceinline__ void operator()(EPI_ARGS) const {
;     ...
;             for (int m = 0; m < 4; ++m) { float z[8]; unpack8(zz[m], z);
;                 const f32x4 a0 = acc[ai][0][m][0], a1 = acc[ai][0][m][1], b0 = acc[ai][1][m][0], b1 = acc[ai][1][m][1]; float o[8];
; #pragma unroll
;                 for (int j = 0; j < 4; ++j) { o[j] = a0[j] * z[j] * __builtin_amdgcn_rcpf((1.0f + __expf(-b0[j])) * (1.0f + __expf(-z[j]))); o[4 + j] = a1[j] * z[4 + j] * __builtin_amdgcn_rcpf((1.0f + __expf(-b1[j])) * (1.0f + __expf(-z[4 + j]))); }
;                 *(u32x4*)(O + (size_t)EPI_ROW * 1024 + col) = pack8(o); } }
	v_lshlrev_b32_e32 v90, 16, v80
	v_and_b32_e32 v91, 0xffff0000, v80
	v_lshlrev_b32_e32 v94, 16, v82
	v_exp_f32_e32 v80, v54
	v_mul_f32_e32 v54, 0xbfb8aa3b, v90
	v_lshlrev_b32_e32 v92, 16, v81
	v_and_b32_e32 v93, 0xffff0000, v81
	v_and_b32_e32 v95, 0xffff0000, v82
	v_exp_f32_e32 v81, v54
	v_exp_f32_e32 v82, v50
	v_mul_f32_e32 v50, 0xbfb8aa3b, v94
	v_lshlrev_b32_e32 v96, 16, v83
	v_and_b32_e32 v97, 0xffff0000, v83
	v_exp_f32_e32 v83, v50
	v_pk_add_f32 v[80:81], v[80:81], 1.0 op_sel_hi:[1,0]
	v_mul_f32_e32 v62, v62, v90
	v_mul_f32_e32 v50, v80, v81
	v_pk_add_f32 v[80:81], v[82:83], 1.0 op_sel_hi:[1,0]
	v_rcp_f32_e32 v50, v50
	v_mul_f32_e32 v54, v80, v81
	v_rcp_f32_e32 v54, v54
	v_mul_f32_e32 v62, v62, v50
	v_mul_f32_e32 v50, v58, v94
	v_mul_f32_e32 v58, v50, v54
	v_mul_f32_e32 v50, 0xbfb8aa3b, v55
	v_exp_f32_e32 v54, v50
	v_mul_f32_e32 v50, 0xbfb8aa3b, v91
	v_exp_f32_e32 v55, v50
	v_mul_f32_e32 v50, 0xbfb8aa3b, v51
	v_mul_f32_e32 v51, 0xbfb8aa3b, v95
	v_exp_f32_e32 v50, v50
	v_exp_f32_e32 v51, v51
	v_pk_add_f32 v[54:55], v[54:55], 1.0 op_sel_hi:[1,0]
	v_pk_add_f32 v[50:51], v[50:51], 1.0 op_sel_hi:[1,0]
	v_mul_f32_e32 v54, v54, v55
	v_rcp_f32_e32 v54, v54
	v_mul_f32_e32 v50, v50, v51
	v_rcp_f32_e32 v50, v50
	v_mul_f32_e32 v51, v63, v91
	v_mul_f32_e32 v63, v51, v54
	v_mul_f32_e32 v51, v59, v95
	v_mul_f32_e32 v59, v51, v50
	v_mul_f32_e32 v50, 0xbfb8aa3b, v56
	v_mul_f32_e32 v51, 0xbfb8aa3b, v92
	v_exp_f32_e32 v50, v50
	v_exp_f32_e32 v51, v51
	v_exp_f32_e32 v54, v52
	v_mul_f32_e32 v52, 0xbfb8aa3b, v96
	v_exp_f32_e32 v55, v52
	v_pk_add_f32 v[50:51], v[50:51], 1.0 op_sel_hi:[1,0]
	s_nop 0
	v_mul_f32_e32 v50, v50, v51
	v_rcp_f32_e32 v52, v50
	v_pk_add_f32 v[50:51], v[54:55], 1.0 op_sel_hi:[1,0]
	s_nop 0
	v_mul_f32_e32 v50, v50, v51
	v_rcp_f32_e32 v50, v50
	v_mul_f32_e32 v51, v64, v92
	v_mul_f32_e32 v54, v51, v52
	v_mul_f32_e32 v51, v60, v96
	v_mul_f32_e32 v55, v51, v50
	v_mul_f32_e32 v50, 0xbfb8aa3b, v57
	v_mul_f32_e32 v51, 0xbfb8aa3b, v93
	v_exp_f32_e32 v50, v50
	v_exp_f32_e32 v51, v51
	v_mul_f32_e32 v52, 0xbfb8aa3b, v53
	v_mul_f32_e32 v53, 0xbfb8aa3b, v97
	v_exp_f32_e32 v52, v52
	v_exp_f32_e32 v53, v53
	v_pk_add_f32 v[50:51], v[50:51], 1.0 op_sel_hi:[1,0]
	v_lshlrev_b32_e32 v60, 16, v87
	v_mul_f32_e32 v50, v50, v51
	v_rcp_f32_e32 v56, v50
	v_pk_add_f32 v[50:51], v[52:53], 1.0 op_sel_hi:[1,0]
	v_mul_f32_e32 v52, v61, v97
	v_mul_f32_e32 v50, v50, v51
	v_rcp_f32_e32 v50, v50
	v_mul_f32_e32 v51, v65, v93
	v_mul_f32_e32 v51, v51, v56
	v_lshlrev_b32_e32 v56, 16, v85
	v_mul_f32_e32 v53, v52, v50
	v_cvt_pk_bf16_f32 v50, v62, v63
	v_cvt_pk_bf16_f32 v51, v54, v51
	v_cvt_pk_bf16_f32 v52, v58, v59
	v_cvt_pk_bf16_f32 v53, v55, v53
	v_lshl_add_u64 v[54:55], s[6:7], 0, v[88:89]
	v_lshl_add_u64 v[54:55], v[54:55], 0, v[144:145]
	global_store_dwordx4 v[54:55], v[50:53], off
	v_lshlrev_b32_e32 v54, 16, v84
	v_lshlrev_b32_e32 v58, 16, v86
	v_exp_f32_e32 v50, v38
	v_mul_f32_e32 v38, 0xbfb8aa3b, v54
	v_exp_f32_e32 v51, v38
	v_exp_f32_e32 v52, v34
	v_mul_f32_e32 v34, 0xbfb8aa3b, v58
	v_exp_f32_e32 v53, v34
	v_pk_add_f32 v[50:51], v[50:51], 1.0 op_sel_hi:[1,0]
	v_mul_f32_e32 v46, v46, v54
	v_mul_f32_e32 v34, v50, v51
	v_pk_add_f32 v[50:51], v[52:53], 1.0 op_sel_hi:[1,0]
	v_rcp_f32_e32 v34, v34
	v_mul_f32_e32 v38, v50, v51
	v_rcp_f32_e32 v38, v38
	v_and_b32_e32 v55, 0xffff0000, v84
	v_mul_f32_e32 v46, v46, v34
	v_mul_f32_e32 v34, v42, v58
	v_mul_f32_e32 v42, v34, v38
	v_mul_f32_e32 v34, 0xbfb8aa3b, v39
	v_and_b32_e32 v59, 0xffff0000, v86
	v_exp_f32_e32 v38, v34
	v_mul_f32_e32 v34, 0xbfb8aa3b, v55
	v_exp_f32_e32 v39, v34
	v_mul_f32_e32 v34, 0xbfb8aa3b, v35
	v_mul_f32_e32 v35, 0xbfb8aa3b, v59
	v_exp_f32_e32 v34, v34
	v_exp_f32_e32 v35, v35
	v_pk_add_f32 v[38:39], v[38:39], 1.0 op_sel_hi:[1,0]
	v_and_b32_e32 v57, 0xffff0000, v85
	v_mul_f32_e32 v38, v38, v39
	v_pk_add_f32 v[34:35], v[34:35], 1.0 op_sel_hi:[1,0]
	v_rcp_f32_e32 v38, v38
	v_mul_f32_e32 v34, v34, v35
	v_rcp_f32_e32 v34, v34
	v_mul_f32_e32 v35, v47, v55
	v_mul_f32_e32 v47, v35, v38
	v_mul_f32_e32 v35, v43, v59
	v_mul_f32_e32 v43, v35, v34
	v_mul_f32_e32 v34, 0xbfb8aa3b, v40
	v_mul_f32_e32 v35, 0xbfb8aa3b, v56
	v_exp_f32_e32 v34, v34
	v_exp_f32_e32 v35, v35
	v_exp_f32_e32 v38, v36
	v_mul_f32_e32 v36, 0xbfb8aa3b, v60
	v_exp_f32_e32 v39, v36
	v_pk_add_f32 v[34:35], v[34:35], 1.0 op_sel_hi:[1,0]
	v_and_b32_e32 v61, 0xffff0000, v87
	v_mul_f32_e32 v34, v34, v35
	v_rcp_f32_e32 v36, v34
	v_pk_add_f32 v[34:35], v[38:39], 1.0 op_sel_hi:[1,0]
	s_nop 0
	v_mul_f32_e32 v34, v34, v35
	v_rcp_f32_e32 v34, v34
	v_mul_f32_e32 v35, v48, v56
	v_mul_f32_e32 v38, v35, v36
	v_mul_f32_e32 v35, v44, v60
	v_mul_f32_e32 v39, v35, v34
	v_mul_f32_e32 v34, 0xbfb8aa3b, v41
	v_mul_f32_e32 v35, 0xbfb8aa3b, v57
	v_exp_f32_e32 v34, v34
	v_exp_f32_e32 v35, v35
	v_mul_f32_e32 v36, 0xbfb8aa3b, v37
	v_mul_f32_e32 v37, 0xbfb8aa3b, v61
	v_exp_f32_e32 v36, v36
	v_exp_f32_e32 v37, v37
	v_pk_add_f32 v[34:35], v[34:35], 1.0 op_sel_hi:[1,0]
	v_lshlrev_b32_e32 v44, 16, v73
	v_mul_f32_e32 v34, v34, v35
	v_rcp_f32_e32 v40, v34
	v_pk_add_f32 v[34:35], v[36:37], 1.0 op_sel_hi:[1,0]
	v_mul_f32_e32 v36, v45, v61
	v_mul_f32_e32 v34, v34, v35
	v_rcp_f32_e32 v34, v34
	v_mul_f32_e32 v35, v49, v57
	v_mul_f32_e32 v35, v35, v40
	v_lshlrev_b32_e32 v40, 16, v71
	v_mul_f32_e32 v37, v36, v34
	v_cvt_pk_bf16_f32 v34, v46, v47
	v_cvt_pk_bf16_f32 v35, v38, v35
	v_cvt_pk_bf16_f32 v36, v42, v43
	v_cvt_pk_bf16_f32 v37, v39, v37
	v_lshl_add_u64 v[38:39], s[6:7], 0, v[78:79]
; __device__ __forceinline__ u32x4 pack8(const float (&f)[8]) { u32x4 r; r[0] = cvt_pk_bf16(f[0], f[1]); r[1] = cvt_pk_bf16(f[2], f[3]); r[2] = cvt_pk_bf16(f[4], f[5]); r[3] = cvt_pk_bf16(f[6], f[7]); return r; }
; #define PG8_WAIT_V(n) asm volatile("s_waitcnt vmcnt(" #n ")" ::: "memory")
; #define PG8_BAR __builtin_amdgcn_s_barrier()
; template <class Sched, class Epi>
; __device__ __forceinline__ void gemm_phase(LAS unsigned char* lds, const Sched& S, const Epi& E, const int K, const int lda, const int ldb) {
;     ...
;     PG8_WAIT_V(0);
;     if (wr == 0) PG8_BAR;
;     PG8_BAR;
;     __device__ __forceinline__ void operator()(EPI_ARGS) const {
;     ...
;             for (int m = 0; m < 4; ++m) { float z[8]; unpack8(zz[m], z);
;                 const f32x4 a0 = acc[ai][0][m][0], a1 = acc[ai][0][m][1], b0 = acc[ai][1][m][0], b1 = acc[ai][1][m][1]; float o[8];
; #pragma unroll
;                 for (int j = 0; j < 4; ++j) { o[j] = a0[j] * z[j] * __builtin_amdgcn_rcpf((1.0f + __expf(-b0[j])) * (1.0f + __expf(-z[j]))); o[4 + j] = a1[j] * z[4 + j] * __builtin_amdgcn_rcpf((1.0f + __expf(-b1[j])) * (1.0f + __expf(-z[4 + j]))); }
;                 *(u32x4*)(O + (size_t)EPI_ROW * 1024 + col) = pack8(o); } }
	v_lshl_add_u64 v[38:39], v[38:39], 0, v[144:145]
	global_store_dwordx4 v[38:39], v[34:37], off
	v_lshlrev_b32_e32 v38, 16, v70
	v_lshlrev_b32_e32 v42, 16, v72
	v_exp_f32_e32 v34, v22
	v_mul_f32_e32 v22, 0xbfb8aa3b, v38
	v_exp_f32_e32 v35, v22
	v_exp_f32_e32 v36, v18
	v_mul_f32_e32 v18, 0xbfb8aa3b, v42
	v_exp_f32_e32 v37, v18
	v_pk_add_f32 v[34:35], v[34:35], 1.0 op_sel_hi:[1,0]
	v_mul_f32_e32 v30, v30, v38
	v_mul_f32_e32 v18, v34, v35
	v_pk_add_f32 v[34:35], v[36:37], 1.0 op_sel_hi:[1,0]
	v_rcp_f32_e32 v18, v18
	v_mul_f32_e32 v22, v34, v35
	v_rcp_f32_e32 v22, v22
	v_and_b32_e32 v39, 0xffff0000, v70
	v_mul_f32_e32 v30, v30, v18
	v_mul_f32_e32 v18, v26, v42
	v_mul_f32_e32 v26, v18, v22
	v_mul_f32_e32 v18, 0xbfb8aa3b, v23
	v_and_b32_e32 v43, 0xffff0000, v72
	v_exp_f32_e32 v22, v18
	v_mul_f32_e32 v18, 0xbfb8aa3b, v39
	v_exp_f32_e32 v23, v18
	v_mul_f32_e32 v18, 0xbfb8aa3b, v19
	v_mul_f32_e32 v19, 0xbfb8aa3b, v43
	v_exp_f32_e32 v18, v18
	v_exp_f32_e32 v19, v19
	v_pk_add_f32 v[22:23], v[22:23], 1.0 op_sel_hi:[1,0]
	v_and_b32_e32 v41, 0xffff0000, v71
	v_mul_f32_e32 v22, v22, v23
	v_pk_add_f32 v[18:19], v[18:19], 1.0 op_sel_hi:[1,0]
	v_rcp_f32_e32 v22, v22
	v_mul_f32_e32 v18, v18, v19
	v_rcp_f32_e32 v18, v18
	v_mul_f32_e32 v19, v31, v39
	v_mul_f32_e32 v31, v19, v22
	v_mul_f32_e32 v19, v27, v43
	v_mul_f32_e32 v27, v19, v18
	v_mul_f32_e32 v18, 0xbfb8aa3b, v24
	v_mul_f32_e32 v19, 0xbfb8aa3b, v40
	v_exp_f32_e32 v18, v18
	v_exp_f32_e32 v19, v19
	v_exp_f32_e32 v22, v20
	v_mul_f32_e32 v20, 0xbfb8aa3b, v44
	v_exp_f32_e32 v23, v20
	v_pk_add_f32 v[18:19], v[18:19], 1.0 op_sel_hi:[1,0]
	v_and_b32_e32 v45, 0xffff0000, v73
	v_mul_f32_e32 v18, v18, v19
	v_rcp_f32_e32 v20, v18
	v_pk_add_f32 v[18:19], v[22:23], 1.0 op_sel_hi:[1,0]
	s_nop 0
	v_mul_f32_e32 v18, v18, v19
	v_rcp_f32_e32 v18, v18
	v_mul_f32_e32 v19, v32, v40
	v_mul_f32_e32 v22, v19, v20
	v_mul_f32_e32 v19, v28, v44
	v_mul_f32_e32 v23, v19, v18
	v_mul_f32_e32 v18, 0xbfb8aa3b, v25
	v_mul_f32_e32 v19, 0xbfb8aa3b, v41
	v_exp_f32_e32 v18, v18
	v_exp_f32_e32 v19, v19
	v_mul_f32_e32 v20, 0xbfb8aa3b, v21
	v_mul_f32_e32 v21, 0xbfb8aa3b, v45
	v_exp_f32_e32 v20, v20
	v_exp_f32_e32 v21, v21
	v_pk_add_f32 v[18:19], v[18:19], 1.0 op_sel_hi:[1,0]
	v_lshlrev_b32_e32 v28, 16, v69
	v_mul_f32_e32 v18, v18, v19
	v_rcp_f32_e32 v24, v18
	v_pk_add_f32 v[18:19], v[20:21], 1.0 op_sel_hi:[1,0]
	v_mul_f32_e32 v20, v29, v45
	v_mul_f32_e32 v18, v18, v19
	v_rcp_f32_e32 v18, v18
	v_mul_f32_e32 v19, v33, v41
	v_mul_f32_e32 v19, v19, v24
	v_lshlrev_b32_e32 v24, 16, v67
	v_mul_f32_e32 v21, v20, v18
	v_cvt_pk_bf16_f32 v18, v30, v31
	v_cvt_pk_bf16_f32 v19, v22, v19
	v_cvt_pk_bf16_f32 v20, v26, v27
	v_cvt_pk_bf16_f32 v21, v23, v21
	v_lshl_add_u64 v[22:23], s[6:7], 0, v[76:77]
	v_lshl_add_u64 v[22:23], v[22:23], 0, v[144:145]
	global_store_dwordx4 v[22:23], v[18:21], off
	v_lshlrev_b32_e32 v22, 16, v66
	v_lshlrev_b32_e32 v26, 16, v68
	v_exp_f32_e32 v18, v6
	v_mul_f32_e32 v6, 0xbfb8aa3b, v22
	v_exp_f32_e32 v19, v6
	v_exp_f32_e32 v20, v2
	v_mul_f32_e32 v2, 0xbfb8aa3b, v26
	v_exp_f32_e32 v21, v2
	v_pk_add_f32 v[18:19], v[18:19], 1.0 op_sel_hi:[1,0]
	v_mul_f32_e32 v14, v14, v22
	v_mul_f32_e32 v2, v18, v19
	v_pk_add_f32 v[18:19], v[20:21], 1.0 op_sel_hi:[1,0]
	v_rcp_f32_e32 v2, v2
	v_mul_f32_e32 v6, v18, v19
	v_rcp_f32_e32 v6, v6
	v_and_b32_e32 v23, 0xffff0000, v66
	v_mul_f32_e32 v14, v14, v2
	v_mul_f32_e32 v2, v10, v26
	v_mul_f32_e32 v10, v2, v6
	v_mul_f32_e32 v2, 0xbfb8aa3b, v7
	v_and_b32_e32 v27, 0xffff0000, v68
	v_exp_f32_e32 v6, v2
	v_mul_f32_e32 v2, 0xbfb8aa3b, v23
	v_exp_f32_e32 v7, v2
	v_mul_f32_e32 v2, 0xbfb8aa3b, v3
	v_mul_f32_e32 v3, 0xbfb8aa3b, v27
	v_exp_f32_e32 v2, v2
	v_exp_f32_e32 v3, v3
	v_pk_add_f32 v[6:7], v[6:7], 1.0 op_sel_hi:[1,0]
	v_and_b32_e32 v25, 0xffff0000, v67
	v_mul_f32_e32 v6, v6, v7
	v_pk_add_f32 v[2:3], v[2:3], 1.0 op_sel_hi:[1,0]
	v_rcp_f32_e32 v6, v6
	v_mul_f32_e32 v2, v2, v3
	v_rcp_f32_e32 v2, v2
	v_mul_f32_e32 v3, v15, v23
	v_mul_f32_e32 v15, v3, v6
	v_mul_f32_e32 v3, v11, v27
	v_mul_f32_e32 v11, v3, v2
	v_mul_f32_e32 v2, 0xbfb8aa3b, v8
	v_mul_f32_e32 v3, 0xbfb8aa3b, v24
	v_exp_f32_e32 v2, v2
	v_exp_f32_e32 v3, v3
	v_exp_f32_e32 v6, v4
	v_mul_f32_e32 v4, 0xbfb8aa3b, v28
	v_exp_f32_e32 v7, v4
	v_pk_add_f32 v[2:3], v[2:3], 1.0 op_sel_hi:[1,0]
	v_and_b32_e32 v29, 0xffff0000, v69
	v_mul_f32_e32 v2, v2, v3
	v_rcp_f32_e32 v4, v2
	v_pk_add_f32 v[2:3], v[6:7], 1.0 op_sel_hi:[1,0]
	s_nop 0
	v_mul_f32_e32 v2, v2, v3
	v_rcp_f32_e32 v2, v2
	v_mul_f32_e32 v3, v16, v24
	v_mul_f32_e32 v6, v3, v4
	v_mul_f32_e32 v3, v12, v28
	v_mul_f32_e32 v7, v3, v2
	v_mul_f32_e32 v2, 0xbfb8aa3b, v9
	v_mul_f32_e32 v3, 0xbfb8aa3b, v25
	v_exp_f32_e32 v2, v2
	v_exp_f32_e32 v3, v3
	v_mul_f32_e32 v4, 0xbfb8aa3b, v5
	v_mul_f32_e32 v5, 0xbfb8aa3b, v29
	v_exp_f32_e32 v4, v4
	v_exp_f32_e32 v5, v5
	v_pk_add_f32 v[2:3], v[2:3], 1.0 op_sel_hi:[1,0]
	s_nop 0
	v_mul_f32_e32 v2, v2, v3
	v_rcp_f32_e32 v8, v2
	v_pk_add_f32 v[2:3], v[4:5], 1.0 op_sel_hi:[1,0]
	v_mul_f32_e32 v4, v13, v29
	v_mul_f32_e32 v2, v2, v3
	v_rcp_f32_e32 v2, v2
	v_mul_f32_e32 v3, v17, v25
	v_mul_f32_e32 v3, v3, v8
	v_mul_f32_e32 v5, v4, v2
	v_cvt_pk_bf16_f32 v2, v14, v15
	v_cvt_pk_bf16_f32 v3, v6, v3
	v_cvt_pk_bf16_f32 v4, v10, v11
	v_cvt_pk_bf16_f32 v5, v7, v5
	v_lshl_add_u64 v[6:7], s[6:7], 0, v[74:75]
	v_lshl_add_u64 v[6:7], v[6:7], 0, v[144:145]
	global_store_dwordx4 v[6:7], v[2:5], off
	s_cbranch_vccz .LBB0_1408
	s_waitcnt vmcnt(0)
	s_cmpk_gt_u32 s2, 0xff
	s_cbranch_scc1 .LBB0_1419
	s_barrier

; #define PG8_STAGE(bufoff, gbase, voff) do { _Pragma("unroll") for (int _i = 0; _i < 2; ++_i) \
;         __builtin_amdgcn_global_load_lds((const unsigned*)((const char*)(gbase) + (voff)[_i]), (LAS unsigned*)(lds + (bufoff) + ldsw + _i * 8192), 16, 0, 0); } while (0)
; #define PG8_LDA(dst, b, h) do { _Pragma("unroll") for (int m = 0; m < 4; ++m) _Pragma("unroll") for (int k = 0; k < 2; ++k) dst[m][k] = *(const LAS bf16x8*)(lds + PG8_SA(b, h) + aoff + m * 2048 + k * 1024); } while (0)
; #define PG8_LDB(dst, b, h) do { _Pragma("unroll") for (int n = 0; n < 2; ++n) _Pragma("unroll") for (int k = 0; k < 2; ++k) dst[n][k] = *(const LAS bf16x8*)(lds + PG8_SB(b, h) + boff + n * 2048 + k * 1024); } while (0)
; #define PG8_MMA(ai, bj, At, Bt) do { __builtin_amdgcn_s_setprio(1); _Pragma("unroll") for (int m = 0; m < 4; ++m) _Pragma("unroll") for (int n = 0; n < 2; ++n) _Pragma("unroll") for (int k = 0; k < 2; ++k) \
;         acc[ai][bj][m][n] = __builtin_amdgcn_mfma_f32_16x16x32_bf16(Bt[n][k], At[m][k], acc[ai][bj][m][n], 0, 0, 0); __builtin_amdgcn_s_setprio(0); } while (0)
; #define PG8_WAIT_V(n) asm volatile("s_waitcnt vmcnt(" #n ")" ::: "memory")
; #define PG8_WAIT_L(n) asm volatile("s_waitcnt lgkmcnt(" #n ")" ::: "memory")
; #define PG8_BAR __builtin_amdgcn_s_barrier()
; #define PG8_SCHED __builtin_amdgcn_sched_barrier(0)
; template <class Sched, class Epi>
; __device__ __forceinline__ void gemm_phase(LAS unsigned char* lds, const Sched& S, const Epi& E, const int K, const int lda, const int ldb) {
;     ...
;             PG8_LDB(B0, 0, 0); PG8_SCHED; PG8_LDA(At, 0, 0); PG8_STAGE(PG8_SA(1, 1), a1 + hstepA, voffA);
;             PG8_WAIT_L(8); PG8_BAR; PG8_WAIT_L(0); PG8_MMA(0, 0, At, B0); PG8_BAR; PG8_SCHED;
;             PG8_LDB(B1, 0, 1); PG8_STAGE(PG8_SB(0, 0), b2, voffB);
;             PG8_BAR; PG8_WAIT_L(0); PG8_MMA(0, 1, At, B1); PG8_BAR;
;             PG8_LDA(At, 0, 1); PG8_STAGE(PG8_SA(0, 0), a2, voffA);
;             PG8_BAR; PG8_WAIT_L(0); if (!chalf) PG8_MMA(1, 0, At, B0); PG8_BAR; PG8_SCHED;
;             PG8_STAGE(PG8_SB(0, 1), b2 + hstepB, voffB);
;             PG8_WAIT_V(6); PG8_BAR; if (!chalf) PG8_MMA(1, 1, At, B1); PG8_BAR;
.LBB0_1486:
	ds_read_b128 v[130:133], v233
	ds_read_b128 v[134:137], v233 offset:1024
	ds_read_b128 v[138:141], v233 offset:2048
	ds_read_b128 v[142:145], v233 offset:3072
	s_add_u32 s26, s6, 0xfffc0080
	s_addc_u32 s27, s7, -1
	s_cmp_eq_u32 s19, 12
	s_cselect_b32 s29, s21, s27
	s_cselect_b32 s28, s20, s26
	s_cselect_b32 s27, s23, s17
	s_cselect_b32 s26, s22, s15
	s_add_i32 m0, s31, 0xc000
	ds_read_b128 v[146:149], v234
	ds_read_b128 v[150:153], v234 offset:1024
	ds_read_b128 v[154:157], v234 offset:2048
	ds_read_b128 v[158:161], v234 offset:3072
	ds_read_b128 v[162:165], v234 offset:4096
	ds_read_b128 v[166:169], v234 offset:5120
	ds_read_b128 v[170:173], v234 offset:6144
	ds_read_b128 v[174:177], v234 offset:7168
	global_load_lds_dwordx4 v208, s[6:7]
	s_add_i32 m0, s31, 0xe000
	s_nop 0
	global_load_lds_dwordx4 v206, s[6:7]
	s_waitcnt lgkmcnt(8)
	s_barrier
	s_waitcnt lgkmcnt(0)
	s_setprio 1
	s_waitcnt lgkmcnt(0)
	v_mfma_f32_16x16x32_bf16 v[126:129], v[130:133], v[146:149], v[126:129]
	v_mfma_f32_16x16x32_bf16 v[122:125], v[138:141], v[146:149], v[122:125]
	v_mfma_f32_16x16x32_bf16 v[118:121], v[130:133], v[154:157], v[118:121]
	v_mfma_f32_16x16x32_bf16 v[114:117], v[138:141], v[154:157], v[114:117]
	v_mfma_f32_16x16x32_bf16 v[110:113], v[130:133], v[162:165], v[110:113]
	v_mfma_f32_16x16x32_bf16 v[106:109], v[138:141], v[162:165], v[106:109]
	v_mfma_f32_16x16x32_bf16 v[102:105], v[130:133], v[170:173], v[102:105]
	v_mfma_f32_16x16x32_bf16 v[98:101], v[138:141], v[170:173], v[98:101]
	v_mfma_f32_16x16x32_bf16 v[126:129], v[134:137], v[150:153], v[126:129]
	v_mfma_f32_16x16x32_bf16 v[122:125], v[142:145], v[150:153], v[122:125]
	v_mfma_f32_16x16x32_bf16 v[118:121], v[134:137], v[158:161], v[118:121]
	v_mfma_f32_16x16x32_bf16 v[114:117], v[142:145], v[158:161], v[114:117]
	v_mfma_f32_16x16x32_bf16 v[110:113], v[134:137], v[166:169], v[110:113]
	v_mfma_f32_16x16x32_bf16 v[106:109], v[142:145], v[166:169], v[106:109]
	v_mfma_f32_16x16x32_bf16 v[102:105], v[134:137], v[174:177], v[102:105]
	v_mfma_f32_16x16x32_bf16 v[98:101], v[142:145], v[174:177], v[98:101]
	s_setprio 0
	s_barrier
	s_add_i32 s49, s43, s25
	s_add_u32 s52, s26, s12
	s_addc_u32 s53, s27, s13
	s_mov_b32 m0, s49
	ds_read_b128 v[178:181], v235
	ds_read_b128 v[182:185], v235 offset:1024
	ds_read_b128 v[186:189], v235 offset:2048
	ds_read_b128 v[190:193], v235 offset:3072
	global_load_lds_dwordx4 v200, s[26:27]
	s_add_u32 s54, s26, s12
	s_addc_u32 s55, s27, s13
	s_add_i32 m0, s49, 0x2000
	s_nop 0
	global_load_lds_dwordx4 v204, s[26:27]
	s_barrier
	s_waitcnt lgkmcnt(0)
	s_setprio 1
	s_waitcnt lgkmcnt(0)
	v_mfma_f32_16x16x32_bf16 v[94:97], v[178:181], v[146:149], v[94:97]
	v_mfma_f32_16x16x32_bf16 v[90:93], v[186:189], v[146:149], v[90:93]
	v_mfma_f32_16x16x32_bf16 v[86:89], v[178:181], v[154:157], v[86:89]
	v_mfma_f32_16x16x32_bf16 v[82:85], v[186:189], v[154:157], v[82:85]
	v_mfma_f32_16x16x32_bf16 v[78:81], v[178:181], v[162:165], v[78:81]
	v_mfma_f32_16x16x32_bf16 v[74:77], v[186:189], v[162:165], v[74:77]
	v_mfma_f32_16x16x32_bf16 v[70:73], v[178:181], v[170:173], v[70:73]
	v_mfma_f32_16x16x32_bf16 v[66:69], v[186:189], v[170:173], v[66:69]
	v_mfma_f32_16x16x32_bf16 v[94:97], v[182:185], v[150:153], v[94:97]
	v_mfma_f32_16x16x32_bf16 v[90:93], v[190:193], v[150:153], v[90:93]
	v_mfma_f32_16x16x32_bf16 v[86:89], v[182:185], v[158:161], v[86:89]
	v_mfma_f32_16x16x32_bf16 v[82:85], v[190:193], v[158:161], v[82:85]
	v_mfma_f32_16x16x32_bf16 v[78:81], v[182:185], v[166:169], v[78:81]
	v_mfma_f32_16x16x32_bf16 v[74:77], v[190:193], v[166:169], v[74:77]
	v_mfma_f32_16x16x32_bf16 v[70:73], v[182:185], v[174:177], v[70:73]
	v_mfma_f32_16x16x32_bf16 v[66:69], v[190:193], v[174:177], v[66:69]
	s_setprio 0
	s_mov_b32 m0, s31
	s_add_u32 s56, s28, s12
	s_addc_u32 s57, s29, s13
	s_barrier
	ds_read_b128 v[146:149], v234 offset:16384
	ds_read_b128 v[150:153], v234 offset:17408
	ds_read_b128 v[154:157], v234 offset:18432
	ds_read_b128 v[158:161], v234 offset:19456
	ds_read_b128 v[162:165], v234 offset:20480
	ds_read_b128 v[166:169], v234 offset:21504
	ds_read_b128 v[170:173], v234 offset:22528
	ds_read_b128 v[174:177], v234 offset:23552
	global_load_lds_dwordx4 v198, s[28:29]
	s_add_u32 s58, s28, s12
	s_addc_u32 s59, s29, s13
	s_mov_b32 m0, s33
	s_nop 0
	global_load_lds_dwordx4 v202, s[28:29]
	s_barrier
	s_waitcnt lgkmcnt(0)
	s_setprio 1
	s_waitcnt lgkmcnt(0)
	v_mfma_f32_16x16x32_bf16 v[62:65], v[130:133], v[146:149], v[62:65]
	v_mfma_f32_16x16x32_bf16 v[58:61], v[138:141], v[146:149], v[58:61]
	v_mfma_f32_16x16x32_bf16 v[54:57], v[130:133], v[154:157], v[54:57]
	v_mfma_f32_16x16x32_bf16 v[50:53], v[138:141], v[154:157], v[50:53]
	v_mfma_f32_16x16x32_bf16 v[46:49], v[130:133], v[162:165], v[46:49]
	v_mfma_f32_16x16x32_bf16 v[42:45], v[138:141], v[162:165], v[42:45]
	v_mfma_f32_16x16x32_bf16 v[38:41], v[130:133], v[170:173], v[38:41]
	v_mfma_f32_16x16x32_bf16 v[34:37], v[138:141], v[170:173], v[34:37]
	v_mfma_f32_16x16x32_bf16 v[62:65], v[134:137], v[150:153], v[62:65]
	v_mfma_f32_16x16x32_bf16 v[58:61], v[142:145], v[150:153], v[58:61]
	v_mfma_f32_16x16x32_bf16 v[54:57], v[134:137], v[158:161], v[54:57]
	v_mfma_f32_16x16x32_bf16 v[50:53], v[142:145], v[158:161], v[50:53]
	v_mfma_f32_16x16x32_bf16 v[46:49], v[134:137], v[166:169], v[46:49]
	v_mfma_f32_16x16x32_bf16 v[42:45], v[142:145], v[166:169], v[42:45]
	v_mfma_f32_16x16x32_bf16 v[38:41], v[134:137], v[174:177], v[38:41]
	v_mfma_f32_16x16x32_bf16 v[34:37], v[142:145], v[174:177], v[34:37]
	s_setprio 0
	s_barrier
	s_add_u32 s50, s26, 0x40000
	s_addc_u32 s51, s27, 0
	s_add_i32 s49, s44, s25
	s_mov_b32 m0, s49
	s_nop 0
	global_load_lds_dwordx4 v200, s[50:51]
	s_add_i32 m0, s49, 0x2000
	s_nop 0
	global_load_lds_dwordx4 v204, s[50:51]
	s_waitcnt vmcnt(6)
	s_barrier
; #define PG8_STAGE(bufoff, gbase, voff) do { _Pragma("unroll") for (int _i = 0; _i < 2; ++_i) \
;         __builtin_amdgcn_global_load_lds((const unsigned*)((const char*)(gbase) + (voff)[_i]), (LAS unsigned*)(lds + (bufoff) + ldsw + _i * 8192), 16, 0, 0); } while (0)
; #define PG8_LDA(dst, b, h) do { _Pragma("unroll") for (int m = 0; m < 4; ++m) _Pragma("unroll") for (int k = 0; k < 2; ++k) dst[m][k] = *(const LAS bf16x8*)(lds + PG8_SA(b, h) + aoff + m * 2048 + k * 1024); } while (0)
; #define PG8_LDB(dst, b, h) do { _Pragma("unroll") for (int n = 0; n < 2; ++n) _Pragma("unroll") for (int k = 0; k < 2; ++k) dst[n][k] = *(const LAS bf16x8*)(lds + PG8_SB(b, h) + boff + n * 2048 + k * 1024); } while (0)
; #define PG8_MMA(ai, bj, At, Bt) do { __builtin_amdgcn_s_setprio(1); _Pragma("unroll") for (int m = 0; m < 4; ++m) _Pragma("unroll") for (int n = 0; n < 2; ++n) _Pragma("unroll") for (int k = 0; k < 2; ++k) \
;         acc[ai][bj][m][n] = __builtin_amdgcn_mfma_f32_16x16x32_bf16(Bt[n][k], At[m][k], acc[ai][bj][m][n], 0, 0, 0); __builtin_amdgcn_s_setprio(0); } while (0)
; #define PG8_WAIT_V(n) asm volatile("s_waitcnt vmcnt(" #n ")" ::: "memory")
; #define PG8_WAIT_L(n) asm volatile("s_waitcnt lgkmcnt(" #n ")" ::: "memory")
; #define PG8_BAR __builtin_amdgcn_s_barrier()
; #define PG8_SCHED __builtin_amdgcn_sched_barrier(0)
; template <class Sched, class Epi>
; __device__ __forceinline__ void gemm_phase(LAS unsigned char* lds, const Sched& S, const Epi& E, const int K, const int lda, const int ldb) {
;     ...
;             PG8_WAIT_V(6); PG8_BAR; if (!chalf) PG8_MMA(1, 1, At, B1); PG8_BAR;
;             PG8_LDB(B0, 1, 0); PG8_SCHED; PG8_LDA(At, 1, 0); PG8_STAGE(PG8_SA(0, 1), a2 + hstepA, voffA);
;             PG8_WAIT_L(8); PG8_BAR; PG8_WAIT_L(0); PG8_MMA(0, 0, At, B0); PG8_BAR; PG8_SCHED;
;             PG8_LDB(B1, 1, 1); PG8_STAGE(PG8_SB(1, 0), b3, voffB);
;             PG8_BAR; PG8_WAIT_L(0); PG8_MMA(0, 1, At, B1); PG8_BAR;
;             PG8_LDA(At, 1, 1); PG8_STAGE(PG8_SA(1, 0), a3, voffA);
	s_setprio 1
	v_mfma_f32_16x16x32_bf16 v[30:33], v[178:181], v[146:149], v[30:33]
	v_mfma_f32_16x16x32_bf16 v[26:29], v[186:189], v[146:149], v[26:29]
	v_mfma_f32_16x16x32_bf16 v[22:25], v[178:181], v[154:157], v[22:25]
	v_mfma_f32_16x16x32_bf16 v[18:21], v[186:189], v[154:157], v[18:21]
	v_mfma_f32_16x16x32_bf16 v[14:17], v[178:181], v[162:165], v[14:17]
	v_mfma_f32_16x16x32_bf16 v[10:13], v[186:189], v[162:165], v[10:13]
	v_mfma_f32_16x16x32_bf16 v[6:9], v[178:181], v[170:173], v[6:9]
	v_mfma_f32_16x16x32_bf16 v[2:5], v[186:189], v[170:173], v[2:5]
	v_mfma_f32_16x16x32_bf16 v[30:33], v[182:185], v[150:153], v[30:33]
	v_mfma_f32_16x16x32_bf16 v[26:29], v[190:193], v[150:153], v[26:29]
	v_mfma_f32_16x16x32_bf16 v[22:25], v[182:185], v[158:161], v[22:25]
	v_mfma_f32_16x16x32_bf16 v[18:21], v[190:193], v[158:161], v[18:21]
	v_mfma_f32_16x16x32_bf16 v[14:17], v[182:185], v[166:169], v[14:17]
	v_mfma_f32_16x16x32_bf16 v[10:13], v[190:193], v[166:169], v[10:13]
	v_mfma_f32_16x16x32_bf16 v[6:9], v[182:185], v[174:177], v[6:9]
	v_mfma_f32_16x16x32_bf16 v[2:5], v[190:193], v[174:177], v[2:5]
	s_setprio 0
	s_add_i32 s49, 16, 0x18000
	v_add_u32_e32 v142, s49, v224
	s_barrier
	ds_read_b128 v[130:133], v142
	ds_read_b128 v[134:137], v142 offset:1024
	ds_read_b128 v[138:141], v142 offset:2048
	ds_read_b128 v[142:145], v142 offset:3072
	s_add_u32 s28, s28, 0x40000
	s_addc_u32 s29, s29, 0
	s_mov_b32 m0, s34
	ds_read_b128 v[146:149], v234 offset:32768
	ds_read_b128 v[150:153], v234 offset:33792
	ds_read_b128 v[154:157], v234 offset:34816
	ds_read_b128 v[158:161], v234 offset:35840
	ds_read_b128 v[162:165], v234 offset:36864
	ds_read_b128 v[166:169], v234 offset:37888
	ds_read_b128 v[170:173], v234 offset:38912
	ds_read_b128 v[174:177], v234 offset:39936
	global_load_lds_dwordx4 v198, s[28:29]
	s_mov_b32 m0, s35
	s_nop 0
	global_load_lds_dwordx4 v202, s[28:29]
	s_waitcnt lgkmcnt(8)
	s_barrier
	s_waitcnt lgkmcnt(0)
	s_setprio 1
	s_waitcnt lgkmcnt(0)
	v_mfma_f32_16x16x32_bf16 v[126:129], v[130:133], v[146:149], v[126:129]
	v_mfma_f32_16x16x32_bf16 v[122:125], v[138:141], v[146:149], v[122:125]
	v_mfma_f32_16x16x32_bf16 v[118:121], v[130:133], v[154:157], v[118:121]
	v_mfma_f32_16x16x32_bf16 v[114:117], v[138:141], v[154:157], v[114:117]
	v_mfma_f32_16x16x32_bf16 v[110:113], v[130:133], v[162:165], v[110:113]
	v_mfma_f32_16x16x32_bf16 v[106:109], v[138:141], v[162:165], v[106:109]
	v_mfma_f32_16x16x32_bf16 v[102:105], v[130:133], v[170:173], v[102:105]
	v_mfma_f32_16x16x32_bf16 v[98:101], v[138:141], v[170:173], v[98:101]
	v_mfma_f32_16x16x32_bf16 v[126:129], v[134:137], v[150:153], v[126:129]
	v_mfma_f32_16x16x32_bf16 v[122:125], v[142:145], v[150:153], v[122:125]
	v_mfma_f32_16x16x32_bf16 v[118:121], v[134:137], v[158:161], v[118:121]
	v_mfma_f32_16x16x32_bf16 v[114:117], v[142:145], v[158:161], v[114:117]
	v_mfma_f32_16x16x32_bf16 v[110:113], v[134:137], v[166:169], v[110:113]
	v_mfma_f32_16x16x32_bf16 v[106:109], v[142:145], v[166:169], v[106:109]
	v_mfma_f32_16x16x32_bf16 v[102:105], v[134:137], v[174:177], v[102:105]
	v_mfma_f32_16x16x32_bf16 v[98:101], v[142:145], v[174:177], v[98:101]
	s_setprio 0
	s_barrier
	s_add_i32 s28, 16, 0x1c000
	s_add_i32 s29, s49, s25
	v_add_u32_e32 v190, s28, v224
	s_mov_b32 m0, s29
	ds_read_b128 v[178:181], v190
	ds_read_b128 v[182:185], v190 offset:1024
	ds_read_b128 v[186:189], v190 offset:2048
	ds_read_b128 v[190:193], v190 offset:3072
	global_load_lds_dwordx4 v200, s[52:53]
	s_add_i32 m0, s29, 0x2000
	s_nop 0
	global_load_lds_dwordx4 v204, s[54:55]
	s_barrier
	s_waitcnt lgkmcnt(0)
	s_setprio 1
	s_waitcnt lgkmcnt(0)
	v_mfma_f32_16x16x32_bf16 v[94:97], v[178:181], v[146:149], v[94:97]
	v_mfma_f32_16x16x32_bf16 v[90:93], v[186:189], v[146:149], v[90:93]
	v_mfma_f32_16x16x32_bf16 v[86:89], v[178:181], v[154:157], v[86:89]
	v_mfma_f32_16x16x32_bf16 v[82:85], v[186:189], v[154:157], v[82:85]
	v_mfma_f32_16x16x32_bf16 v[78:81], v[178:181], v[162:165], v[78:81]
	v_mfma_f32_16x16x32_bf16 v[74:77], v[186:189], v[162:165], v[74:77]
	v_mfma_f32_16x16x32_bf16 v[70:73], v[178:181], v[170:173], v[70:73]
	v_mfma_f32_16x16x32_bf16 v[66:69], v[186:189], v[170:173], v[66:69]
	v_mfma_f32_16x16x32_bf16 v[94:97], v[182:185], v[150:153], v[94:97]
	v_mfma_f32_16x16x32_bf16 v[90:93], v[190:193], v[150:153], v[90:93]
	v_mfma_f32_16x16x32_bf16 v[86:89], v[182:185], v[158:161], v[86:89]
	v_mfma_f32_16x16x32_bf16 v[82:85], v[190:193], v[158:161], v[82:85]
	v_mfma_f32_16x16x32_bf16 v[78:81], v[182:185], v[166:169], v[78:81]
	v_mfma_f32_16x16x32_bf16 v[74:77], v[190:193], v[166:169], v[74:77]
	v_mfma_f32_16x16x32_bf16 v[70:73], v[182:185], v[174:177], v[70:73]
	v_mfma_f32_16x16x32_bf16 v[66:69], v[190:193], v[174:177], v[66:69]
	s_setprio 0
	s_mov_b32 m0, s39
	s_barrier
; #define PG8_STAGE(bufoff, gbase, voff) do { _Pragma("unroll") for (int _i = 0; _i < 2; ++_i) \
;         __builtin_amdgcn_global_load_lds((const unsigned*)((const char*)(gbase) + (voff)[_i]), (LAS unsigned*)(lds + (bufoff) + ldsw + _i * 8192), 16, 0, 0); } while (0)
; #define PG8_LDA(dst, b, h) do { _Pragma("unroll") for (int m = 0; m < 4; ++m) _Pragma("unroll") for (int k = 0; k < 2; ++k) dst[m][k] = *(const LAS bf16x8*)(lds + PG8_SA(b, h) + aoff + m * 2048 + k * 1024); } while (0)
; #define PG8_MMA(ai, bj, At, Bt) do { __builtin_amdgcn_s_setprio(1); _Pragma("unroll") for (int m = 0; m < 4; ++m) _Pragma("unroll") for (int n = 0; n < 2; ++n) _Pragma("unroll") for (int k = 0; k < 2; ++k) \
;         acc[ai][bj][m][n] = __builtin_amdgcn_mfma_f32_16x16x32_bf16(Bt[n][k], At[m][k], acc[ai][bj][m][n], 0, 0, 0); __builtin_amdgcn_s_setprio(0); } while (0)
; #define PG8_WAIT_V(n) asm volatile("s_waitcnt vmcnt(" #n ")" ::: "memory")
; #define PG8_WAIT_L(n) asm volatile("s_waitcnt lgkmcnt(" #n ")" ::: "memory")
; #define PG8_BAR __builtin_amdgcn_s_barrier()
; #define PG8_SCHED __builtin_amdgcn_sched_barrier(0)
; template <class Sched, class Epi>
; __device__ __forceinline__ void gemm_phase(LAS unsigned char* lds, const Sched& S, const Epi& E, const int K, const int lda, const int ldb) {
;     ...
;             PG8_LDA(At, 1, 1); PG8_STAGE(PG8_SA(1, 0), a3, voffA);
;             PG8_BAR; PG8_WAIT_L(0); if (!chalf) PG8_MMA(1, 0, At, B0); PG8_BAR; PG8_SCHED;
;             PG8_STAGE(PG8_SB(1, 1), b3 + hstepB, voffB);
;             PG8_WAIT_V(6); PG8_BAR; if (!chalf) PG8_MMA(1, 1, At, B1); PG8_BAR;
;         }
;         E(acc, cur, wr, wc, fr, fq);
	ds_read_b128 v[146:149], v234 offset:49152
	ds_read_b128 v[150:153], v234 offset:50176
	ds_read_b128 v[154:157], v234 offset:51200
	ds_read_b128 v[158:161], v234 offset:52224
	ds_read_b128 v[162:165], v234 offset:53248
	ds_read_b128 v[166:169], v234 offset:54272
	ds_read_b128 v[170:173], v234 offset:55296
	ds_read_b128 v[174:177], v234 offset:56320
	global_load_lds_dwordx4 v198, s[56:57]
	s_mov_b32 m0, s40
	s_nop 0
	global_load_lds_dwordx4 v202, s[58:59]
	s_barrier
	s_waitcnt lgkmcnt(0)
	s_setprio 1
	s_waitcnt lgkmcnt(0)
	v_mfma_f32_16x16x32_bf16 v[62:65], v[130:133], v[146:149], v[62:65]
	v_mfma_f32_16x16x32_bf16 v[58:61], v[138:141], v[146:149], v[58:61]
	v_mfma_f32_16x16x32_bf16 v[54:57], v[130:133], v[154:157], v[54:57]
	v_mfma_f32_16x16x32_bf16 v[50:53], v[138:141], v[154:157], v[50:53]
	v_mfma_f32_16x16x32_bf16 v[46:49], v[130:133], v[162:165], v[46:49]
	v_mfma_f32_16x16x32_bf16 v[42:45], v[138:141], v[162:165], v[42:45]
	v_mfma_f32_16x16x32_bf16 v[38:41], v[130:133], v[170:173], v[38:41]
	v_mfma_f32_16x16x32_bf16 v[34:37], v[138:141], v[170:173], v[34:37]
	v_mfma_f32_16x16x32_bf16 v[62:65], v[134:137], v[150:153], v[62:65]
	v_mfma_f32_16x16x32_bf16 v[58:61], v[142:145], v[150:153], v[58:61]
	v_mfma_f32_16x16x32_bf16 v[54:57], v[134:137], v[158:161], v[54:57]
	v_mfma_f32_16x16x32_bf16 v[50:53], v[142:145], v[158:161], v[50:53]
	v_mfma_f32_16x16x32_bf16 v[46:49], v[134:137], v[166:169], v[46:49]
	v_mfma_f32_16x16x32_bf16 v[42:45], v[142:145], v[166:169], v[42:45]
	v_mfma_f32_16x16x32_bf16 v[38:41], v[134:137], v[174:177], v[38:41]
	v_mfma_f32_16x16x32_bf16 v[34:37], v[142:145], v[174:177], v[34:37]
	s_setprio 0
	s_barrier
	s_add_u32 s26, s26, 0x40080
	s_addc_u32 s27, s27, 0
	s_add_i32 s28, s28, s25
	s_mov_b32 m0, s28
	s_nop 0
	global_load_lds_dwordx4 v200, s[26:27]
	s_add_i32 m0, s28, 0x2000
	s_nop 0
	global_load_lds_dwordx4 v204, s[26:27]
	s_waitcnt vmcnt(6)
	s_barrier
	s_setprio 1
	v_mfma_f32_16x16x32_bf16 v[30:33], v[178:181], v[146:149], v[30:33]
	v_mfma_f32_16x16x32_bf16 v[26:29], v[186:189], v[146:149], v[26:29]
	v_mfma_f32_16x16x32_bf16 v[22:25], v[178:181], v[154:157], v[22:25]
	v_mfma_f32_16x16x32_bf16 v[18:21], v[186:189], v[154:157], v[18:21]
	v_mfma_f32_16x16x32_bf16 v[14:17], v[178:181], v[162:165], v[14:17]
	v_mfma_f32_16x16x32_bf16 v[10:13], v[186:189], v[162:165], v[10:13]
	v_mfma_f32_16x16x32_bf16 v[6:9], v[178:181], v[170:173], v[6:9]
	v_mfma_f32_16x16x32_bf16 v[2:5], v[186:189], v[170:173], v[2:5]
	v_mfma_f32_16x16x32_bf16 v[30:33], v[182:185], v[150:153], v[30:33]
	v_mfma_f32_16x16x32_bf16 v[26:29], v[190:193], v[150:153], v[26:29]
	v_mfma_f32_16x16x32_bf16 v[22:25], v[182:185], v[158:161], v[22:25]
	v_mfma_f32_16x16x32_bf16 v[18:21], v[190:193], v[158:161], v[18:21]
	v_mfma_f32_16x16x32_bf16 v[14:17], v[182:185], v[166:169], v[14:17]
	v_mfma_f32_16x16x32_bf16 v[10:13], v[190:193], v[166:169], v[10:13]
	v_mfma_f32_16x16x32_bf16 v[6:9], v[182:185], v[174:177], v[6:9]
	v_mfma_f32_16x16x32_bf16 v[2:5], v[190:193], v[174:177], v[2:5]
	s_setprio 0
	s_add_i32 s19, s19, 2
	s_add_u32 s15, s15, 0x100
	s_addc_u32 s17, s17, 0
	s_add_u32 s6, s6, 0x100
	s_addc_u32 s7, s7, 0
	s_cmp_gt_u32 s19, 13
	s_barrier
	s_cbranch_scc0 .LBB0_1486
	s_lshl_b32 s6, s48, 11
	s_ashr_i32 s7, s6, 31
	s_lshl_b64 s[26:27], s[6:7], 1
	v_lshl_or_b32 v134, s47, 8, v232
	s_add_u32 s6, s41, s26
	v_ashrrev_i32_e32 v135, 31, v134
	s_addc_u32 s7, s42, s27
	v_lshlrev_b64 v[212:213], 1, v[134:135]
	v_add_u32_e32 v130, s24, v1
	v_lshl_add_u64 v[216:217], s[6:7], 0, v[212:213]
	v_mad_i64_i32 v[132:133], s[6:7], v130, s45, v[216:217]
	global_load_dwordx4 v[194:197], v[132:133], off
	v_ashrrev_i32_e32 v131, 31, v130
	s_cmp_gt_i32 s48, 0
	v_lshl_add_u64 v[218:219], s[8:9], 0, v[212:213]
	v_lshlrev_b64 v[132:133], 12, v[130:131]
	s_cselect_b64 s[28:29], -1, 0
	s_cmp_lt_i32 s48, 1
	v_lshl_add_u64 v[136:137], v[218:219], 0, v[132:133]
	s_cbranch_scc1 .LBB0_1489
	global_load_dwordx4 v[190:193], v[136:137], off
	s_branch .LBB0_1490

; #define PG8_STAGE(bufoff, gbase, voff) do { _Pragma("unroll") for (int _i = 0; _i < 2; ++_i) \
;         __builtin_amdgcn_global_load_lds((const unsigned*)((const char*)(gbase) + (voff)[_i]), (LAS unsigned*)(lds + (bufoff) + ldsw + _i * 8192), 16, 0, 0); } while (0)
; #define PG8_LDA(dst, b, h) do { _Pragma("unroll") for (int m = 0; m < 4; ++m) _Pragma("unroll") for (int k = 0; k < 2; ++k) dst[m][k] = *(const LAS bf16x8*)(lds + PG8_SA(b, h) + aoff + m * 2048 + k * 1024); } while (0)
; #define PG8_LDB(dst, b, h) do { _Pragma("unroll") for (int n = 0; n < 2; ++n) _Pragma("unroll") for (int k = 0; k < 2; ++k) dst[n][k] = *(const LAS bf16x8*)(lds + PG8_SB(b, h) + boff + n * 2048 + k * 1024); } while (0)
; #define PG8_MMA(ai, bj, At, Bt) do { __builtin_amdgcn_s_setprio(1); _Pragma("unroll") for (int m = 0; m < 4; ++m) _Pragma("unroll") for (int n = 0; n < 2; ++n) _Pragma("unroll") for (int k = 0; k < 2; ++k) \
;         acc[ai][bj][m][n] = __builtin_amdgcn_mfma_f32_16x16x32_bf16(Bt[n][k], At[m][k], acc[ai][bj][m][n], 0, 0, 0); __builtin_amdgcn_s_setprio(0); } while (0)
; #define PG8_WAIT_V(n) asm volatile("s_waitcnt vmcnt(" #n ")" ::: "memory")
; #define PG8_WAIT_L(n) asm volatile("s_waitcnt lgkmcnt(" #n ")" ::: "memory")
; #define PG8_BAR __builtin_amdgcn_s_barrier()
; #define PG8_SCHED __builtin_amdgcn_sched_barrier(0)
; template <class Sched, class Epi>
; __device__ __forceinline__ void gemm_phase(LAS unsigned char* lds, const Sched& S, const Epi& E, const int K, const int lda, const int ldb) {
;     ...
;             PG8_LDB(B0, 0, 0); PG8_SCHED; PG8_LDA(At, 0, 0); PG8_STAGE(PG8_SA(1, 1), a1 + hstepA, voffA);
;             PG8_WAIT_L(8); PG8_BAR; PG8_WAIT_L(0); PG8_MMA(0, 0, At, B0); PG8_BAR; PG8_SCHED;
;             PG8_LDB(B1, 0, 1); PG8_STAGE(PG8_SB(0, 0), b2, voffB);
;             PG8_BAR; PG8_WAIT_L(0); PG8_MMA(0, 1, At, B1); PG8_BAR;
;             PG8_LDA(At, 0, 1); PG8_STAGE(PG8_SA(0, 0), a2, voffA);
;             PG8_BAR; PG8_WAIT_L(0); if (!chalf) PG8_MMA(1, 0, At, B0); PG8_BAR; PG8_SCHED;
;             PG8_STAGE(PG8_SB(0, 1), b2 + hstepB, voffB);
;             PG8_WAIT_V(6); PG8_BAR; if (!chalf) PG8_MMA(1, 1, At, B1); PG8_BAR;
.LBB0_1593:
	ds_read_b128 v[156:159], v153
	ds_read_b128 v[160:163], v153 offset:1024
	ds_read_b128 v[164:167], v153 offset:2048
	ds_read_b128 v[168:171], v153 offset:3072
	s_add_u32 s28, s26, 0xfff80080
	s_addc_u32 s29, s27, -1
	s_cmp_eq_u32 s46, 28
	s_cselect_b32 s35, s23, s29
	s_cselect_b32 s34, s22, s28
	s_cselect_b32 s29, s25, s17
	s_cselect_b32 s28, s24, s15
	s_add_i32 m0, s5, 0xc000
	ds_read_b128 v[172:175], v154
	ds_read_b128 v[176:179], v154 offset:1024
	ds_read_b128 v[180:183], v154 offset:2048
	ds_read_b128 v[184:187], v154 offset:3072
	ds_read_b128 v[188:191], v154 offset:4096
	ds_read_b128 v[192:195], v154 offset:5120
	ds_read_b128 v[196:199], v154 offset:6144
	ds_read_b128 v[200:203], v154 offset:7168
	global_load_lds_dwordx4 v140, s[26:27]
	s_add_i32 m0, s5, 0xe000
	s_nop 0
	global_load_lds_dwordx4 v138, s[26:27]
	s_waitcnt lgkmcnt(8)
	s_barrier
	s_waitcnt lgkmcnt(0)
	s_setprio 1
	s_waitcnt lgkmcnt(0)
	v_mfma_f32_16x16x32_bf16 v[126:129], v[156:159], v[172:175], v[126:129]
	v_mfma_f32_16x16x32_bf16 v[122:125], v[164:167], v[172:175], v[122:125]
	v_mfma_f32_16x16x32_bf16 v[114:117], v[156:159], v[180:183], v[114:117]
	v_mfma_f32_16x16x32_bf16 v[106:109], v[164:167], v[180:183], v[106:109]
	v_mfma_f32_16x16x32_bf16 v[98:101], v[156:159], v[188:191], v[98:101]
	v_mfma_f32_16x16x32_bf16 v[90:93], v[164:167], v[188:191], v[90:93]
	v_mfma_f32_16x16x32_bf16 v[82:85], v[156:159], v[196:199], v[82:85]
	v_mfma_f32_16x16x32_bf16 v[74:77], v[164:167], v[196:199], v[74:77]
	v_mfma_f32_16x16x32_bf16 v[126:129], v[160:163], v[176:179], v[126:129]
	v_mfma_f32_16x16x32_bf16 v[122:125], v[168:171], v[176:179], v[122:125]
	v_mfma_f32_16x16x32_bf16 v[114:117], v[160:163], v[184:187], v[114:117]
	v_mfma_f32_16x16x32_bf16 v[106:109], v[168:171], v[184:187], v[106:109]
	v_mfma_f32_16x16x32_bf16 v[98:101], v[160:163], v[192:195], v[98:101]
	v_mfma_f32_16x16x32_bf16 v[90:93], v[168:171], v[192:195], v[90:93]
	v_mfma_f32_16x16x32_bf16 v[82:85], v[160:163], v[200:203], v[82:85]
	v_mfma_f32_16x16x32_bf16 v[74:77], v[168:171], v[200:203], v[74:77]
	s_setprio 0
	s_barrier
	s_add_i32 s47, s43, s31
	s_add_u32 s52, s28, s8
	s_addc_u32 s53, s29, s9
	s_mov_b32 m0, s47
	ds_read_b128 v[204:207], v155
	ds_read_b128 v[208:211], v155 offset:1024
	ds_read_b128 v[212:215], v155 offset:2048
	ds_read_b128 v[216:219], v155 offset:3072
	global_load_lds_dwordx4 v132, s[28:29]
	s_add_u32 s54, s28, s8
	s_addc_u32 s55, s29, s9
	s_add_i32 m0, s47, 0x2000
	s_nop 0
	global_load_lds_dwordx4 v136, s[28:29]
	s_barrier
	s_waitcnt lgkmcnt(0)
	s_setprio 1
	s_waitcnt lgkmcnt(0)
	v_mfma_f32_16x16x32_bf16 v[118:121], v[204:207], v[172:175], v[118:121]
	v_mfma_f32_16x16x32_bf16 v[110:113], v[212:215], v[172:175], v[110:113]
	v_mfma_f32_16x16x32_bf16 v[102:105], v[204:207], v[180:183], v[102:105]
	v_mfma_f32_16x16x32_bf16 v[94:97], v[212:215], v[180:183], v[94:97]
	v_mfma_f32_16x16x32_bf16 v[86:89], v[204:207], v[188:191], v[86:89]
	v_mfma_f32_16x16x32_bf16 v[78:81], v[212:215], v[188:191], v[78:81]
	v_mfma_f32_16x16x32_bf16 v[70:73], v[204:207], v[196:199], v[70:73]
	v_mfma_f32_16x16x32_bf16 v[66:69], v[212:215], v[196:199], v[66:69]
	v_mfma_f32_16x16x32_bf16 v[118:121], v[208:211], v[176:179], v[118:121]
	v_mfma_f32_16x16x32_bf16 v[110:113], v[216:219], v[176:179], v[110:113]
	v_mfma_f32_16x16x32_bf16 v[102:105], v[208:211], v[184:187], v[102:105]
	v_mfma_f32_16x16x32_bf16 v[94:97], v[216:219], v[184:187], v[94:97]
	v_mfma_f32_16x16x32_bf16 v[86:89], v[208:211], v[192:195], v[86:89]
	v_mfma_f32_16x16x32_bf16 v[78:81], v[216:219], v[192:195], v[78:81]
	v_mfma_f32_16x16x32_bf16 v[70:73], v[208:211], v[200:203], v[70:73]
	v_mfma_f32_16x16x32_bf16 v[66:69], v[216:219], v[200:203], v[66:69]
	s_setprio 0
	s_mov_b32 m0, s5
	s_add_u32 s56, s34, s8
	s_addc_u32 s57, s35, s9
	s_barrier
	ds_read_b128 v[172:175], v154 offset:16384
	ds_read_b128 v[176:179], v154 offset:17408
	ds_read_b128 v[180:183], v154 offset:18432
	ds_read_b128 v[184:187], v154 offset:19456
	ds_read_b128 v[188:191], v154 offset:20480
	ds_read_b128 v[192:195], v154 offset:21504
	ds_read_b128 v[196:199], v154 offset:22528
	ds_read_b128 v[200:203], v154 offset:23552
	global_load_lds_dwordx4 v130, s[34:35]
	s_add_u32 s58, s34, s8
	s_addc_u32 s59, s35, s9
	s_mov_b32 m0, s33
	s_nop 0
	global_load_lds_dwordx4 v134, s[34:35]
	s_barrier
	s_waitcnt lgkmcnt(0)
	s_setprio 1
	s_waitcnt lgkmcnt(0)
	v_mfma_f32_16x16x32_bf16 v[62:65], v[156:159], v[172:175], v[62:65]
	v_mfma_f32_16x16x32_bf16 v[58:61], v[164:167], v[172:175], v[58:61]
	v_mfma_f32_16x16x32_bf16 v[54:57], v[156:159], v[180:183], v[54:57]
	v_mfma_f32_16x16x32_bf16 v[46:49], v[164:167], v[180:183], v[46:49]
	v_mfma_f32_16x16x32_bf16 v[38:41], v[156:159], v[188:191], v[38:41]
	v_mfma_f32_16x16x32_bf16 v[30:33], v[164:167], v[188:191], v[30:33]
	v_mfma_f32_16x16x32_bf16 v[22:25], v[156:159], v[196:199], v[22:25]
	v_mfma_f32_16x16x32_bf16 v[14:17], v[164:167], v[196:199], v[14:17]
	v_mfma_f32_16x16x32_bf16 v[62:65], v[160:163], v[176:179], v[62:65]
	v_mfma_f32_16x16x32_bf16 v[58:61], v[168:171], v[176:179], v[58:61]
	v_mfma_f32_16x16x32_bf16 v[54:57], v[160:163], v[184:187], v[54:57]
	v_mfma_f32_16x16x32_bf16 v[46:49], v[168:171], v[184:187], v[46:49]
	v_mfma_f32_16x16x32_bf16 v[38:41], v[160:163], v[192:195], v[38:41]
	v_mfma_f32_16x16x32_bf16 v[30:33], v[168:171], v[192:195], v[30:33]
	v_mfma_f32_16x16x32_bf16 v[22:25], v[160:163], v[200:203], v[22:25]
	v_mfma_f32_16x16x32_bf16 v[14:17], v[168:171], v[200:203], v[14:17]
	s_setprio 0
	s_barrier
	s_add_u32 s48, s28, 0x80000
	s_addc_u32 s49, s29, 0
	s_add_i32 s47, s44, s31
	s_mov_b32 m0, s47
	s_nop 0
	global_load_lds_dwordx4 v132, s[48:49]
	s_add_i32 m0, s47, 0x2000
	s_nop 0
	global_load_lds_dwordx4 v136, s[48:49]
	s_waitcnt vmcnt(6)
	s_barrier
; #define PG8_STAGE(bufoff, gbase, voff) do { _Pragma("unroll") for (int _i = 0; _i < 2; ++_i) \
;         __builtin_amdgcn_global_load_lds((const unsigned*)((const char*)(gbase) + (voff)[_i]), (LAS unsigned*)(lds + (bufoff) + ldsw + _i * 8192), 16, 0, 0); } while (0)
; #define PG8_LDA(dst, b, h) do { _Pragma("unroll") for (int m = 0; m < 4; ++m) _Pragma("unroll") for (int k = 0; k < 2; ++k) dst[m][k] = *(const LAS bf16x8*)(lds + PG8_SA(b, h) + aoff + m * 2048 + k * 1024); } while (0)
; #define PG8_LDB(dst, b, h) do { _Pragma("unroll") for (int n = 0; n < 2; ++n) _Pragma("unroll") for (int k = 0; k < 2; ++k) dst[n][k] = *(const LAS bf16x8*)(lds + PG8_SB(b, h) + boff + n * 2048 + k * 1024); } while (0)
; #define PG8_MMA(ai, bj, At, Bt) do { __builtin_amdgcn_s_setprio(1); _Pragma("unroll") for (int m = 0; m < 4; ++m) _Pragma("unroll") for (int n = 0; n < 2; ++n) _Pragma("unroll") for (int k = 0; k < 2; ++k) \
;         acc[ai][bj][m][n] = __builtin_amdgcn_mfma_f32_16x16x32_bf16(Bt[n][k], At[m][k], acc[ai][bj][m][n], 0, 0, 0); __builtin_amdgcn_s_setprio(0); } while (0)
; #define PG8_WAIT_V(n) asm volatile("s_waitcnt vmcnt(" #n ")" ::: "memory")
; #define PG8_WAIT_L(n) asm volatile("s_waitcnt lgkmcnt(" #n ")" ::: "memory")
; #define PG8_BAR __builtin_amdgcn_s_barrier()
; #define PG8_SCHED __builtin_amdgcn_sched_barrier(0)
; template <class Sched, class Epi>
; __device__ __forceinline__ void gemm_phase(LAS unsigned char* lds, const Sched& S, const Epi& E, const int K, const int lda, const int ldb) {
;     ...
;             PG8_WAIT_V(6); PG8_BAR; if (!chalf) PG8_MMA(1, 1, At, B1); PG8_BAR;
;             PG8_LDB(B0, 1, 0); PG8_SCHED; PG8_LDA(At, 1, 0); PG8_STAGE(PG8_SA(0, 1), a2 + hstepA, voffA);
;             PG8_WAIT_L(8); PG8_BAR; PG8_WAIT_L(0); PG8_MMA(0, 0, At, B0); PG8_BAR; PG8_SCHED;
;             PG8_LDB(B1, 1, 1); PG8_STAGE(PG8_SB(1, 0), b3, voffB);
;             PG8_BAR; PG8_WAIT_L(0); PG8_MMA(0, 1, At, B1); PG8_BAR;
;             PG8_LDA(At, 1, 1); PG8_STAGE(PG8_SA(1, 0), a3, voffA);
	s_setprio 1
	v_mfma_f32_16x16x32_bf16 v[50:53], v[204:207], v[172:175], v[50:53]
	v_mfma_f32_16x16x32_bf16 v[42:45], v[212:215], v[172:175], v[42:45]
	v_mfma_f32_16x16x32_bf16 v[34:37], v[204:207], v[180:183], v[34:37]
	v_mfma_f32_16x16x32_bf16 v[26:29], v[212:215], v[180:183], v[26:29]
	v_mfma_f32_16x16x32_bf16 v[18:21], v[204:207], v[188:191], v[18:21]
	v_mfma_f32_16x16x32_bf16 v[10:13], v[212:215], v[188:191], v[10:13]
	v_mfma_f32_16x16x32_bf16 v[6:9], v[204:207], v[196:199], v[6:9]
	v_mfma_f32_16x16x32_bf16 v[2:5], v[212:215], v[196:199], v[2:5]
	v_mfma_f32_16x16x32_bf16 v[50:53], v[208:211], v[176:179], v[50:53]
	v_mfma_f32_16x16x32_bf16 v[42:45], v[216:219], v[176:179], v[42:45]
	v_mfma_f32_16x16x32_bf16 v[34:37], v[208:211], v[184:187], v[34:37]
	v_mfma_f32_16x16x32_bf16 v[26:29], v[216:219], v[184:187], v[26:29]
	v_mfma_f32_16x16x32_bf16 v[18:21], v[208:211], v[192:195], v[18:21]
	v_mfma_f32_16x16x32_bf16 v[10:13], v[216:219], v[192:195], v[10:13]
	v_mfma_f32_16x16x32_bf16 v[6:9], v[208:211], v[200:203], v[6:9]
	v_mfma_f32_16x16x32_bf16 v[2:5], v[216:219], v[200:203], v[2:5]
	s_setprio 0
	s_add_i32 s47, 16, 0x18000
	v_add_u32_e32 v168, s47, v144
	s_barrier
	ds_read_b128 v[156:159], v168
	ds_read_b128 v[160:163], v168 offset:1024
	ds_read_b128 v[164:167], v168 offset:2048
	ds_read_b128 v[168:171], v168 offset:3072
	s_add_u32 s34, s34, 0x80000
	s_addc_u32 s35, s35, 0
	s_mov_b32 m0, s36
	ds_read_b128 v[172:175], v154 offset:32768
	ds_read_b128 v[176:179], v154 offset:33792
	ds_read_b128 v[180:183], v154 offset:34816
	ds_read_b128 v[184:187], v154 offset:35840
	ds_read_b128 v[188:191], v154 offset:36864
	ds_read_b128 v[192:195], v154 offset:37888
	ds_read_b128 v[196:199], v154 offset:38912
	ds_read_b128 v[200:203], v154 offset:39936
	global_load_lds_dwordx4 v130, s[34:35]
	s_mov_b32 m0, s37
	s_nop 0
	global_load_lds_dwordx4 v134, s[34:35]
	s_waitcnt lgkmcnt(8)
	s_barrier
	s_waitcnt lgkmcnt(0)
	s_setprio 1
	s_waitcnt lgkmcnt(0)
	v_mfma_f32_16x16x32_bf16 v[126:129], v[156:159], v[172:175], v[126:129]
	v_mfma_f32_16x16x32_bf16 v[122:125], v[164:167], v[172:175], v[122:125]
	v_mfma_f32_16x16x32_bf16 v[114:117], v[156:159], v[180:183], v[114:117]
	v_mfma_f32_16x16x32_bf16 v[106:109], v[164:167], v[180:183], v[106:109]
	v_mfma_f32_16x16x32_bf16 v[98:101], v[156:159], v[188:191], v[98:101]
	v_mfma_f32_16x16x32_bf16 v[90:93], v[164:167], v[188:191], v[90:93]
	v_mfma_f32_16x16x32_bf16 v[82:85], v[156:159], v[196:199], v[82:85]
	v_mfma_f32_16x16x32_bf16 v[74:77], v[164:167], v[196:199], v[74:77]
	v_mfma_f32_16x16x32_bf16 v[126:129], v[160:163], v[176:179], v[126:129]
	v_mfma_f32_16x16x32_bf16 v[122:125], v[168:171], v[176:179], v[122:125]
	v_mfma_f32_16x16x32_bf16 v[114:117], v[160:163], v[184:187], v[114:117]
	v_mfma_f32_16x16x32_bf16 v[106:109], v[168:171], v[184:187], v[106:109]
	v_mfma_f32_16x16x32_bf16 v[98:101], v[160:163], v[192:195], v[98:101]
	v_mfma_f32_16x16x32_bf16 v[90:93], v[168:171], v[192:195], v[90:93]
	v_mfma_f32_16x16x32_bf16 v[82:85], v[160:163], v[200:203], v[82:85]
	v_mfma_f32_16x16x32_bf16 v[74:77], v[168:171], v[200:203], v[74:77]
	s_setprio 0
	s_barrier
	s_add_i32 s34, 16, 0x1c000
	s_add_i32 s35, s47, s31
	v_add_u32_e32 v216, s34, v144
	s_mov_b32 m0, s35
	ds_read_b128 v[204:207], v216
	ds_read_b128 v[208:211], v216 offset:1024
	ds_read_b128 v[212:215], v216 offset:2048
	ds_read_b128 v[216:219], v216 offset:3072
	global_load_lds_dwordx4 v132, s[52:53]
	s_add_i32 m0, s35, 0x2000
	s_nop 0
	global_load_lds_dwordx4 v136, s[54:55]
	s_barrier
	s_waitcnt lgkmcnt(0)
	s_setprio 1
	s_waitcnt lgkmcnt(0)
	v_mfma_f32_16x16x32_bf16 v[118:121], v[204:207], v[172:175], v[118:121]
	v_mfma_f32_16x16x32_bf16 v[110:113], v[212:215], v[172:175], v[110:113]
	v_mfma_f32_16x16x32_bf16 v[102:105], v[204:207], v[180:183], v[102:105]
	v_mfma_f32_16x16x32_bf16 v[94:97], v[212:215], v[180:183], v[94:97]
	v_mfma_f32_16x16x32_bf16 v[86:89], v[204:207], v[188:191], v[86:89]
	v_mfma_f32_16x16x32_bf16 v[78:81], v[212:215], v[188:191], v[78:81]
	v_mfma_f32_16x16x32_bf16 v[70:73], v[204:207], v[196:199], v[70:73]
	v_mfma_f32_16x16x32_bf16 v[66:69], v[212:215], v[196:199], v[66:69]
	v_mfma_f32_16x16x32_bf16 v[118:121], v[208:211], v[176:179], v[118:121]
	v_mfma_f32_16x16x32_bf16 v[110:113], v[216:219], v[176:179], v[110:113]
	v_mfma_f32_16x16x32_bf16 v[102:105], v[208:211], v[184:187], v[102:105]
	v_mfma_f32_16x16x32_bf16 v[94:97], v[216:219], v[184:187], v[94:97]
	v_mfma_f32_16x16x32_bf16 v[86:89], v[208:211], v[192:195], v[86:89]
	v_mfma_f32_16x16x32_bf16 v[78:81], v[216:219], v[192:195], v[78:81]
	v_mfma_f32_16x16x32_bf16 v[70:73], v[208:211], v[200:203], v[70:73]
	v_mfma_f32_16x16x32_bf16 v[66:69], v[216:219], v[200:203], v[66:69]
	s_setprio 0
	s_mov_b32 m0, s39
	s_barrier
	ds_read_b128 v[172:175], v154 offset:49152
	ds_read_b128 v[176:179], v154 offset:50176
	ds_read_b128 v[180:183], v154 offset:51200
	ds_read_b128 v[184:187], v154 offset:52224
	ds_read_b128 v[188:191], v154 offset:53248
	ds_read_b128 v[192:195], v154 offset:54272
	ds_read_b128 v[196:199], v154 offset:55296
	ds_read_b128 v[200:203], v154 offset:56320
	global_load_lds_dwordx4 v130, s[56:57]
	s_mov_b32 m0, s40
	s_nop 0
	global_load_lds_dwordx4 v134, s[58:59]
	s_barrier
; #define PG8_STAGE(bufoff, gbase, voff) do { _Pragma("unroll") for (int _i = 0; _i < 2; ++_i) \
;         __builtin_amdgcn_global_load_lds((const unsigned*)((const char*)(gbase) + (voff)[_i]), (LAS unsigned*)(lds + (bufoff) + ldsw + _i * 8192), 16, 0, 0); } while (0)
; #define PG8_LDA(dst, b, h) do { _Pragma("unroll") for (int m = 0; m < 4; ++m) _Pragma("unroll") for (int k = 0; k < 2; ++k) dst[m][k] = *(const LAS bf16x8*)(lds + PG8_SA(b, h) + aoff + m * 2048 + k * 1024); } while (0)
; #define PG8_MMA(ai, bj, At, Bt) do { __builtin_amdgcn_s_setprio(1); _Pragma("unroll") for (int m = 0; m < 4; ++m) _Pragma("unroll") for (int n = 0; n < 2; ++n) _Pragma("unroll") for (int k = 0; k < 2; ++k) \
;         acc[ai][bj][m][n] = __builtin_amdgcn_mfma_f32_16x16x32_bf16(Bt[n][k], At[m][k], acc[ai][bj][m][n], 0, 0, 0); __builtin_amdgcn_s_setprio(0); } while (0)
; #define PG8_WAIT_V(n) asm volatile("s_waitcnt vmcnt(" #n ")" ::: "memory")
; #define PG8_WAIT_L(n) asm volatile("s_waitcnt lgkmcnt(" #n ")" ::: "memory")
; #define PG8_BAR __builtin_amdgcn_s_barrier()
; #define PG8_SCHED __builtin_amdgcn_sched_barrier(0)
; template <class Sched, class Epi>
; __device__ __forceinline__ void gemm_phase(LAS unsigned char* lds, const Sched& S, const Epi& E, const int K, const int lda, const int ldb) {
;     ...
;             PG8_LDA(At, 1, 1); PG8_STAGE(PG8_SA(1, 0), a3, voffA);
;             PG8_BAR; PG8_WAIT_L(0); if (!chalf) PG8_MMA(1, 0, At, B0); PG8_BAR; PG8_SCHED;
;             PG8_STAGE(PG8_SB(1, 1), b3 + hstepB, voffB);
;             PG8_WAIT_V(6); PG8_BAR; if (!chalf) PG8_MMA(1, 1, At, B1); PG8_BAR;
	s_waitcnt lgkmcnt(0)
	s_setprio 1
	s_waitcnt lgkmcnt(0)
	v_mfma_f32_16x16x32_bf16 v[62:65], v[156:159], v[172:175], v[62:65]
	v_mfma_f32_16x16x32_bf16 v[58:61], v[164:167], v[172:175], v[58:61]
	v_mfma_f32_16x16x32_bf16 v[54:57], v[156:159], v[180:183], v[54:57]
	v_mfma_f32_16x16x32_bf16 v[46:49], v[164:167], v[180:183], v[46:49]
	v_mfma_f32_16x16x32_bf16 v[38:41], v[156:159], v[188:191], v[38:41]
	v_mfma_f32_16x16x32_bf16 v[30:33], v[164:167], v[188:191], v[30:33]
	v_mfma_f32_16x16x32_bf16 v[22:25], v[156:159], v[196:199], v[22:25]
	v_mfma_f32_16x16x32_bf16 v[14:17], v[164:167], v[196:199], v[14:17]
	v_mfma_f32_16x16x32_bf16 v[62:65], v[160:163], v[176:179], v[62:65]
	v_mfma_f32_16x16x32_bf16 v[58:61], v[168:171], v[176:179], v[58:61]
	v_mfma_f32_16x16x32_bf16 v[54:57], v[160:163], v[184:187], v[54:57]
	v_mfma_f32_16x16x32_bf16 v[46:49], v[168:171], v[184:187], v[46:49]
	v_mfma_f32_16x16x32_bf16 v[38:41], v[160:163], v[192:195], v[38:41]
	v_mfma_f32_16x16x32_bf16 v[30:33], v[168:171], v[192:195], v[30:33]
	v_mfma_f32_16x16x32_bf16 v[22:25], v[160:163], v[200:203], v[22:25]
	v_mfma_f32_16x16x32_bf16 v[14:17], v[168:171], v[200:203], v[14:17]
	s_setprio 0
	s_barrier
	s_add_u32 s28, s28, 0x80080
	s_addc_u32 s29, s29, 0
	s_add_i32 s34, s34, s31
	s_mov_b32 m0, s34
	s_nop 0
	global_load_lds_dwordx4 v132, s[28:29]
	s_add_i32 m0, s34, 0x2000
	s_nop 0
	global_load_lds_dwordx4 v136, s[28:29]
	s_waitcnt vmcnt(6)
	s_barrier
	s_setprio 1
	v_mfma_f32_16x16x32_bf16 v[50:53], v[204:207], v[172:175], v[50:53]
	v_mfma_f32_16x16x32_bf16 v[42:45], v[212:215], v[172:175], v[42:45]
	v_mfma_f32_16x16x32_bf16 v[34:37], v[204:207], v[180:183], v[34:37]
	v_mfma_f32_16x16x32_bf16 v[26:29], v[212:215], v[180:183], v[26:29]
	v_mfma_f32_16x16x32_bf16 v[18:21], v[204:207], v[188:191], v[18:21]
	v_mfma_f32_16x16x32_bf16 v[10:13], v[212:215], v[188:191], v[10:13]
	v_mfma_f32_16x16x32_bf16 v[6:9], v[204:207], v[196:199], v[6:9]
	v_mfma_f32_16x16x32_bf16 v[2:5], v[212:215], v[196:199], v[2:5]
	v_mfma_f32_16x16x32_bf16 v[50:53], v[208:211], v[176:179], v[50:53]
	v_mfma_f32_16x16x32_bf16 v[42:45], v[216:219], v[176:179], v[42:45]
	v_mfma_f32_16x16x32_bf16 v[34:37], v[208:211], v[184:187], v[34:37]
	v_mfma_f32_16x16x32_bf16 v[26:29], v[216:219], v[184:187], v[26:29]
	v_mfma_f32_16x16x32_bf16 v[18:21], v[208:211], v[192:195], v[18:21]
	v_mfma_f32_16x16x32_bf16 v[10:13], v[216:219], v[192:195], v[10:13]
	v_mfma_f32_16x16x32_bf16 v[6:9], v[208:211], v[200:203], v[6:9]
	v_mfma_f32_16x16x32_bf16 v[2:5], v[216:219], v[200:203], v[2:5]
	s_setprio 0
	s_add_i32 s46, s46, 2
	s_add_u32 s15, s15, 0x100
	s_addc_u32 s17, s17, 0
	s_add_u32 s26, s26, 0x100
	s_addc_u32 s27, s27, 0
	s_cmp_gt_u32 s46, 29
	s_barrier
	s_cbranch_scc0 .LBB0_1593
; __device__ __forceinline__ unsigned cvt_pk_bf16(float lo, float hi) { unsigned r; asm volatile("v_cvt_pk_bf16_f32 %0, %1, %2" : "=v"(r) : "v"(lo), "v"(hi)); return r; }
; #define PG8_WAIT_V(n) asm volatile("s_waitcnt vmcnt(" #n ")" ::: "memory")
; #define PG8_BAR __builtin_amdgcn_s_barrier()
; #define EPI_FOR_ROWS _Pragma("unroll") for (int ai = 0; ai < 2; ++ai) if (ai == 0 || !u.half) _Pragma("unroll") for (int m = 0; m < 4; ++m)
; template <class Sched, class Epi>
; __device__ __forceinline__ void gemm_phase(LAS unsigned char* lds, const Sched& S, const Epi& E, const int K, const int lda, const int ldb) {
;     ...
;     PG8_WAIT_V(0);
;     if (wr == 0) PG8_BAR;
;     PG8_BAR;
;     __device__ __forceinline__ void operator()(EPI_ARGS) const {
;         EPI_FOR_ROWS { bf16_t* rp = O + (size_t)EPI_ROW * ldc;
; #pragma unroll
;             for (int bj = 0; bj < 2; ++bj) { const f32x4 v0 = acc[ai][bj][m][0], v1 = acc[ai][bj][m][1]; u32x4 o;
;                 o[0] = cvt_pk_bf16(v0[0], v0[1]); o[1] = cvt_pk_bf16(v0[2], v0[3]); o[2] = cvt_pk_bf16(v1[0], v1[1]); o[3] = cvt_pk_bf16(v1[2], v1[3]);
;                 *(u32x4*)(rp + EPI_COL(bj)) = o; } }
	v_add_u32_e32 v156, s4, v1
	v_ashrrev_i32_e32 v157, 31, v156
	v_cvt_pk_bf16_f32 v126, v126, v127
	v_cvt_pk_bf16_f32 v127, v128, v129
	v_cvt_pk_bf16_f32 v128, v122, v123
	v_lshl_or_b32 v122, s45, 8, v152
	v_lshlrev_b64 v[156:157], 12, v[156:157]
	v_ashrrev_i32_e32 v123, 31, v122
	v_lshl_add_u64 v[156:157], s[6:7], 0, v[156:157]
	v_lshlrev_b64 v[122:123], 1, v[122:123]
	v_cvt_pk_bf16_f32 v129, v124, v125
	v_lshl_add_u64 v[124:125], v[156:157], 0, v[122:123]
	global_store_dwordx4 v[124:125], v[126:129], off
	v_cvt_pk_bf16_f32 v118, v118, v119
	v_cvt_pk_bf16_f32 v119, v120, v121
	v_cvt_pk_bf16_f32 v120, v110, v111
	v_add_u32_e32 v110, s4, v145
	v_ashrrev_i32_e32 v111, 31, v110
	v_lshlrev_b64 v[110:111], 12, v[110:111]
	v_cvt_pk_bf16_f32 v121, v112, v113
	global_store_dwordx4 v[124:125], v[118:121], off offset:256
	s_and_b64 vcc, exec, s[12:13]
	s_mov_b32 s45, s14
	v_lshl_add_u64 v[118:119], s[6:7], 0, v[110:111]
	v_cvt_pk_bf16_f32 v110, v114, v115
	v_cvt_pk_bf16_f32 v111, v116, v117
	v_cvt_pk_bf16_f32 v112, v106, v107
	v_lshl_add_u64 v[106:107], v[118:119], 0, v[122:123]
	v_cvt_pk_bf16_f32 v113, v108, v109
	global_store_dwordx4 v[106:107], v[110:113], off
	v_cvt_pk_bf16_f32 v102, v102, v103
	v_cvt_pk_bf16_f32 v103, v104, v105
	v_cvt_pk_bf16_f32 v104, v94, v95
	v_add_u32_e32 v94, s4, v146
	v_ashrrev_i32_e32 v95, 31, v94
	v_lshlrev_b64 v[94:95], 12, v[94:95]
	v_cvt_pk_bf16_f32 v105, v96, v97
	global_store_dwordx4 v[106:107], v[102:105], off offset:256
	s_mov_b64 s[28:29], s[20:21]
	s_mov_b64 s[26:27], s[18:19]
	v_lshl_add_u64 v[102:103], s[6:7], 0, v[94:95]
	v_cvt_pk_bf16_f32 v94, v98, v99
	v_cvt_pk_bf16_f32 v95, v100, v101
	v_cvt_pk_bf16_f32 v96, v90, v91
	v_lshl_add_u64 v[90:91], v[102:103], 0, v[122:123]
	v_cvt_pk_bf16_f32 v97, v92, v93
	global_store_dwordx4 v[90:91], v[94:97], off
	v_cvt_pk_bf16_f32 v86, v86, v87
	v_cvt_pk_bf16_f32 v87, v88, v89
	v_cvt_pk_bf16_f32 v88, v78, v79
	v_add_u32_e32 v78, s4, v147
	v_ashrrev_i32_e32 v79, 31, v78
	v_lshlrev_b64 v[78:79], 12, v[78:79]
	v_cvt_pk_bf16_f32 v89, v80, v81
	global_store_dwordx4 v[90:91], v[86:89], off offset:256
	s_nop 1
	v_lshl_add_u64 v[86:87], s[6:7], 0, v[78:79]
	v_cvt_pk_bf16_f32 v78, v82, v83
	v_cvt_pk_bf16_f32 v79, v84, v85
	v_cvt_pk_bf16_f32 v80, v74, v75
	v_lshl_add_u64 v[74:75], v[86:87], 0, v[122:123]
	v_cvt_pk_bf16_f32 v81, v76, v77
	global_store_dwordx4 v[74:75], v[78:81], off
	v_cvt_pk_bf16_f32 v70, v70, v71
	v_cvt_pk_bf16_f32 v71, v72, v73
	v_cvt_pk_bf16_f32 v72, v66, v67
	v_add_u32_e32 v66, s4, v148
	v_ashrrev_i32_e32 v67, 31, v66
	v_lshlrev_b64 v[66:67], 12, v[66:67]
	v_lshl_add_u64 v[66:67], s[6:7], 0, v[66:67]
	v_cvt_pk_bf16_f32 v73, v68, v69
	global_store_dwordx4 v[74:75], v[70:73], off offset:256
	v_cvt_pk_bf16_f32 v62, v62, v63
	v_cvt_pk_bf16_f32 v63, v64, v65
	v_cvt_pk_bf16_f32 v64, v58, v59
	v_lshl_add_u64 v[58:59], v[66:67], 0, v[122:123]
	v_cvt_pk_bf16_f32 v65, v60, v61
	global_store_dwordx4 v[58:59], v[62:65], off
	v_cvt_pk_bf16_f32 v50, v50, v51
	v_cvt_pk_bf16_f32 v51, v52, v53
	v_cvt_pk_bf16_f32 v52, v42, v43
	v_add_u32_e32 v42, s4, v149
	v_ashrrev_i32_e32 v43, 31, v42
	v_lshlrev_b64 v[42:43], 12, v[42:43]
	v_cvt_pk_bf16_f32 v53, v44, v45
	global_store_dwordx4 v[58:59], v[50:53], off offset:256
	s_nop 1
	v_lshl_add_u64 v[50:51], s[6:7], 0, v[42:43]
	v_cvt_pk_bf16_f32 v42, v54, v55
	v_cvt_pk_bf16_f32 v43, v56, v57
	v_cvt_pk_bf16_f32 v44, v46, v47
	v_lshl_add_u64 v[46:47], v[50:51], 0, v[122:123]
	v_cvt_pk_bf16_f32 v45, v48, v49
	global_store_dwordx4 v[46:47], v[42:45], off
	v_cvt_pk_bf16_f32 v34, v34, v35
	v_cvt_pk_bf16_f32 v35, v36, v37
	v_cvt_pk_bf16_f32 v36, v26, v27
	v_add_u32_e32 v26, s4, v150
	v_ashrrev_i32_e32 v27, 31, v26
	v_lshlrev_b64 v[26:27], 12, v[26:27]
	v_cvt_pk_bf16_f32 v37, v28, v29
	global_store_dwordx4 v[46:47], v[34:37], off offset:256
	s_nop 1
	v_lshl_add_u64 v[34:35], s[6:7], 0, v[26:27]
	v_cvt_pk_bf16_f32 v26, v38, v39
	v_cvt_pk_bf16_f32 v27, v40, v41
	v_cvt_pk_bf16_f32 v28, v30, v31
	v_lshl_add_u64 v[30:31], v[34:35], 0, v[122:123]
	v_cvt_pk_bf16_f32 v29, v32, v33
	global_store_dwordx4 v[30:31], v[26:29], off
	v_cvt_pk_bf16_f32 v18, v18, v19
	v_cvt_pk_bf16_f32 v19, v20, v21
	v_cvt_pk_bf16_f32 v20, v10, v11
	v_add_u32_e32 v10, s4, v151
	v_ashrrev_i32_e32 v11, 31, v10
	v_lshlrev_b64 v[10:11], 12, v[10:11]
	v_cvt_pk_bf16_f32 v21, v12, v13
	global_store_dwordx4 v[30:31], v[18:21], off offset:256
	s_mov_b32 s4, s16
	s_nop 0
	v_lshl_add_u64 v[18:19], s[6:7], 0, v[10:11]
	v_cvt_pk_bf16_f32 v10, v22, v23
	v_cvt_pk_bf16_f32 v11, v24, v25
	v_cvt_pk_bf16_f32 v12, v14, v15
	v_lshl_add_u64 v[14:15], v[18:19], 0, v[122:123]
	v_cvt_pk_bf16_f32 v13, v16, v17
	global_store_dwordx4 v[14:15], v[10:13], off
	v_cvt_pk_bf16_f32 v6, v6, v7
	v_cvt_pk_bf16_f32 v7, v8, v9
	v_cvt_pk_bf16_f32 v8, v2, v3
	v_cvt_pk_bf16_f32 v9, v4, v5
	global_store_dwordx4 v[14:15], v[6:9], off offset:256
	s_cbranch_vccz .LBB0_1586
	s_waitcnt vmcnt(0)
	s_cmpk_gt_u32 s1, 0xff
	s_cbranch_scc1 .LBB0_1597
	s_barrier
